# v27 + each MFMA burst's closing s_barrier moved up 2 MFMAs with s_setprio 2 before it
# speedup vs baseline: 1.0152x; 1.0041x over previous
.LBB0_379:
	v_add_u32_e32 v14, s56, v140
	v_add_u32_e32 v30, s57, v140
	ds_read_b128 v[2:5], v14
	ds_read_b128 v[6:9], v14 offset:1024
	ds_read_b128 v[10:13], v14 offset:2048
	ds_read_b128 v[14:17], v14 offset:3072
	ds_read_b128 v[18:21], v30
	ds_read_b128 v[22:25], v30 offset:1024
	ds_read_b128 v[26:29], v30 offset:2048
	ds_read_b128 v[30:33], v30 offset:3072
	v_add_u32_e32 v141, 0, v1
	ds_read_b128 v[34:37], v141
	ds_read_b128 v[38:41], v141 offset:1024
	ds_read_b128 v[42:45], v141 offset:2048
	ds_read_b128 v[46:49], v141 offset:3072
	ds_read_b128 v[50:53], v141 offset:4096
	ds_read_b128 v[54:57], v141 offset:5120
	ds_read_b128 v[58:61], v141 offset:6144
	ds_read_b128 v[62:65], v141 offset:7168
	s_waitcnt vmcnt(8)
	s_waitcnt lgkmcnt(0)
	s_barrier
	s_setprio 1
	s_waitcnt lgkmcnt(0)
	v_mfma_f32_16x16x32_bf16 v[66:69], v[2:5], v[34:37], 0
	v_mfma_f32_16x16x32_bf16 v[66:69], v[6:9], v[38:41], v[66:69]
	v_mfma_f32_16x16x32_bf16 v[70:73], v[10:13], v[34:37], 0
	v_mfma_f32_16x16x32_bf16 v[70:73], v[14:17], v[38:41], v[70:73]
	v_mfma_f32_16x16x32_bf16 v[78:81], v[10:13], v[42:45], 0
	v_mfma_f32_16x16x32_bf16 v[78:81], v[14:17], v[46:49], v[78:81]
	v_mfma_f32_16x16x32_bf16 v[74:77], v[2:5], v[42:45], 0
	v_mfma_f32_16x16x32_bf16 v[74:77], v[6:9], v[46:49], v[74:77]
	v_mfma_f32_16x16x32_bf16 v[82:85], v[2:5], v[50:53], 0
	v_mfma_f32_16x16x32_bf16 v[82:85], v[6:9], v[54:57], v[82:85]
	v_mfma_f32_16x16x32_bf16 v[86:89], v[10:13], v[50:53], 0
	v_mfma_f32_16x16x32_bf16 v[86:89], v[14:17], v[54:57], v[86:89]
	v_mfma_f32_16x16x32_bf16 v[94:97], v[10:13], v[58:61], 0
	v_mfma_f32_16x16x32_bf16 v[94:97], v[14:17], v[62:65], v[94:97]
	v_mfma_f32_16x16x32_bf16 v[90:93], v[2:5], v[58:61], 0
	v_mfma_f32_16x16x32_bf16 v[90:93], v[6:9], v[62:65], v[90:93]
	s_setprio 0
	s_setprio 1
	v_mfma_f32_16x16x32_bf16 v[98:101], v[18:21], v[34:37], 0
	v_mfma_f32_16x16x32_bf16 v[34:37], v[26:29], v[34:37], 0
	v_mfma_f32_16x16x32_bf16 v[102:105], v[18:21], v[42:45], 0
	v_mfma_f32_16x16x32_bf16 v[42:45], v[26:29], v[42:45], 0
	v_mfma_f32_16x16x32_bf16 v[106:109], v[18:21], v[50:53], 0
	v_mfma_f32_16x16x32_bf16 v[50:53], v[26:29], v[50:53], 0
	v_mfma_f32_16x16x32_bf16 v[110:113], v[18:21], v[58:61], 0
	v_mfma_f32_16x16x32_bf16 v[58:61], v[26:29], v[58:61], 0
	v_mfma_f32_16x16x32_bf16 v[98:101], v[22:25], v[38:41], v[98:101]
	v_mfma_f32_16x16x32_bf16 v[38:41], v[30:33], v[38:41], v[34:37]
	v_mfma_f32_16x16x32_bf16 v[102:105], v[22:25], v[46:49], v[102:105]
	v_mfma_f32_16x16x32_bf16 v[46:49], v[30:33], v[46:49], v[42:45]
	v_mfma_f32_16x16x32_bf16 v[106:109], v[22:25], v[54:57], v[106:109]
	v_mfma_f32_16x16x32_bf16 v[54:57], v[30:33], v[54:57], v[50:53]
	s_setprio 2
	s_barrier
	v_mfma_f32_16x16x32_bf16 v[110:113], v[22:25], v[62:65], v[110:113]
	v_mfma_f32_16x16x32_bf16 v[62:65], v[30:33], v[62:65], v[58:61]
	s_setprio 0
	v_lshl_add_u64 v[136:137], s[38:39], 0, v[130:131]
	s_add_i32 s60, s56, s21
	v_mov_b32_e32 v135, v131
	v_lshl_add_u64 v[142:143], v[136:137], 0, s[10:11]
	s_mov_b32 m0, s60
	v_lshl_add_u64 v[244:245], s[38:39], 0, v[134:135]
	ds_read_b128 v[34:37], v141 offset:16384
	ds_read_b128 v[42:45], v141 offset:17408
	ds_read_b128 v[50:53], v141 offset:18432
	ds_read_b128 v[58:61], v141 offset:19456
	ds_read_b128 v[114:117], v141 offset:20480
	ds_read_b128 v[118:121], v141 offset:21504
	ds_read_b128 v[122:125], v141 offset:22528
	ds_read_b128 v[126:129], v141 offset:23552
	global_load_lds_dwordx4 v[142:143], off
	v_lshl_add_u64 v[142:143], v[244:245], 0, s[10:11]
	s_add_i32 m0, s60, 0x2000
	s_add_i32 s60, s57, s21
	global_load_lds_dwordx4 v[142:143], off
	s_mov_b32 m0, s60
	v_mov_b32_e32 v139, v131
	global_load_lds_dwordx4 v130, s[40:41]
	s_add_i32 m0, s60, 0x2000
	v_lshl_add_u64 v[246:247], s[36:37], 0, v[138:139]
	v_mov_b32_e32 v133, v131
	global_load_lds_dwordx4 v134, s[40:41]
	v_lshl_add_u64 v[142:143], v[246:247], 0, s[10:11]
	s_mov_b32 m0, s33
	v_lshl_add_u64 v[248:249], s[36:37], 0, v[132:133]
	global_load_lds_dwordx4 v[142:143], off
	v_lshl_add_u64 v[142:143], v[248:249], 0, s[10:11]
	s_mov_b32 m0, s46
	s_nop 0
	global_load_lds_dwordx4 v[142:143], off
	s_waitcnt vmcnt(8)
	s_waitcnt lgkmcnt(0)
	s_barrier
	s_setprio 1
	s_waitcnt lgkmcnt(0)
	v_mfma_f32_16x16x32_bf16 v[142:145], v[2:5], v[34:37], 0
	v_mfma_f32_16x16x32_bf16 v[148:151], v[10:13], v[34:37], 0
	v_mfma_f32_16x16x32_bf16 v[152:155], v[2:5], v[50:53], 0
	v_mfma_f32_16x16x32_bf16 v[156:159], v[10:13], v[50:53], 0
	v_mfma_f32_16x16x32_bf16 v[160:163], v[2:5], v[114:117], 0
	v_mfma_f32_16x16x32_bf16 v[164:167], v[10:13], v[114:117], 0
	v_mfma_f32_16x16x32_bf16 v[2:5], v[2:5], v[122:125], 0
	v_mfma_f32_16x16x32_bf16 v[10:13], v[10:13], v[122:125], 0
	v_mfma_f32_16x16x32_bf16 v[142:145], v[6:9], v[42:45], v[142:145]
	v_mfma_f32_16x16x32_bf16 v[148:151], v[14:17], v[42:45], v[148:151]
	v_mfma_f32_16x16x32_bf16 v[152:155], v[6:9], v[58:61], v[152:155]
	v_mfma_f32_16x16x32_bf16 v[156:159], v[14:17], v[58:61], v[156:159]
	v_mfma_f32_16x16x32_bf16 v[160:163], v[6:9], v[118:121], v[160:163]
	v_mfma_f32_16x16x32_bf16 v[164:167], v[14:17], v[118:121], v[164:167]
	v_mfma_f32_16x16x32_bf16 v[168:171], v[6:9], v[126:129], v[2:5]
	v_mfma_f32_16x16x32_bf16 v[172:175], v[14:17], v[126:129], v[10:13]
	s_setprio 0
	s_setprio 1
	v_mfma_f32_16x16x32_bf16 v[2:5], v[18:21], v[34:37], 0
	v_mfma_f32_16x16x32_bf16 v[6:9], v[26:29], v[34:37], 0
	v_mfma_f32_16x16x32_bf16 v[10:13], v[18:21], v[50:53], 0
	v_mfma_f32_16x16x32_bf16 v[14:17], v[26:29], v[50:53], 0
	v_mfma_f32_16x16x32_bf16 v[34:37], v[18:21], v[114:117], 0
	v_mfma_f32_16x16x32_bf16 v[50:53], v[26:29], v[114:117], 0
	v_mfma_f32_16x16x32_bf16 v[18:21], v[18:21], v[122:125], 0
	v_mfma_f32_16x16x32_bf16 v[26:29], v[26:29], v[122:125], 0
	v_mfma_f32_16x16x32_bf16 v[114:117], v[22:25], v[42:45], v[2:5]
	v_mfma_f32_16x16x32_bf16 v[188:191], v[22:25], v[118:121], v[34:37]
	v_mfma_f32_16x16x32_bf16 v[118:121], v[30:33], v[118:121], v[50:53]
	v_mfma_f32_16x16x32_bf16 v[176:179], v[30:33], v[42:45], v[6:9]
	v_mfma_f32_16x16x32_bf16 v[180:183], v[22:25], v[58:61], v[10:13]
	v_mfma_f32_16x16x32_bf16 v[184:187], v[30:33], v[58:61], v[14:17]
	s_setprio 2
	s_barrier
	v_mfma_f32_16x16x32_bf16 v[192:195], v[22:25], v[126:129], v[18:21]
	v_mfma_f32_16x16x32_bf16 v[196:199], v[30:33], v[126:129], v[26:29]
	s_setprio 0
	s_add_i32 s60, 0, 0x18000
	v_add_u32_e32 v2, s60, v140
	s_add_i32 s61, 0, 0x1c000
	ds_read_b128 v[200:203], v2
	ds_read_b128 v[204:207], v2 offset:1024
	ds_read_b128 v[208:211], v2 offset:2048
	ds_read_b128 v[212:215], v2 offset:3072
	v_add_u32_e32 v2, s61, v140
	ds_read_b128 v[216:219], v2
	ds_read_b128 v[220:223], v2 offset:1024
	ds_read_b128 v[224:227], v2 offset:2048
	ds_read_b128 v[228:231], v2 offset:3072
	s_mov_b32 m0, s47
	ds_read_b128 v[42:45], v141 offset:32768
	ds_read_b128 v[50:53], v141 offset:33792
	ds_read_b128 v[58:61], v141 offset:34816
	ds_read_b128 v[122:125], v141 offset:35840
	ds_read_b128 v[126:129], v141 offset:36864
	ds_read_b128 v[232:235], v141 offset:37888
	ds_read_b128 v[236:239], v141 offset:38912
	ds_read_b128 v[240:243], v141 offset:39936
	global_load_lds_dwordx4 v138, s[42:43]
	s_mov_b32 m0, s48
	s_nop 0
	global_load_lds_dwordx4 v132, s[42:43]
	s_waitcnt vmcnt(8)
	s_waitcnt lgkmcnt(0)
	s_barrier
	s_setprio 1
	s_waitcnt lgkmcnt(0)
	v_mfma_f32_16x16x32_bf16 v[2:5], v[200:203], v[42:45], v[66:69]
	v_mfma_f32_16x16x32_bf16 v[6:9], v[208:211], v[42:45], v[70:73]
	v_mfma_f32_16x16x32_bf16 v[10:13], v[200:203], v[58:61], v[74:77]
	v_mfma_f32_16x16x32_bf16 v[14:17], v[208:211], v[58:61], v[78:81]
	v_mfma_f32_16x16x32_bf16 v[18:21], v[200:203], v[126:129], v[82:85]
	v_mfma_f32_16x16x32_bf16 v[22:25], v[208:211], v[126:129], v[86:89]
	v_mfma_f32_16x16x32_bf16 v[26:29], v[200:203], v[236:239], v[90:93]
	v_mfma_f32_16x16x32_bf16 v[30:33], v[208:211], v[236:239], v[94:97]
	v_mfma_f32_16x16x32_bf16 v[2:5], v[204:207], v[50:53], v[2:5]
	v_mfma_f32_16x16x32_bf16 v[6:9], v[212:215], v[50:53], v[6:9]
	v_mfma_f32_16x16x32_bf16 v[10:13], v[204:207], v[122:125], v[10:13]
	v_mfma_f32_16x16x32_bf16 v[14:17], v[212:215], v[122:125], v[14:17]
	v_mfma_f32_16x16x32_bf16 v[18:21], v[204:207], v[232:235], v[18:21]
	v_mfma_f32_16x16x32_bf16 v[22:25], v[212:215], v[232:235], v[22:25]
	v_mfma_f32_16x16x32_bf16 v[26:29], v[204:207], v[240:243], v[26:29]
	v_mfma_f32_16x16x32_bf16 v[30:33], v[212:215], v[240:243], v[30:33]
	s_setprio 0
	s_setprio 1
	v_mfma_f32_16x16x32_bf16 v[34:37], v[216:219], v[42:45], v[98:101]
	v_mfma_f32_16x16x32_bf16 v[38:41], v[224:227], v[42:45], v[38:41]
	v_mfma_f32_16x16x32_bf16 v[34:37], v[220:223], v[50:53], v[34:37]
	v_mfma_f32_16x16x32_bf16 v[38:41], v[228:231], v[50:53], v[38:41]
	v_mfma_f32_16x16x32_bf16 v[42:45], v[216:219], v[58:61], v[102:105]
	v_mfma_f32_16x16x32_bf16 v[46:49], v[224:227], v[58:61], v[46:49]
	v_mfma_f32_16x16x32_bf16 v[50:53], v[216:219], v[126:129], v[106:109]
	v_mfma_f32_16x16x32_bf16 v[54:57], v[224:227], v[126:129], v[54:57]
	v_mfma_f32_16x16x32_bf16 v[58:61], v[216:219], v[236:239], v[110:113]
	v_mfma_f32_16x16x32_bf16 v[62:65], v[224:227], v[236:239], v[62:65]
	v_mfma_f32_16x16x32_bf16 v[42:45], v[220:223], v[122:125], v[42:45]
	v_mfma_f32_16x16x32_bf16 v[46:49], v[228:231], v[122:125], v[46:49]
	v_mfma_f32_16x16x32_bf16 v[50:53], v[220:223], v[232:235], v[50:53]
	v_mfma_f32_16x16x32_bf16 v[54:57], v[228:231], v[232:235], v[54:57]
	s_setprio 2
	s_barrier
	v_mfma_f32_16x16x32_bf16 v[58:61], v[220:223], v[240:243], v[58:61]
	v_mfma_f32_16x16x32_bf16 v[62:65], v[228:231], v[240:243], v[62:65]
	s_setprio 0
	s_add_i32 s60, s60, s21
	v_lshl_add_u64 v[66:67], v[136:137], 0, s[12:13]
	s_mov_b32 m0, s60
	ds_read_b128 v[94:97], v141 offset:49152
	ds_read_b128 v[98:101], v141 offset:50176
	ds_read_b128 v[102:105], v141 offset:51200
	ds_read_b128 v[106:109], v141 offset:52224
	ds_read_b128 v[110:113], v141 offset:53248
	ds_read_b128 v[232:235], v141 offset:54272
	ds_read_b128 v[236:239], v141 offset:55296
	ds_read_b128 v[240:243], v141 offset:56320
	global_load_lds_dwordx4 v[66:67], off
	v_lshl_add_u64 v[66:67], v[244:245], 0, s[12:13]
	s_add_i32 m0, s60, 0x2000
	s_add_i32 s60, s61, s21
	global_load_lds_dwordx4 v[66:67], off
	s_mov_b32 m0, s60
	v_lshl_add_u64 v[66:67], v[246:247], 0, s[12:13]
	global_load_lds_dwordx4 v130, s[44:45]
	s_add_i32 m0, s60, 0x2000
	s_nop 0
	global_load_lds_dwordx4 v134, s[44:45]
	s_mov_b32 m0, s52
	s_nop 0
	global_load_lds_dwordx4 v[66:67], off
	v_lshl_add_u64 v[66:67], v[248:249], 0, s[12:13]
	s_mov_b32 m0, s53
	s_nop 0
	global_load_lds_dwordx4 v[66:67], off
	s_waitcnt vmcnt(8)
	s_waitcnt lgkmcnt(0)
	s_barrier
	s_setprio 1
	s_waitcnt lgkmcnt(0)
	v_mfma_f32_16x16x32_bf16 v[66:69], v[200:203], v[94:97], v[142:145]
	v_mfma_f32_16x16x32_bf16 v[122:125], v[204:207], v[98:101], v[66:69]
	v_mfma_f32_16x16x32_bf16 v[66:69], v[208:211], v[94:97], v[148:151]
	v_mfma_f32_16x16x32_bf16 v[126:129], v[212:215], v[98:101], v[66:69]
	v_mfma_f32_16x16x32_bf16 v[66:69], v[200:203], v[102:105], v[152:155]
	v_mfma_f32_16x16x32_bf16 v[70:73], v[208:211], v[102:105], v[156:159]
	v_mfma_f32_16x16x32_bf16 v[74:77], v[200:203], v[110:113], v[160:163]
	v_mfma_f32_16x16x32_bf16 v[78:81], v[208:211], v[110:113], v[164:167]
	v_mfma_f32_16x16x32_bf16 v[82:85], v[200:203], v[236:239], v[168:171]
	v_mfma_f32_16x16x32_bf16 v[86:89], v[208:211], v[236:239], v[172:175]
	v_mfma_f32_16x16x32_bf16 v[66:69], v[204:207], v[106:109], v[66:69]
	v_mfma_f32_16x16x32_bf16 v[70:73], v[212:215], v[106:109], v[70:73]
	v_mfma_f32_16x16x32_bf16 v[74:77], v[204:207], v[232:235], v[74:77]
	v_mfma_f32_16x16x32_bf16 v[78:81], v[212:215], v[232:235], v[78:81]
	v_mfma_f32_16x16x32_bf16 v[82:85], v[204:207], v[240:243], v[82:85]
	v_mfma_f32_16x16x32_bf16 v[86:89], v[212:215], v[240:243], v[86:89]
	s_setprio 0
	s_setprio 1
	v_mfma_f32_16x16x32_bf16 v[90:93], v[216:219], v[94:97], v[114:117]
	v_mfma_f32_16x16x32_bf16 v[94:97], v[224:227], v[94:97], v[176:179]
	v_mfma_f32_16x16x32_bf16 v[90:93], v[220:223], v[98:101], v[90:93]
	v_mfma_f32_16x16x32_bf16 v[94:97], v[228:231], v[98:101], v[94:97]
	v_mfma_f32_16x16x32_bf16 v[98:101], v[216:219], v[102:105], v[180:183]
	v_mfma_f32_16x16x32_bf16 v[102:105], v[224:227], v[102:105], v[184:187]
	v_mfma_f32_16x16x32_bf16 v[98:101], v[220:223], v[106:109], v[98:101]
	v_mfma_f32_16x16x32_bf16 v[102:105], v[228:231], v[106:109], v[102:105]
	v_mfma_f32_16x16x32_bf16 v[106:109], v[216:219], v[110:113], v[188:191]
	v_mfma_f32_16x16x32_bf16 v[110:113], v[224:227], v[110:113], v[118:121]
	v_mfma_f32_16x16x32_bf16 v[114:117], v[216:219], v[236:239], v[192:195]
	v_mfma_f32_16x16x32_bf16 v[118:121], v[224:227], v[236:239], v[196:199]
	v_mfma_f32_16x16x32_bf16 v[106:109], v[220:223], v[232:235], v[106:109]
	v_mfma_f32_16x16x32_bf16 v[110:113], v[228:231], v[232:235], v[110:113]
	s_setprio 2
	s_barrier
	v_mfma_f32_16x16x32_bf16 v[114:117], v[220:223], v[240:243], v[114:117]
	v_mfma_f32_16x16x32_bf16 v[118:121], v[228:231], v[240:243], v[118:121]
	s_setprio 0
	s_add_i32 s59, s59, 2
	s_cmp_ge_i32 s59, s15
	s_cbranch_scc0 .LBB0_379
	v_mov_b32_e32 v136, v130
	s_branch .LBB0_382

.LBB0_383:
	v_add_u32_e32 v133, s56, v140
	ds_read_b128 v[142:145], v133
	ds_read_b128 v[148:151], v133 offset:1024
	ds_read_b128 v[152:155], v133 offset:2048
	ds_read_b128 v[156:159], v133 offset:3072
	v_add_u32_e32 v133, s57, v140
	ds_read_b128 v[160:163], v133
	ds_read_b128 v[164:167], v133 offset:1024
	ds_read_b128 v[168:171], v133 offset:2048
	ds_read_b128 v[172:175], v133 offset:3072
	s_add_u32 s38, s36, 0xfff80080
	s_addc_u32 s39, s37, -1
	s_cmp_eq_u32 s43, 28
	s_cselect_b32 s41, s31, s39
	s_cselect_b32 s40, s30, s38
	s_cselect_b32 s39, s35, s42
	s_cselect_b32 s38, s34, s15
	s_mov_b32 m0, s54
	v_add_u32_e32 v141, 0, v1
	ds_read_b128 v[176:179], v141
	ds_read_b128 v[180:183], v141 offset:1024
	ds_read_b128 v[184:187], v141 offset:2048
	ds_read_b128 v[188:191], v141 offset:3072
	ds_read_b128 v[192:195], v141 offset:4096
	ds_read_b128 v[196:199], v141 offset:5120
	ds_read_b128 v[200:203], v141 offset:6144
	ds_read_b128 v[204:207], v141 offset:7168
	global_load_lds_dwordx4 v130, s[36:37]
	s_mov_b32 m0, s55
	v_mov_b32_e32 v133, v131
	global_load_lds_dwordx4 v132, s[36:37]
	s_waitcnt vmcnt(8)
	s_waitcnt lgkmcnt(0)
	s_barrier
	s_setprio 1
	s_waitcnt lgkmcnt(0)
	v_mfma_f32_16x16x32_bf16 v[2:5], v[142:145], v[176:179], v[2:5]
	v_mfma_f32_16x16x32_bf16 v[2:5], v[148:151], v[180:183], v[2:5]
	v_mfma_f32_16x16x32_bf16 v[6:9], v[156:159], v[180:183], v[6:9]
	v_mfma_f32_16x16x32_bf16 v[6:9], v[152:155], v[176:179], v[6:9]
	v_mfma_f32_16x16x32_bf16 v[14:17], v[152:155], v[184:187], v[14:17]
	v_mfma_f32_16x16x32_bf16 v[14:17], v[156:159], v[188:191], v[14:17]
	v_mfma_f32_16x16x32_bf16 v[10:13], v[148:151], v[188:191], v[10:13]
	v_mfma_f32_16x16x32_bf16 v[10:13], v[142:145], v[184:187], v[10:13]
	v_mfma_f32_16x16x32_bf16 v[18:21], v[142:145], v[192:195], v[18:21]
	v_mfma_f32_16x16x32_bf16 v[18:21], v[148:151], v[196:199], v[18:21]
	v_mfma_f32_16x16x32_bf16 v[22:25], v[156:159], v[196:199], v[22:25]
	v_mfma_f32_16x16x32_bf16 v[22:25], v[152:155], v[192:195], v[22:25]
	v_mfma_f32_16x16x32_bf16 v[30:33], v[152:155], v[200:203], v[30:33]
	v_mfma_f32_16x16x32_bf16 v[30:33], v[156:159], v[204:207], v[30:33]
	v_mfma_f32_16x16x32_bf16 v[26:29], v[148:151], v[204:207], v[26:29]
	v_mfma_f32_16x16x32_bf16 v[26:29], v[142:145], v[200:203], v[26:29]
	s_setprio 0
	s_setprio 1
	v_mfma_f32_16x16x32_bf16 v[34:37], v[160:163], v[176:179], v[34:37]
	v_mfma_f32_16x16x32_bf16 v[34:37], v[164:167], v[180:183], v[34:37]
	v_mfma_f32_16x16x32_bf16 v[38:41], v[172:175], v[180:183], v[38:41]
	v_mfma_f32_16x16x32_bf16 v[38:41], v[168:171], v[176:179], v[38:41]
	v_mfma_f32_16x16x32_bf16 v[46:49], v[168:171], v[184:187], v[46:49]
	v_mfma_f32_16x16x32_bf16 v[46:49], v[172:175], v[188:191], v[46:49]
	v_mfma_f32_16x16x32_bf16 v[42:45], v[164:167], v[188:191], v[42:45]
	v_mfma_f32_16x16x32_bf16 v[42:45], v[160:163], v[184:187], v[42:45]
	v_mfma_f32_16x16x32_bf16 v[50:53], v[160:163], v[192:195], v[50:53]
	v_mfma_f32_16x16x32_bf16 v[50:53], v[164:167], v[196:199], v[50:53]
	v_mfma_f32_16x16x32_bf16 v[54:57], v[172:175], v[196:199], v[54:57]
	v_mfma_f32_16x16x32_bf16 v[54:57], v[168:171], v[192:195], v[54:57]
	v_mfma_f32_16x16x32_bf16 v[62:65], v[168:171], v[200:203], v[62:65]
	v_mfma_f32_16x16x32_bf16 v[62:65], v[172:175], v[204:207], v[62:65]
	s_setprio 2
	s_barrier
	v_mfma_f32_16x16x32_bf16 v[58:61], v[164:167], v[204:207], v[58:61]
	v_mfma_f32_16x16x32_bf16 v[58:61], v[160:163], v[200:203], v[58:61]
	s_setprio 0
	s_add_i32 s44, s56, s21
	s_mov_b32 m0, s44
	ds_read_b128 v[176:179], v141 offset:16384
	ds_read_b128 v[180:183], v141 offset:17408
	ds_read_b128 v[184:187], v141 offset:18432
	ds_read_b128 v[188:191], v141 offset:19456
	ds_read_b128 v[192:195], v141 offset:20480
	ds_read_b128 v[196:199], v141 offset:21504
	ds_read_b128 v[200:203], v141 offset:22528
	ds_read_b128 v[204:207], v141 offset:23552
	global_load_lds_dwordx4 v136, s[38:39]
	s_add_i32 m0, s44, 0x2000
	s_add_u32 s44, s38, 0x80000
	s_addc_u32 s45, s39, 0
	s_add_i32 s59, s57, s21
	global_load_lds_dwordx4 v134, s[38:39]
	s_mov_b32 m0, s59
	v_mov_b32_e32 v137, v131
	global_load_lds_dwordx4 v136, s[44:45]
	s_add_i32 m0, s59, 0x2000
	v_mov_b32_e32 v135, v131
	global_load_lds_dwordx4 v134, s[44:45]
	s_mov_b32 m0, s33
	v_lshl_add_u64 v[138:139], s[38:39], 0, v[136:137]
	global_load_lds_dwordx4 v130, s[40:41]
	s_mov_b32 m0, s46
	v_lshl_add_u64 v[208:209], s[38:39], 0, v[134:135]
	global_load_lds_dwordx4 v132, s[40:41]
	s_waitcnt vmcnt(8)
	s_waitcnt lgkmcnt(0)
	v_lshl_add_u64 v[210:211], s[40:41], 0, v[130:131]
	v_lshl_add_u64 v[212:213], s[40:41], 0, v[132:133]
	s_barrier
	s_setprio 1
	s_waitcnt lgkmcnt(0)
	v_mfma_f32_16x16x32_bf16 v[122:125], v[142:145], v[176:179], v[122:125]
	v_mfma_f32_16x16x32_bf16 v[122:125], v[148:151], v[180:183], v[122:125]
	v_mfma_f32_16x16x32_bf16 v[126:129], v[156:159], v[180:183], v[126:129]
	v_mfma_f32_16x16x32_bf16 v[126:129], v[152:155], v[176:179], v[126:129]
	v_mfma_f32_16x16x32_bf16 v[70:73], v[152:155], v[184:187], v[70:73]
	v_mfma_f32_16x16x32_bf16 v[70:73], v[156:159], v[188:191], v[70:73]
	v_mfma_f32_16x16x32_bf16 v[66:69], v[148:151], v[188:191], v[66:69]
	v_mfma_f32_16x16x32_bf16 v[66:69], v[142:145], v[184:187], v[66:69]
	v_mfma_f32_16x16x32_bf16 v[74:77], v[142:145], v[192:195], v[74:77]
	v_mfma_f32_16x16x32_bf16 v[74:77], v[148:151], v[196:199], v[74:77]
	v_mfma_f32_16x16x32_bf16 v[78:81], v[156:159], v[196:199], v[78:81]
	v_mfma_f32_16x16x32_bf16 v[78:81], v[152:155], v[192:195], v[78:81]
	v_mfma_f32_16x16x32_bf16 v[86:89], v[152:155], v[200:203], v[86:89]
	v_mfma_f32_16x16x32_bf16 v[86:89], v[156:159], v[204:207], v[86:89]
	v_mfma_f32_16x16x32_bf16 v[82:85], v[148:151], v[204:207], v[82:85]
	v_mfma_f32_16x16x32_bf16 v[82:85], v[142:145], v[200:203], v[82:85]
	s_setprio 0
	s_setprio 1
	v_mfma_f32_16x16x32_bf16 v[90:93], v[160:163], v[176:179], v[90:93]
	v_mfma_f32_16x16x32_bf16 v[90:93], v[164:167], v[180:183], v[90:93]
	v_mfma_f32_16x16x32_bf16 v[94:97], v[172:175], v[180:183], v[94:97]
	v_mfma_f32_16x16x32_bf16 v[94:97], v[168:171], v[176:179], v[94:97]
	v_mfma_f32_16x16x32_bf16 v[102:105], v[168:171], v[184:187], v[102:105]
	v_mfma_f32_16x16x32_bf16 v[102:105], v[172:175], v[188:191], v[102:105]
	v_mfma_f32_16x16x32_bf16 v[98:101], v[164:167], v[188:191], v[98:101]
	v_mfma_f32_16x16x32_bf16 v[98:101], v[160:163], v[184:187], v[98:101]
	v_mfma_f32_16x16x32_bf16 v[106:109], v[160:163], v[192:195], v[106:109]
	v_mfma_f32_16x16x32_bf16 v[106:109], v[164:167], v[196:199], v[106:109]
	v_mfma_f32_16x16x32_bf16 v[110:113], v[172:175], v[196:199], v[110:113]
	v_mfma_f32_16x16x32_bf16 v[110:113], v[168:171], v[192:195], v[110:113]
	v_mfma_f32_16x16x32_bf16 v[118:121], v[168:171], v[200:203], v[118:121]
	v_mfma_f32_16x16x32_bf16 v[118:121], v[172:175], v[204:207], v[118:121]
	s_setprio 2
	s_barrier
	v_mfma_f32_16x16x32_bf16 v[114:117], v[164:167], v[204:207], v[114:117]
	v_mfma_f32_16x16x32_bf16 v[114:117], v[160:163], v[200:203], v[114:117]
	s_setprio 0
	s_add_i32 s44, 0, 0x18000
	v_add_u32_e32 v135, s44, v140
	s_add_i32 s45, 0, 0x1c000
	ds_read_b128 v[142:145], v135
	ds_read_b128 v[148:151], v135 offset:1024
	ds_read_b128 v[152:155], v135 offset:2048
	ds_read_b128 v[156:159], v135 offset:3072
	v_add_u32_e32 v135, s45, v140
	ds_read_b128 v[160:163], v135
	ds_read_b128 v[164:167], v135 offset:1024
	ds_read_b128 v[168:171], v135 offset:2048
	ds_read_b128 v[172:175], v135 offset:3072
	s_add_u32 s40, s40, 0x80000
	s_addc_u32 s41, s41, 0
	s_mov_b32 m0, s47
	ds_read_b128 v[176:179], v141 offset:32768
	ds_read_b128 v[180:183], v141 offset:33792
	ds_read_b128 v[184:187], v141 offset:34816
	ds_read_b128 v[188:191], v141 offset:35840
	ds_read_b128 v[192:195], v141 offset:36864
	ds_read_b128 v[196:199], v141 offset:37888
	ds_read_b128 v[200:203], v141 offset:38912
	ds_read_b128 v[204:207], v141 offset:39936
	global_load_lds_dwordx4 v130, s[40:41]
	s_mov_b32 m0, s48
	s_nop 0
	global_load_lds_dwordx4 v132, s[40:41]
	s_waitcnt vmcnt(8)
	s_waitcnt lgkmcnt(0)
	s_barrier
	s_setprio 1
	s_waitcnt lgkmcnt(0)
	v_mfma_f32_16x16x32_bf16 v[2:5], v[142:145], v[176:179], v[2:5]
	v_mfma_f32_16x16x32_bf16 v[2:5], v[148:151], v[180:183], v[2:5]
	v_mfma_f32_16x16x32_bf16 v[6:9], v[156:159], v[180:183], v[6:9]
	v_mfma_f32_16x16x32_bf16 v[6:9], v[152:155], v[176:179], v[6:9]
	v_mfma_f32_16x16x32_bf16 v[14:17], v[152:155], v[184:187], v[14:17]
	v_mfma_f32_16x16x32_bf16 v[14:17], v[156:159], v[188:191], v[14:17]
	v_mfma_f32_16x16x32_bf16 v[10:13], v[148:151], v[188:191], v[10:13]
	v_mfma_f32_16x16x32_bf16 v[10:13], v[142:145], v[184:187], v[10:13]
	v_mfma_f32_16x16x32_bf16 v[18:21], v[142:145], v[192:195], v[18:21]
	v_mfma_f32_16x16x32_bf16 v[18:21], v[148:151], v[196:199], v[18:21]
	v_mfma_f32_16x16x32_bf16 v[22:25], v[156:159], v[196:199], v[22:25]
	v_mfma_f32_16x16x32_bf16 v[22:25], v[152:155], v[192:195], v[22:25]
	v_mfma_f32_16x16x32_bf16 v[30:33], v[152:155], v[200:203], v[30:33]
	v_mfma_f32_16x16x32_bf16 v[30:33], v[156:159], v[204:207], v[30:33]
	v_mfma_f32_16x16x32_bf16 v[26:29], v[148:151], v[204:207], v[26:29]
	v_mfma_f32_16x16x32_bf16 v[26:29], v[142:145], v[200:203], v[26:29]
	s_setprio 0
	s_setprio 1
	v_mfma_f32_16x16x32_bf16 v[34:37], v[160:163], v[176:179], v[34:37]
	v_mfma_f32_16x16x32_bf16 v[34:37], v[164:167], v[180:183], v[34:37]
	v_mfma_f32_16x16x32_bf16 v[38:41], v[172:175], v[180:183], v[38:41]
	v_mfma_f32_16x16x32_bf16 v[38:41], v[168:171], v[176:179], v[38:41]
	v_mfma_f32_16x16x32_bf16 v[46:49], v[168:171], v[184:187], v[46:49]
	v_mfma_f32_16x16x32_bf16 v[46:49], v[172:175], v[188:191], v[46:49]
	v_mfma_f32_16x16x32_bf16 v[42:45], v[164:167], v[188:191], v[42:45]
	v_mfma_f32_16x16x32_bf16 v[42:45], v[160:163], v[184:187], v[42:45]
	v_mfma_f32_16x16x32_bf16 v[50:53], v[160:163], v[192:195], v[50:53]
	v_mfma_f32_16x16x32_bf16 v[50:53], v[164:167], v[196:199], v[50:53]
	v_mfma_f32_16x16x32_bf16 v[54:57], v[172:175], v[196:199], v[54:57]
	v_mfma_f32_16x16x32_bf16 v[54:57], v[168:171], v[192:195], v[54:57]
	v_mfma_f32_16x16x32_bf16 v[62:65], v[168:171], v[200:203], v[62:65]
	v_mfma_f32_16x16x32_bf16 v[62:65], v[172:175], v[204:207], v[62:65]
	s_setprio 2
	s_barrier
	v_mfma_f32_16x16x32_bf16 v[58:61], v[164:167], v[204:207], v[58:61]
	v_mfma_f32_16x16x32_bf16 v[58:61], v[160:163], v[200:203], v[58:61]
	s_setprio 0
	s_add_i32 s40, s44, s21
	v_lshl_add_u64 v[138:139], v[138:139], 0, s[6:7]
	s_mov_b32 m0, s40
	ds_read_b128 v[176:179], v141 offset:49152
	ds_read_b128 v[180:183], v141 offset:50176
	ds_read_b128 v[184:187], v141 offset:51200
	ds_read_b128 v[188:191], v141 offset:52224
	ds_read_b128 v[192:195], v141 offset:53248
	ds_read_b128 v[196:199], v141 offset:54272
	ds_read_b128 v[200:203], v141 offset:55296
	ds_read_b128 v[204:207], v141 offset:56320
	global_load_lds_dwordx4 v[138:139], off
	s_add_i32 m0, s40, 0x2000
	s_add_u32 s38, s38, 0x80080
	v_lshl_add_u64 v[138:139], v[208:209], 0, s[6:7]
	s_addc_u32 s39, s39, 0
	s_add_i32 s40, s45, s21
	global_load_lds_dwordx4 v[138:139], off
	s_mov_b32 m0, s40
	v_lshl_add_u64 v[138:139], v[210:211], 0, s[6:7]
	global_load_lds_dwordx4 v136, s[38:39]
	s_add_i32 m0, s40, 0x2000
	s_nop 0
	global_load_lds_dwordx4 v134, s[38:39]
	s_mov_b32 m0, s52
	s_nop 0
	global_load_lds_dwordx4 v[138:139], off
	v_lshl_add_u64 v[138:139], v[212:213], 0, s[6:7]
	s_mov_b32 m0, s53
	s_nop 0
	global_load_lds_dwordx4 v[138:139], off
	s_waitcnt vmcnt(8)
	s_waitcnt lgkmcnt(0)
	s_barrier
	s_setprio 1
	s_waitcnt lgkmcnt(0)
	v_mfma_f32_16x16x32_bf16 v[122:125], v[142:145], v[176:179], v[122:125]
	v_mfma_f32_16x16x32_bf16 v[122:125], v[148:151], v[180:183], v[122:125]
	v_mfma_f32_16x16x32_bf16 v[126:129], v[156:159], v[180:183], v[126:129]
	v_mfma_f32_16x16x32_bf16 v[126:129], v[152:155], v[176:179], v[126:129]
	v_mfma_f32_16x16x32_bf16 v[70:73], v[152:155], v[184:187], v[70:73]
	v_mfma_f32_16x16x32_bf16 v[70:73], v[156:159], v[188:191], v[70:73]
	v_mfma_f32_16x16x32_bf16 v[66:69], v[148:151], v[188:191], v[66:69]
	v_mfma_f32_16x16x32_bf16 v[66:69], v[142:145], v[184:187], v[66:69]
	v_mfma_f32_16x16x32_bf16 v[74:77], v[142:145], v[192:195], v[74:77]
	v_mfma_f32_16x16x32_bf16 v[74:77], v[148:151], v[196:199], v[74:77]
	v_mfma_f32_16x16x32_bf16 v[78:81], v[156:159], v[196:199], v[78:81]
	v_mfma_f32_16x16x32_bf16 v[78:81], v[152:155], v[192:195], v[78:81]
	v_mfma_f32_16x16x32_bf16 v[86:89], v[152:155], v[200:203], v[86:89]
	v_mfma_f32_16x16x32_bf16 v[86:89], v[156:159], v[204:207], v[86:89]
	v_mfma_f32_16x16x32_bf16 v[82:85], v[148:151], v[204:207], v[82:85]
	v_mfma_f32_16x16x32_bf16 v[82:85], v[142:145], v[200:203], v[82:85]
	s_setprio 0
	s_setprio 1
	v_mfma_f32_16x16x32_bf16 v[90:93], v[160:163], v[176:179], v[90:93]
	v_mfma_f32_16x16x32_bf16 v[90:93], v[164:167], v[180:183], v[90:93]
	v_mfma_f32_16x16x32_bf16 v[94:97], v[172:175], v[180:183], v[94:97]
	v_mfma_f32_16x16x32_bf16 v[94:97], v[168:171], v[176:179], v[94:97]
	v_mfma_f32_16x16x32_bf16 v[102:105], v[168:171], v[184:187], v[102:105]
	v_mfma_f32_16x16x32_bf16 v[102:105], v[172:175], v[188:191], v[102:105]
	v_mfma_f32_16x16x32_bf16 v[98:101], v[164:167], v[188:191], v[98:101]
	v_mfma_f32_16x16x32_bf16 v[98:101], v[160:163], v[184:187], v[98:101]
	v_mfma_f32_16x16x32_bf16 v[106:109], v[160:163], v[192:195], v[106:109]
	v_mfma_f32_16x16x32_bf16 v[106:109], v[164:167], v[196:199], v[106:109]
	v_mfma_f32_16x16x32_bf16 v[110:113], v[172:175], v[196:199], v[110:113]
	v_mfma_f32_16x16x32_bf16 v[110:113], v[168:171], v[192:195], v[110:113]
	v_mfma_f32_16x16x32_bf16 v[118:121], v[168:171], v[200:203], v[118:121]
	v_mfma_f32_16x16x32_bf16 v[118:121], v[172:175], v[204:207], v[118:121]
	s_setprio 2
	s_barrier
	v_mfma_f32_16x16x32_bf16 v[114:117], v[164:167], v[204:207], v[114:117]
	v_mfma_f32_16x16x32_bf16 v[114:117], v[160:163], v[200:203], v[114:117]
	s_setprio 0
	s_add_i32 s43, s43, 2
	s_add_u32 s36, s36, 0x100
	s_addc_u32 s37, s37, 0
	s_add_u32 s15, s15, 0x100
	s_addc_u32 s42, s42, 0
	s_cmp_gt_u32 s43, 29
	s_cbranch_scc0 .LBB0_383
	s_and_b64 vcc, exec, s[8:9]
	s_cbranch_vccz .LBB0_386
	s_barrier

.LBB0_462:
	v_add_u32_e32 v14, s54, v140
	v_add_u32_e32 v30, s55, v140
	ds_read_b128 v[2:5], v14
	ds_read_b128 v[6:9], v14 offset:1024
	ds_read_b128 v[10:13], v14 offset:2048
	ds_read_b128 v[14:17], v14 offset:3072
	ds_read_b128 v[18:21], v30
	ds_read_b128 v[22:25], v30 offset:1024
	ds_read_b128 v[26:29], v30 offset:2048
	ds_read_b128 v[30:33], v30 offset:3072
	v_add_u32_e32 v141, 0, v1
	ds_read_b128 v[34:37], v141
	ds_read_b128 v[38:41], v141 offset:1024
	ds_read_b128 v[42:45], v141 offset:2048
	ds_read_b128 v[46:49], v141 offset:3072
	ds_read_b128 v[50:53], v141 offset:4096
	ds_read_b128 v[54:57], v141 offset:5120
	ds_read_b128 v[58:61], v141 offset:6144
	ds_read_b128 v[62:65], v141 offset:7168
	s_waitcnt vmcnt(8)
	s_waitcnt lgkmcnt(0)
	s_barrier
	s_setprio 1
	s_waitcnt lgkmcnt(0)
	v_mfma_f32_16x16x32_bf16 v[66:69], v[2:5], v[34:37], 0
	v_mfma_f32_16x16x32_bf16 v[66:69], v[6:9], v[38:41], v[66:69]
	v_mfma_f32_16x16x32_bf16 v[70:73], v[10:13], v[34:37], 0
	v_mfma_f32_16x16x32_bf16 v[70:73], v[14:17], v[38:41], v[70:73]
	v_mfma_f32_16x16x32_bf16 v[78:81], v[10:13], v[42:45], 0
	v_mfma_f32_16x16x32_bf16 v[78:81], v[14:17], v[46:49], v[78:81]
	v_mfma_f32_16x16x32_bf16 v[74:77], v[2:5], v[42:45], 0
	v_mfma_f32_16x16x32_bf16 v[74:77], v[6:9], v[46:49], v[74:77]
	v_mfma_f32_16x16x32_bf16 v[82:85], v[2:5], v[50:53], 0
	v_mfma_f32_16x16x32_bf16 v[82:85], v[6:9], v[54:57], v[82:85]
	v_mfma_f32_16x16x32_bf16 v[86:89], v[10:13], v[50:53], 0
	v_mfma_f32_16x16x32_bf16 v[86:89], v[14:17], v[54:57], v[86:89]
	v_mfma_f32_16x16x32_bf16 v[94:97], v[10:13], v[58:61], 0
	v_mfma_f32_16x16x32_bf16 v[94:97], v[14:17], v[62:65], v[94:97]
	v_mfma_f32_16x16x32_bf16 v[90:93], v[2:5], v[58:61], 0
	v_mfma_f32_16x16x32_bf16 v[90:93], v[6:9], v[62:65], v[90:93]
	s_setprio 0
	s_setprio 1
	v_mfma_f32_16x16x32_bf16 v[98:101], v[18:21], v[34:37], 0
	v_mfma_f32_16x16x32_bf16 v[34:37], v[26:29], v[34:37], 0
	v_mfma_f32_16x16x32_bf16 v[102:105], v[18:21], v[42:45], 0
	v_mfma_f32_16x16x32_bf16 v[42:45], v[26:29], v[42:45], 0
	v_mfma_f32_16x16x32_bf16 v[106:109], v[18:21], v[50:53], 0
	v_mfma_f32_16x16x32_bf16 v[50:53], v[26:29], v[50:53], 0
	v_mfma_f32_16x16x32_bf16 v[110:113], v[18:21], v[58:61], 0
	v_mfma_f32_16x16x32_bf16 v[58:61], v[26:29], v[58:61], 0
	v_mfma_f32_16x16x32_bf16 v[98:101], v[22:25], v[38:41], v[98:101]
	v_mfma_f32_16x16x32_bf16 v[38:41], v[30:33], v[38:41], v[34:37]
	v_mfma_f32_16x16x32_bf16 v[102:105], v[22:25], v[46:49], v[102:105]
	v_mfma_f32_16x16x32_bf16 v[46:49], v[30:33], v[46:49], v[42:45]
	v_mfma_f32_16x16x32_bf16 v[106:109], v[22:25], v[54:57], v[106:109]
	v_mfma_f32_16x16x32_bf16 v[54:57], v[30:33], v[54:57], v[50:53]
	s_setprio 2
	s_barrier
	v_mfma_f32_16x16x32_bf16 v[110:113], v[22:25], v[62:65], v[110:113]
	v_mfma_f32_16x16x32_bf16 v[62:65], v[30:33], v[62:65], v[58:61]
	s_setprio 0
	v_lshl_add_u64 v[136:137], s[36:37], 0, v[130:131]
	s_add_i32 s62, s54, s21
	v_mov_b32_e32 v135, v131
	v_lshl_add_u64 v[142:143], v[136:137], 0, s[12:13]
	s_mov_b32 m0, s62
	v_lshl_add_u64 v[244:245], s[36:37], 0, v[134:135]
	ds_read_b128 v[34:37], v141 offset:16384
	ds_read_b128 v[42:45], v141 offset:17408
	ds_read_b128 v[50:53], v141 offset:18432
	ds_read_b128 v[58:61], v141 offset:19456
	ds_read_b128 v[114:117], v141 offset:20480
	ds_read_b128 v[118:121], v141 offset:21504
	ds_read_b128 v[122:125], v141 offset:22528
	ds_read_b128 v[126:129], v141 offset:23552
	global_load_lds_dwordx4 v[142:143], off
	v_lshl_add_u64 v[142:143], v[244:245], 0, s[12:13]
	s_add_i32 m0, s62, 0x2000
	s_add_i32 s62, s55, s21
	global_load_lds_dwordx4 v[142:143], off
	s_mov_b32 m0, s62
	v_mov_b32_e32 v139, v131
	global_load_lds_dwordx4 v130, s[38:39]
	s_add_i32 m0, s62, 0x2000
	v_lshl_add_u64 v[246:247], s[34:35], 0, v[138:139]
	v_mov_b32_e32 v133, v131
	global_load_lds_dwordx4 v134, s[38:39]
	v_lshl_add_u64 v[142:143], v[246:247], 0, s[12:13]
	s_mov_b32 m0, s33
	v_lshl_add_u64 v[248:249], s[34:35], 0, v[132:133]
	global_load_lds_dwordx4 v[142:143], off
	v_lshl_add_u64 v[142:143], v[248:249], 0, s[12:13]
	s_mov_b32 m0, s44
	s_nop 0
	global_load_lds_dwordx4 v[142:143], off
	s_waitcnt vmcnt(8)
	s_waitcnt lgkmcnt(0)
	s_barrier
	s_setprio 1
	s_waitcnt lgkmcnt(0)
	v_mfma_f32_16x16x32_bf16 v[142:145], v[2:5], v[34:37], 0
	v_mfma_f32_16x16x32_bf16 v[148:151], v[10:13], v[34:37], 0
	v_mfma_f32_16x16x32_bf16 v[152:155], v[2:5], v[50:53], 0
	v_mfma_f32_16x16x32_bf16 v[156:159], v[10:13], v[50:53], 0
	v_mfma_f32_16x16x32_bf16 v[160:163], v[2:5], v[114:117], 0
	v_mfma_f32_16x16x32_bf16 v[164:167], v[10:13], v[114:117], 0
	v_mfma_f32_16x16x32_bf16 v[2:5], v[2:5], v[122:125], 0
	v_mfma_f32_16x16x32_bf16 v[10:13], v[10:13], v[122:125], 0
	v_mfma_f32_16x16x32_bf16 v[142:145], v[6:9], v[42:45], v[142:145]
	v_mfma_f32_16x16x32_bf16 v[148:151], v[14:17], v[42:45], v[148:151]
	v_mfma_f32_16x16x32_bf16 v[152:155], v[6:9], v[58:61], v[152:155]
	v_mfma_f32_16x16x32_bf16 v[156:159], v[14:17], v[58:61], v[156:159]
	v_mfma_f32_16x16x32_bf16 v[160:163], v[6:9], v[118:121], v[160:163]
	v_mfma_f32_16x16x32_bf16 v[164:167], v[14:17], v[118:121], v[164:167]
	v_mfma_f32_16x16x32_bf16 v[168:171], v[6:9], v[126:129], v[2:5]
	v_mfma_f32_16x16x32_bf16 v[172:175], v[14:17], v[126:129], v[10:13]
	s_setprio 0
	s_setprio 1
	v_mfma_f32_16x16x32_bf16 v[2:5], v[18:21], v[34:37], 0
	v_mfma_f32_16x16x32_bf16 v[6:9], v[26:29], v[34:37], 0
	v_mfma_f32_16x16x32_bf16 v[10:13], v[18:21], v[50:53], 0
	v_mfma_f32_16x16x32_bf16 v[14:17], v[26:29], v[50:53], 0
	v_mfma_f32_16x16x32_bf16 v[34:37], v[18:21], v[114:117], 0
	v_mfma_f32_16x16x32_bf16 v[50:53], v[26:29], v[114:117], 0
	v_mfma_f32_16x16x32_bf16 v[18:21], v[18:21], v[122:125], 0
	v_mfma_f32_16x16x32_bf16 v[26:29], v[26:29], v[122:125], 0
	v_mfma_f32_16x16x32_bf16 v[114:117], v[22:25], v[42:45], v[2:5]
	v_mfma_f32_16x16x32_bf16 v[122:125], v[30:33], v[42:45], v[6:9]
	v_mfma_f32_16x16x32_bf16 v[184:187], v[22:25], v[118:121], v[34:37]
	v_mfma_f32_16x16x32_bf16 v[118:121], v[30:33], v[118:121], v[50:53]
	v_mfma_f32_16x16x32_bf16 v[188:191], v[22:25], v[126:129], v[18:21]
	v_mfma_f32_16x16x32_bf16 v[126:129], v[30:33], v[126:129], v[26:29]
	s_setprio 2
	s_barrier
	v_mfma_f32_16x16x32_bf16 v[176:179], v[22:25], v[58:61], v[10:13]
	v_mfma_f32_16x16x32_bf16 v[180:183], v[30:33], v[58:61], v[14:17]
	s_setprio 0
	s_add_i32 s62, 0, 0x18000
	v_add_u32_e32 v2, s62, v140
	s_add_i32 s63, 0, 0x1c000
	ds_read_b128 v[192:195], v2
	ds_read_b128 v[196:199], v2 offset:1024
	ds_read_b128 v[200:203], v2 offset:2048
	ds_read_b128 v[204:207], v2 offset:3072
	v_add_u32_e32 v2, s63, v140
	ds_read_b128 v[208:211], v2
	ds_read_b128 v[212:215], v2 offset:1024
	ds_read_b128 v[216:219], v2 offset:2048
	ds_read_b128 v[220:223], v2 offset:3072
	s_mov_b32 m0, s45
	ds_read_b128 v[42:45], v141 offset:32768
	ds_read_b128 v[50:53], v141 offset:33792
	ds_read_b128 v[58:61], v141 offset:34816
	ds_read_b128 v[224:227], v141 offset:35840
	ds_read_b128 v[228:231], v141 offset:36864
	ds_read_b128 v[232:235], v141 offset:37888
	ds_read_b128 v[236:239], v141 offset:38912
	ds_read_b128 v[240:243], v141 offset:39936
	global_load_lds_dwordx4 v138, s[40:41]
	s_mov_b32 m0, s46
	s_nop 0
	global_load_lds_dwordx4 v132, s[40:41]
	s_waitcnt vmcnt(8)
	s_waitcnt lgkmcnt(0)
	s_barrier
	s_setprio 1
	s_waitcnt lgkmcnt(0)
	v_mfma_f32_16x16x32_bf16 v[2:5], v[192:195], v[42:45], v[66:69]
	v_mfma_f32_16x16x32_bf16 v[6:9], v[200:203], v[42:45], v[70:73]
	v_mfma_f32_16x16x32_bf16 v[10:13], v[192:195], v[58:61], v[74:77]
	v_mfma_f32_16x16x32_bf16 v[14:17], v[200:203], v[58:61], v[78:81]
	v_mfma_f32_16x16x32_bf16 v[18:21], v[192:195], v[228:231], v[82:85]
	v_mfma_f32_16x16x32_bf16 v[22:25], v[200:203], v[228:231], v[86:89]
	v_mfma_f32_16x16x32_bf16 v[26:29], v[192:195], v[236:239], v[90:93]
	v_mfma_f32_16x16x32_bf16 v[30:33], v[200:203], v[236:239], v[94:97]
	v_mfma_f32_16x16x32_bf16 v[2:5], v[196:199], v[50:53], v[2:5]
	v_mfma_f32_16x16x32_bf16 v[6:9], v[204:207], v[50:53], v[6:9]
	v_mfma_f32_16x16x32_bf16 v[10:13], v[196:199], v[224:227], v[10:13]
	v_mfma_f32_16x16x32_bf16 v[14:17], v[204:207], v[224:227], v[14:17]
	v_mfma_f32_16x16x32_bf16 v[18:21], v[196:199], v[232:235], v[18:21]
	v_mfma_f32_16x16x32_bf16 v[22:25], v[204:207], v[232:235], v[22:25]
	v_mfma_f32_16x16x32_bf16 v[26:29], v[196:199], v[240:243], v[26:29]
	v_mfma_f32_16x16x32_bf16 v[30:33], v[204:207], v[240:243], v[30:33]
	s_setprio 0
	s_setprio 1
	v_mfma_f32_16x16x32_bf16 v[34:37], v[208:211], v[42:45], v[98:101]
	v_mfma_f32_16x16x32_bf16 v[38:41], v[216:219], v[42:45], v[38:41]
	v_mfma_f32_16x16x32_bf16 v[34:37], v[212:215], v[50:53], v[34:37]
	v_mfma_f32_16x16x32_bf16 v[38:41], v[220:223], v[50:53], v[38:41]
	v_mfma_f32_16x16x32_bf16 v[42:45], v[208:211], v[58:61], v[102:105]
	v_mfma_f32_16x16x32_bf16 v[46:49], v[216:219], v[58:61], v[46:49]
	v_mfma_f32_16x16x32_bf16 v[50:53], v[208:211], v[228:231], v[106:109]
	v_mfma_f32_16x16x32_bf16 v[54:57], v[216:219], v[228:231], v[54:57]
	v_mfma_f32_16x16x32_bf16 v[58:61], v[208:211], v[236:239], v[110:113]
	v_mfma_f32_16x16x32_bf16 v[62:65], v[216:219], v[236:239], v[62:65]
	v_mfma_f32_16x16x32_bf16 v[42:45], v[212:215], v[224:227], v[42:45]
	v_mfma_f32_16x16x32_bf16 v[46:49], v[220:223], v[224:227], v[46:49]
	v_mfma_f32_16x16x32_bf16 v[50:53], v[212:215], v[232:235], v[50:53]
	v_mfma_f32_16x16x32_bf16 v[54:57], v[220:223], v[232:235], v[54:57]
	s_setprio 2
	s_barrier
	v_mfma_f32_16x16x32_bf16 v[58:61], v[212:215], v[240:243], v[58:61]
	v_mfma_f32_16x16x32_bf16 v[62:65], v[220:223], v[240:243], v[62:65]
	s_setprio 0
	s_add_i32 s62, s62, s21
	v_lshl_add_u64 v[66:67], v[136:137], 0, s[14:15]
	s_mov_b32 m0, s62
	ds_read_b128 v[102:105], v141 offset:49152
	ds_read_b128 v[106:109], v141 offset:50176
	ds_read_b128 v[110:113], v141 offset:51200
	ds_read_b128 v[224:227], v141 offset:52224
	ds_read_b128 v[228:231], v141 offset:53248
	ds_read_b128 v[232:235], v141 offset:54272
	ds_read_b128 v[236:239], v141 offset:55296
	ds_read_b128 v[240:243], v141 offset:56320
	global_load_lds_dwordx4 v[66:67], off
	v_lshl_add_u64 v[66:67], v[244:245], 0, s[14:15]
	s_add_i32 m0, s62, 0x2000
	s_add_i32 s62, s63, s21
	global_load_lds_dwordx4 v[66:67], off
	s_mov_b32 m0, s62
	v_lshl_add_u64 v[66:67], v[246:247], 0, s[14:15]
	global_load_lds_dwordx4 v130, s[42:43]
	s_add_i32 m0, s62, 0x2000
	s_nop 0
	global_load_lds_dwordx4 v134, s[42:43]
	s_mov_b32 m0, s50
	s_nop 0
	global_load_lds_dwordx4 v[66:67], off
	v_lshl_add_u64 v[66:67], v[248:249], 0, s[14:15]
	s_mov_b32 m0, s51
	s_nop 0
	global_load_lds_dwordx4 v[66:67], off
	s_waitcnt vmcnt(8)
	s_waitcnt lgkmcnt(0)
	s_barrier
	s_setprio 1
	s_waitcnt lgkmcnt(0)
	v_mfma_f32_16x16x32_bf16 v[66:69], v[192:195], v[102:105], v[142:145]
	v_mfma_f32_16x16x32_bf16 v[70:73], v[200:203], v[102:105], v[148:151]
	v_mfma_f32_16x16x32_bf16 v[74:77], v[192:195], v[110:113], v[152:155]
	v_mfma_f32_16x16x32_bf16 v[78:81], v[200:203], v[110:113], v[156:159]
	v_mfma_f32_16x16x32_bf16 v[82:85], v[192:195], v[228:231], v[160:163]
	v_mfma_f32_16x16x32_bf16 v[86:89], v[200:203], v[228:231], v[164:167]
	v_mfma_f32_16x16x32_bf16 v[90:93], v[192:195], v[236:239], v[168:171]
	v_mfma_f32_16x16x32_bf16 v[94:97], v[200:203], v[236:239], v[172:175]
	v_mfma_f32_16x16x32_bf16 v[66:69], v[196:199], v[106:109], v[66:69]
	v_mfma_f32_16x16x32_bf16 v[70:73], v[204:207], v[106:109], v[70:73]
	v_mfma_f32_16x16x32_bf16 v[74:77], v[196:199], v[224:227], v[74:77]
	v_mfma_f32_16x16x32_bf16 v[78:81], v[204:207], v[224:227], v[78:81]
	v_mfma_f32_16x16x32_bf16 v[82:85], v[196:199], v[232:235], v[82:85]
	v_mfma_f32_16x16x32_bf16 v[86:89], v[204:207], v[232:235], v[86:89]
	v_mfma_f32_16x16x32_bf16 v[90:93], v[196:199], v[240:243], v[90:93]
	v_mfma_f32_16x16x32_bf16 v[94:97], v[204:207], v[240:243], v[94:97]
	s_setprio 0
	s_setprio 1
	v_mfma_f32_16x16x32_bf16 v[98:101], v[208:211], v[102:105], v[114:117]
	v_mfma_f32_16x16x32_bf16 v[102:105], v[216:219], v[102:105], v[122:125]
	v_mfma_f32_16x16x32_bf16 v[98:101], v[212:215], v[106:109], v[98:101]
	v_mfma_f32_16x16x32_bf16 v[102:105], v[220:223], v[106:109], v[102:105]
	v_mfma_f32_16x16x32_bf16 v[106:109], v[208:211], v[110:113], v[176:179]
	v_mfma_f32_16x16x32_bf16 v[110:113], v[216:219], v[110:113], v[180:183]
	v_mfma_f32_16x16x32_bf16 v[114:117], v[208:211], v[228:231], v[184:187]
	v_mfma_f32_16x16x32_bf16 v[118:121], v[216:219], v[228:231], v[118:121]
	v_mfma_f32_16x16x32_bf16 v[122:125], v[208:211], v[236:239], v[188:191]
	v_mfma_f32_16x16x32_bf16 v[126:129], v[216:219], v[236:239], v[126:129]
	v_mfma_f32_16x16x32_bf16 v[106:109], v[212:215], v[224:227], v[106:109]
	v_mfma_f32_16x16x32_bf16 v[110:113], v[220:223], v[224:227], v[110:113]
	v_mfma_f32_16x16x32_bf16 v[114:117], v[212:215], v[232:235], v[114:117]
	v_mfma_f32_16x16x32_bf16 v[118:121], v[220:223], v[232:235], v[118:121]
	s_setprio 2
	s_barrier
	v_mfma_f32_16x16x32_bf16 v[122:125], v[212:215], v[240:243], v[122:125]
	v_mfma_f32_16x16x32_bf16 v[126:129], v[220:223], v[240:243], v[126:129]
	s_setprio 0
	s_add_i32 s61, s61, 2
	s_cmp_ge_i32 s61, s60
	s_cbranch_scc0 .LBB0_462
	v_mov_b32_e32 v136, v130
	s_branch .LBB0_465

.LBB0_466:
	v_add_u32_e32 v133, s54, v140
	ds_read_b128 v[142:145], v133
	ds_read_b128 v[148:151], v133 offset:1024
	ds_read_b128 v[152:155], v133 offset:2048
	ds_read_b128 v[156:159], v133 offset:3072
	v_add_u32_e32 v133, s55, v140
	ds_read_b128 v[160:163], v133
	ds_read_b128 v[164:167], v133 offset:1024
	ds_read_b128 v[168:171], v133 offset:2048
	ds_read_b128 v[172:175], v133 offset:3072
	s_add_u32 s36, s34, 0xffc00080
	s_addc_u32 s37, s35, -1
	s_cmp_eq_u32 s42, 4
	s_cselect_b32 s39, s29, s37
	s_cselect_b32 s38, s28, s36
	s_cselect_b32 s37, s31, s41
	s_cselect_b32 s36, s30, s40
	s_mov_b32 m0, s52
	v_add_u32_e32 v141, 0, v1
	ds_read_b128 v[176:179], v141
	ds_read_b128 v[180:183], v141 offset:1024
	ds_read_b128 v[184:187], v141 offset:2048
	ds_read_b128 v[188:191], v141 offset:3072
	ds_read_b128 v[192:195], v141 offset:4096
	ds_read_b128 v[196:199], v141 offset:5120
	ds_read_b128 v[200:203], v141 offset:6144
	ds_read_b128 v[204:207], v141 offset:7168
	global_load_lds_dwordx4 v130, s[34:35]
	s_mov_b32 m0, s53
	v_mov_b32_e32 v133, v131
	global_load_lds_dwordx4 v132, s[34:35]
	s_waitcnt vmcnt(8)
	s_waitcnt lgkmcnt(0)
	s_barrier
	s_setprio 1
	s_waitcnt lgkmcnt(0)
	v_mfma_f32_16x16x32_bf16 v[2:5], v[142:145], v[176:179], v[2:5]
	v_mfma_f32_16x16x32_bf16 v[2:5], v[148:151], v[180:183], v[2:5]
	v_mfma_f32_16x16x32_bf16 v[6:9], v[156:159], v[180:183], v[6:9]
	v_mfma_f32_16x16x32_bf16 v[6:9], v[152:155], v[176:179], v[6:9]
	v_mfma_f32_16x16x32_bf16 v[14:17], v[152:155], v[184:187], v[14:17]
	v_mfma_f32_16x16x32_bf16 v[14:17], v[156:159], v[188:191], v[14:17]
	v_mfma_f32_16x16x32_bf16 v[10:13], v[148:151], v[188:191], v[10:13]
	v_mfma_f32_16x16x32_bf16 v[10:13], v[142:145], v[184:187], v[10:13]
	v_mfma_f32_16x16x32_bf16 v[18:21], v[142:145], v[192:195], v[18:21]
	v_mfma_f32_16x16x32_bf16 v[18:21], v[148:151], v[196:199], v[18:21]
	v_mfma_f32_16x16x32_bf16 v[22:25], v[156:159], v[196:199], v[22:25]
	v_mfma_f32_16x16x32_bf16 v[22:25], v[152:155], v[192:195], v[22:25]
	v_mfma_f32_16x16x32_bf16 v[30:33], v[152:155], v[200:203], v[30:33]
	v_mfma_f32_16x16x32_bf16 v[30:33], v[156:159], v[204:207], v[30:33]
	v_mfma_f32_16x16x32_bf16 v[26:29], v[148:151], v[204:207], v[26:29]
	v_mfma_f32_16x16x32_bf16 v[26:29], v[142:145], v[200:203], v[26:29]
	s_setprio 0
	s_setprio 1
	v_mfma_f32_16x16x32_bf16 v[34:37], v[160:163], v[176:179], v[34:37]
	v_mfma_f32_16x16x32_bf16 v[34:37], v[164:167], v[180:183], v[34:37]
	v_mfma_f32_16x16x32_bf16 v[38:41], v[172:175], v[180:183], v[38:41]
	v_mfma_f32_16x16x32_bf16 v[38:41], v[168:171], v[176:179], v[38:41]
	v_mfma_f32_16x16x32_bf16 v[46:49], v[168:171], v[184:187], v[46:49]
	v_mfma_f32_16x16x32_bf16 v[46:49], v[172:175], v[188:191], v[46:49]
	v_mfma_f32_16x16x32_bf16 v[42:45], v[164:167], v[188:191], v[42:45]
	v_mfma_f32_16x16x32_bf16 v[42:45], v[160:163], v[184:187], v[42:45]
	v_mfma_f32_16x16x32_bf16 v[50:53], v[160:163], v[192:195], v[50:53]
	v_mfma_f32_16x16x32_bf16 v[50:53], v[164:167], v[196:199], v[50:53]
	v_mfma_f32_16x16x32_bf16 v[54:57], v[172:175], v[196:199], v[54:57]
	v_mfma_f32_16x16x32_bf16 v[54:57], v[168:171], v[192:195], v[54:57]
	v_mfma_f32_16x16x32_bf16 v[62:65], v[168:171], v[200:203], v[62:65]
	v_mfma_f32_16x16x32_bf16 v[62:65], v[172:175], v[204:207], v[62:65]
	s_setprio 2
	s_barrier
	v_mfma_f32_16x16x32_bf16 v[58:61], v[164:167], v[204:207], v[58:61]
	v_mfma_f32_16x16x32_bf16 v[58:61], v[160:163], v[200:203], v[58:61]
	s_setprio 0
	s_add_i32 s43, s54, s21
	s_mov_b32 m0, s43
	ds_read_b128 v[176:179], v141 offset:16384
	ds_read_b128 v[180:183], v141 offset:17408
	ds_read_b128 v[184:187], v141 offset:18432
	ds_read_b128 v[188:191], v141 offset:19456
	ds_read_b128 v[192:195], v141 offset:20480
	ds_read_b128 v[196:199], v141 offset:21504
	ds_read_b128 v[200:203], v141 offset:22528
	ds_read_b128 v[204:207], v141 offset:23552
	global_load_lds_dwordx4 v136, s[36:37]
	s_add_i32 m0, s43, 0x2000
	s_add_u32 s60, s36, 0x80000
	s_addc_u32 s61, s37, 0
	s_add_i32 s43, s55, s21
	global_load_lds_dwordx4 v134, s[36:37]
	s_mov_b32 m0, s43
	v_mov_b32_e32 v137, v131
	global_load_lds_dwordx4 v136, s[60:61]
	s_add_i32 m0, s43, 0x2000
	v_mov_b32_e32 v135, v131
	global_load_lds_dwordx4 v134, s[60:61]
	s_mov_b32 m0, s33
	v_lshl_add_u64 v[138:139], s[36:37], 0, v[136:137]
	global_load_lds_dwordx4 v130, s[38:39]
	s_mov_b32 m0, s44
	v_lshl_add_u64 v[208:209], s[36:37], 0, v[134:135]
	global_load_lds_dwordx4 v132, s[38:39]
	s_waitcnt vmcnt(8)
	s_waitcnt lgkmcnt(0)
	v_lshl_add_u64 v[210:211], s[38:39], 0, v[130:131]
	v_lshl_add_u64 v[212:213], s[38:39], 0, v[132:133]
	s_barrier
	s_setprio 1
	s_waitcnt lgkmcnt(0)
	v_mfma_f32_16x16x32_bf16 v[66:69], v[142:145], v[176:179], v[66:69]
	v_mfma_f32_16x16x32_bf16 v[66:69], v[148:151], v[180:183], v[66:69]
	v_mfma_f32_16x16x32_bf16 v[70:73], v[156:159], v[180:183], v[70:73]
	v_mfma_f32_16x16x32_bf16 v[70:73], v[152:155], v[176:179], v[70:73]
	v_mfma_f32_16x16x32_bf16 v[78:81], v[152:155], v[184:187], v[78:81]
	v_mfma_f32_16x16x32_bf16 v[78:81], v[156:159], v[188:191], v[78:81]
	v_mfma_f32_16x16x32_bf16 v[74:77], v[148:151], v[188:191], v[74:77]
	v_mfma_f32_16x16x32_bf16 v[74:77], v[142:145], v[184:187], v[74:77]
	v_mfma_f32_16x16x32_bf16 v[82:85], v[142:145], v[192:195], v[82:85]
	v_mfma_f32_16x16x32_bf16 v[82:85], v[148:151], v[196:199], v[82:85]
	v_mfma_f32_16x16x32_bf16 v[86:89], v[156:159], v[196:199], v[86:89]
	v_mfma_f32_16x16x32_bf16 v[86:89], v[152:155], v[192:195], v[86:89]
	v_mfma_f32_16x16x32_bf16 v[94:97], v[152:155], v[200:203], v[94:97]
	v_mfma_f32_16x16x32_bf16 v[94:97], v[156:159], v[204:207], v[94:97]
	v_mfma_f32_16x16x32_bf16 v[90:93], v[148:151], v[204:207], v[90:93]
	v_mfma_f32_16x16x32_bf16 v[90:93], v[142:145], v[200:203], v[90:93]
	s_setprio 0
	s_setprio 1
	v_mfma_f32_16x16x32_bf16 v[98:101], v[160:163], v[176:179], v[98:101]
	v_mfma_f32_16x16x32_bf16 v[98:101], v[164:167], v[180:183], v[98:101]
	v_mfma_f32_16x16x32_bf16 v[102:105], v[172:175], v[180:183], v[102:105]
	v_mfma_f32_16x16x32_bf16 v[102:105], v[168:171], v[176:179], v[102:105]
	v_mfma_f32_16x16x32_bf16 v[110:113], v[168:171], v[184:187], v[110:113]
	v_mfma_f32_16x16x32_bf16 v[110:113], v[172:175], v[188:191], v[110:113]
	v_mfma_f32_16x16x32_bf16 v[106:109], v[164:167], v[188:191], v[106:109]
	v_mfma_f32_16x16x32_bf16 v[106:109], v[160:163], v[184:187], v[106:109]
	v_mfma_f32_16x16x32_bf16 v[114:117], v[160:163], v[192:195], v[114:117]
	v_mfma_f32_16x16x32_bf16 v[114:117], v[164:167], v[196:199], v[114:117]
	v_mfma_f32_16x16x32_bf16 v[118:121], v[172:175], v[196:199], v[118:121]
	v_mfma_f32_16x16x32_bf16 v[118:121], v[168:171], v[192:195], v[118:121]
	v_mfma_f32_16x16x32_bf16 v[126:129], v[168:171], v[200:203], v[126:129]
	v_mfma_f32_16x16x32_bf16 v[126:129], v[172:175], v[204:207], v[126:129]
	s_setprio 2
	s_barrier
	v_mfma_f32_16x16x32_bf16 v[122:125], v[164:167], v[204:207], v[122:125]
	v_mfma_f32_16x16x32_bf16 v[122:125], v[160:163], v[200:203], v[122:125]
	s_setprio 0
	s_add_i32 s43, 0, 0x18000
	v_add_u32_e32 v135, s43, v140
	s_add_i32 s60, 0, 0x1c000
	ds_read_b128 v[142:145], v135
	ds_read_b128 v[148:151], v135 offset:1024
	ds_read_b128 v[152:155], v135 offset:2048
	ds_read_b128 v[156:159], v135 offset:3072
	v_add_u32_e32 v135, s60, v140
	ds_read_b128 v[160:163], v135
	ds_read_b128 v[164:167], v135 offset:1024
	ds_read_b128 v[168:171], v135 offset:2048
	ds_read_b128 v[172:175], v135 offset:3072
	s_add_u32 s38, s38, 0x400000
	s_addc_u32 s39, s39, 0
	s_mov_b32 m0, s45
	ds_read_b128 v[176:179], v141 offset:32768
	ds_read_b128 v[180:183], v141 offset:33792
	ds_read_b128 v[184:187], v141 offset:34816
	ds_read_b128 v[188:191], v141 offset:35840
	ds_read_b128 v[192:195], v141 offset:36864
	ds_read_b128 v[196:199], v141 offset:37888
	ds_read_b128 v[200:203], v141 offset:38912
	ds_read_b128 v[204:207], v141 offset:39936
	global_load_lds_dwordx4 v130, s[38:39]
	s_mov_b32 m0, s46
	s_nop 0
	global_load_lds_dwordx4 v132, s[38:39]
	s_waitcnt vmcnt(8)
	s_waitcnt lgkmcnt(0)
	s_barrier
	s_setprio 1
	s_waitcnt lgkmcnt(0)
	v_mfma_f32_16x16x32_bf16 v[2:5], v[142:145], v[176:179], v[2:5]
	v_mfma_f32_16x16x32_bf16 v[2:5], v[148:151], v[180:183], v[2:5]
	v_mfma_f32_16x16x32_bf16 v[6:9], v[156:159], v[180:183], v[6:9]
	v_mfma_f32_16x16x32_bf16 v[6:9], v[152:155], v[176:179], v[6:9]
	v_mfma_f32_16x16x32_bf16 v[14:17], v[152:155], v[184:187], v[14:17]
	v_mfma_f32_16x16x32_bf16 v[14:17], v[156:159], v[188:191], v[14:17]
	v_mfma_f32_16x16x32_bf16 v[10:13], v[148:151], v[188:191], v[10:13]
	v_mfma_f32_16x16x32_bf16 v[10:13], v[142:145], v[184:187], v[10:13]
	v_mfma_f32_16x16x32_bf16 v[18:21], v[142:145], v[192:195], v[18:21]
	v_mfma_f32_16x16x32_bf16 v[18:21], v[148:151], v[196:199], v[18:21]
	v_mfma_f32_16x16x32_bf16 v[22:25], v[156:159], v[196:199], v[22:25]
	v_mfma_f32_16x16x32_bf16 v[22:25], v[152:155], v[192:195], v[22:25]
	v_mfma_f32_16x16x32_bf16 v[30:33], v[152:155], v[200:203], v[30:33]
	v_mfma_f32_16x16x32_bf16 v[30:33], v[156:159], v[204:207], v[30:33]
	v_mfma_f32_16x16x32_bf16 v[26:29], v[148:151], v[204:207], v[26:29]
	v_mfma_f32_16x16x32_bf16 v[26:29], v[142:145], v[200:203], v[26:29]
	s_setprio 0
	s_setprio 1
	v_mfma_f32_16x16x32_bf16 v[34:37], v[160:163], v[176:179], v[34:37]
	v_mfma_f32_16x16x32_bf16 v[34:37], v[164:167], v[180:183], v[34:37]
	v_mfma_f32_16x16x32_bf16 v[38:41], v[172:175], v[180:183], v[38:41]
	v_mfma_f32_16x16x32_bf16 v[38:41], v[168:171], v[176:179], v[38:41]
	v_mfma_f32_16x16x32_bf16 v[46:49], v[168:171], v[184:187], v[46:49]
	v_mfma_f32_16x16x32_bf16 v[46:49], v[172:175], v[188:191], v[46:49]
	v_mfma_f32_16x16x32_bf16 v[42:45], v[164:167], v[188:191], v[42:45]
	v_mfma_f32_16x16x32_bf16 v[42:45], v[160:163], v[184:187], v[42:45]
	v_mfma_f32_16x16x32_bf16 v[50:53], v[160:163], v[192:195], v[50:53]
	v_mfma_f32_16x16x32_bf16 v[50:53], v[164:167], v[196:199], v[50:53]
	v_mfma_f32_16x16x32_bf16 v[54:57], v[172:175], v[196:199], v[54:57]
	v_mfma_f32_16x16x32_bf16 v[54:57], v[168:171], v[192:195], v[54:57]
	v_mfma_f32_16x16x32_bf16 v[62:65], v[168:171], v[200:203], v[62:65]
	v_mfma_f32_16x16x32_bf16 v[62:65], v[172:175], v[204:207], v[62:65]
	s_setprio 2
	s_barrier
	v_mfma_f32_16x16x32_bf16 v[58:61], v[164:167], v[204:207], v[58:61]
	v_mfma_f32_16x16x32_bf16 v[58:61], v[160:163], v[200:203], v[58:61]
	s_setprio 0
	s_add_i32 s38, s43, s21
	v_lshl_add_u64 v[138:139], v[138:139], 0, s[8:9]
	s_mov_b32 m0, s38
	ds_read_b128 v[176:179], v141 offset:49152
	ds_read_b128 v[180:183], v141 offset:50176
	ds_read_b128 v[184:187], v141 offset:51200
	ds_read_b128 v[188:191], v141 offset:52224
	ds_read_b128 v[192:195], v141 offset:53248
	ds_read_b128 v[196:199], v141 offset:54272
	ds_read_b128 v[200:203], v141 offset:55296
	ds_read_b128 v[204:207], v141 offset:56320
	global_load_lds_dwordx4 v[138:139], off
	s_add_i32 m0, s38, 0x2000
	s_add_u32 s36, s36, 0x80080
	v_lshl_add_u64 v[138:139], v[208:209], 0, s[8:9]
	s_addc_u32 s37, s37, 0
	s_add_i32 s38, s60, s21
	global_load_lds_dwordx4 v[138:139], off
	s_mov_b32 m0, s38
	v_lshl_add_u64 v[138:139], v[210:211], 0, s[8:9]
	global_load_lds_dwordx4 v136, s[36:37]
	s_add_i32 m0, s38, 0x2000
	s_nop 0
	global_load_lds_dwordx4 v134, s[36:37]
	s_mov_b32 m0, s50
	s_nop 0
	global_load_lds_dwordx4 v[138:139], off
	v_lshl_add_u64 v[138:139], v[212:213], 0, s[8:9]
	s_mov_b32 m0, s51
	s_nop 0
	global_load_lds_dwordx4 v[138:139], off
	s_waitcnt vmcnt(8)
	s_waitcnt lgkmcnt(0)
	s_barrier
	s_setprio 1
	s_waitcnt lgkmcnt(0)
	v_mfma_f32_16x16x32_bf16 v[66:69], v[142:145], v[176:179], v[66:69]
	v_mfma_f32_16x16x32_bf16 v[66:69], v[148:151], v[180:183], v[66:69]
	v_mfma_f32_16x16x32_bf16 v[70:73], v[156:159], v[180:183], v[70:73]
	v_mfma_f32_16x16x32_bf16 v[70:73], v[152:155], v[176:179], v[70:73]
	v_mfma_f32_16x16x32_bf16 v[78:81], v[152:155], v[184:187], v[78:81]
	v_mfma_f32_16x16x32_bf16 v[78:81], v[156:159], v[188:191], v[78:81]
	v_mfma_f32_16x16x32_bf16 v[74:77], v[148:151], v[188:191], v[74:77]
	v_mfma_f32_16x16x32_bf16 v[74:77], v[142:145], v[184:187], v[74:77]
	v_mfma_f32_16x16x32_bf16 v[82:85], v[142:145], v[192:195], v[82:85]
	v_mfma_f32_16x16x32_bf16 v[82:85], v[148:151], v[196:199], v[82:85]
	v_mfma_f32_16x16x32_bf16 v[86:89], v[156:159], v[196:199], v[86:89]
	v_mfma_f32_16x16x32_bf16 v[86:89], v[152:155], v[192:195], v[86:89]
	v_mfma_f32_16x16x32_bf16 v[94:97], v[152:155], v[200:203], v[94:97]
	v_mfma_f32_16x16x32_bf16 v[94:97], v[156:159], v[204:207], v[94:97]
	v_mfma_f32_16x16x32_bf16 v[90:93], v[148:151], v[204:207], v[90:93]
	v_mfma_f32_16x16x32_bf16 v[90:93], v[142:145], v[200:203], v[90:93]
	s_setprio 0
	s_setprio 1
	v_mfma_f32_16x16x32_bf16 v[98:101], v[160:163], v[176:179], v[98:101]
	v_mfma_f32_16x16x32_bf16 v[98:101], v[164:167], v[180:183], v[98:101]
	v_mfma_f32_16x16x32_bf16 v[102:105], v[172:175], v[180:183], v[102:105]
	v_mfma_f32_16x16x32_bf16 v[102:105], v[168:171], v[176:179], v[102:105]
	v_mfma_f32_16x16x32_bf16 v[110:113], v[168:171], v[184:187], v[110:113]
	v_mfma_f32_16x16x32_bf16 v[110:113], v[172:175], v[188:191], v[110:113]
	v_mfma_f32_16x16x32_bf16 v[106:109], v[164:167], v[188:191], v[106:109]
	v_mfma_f32_16x16x32_bf16 v[106:109], v[160:163], v[184:187], v[106:109]
	v_mfma_f32_16x16x32_bf16 v[114:117], v[160:163], v[192:195], v[114:117]
	v_mfma_f32_16x16x32_bf16 v[114:117], v[164:167], v[196:199], v[114:117]
	v_mfma_f32_16x16x32_bf16 v[118:121], v[172:175], v[196:199], v[118:121]
	v_mfma_f32_16x16x32_bf16 v[118:121], v[168:171], v[192:195], v[118:121]
	v_mfma_f32_16x16x32_bf16 v[126:129], v[168:171], v[200:203], v[126:129]
	v_mfma_f32_16x16x32_bf16 v[126:129], v[172:175], v[204:207], v[126:129]
	s_setprio 2
	s_barrier
	v_mfma_f32_16x16x32_bf16 v[122:125], v[164:167], v[204:207], v[122:125]
	v_mfma_f32_16x16x32_bf16 v[122:125], v[160:163], v[200:203], v[122:125]
	s_setprio 0
	s_add_i32 s42, s42, 2
	s_add_u32 s34, s34, 0x100
	s_addc_u32 s35, s35, 0
	s_add_u32 s40, s40, 0x100
	s_addc_u32 s41, s41, 0
	s_cmp_gt_u32 s42, 5
	s_cbranch_scc0 .LBB0_466
	s_and_b64 vcc, exec, s[10:11]
	s_cbranch_vccz .LBB0_469
	s_barrier

.LBB0_495:
	v_add_u32_e32 v14, s58, v140
	v_add_u32_e32 v30, s59, v140
	ds_read_b128 v[2:5], v14
	ds_read_b128 v[6:9], v14 offset:1024
	ds_read_b128 v[10:13], v14 offset:2048
	ds_read_b128 v[14:17], v14 offset:3072
	ds_read_b128 v[18:21], v30
	ds_read_b128 v[22:25], v30 offset:1024
	ds_read_b128 v[26:29], v30 offset:2048
	ds_read_b128 v[30:33], v30 offset:3072
	v_add_u32_e32 v141, 0, v1
	ds_read_b128 v[34:37], v141
	ds_read_b128 v[38:41], v141 offset:1024
	ds_read_b128 v[42:45], v141 offset:2048
	ds_read_b128 v[46:49], v141 offset:3072
	ds_read_b128 v[50:53], v141 offset:4096
	ds_read_b128 v[54:57], v141 offset:5120
	ds_read_b128 v[58:61], v141 offset:6144
	ds_read_b128 v[62:65], v141 offset:7168
	s_waitcnt vmcnt(8)
	s_waitcnt lgkmcnt(0)
	s_barrier
	s_setprio 1
	s_waitcnt lgkmcnt(0)
	v_mfma_f32_16x16x32_bf16 v[66:69], v[2:5], v[34:37], 0
	v_mfma_f32_16x16x32_bf16 v[66:69], v[6:9], v[38:41], v[66:69]
	v_mfma_f32_16x16x32_bf16 v[70:73], v[10:13], v[34:37], 0
	v_mfma_f32_16x16x32_bf16 v[70:73], v[14:17], v[38:41], v[70:73]
	v_mfma_f32_16x16x32_bf16 v[78:81], v[10:13], v[42:45], 0
	v_mfma_f32_16x16x32_bf16 v[78:81], v[14:17], v[46:49], v[78:81]
	v_mfma_f32_16x16x32_bf16 v[74:77], v[2:5], v[42:45], 0
	v_mfma_f32_16x16x32_bf16 v[74:77], v[6:9], v[46:49], v[74:77]
	v_mfma_f32_16x16x32_bf16 v[82:85], v[2:5], v[50:53], 0
	v_mfma_f32_16x16x32_bf16 v[82:85], v[6:9], v[54:57], v[82:85]
	v_mfma_f32_16x16x32_bf16 v[86:89], v[10:13], v[50:53], 0
	v_mfma_f32_16x16x32_bf16 v[86:89], v[14:17], v[54:57], v[86:89]
	v_mfma_f32_16x16x32_bf16 v[94:97], v[10:13], v[58:61], 0
	v_mfma_f32_16x16x32_bf16 v[94:97], v[14:17], v[62:65], v[94:97]
	v_mfma_f32_16x16x32_bf16 v[90:93], v[2:5], v[58:61], 0
	v_mfma_f32_16x16x32_bf16 v[90:93], v[6:9], v[62:65], v[90:93]
	s_setprio 0
	s_setprio 1
	v_mfma_f32_16x16x32_bf16 v[98:101], v[18:21], v[34:37], 0
	v_mfma_f32_16x16x32_bf16 v[34:37], v[26:29], v[34:37], 0
	v_mfma_f32_16x16x32_bf16 v[102:105], v[18:21], v[42:45], 0
	v_mfma_f32_16x16x32_bf16 v[42:45], v[26:29], v[42:45], 0
	v_mfma_f32_16x16x32_bf16 v[106:109], v[18:21], v[50:53], 0
	v_mfma_f32_16x16x32_bf16 v[50:53], v[26:29], v[50:53], 0
	v_mfma_f32_16x16x32_bf16 v[110:113], v[18:21], v[58:61], 0
	v_mfma_f32_16x16x32_bf16 v[58:61], v[26:29], v[58:61], 0
	v_mfma_f32_16x16x32_bf16 v[98:101], v[22:25], v[38:41], v[98:101]
	v_mfma_f32_16x16x32_bf16 v[38:41], v[30:33], v[38:41], v[34:37]
	v_mfma_f32_16x16x32_bf16 v[102:105], v[22:25], v[46:49], v[102:105]
	v_mfma_f32_16x16x32_bf16 v[46:49], v[30:33], v[46:49], v[42:45]
	v_mfma_f32_16x16x32_bf16 v[106:109], v[22:25], v[54:57], v[106:109]
	v_mfma_f32_16x16x32_bf16 v[54:57], v[30:33], v[54:57], v[50:53]
	s_setprio 2
	s_barrier
	v_mfma_f32_16x16x32_bf16 v[110:113], v[22:25], v[62:65], v[110:113]
	v_mfma_f32_16x16x32_bf16 v[62:65], v[30:33], v[62:65], v[58:61]
	s_setprio 0
	v_lshl_add_u64 v[136:137], s[38:39], 0, v[130:131]
	s_add_i32 s62, s58, s46
	v_mov_b32_e32 v135, v131
	v_lshl_add_u64 v[142:143], v[136:137], 0, s[10:11]
	s_mov_b32 m0, s62
	v_lshl_add_u64 v[244:245], s[38:39], 0, v[134:135]
	ds_read_b128 v[34:37], v141 offset:16384
	ds_read_b128 v[42:45], v141 offset:17408
	ds_read_b128 v[50:53], v141 offset:18432
	ds_read_b128 v[58:61], v141 offset:19456
	ds_read_b128 v[114:117], v141 offset:20480
	ds_read_b128 v[118:121], v141 offset:21504
	ds_read_b128 v[122:125], v141 offset:22528
	ds_read_b128 v[126:129], v141 offset:23552
	global_load_lds_dwordx4 v[142:143], off
	v_lshl_add_u64 v[142:143], v[244:245], 0, s[10:11]
	s_add_i32 m0, s62, 0x2000
	s_add_i32 s62, s59, s46
	global_load_lds_dwordx4 v[142:143], off
	s_mov_b32 m0, s62
	v_mov_b32_e32 v139, v131
	global_load_lds_dwordx4 v130, s[40:41]
	s_add_i32 m0, s62, 0x2000
	v_lshl_add_u64 v[246:247], s[36:37], 0, v[138:139]
	v_mov_b32_e32 v133, v131
	global_load_lds_dwordx4 v134, s[40:41]
	v_lshl_add_u64 v[142:143], v[246:247], 0, s[10:11]
	s_mov_b32 m0, s47
	v_lshl_add_u64 v[248:249], s[36:37], 0, v[132:133]
	global_load_lds_dwordx4 v[142:143], off
	v_lshl_add_u64 v[142:143], v[248:249], 0, s[10:11]
	s_mov_b32 m0, s48
	s_nop 0
	global_load_lds_dwordx4 v[142:143], off
	s_waitcnt vmcnt(8)
	s_waitcnt lgkmcnt(0)
	s_barrier
	s_setprio 1
	s_waitcnt lgkmcnt(0)
	v_mfma_f32_16x16x32_bf16 v[142:145], v[2:5], v[34:37], 0
	v_mfma_f32_16x16x32_bf16 v[148:151], v[10:13], v[34:37], 0
	v_mfma_f32_16x16x32_bf16 v[152:155], v[2:5], v[50:53], 0
	v_mfma_f32_16x16x32_bf16 v[156:159], v[10:13], v[50:53], 0
	v_mfma_f32_16x16x32_bf16 v[160:163], v[2:5], v[114:117], 0
	v_mfma_f32_16x16x32_bf16 v[164:167], v[10:13], v[114:117], 0
	v_mfma_f32_16x16x32_bf16 v[2:5], v[2:5], v[122:125], 0
	v_mfma_f32_16x16x32_bf16 v[10:13], v[10:13], v[122:125], 0
	v_mfma_f32_16x16x32_bf16 v[142:145], v[6:9], v[42:45], v[142:145]
	v_mfma_f32_16x16x32_bf16 v[148:151], v[14:17], v[42:45], v[148:151]
	v_mfma_f32_16x16x32_bf16 v[152:155], v[6:9], v[58:61], v[152:155]
	v_mfma_f32_16x16x32_bf16 v[156:159], v[14:17], v[58:61], v[156:159]
	v_mfma_f32_16x16x32_bf16 v[160:163], v[6:9], v[118:121], v[160:163]
	v_mfma_f32_16x16x32_bf16 v[164:167], v[14:17], v[118:121], v[164:167]
	v_mfma_f32_16x16x32_bf16 v[168:171], v[6:9], v[126:129], v[2:5]
	v_mfma_f32_16x16x32_bf16 v[172:175], v[14:17], v[126:129], v[10:13]
	s_setprio 0
	s_setprio 1
	v_mfma_f32_16x16x32_bf16 v[2:5], v[18:21], v[34:37], 0
	v_mfma_f32_16x16x32_bf16 v[6:9], v[26:29], v[34:37], 0
	v_mfma_f32_16x16x32_bf16 v[10:13], v[18:21], v[50:53], 0
	v_mfma_f32_16x16x32_bf16 v[14:17], v[26:29], v[50:53], 0
	v_mfma_f32_16x16x32_bf16 v[34:37], v[18:21], v[114:117], 0
	v_mfma_f32_16x16x32_bf16 v[50:53], v[26:29], v[114:117], 0
	v_mfma_f32_16x16x32_bf16 v[18:21], v[18:21], v[122:125], 0
	v_mfma_f32_16x16x32_bf16 v[26:29], v[26:29], v[122:125], 0
	v_mfma_f32_16x16x32_bf16 v[114:117], v[22:25], v[42:45], v[2:5]
	v_mfma_f32_16x16x32_bf16 v[122:125], v[30:33], v[42:45], v[6:9]
	v_mfma_f32_16x16x32_bf16 v[184:187], v[22:25], v[118:121], v[34:37]
	v_mfma_f32_16x16x32_bf16 v[118:121], v[30:33], v[118:121], v[50:53]
	v_mfma_f32_16x16x32_bf16 v[188:191], v[22:25], v[126:129], v[18:21]
	v_mfma_f32_16x16x32_bf16 v[126:129], v[30:33], v[126:129], v[26:29]
	s_setprio 2
	s_barrier
	v_mfma_f32_16x16x32_bf16 v[176:179], v[22:25], v[58:61], v[10:13]
	v_mfma_f32_16x16x32_bf16 v[180:183], v[30:33], v[58:61], v[14:17]
	s_setprio 0
	s_add_i32 s62, 0, 0x18000
	v_add_u32_e32 v2, s62, v140
	s_add_i32 s63, 0, 0x1c000
	ds_read_b128 v[192:195], v2
	ds_read_b128 v[196:199], v2 offset:1024
	ds_read_b128 v[200:203], v2 offset:2048
	ds_read_b128 v[204:207], v2 offset:3072
	v_add_u32_e32 v2, s63, v140
	ds_read_b128 v[208:211], v2
	ds_read_b128 v[212:215], v2 offset:1024
	ds_read_b128 v[216:219], v2 offset:2048
	ds_read_b128 v[220:223], v2 offset:3072
	s_mov_b32 m0, s49
	ds_read_b128 v[42:45], v141 offset:32768
	ds_read_b128 v[50:53], v141 offset:33792
	ds_read_b128 v[58:61], v141 offset:34816
	ds_read_b128 v[224:227], v141 offset:35840
	ds_read_b128 v[228:231], v141 offset:36864
	ds_read_b128 v[232:235], v141 offset:37888
	ds_read_b128 v[236:239], v141 offset:38912
	ds_read_b128 v[240:243], v141 offset:39936
	global_load_lds_dwordx4 v138, s[42:43]
	s_mov_b32 m0, s50
	s_nop 0
	global_load_lds_dwordx4 v132, s[42:43]
	s_waitcnt vmcnt(8)
	s_waitcnt lgkmcnt(0)
	s_barrier
	s_setprio 1
	s_waitcnt lgkmcnt(0)
	v_mfma_f32_16x16x32_bf16 v[2:5], v[192:195], v[42:45], v[66:69]
	v_mfma_f32_16x16x32_bf16 v[6:9], v[200:203], v[42:45], v[70:73]
	v_mfma_f32_16x16x32_bf16 v[10:13], v[192:195], v[58:61], v[74:77]
	v_mfma_f32_16x16x32_bf16 v[14:17], v[200:203], v[58:61], v[78:81]
	v_mfma_f32_16x16x32_bf16 v[18:21], v[192:195], v[228:231], v[82:85]
	v_mfma_f32_16x16x32_bf16 v[22:25], v[200:203], v[228:231], v[86:89]
	v_mfma_f32_16x16x32_bf16 v[26:29], v[192:195], v[236:239], v[90:93]
	v_mfma_f32_16x16x32_bf16 v[30:33], v[200:203], v[236:239], v[94:97]
	v_mfma_f32_16x16x32_bf16 v[2:5], v[196:199], v[50:53], v[2:5]
	v_mfma_f32_16x16x32_bf16 v[6:9], v[204:207], v[50:53], v[6:9]
	v_mfma_f32_16x16x32_bf16 v[10:13], v[196:199], v[224:227], v[10:13]
	v_mfma_f32_16x16x32_bf16 v[14:17], v[204:207], v[224:227], v[14:17]
	v_mfma_f32_16x16x32_bf16 v[18:21], v[196:199], v[232:235], v[18:21]
	v_mfma_f32_16x16x32_bf16 v[22:25], v[204:207], v[232:235], v[22:25]
	v_mfma_f32_16x16x32_bf16 v[26:29], v[196:199], v[240:243], v[26:29]
	v_mfma_f32_16x16x32_bf16 v[30:33], v[204:207], v[240:243], v[30:33]
	s_setprio 0
	s_setprio 1
	v_mfma_f32_16x16x32_bf16 v[34:37], v[208:211], v[42:45], v[98:101]
	v_mfma_f32_16x16x32_bf16 v[38:41], v[216:219], v[42:45], v[38:41]
	v_mfma_f32_16x16x32_bf16 v[34:37], v[212:215], v[50:53], v[34:37]
	v_mfma_f32_16x16x32_bf16 v[38:41], v[220:223], v[50:53], v[38:41]
	v_mfma_f32_16x16x32_bf16 v[42:45], v[208:211], v[58:61], v[102:105]
	v_mfma_f32_16x16x32_bf16 v[46:49], v[216:219], v[58:61], v[46:49]
	v_mfma_f32_16x16x32_bf16 v[50:53], v[208:211], v[228:231], v[106:109]
	v_mfma_f32_16x16x32_bf16 v[54:57], v[216:219], v[228:231], v[54:57]
	v_mfma_f32_16x16x32_bf16 v[58:61], v[208:211], v[236:239], v[110:113]
	v_mfma_f32_16x16x32_bf16 v[62:65], v[216:219], v[236:239], v[62:65]
	v_mfma_f32_16x16x32_bf16 v[42:45], v[212:215], v[224:227], v[42:45]
	v_mfma_f32_16x16x32_bf16 v[46:49], v[220:223], v[224:227], v[46:49]
	v_mfma_f32_16x16x32_bf16 v[50:53], v[212:215], v[232:235], v[50:53]
	v_mfma_f32_16x16x32_bf16 v[54:57], v[220:223], v[232:235], v[54:57]
	s_setprio 2
	s_barrier
	v_mfma_f32_16x16x32_bf16 v[58:61], v[212:215], v[240:243], v[58:61]
	v_mfma_f32_16x16x32_bf16 v[62:65], v[220:223], v[240:243], v[62:65]
	s_setprio 0
	s_add_i32 s62, s62, s46
	v_lshl_add_u64 v[66:67], v[136:137], 0, s[12:13]
	s_mov_b32 m0, s62
	ds_read_b128 v[102:105], v141 offset:49152
	ds_read_b128 v[106:109], v141 offset:50176
	ds_read_b128 v[110:113], v141 offset:51200
	ds_read_b128 v[224:227], v141 offset:52224
	ds_read_b128 v[228:231], v141 offset:53248
	ds_read_b128 v[232:235], v141 offset:54272
	ds_read_b128 v[236:239], v141 offset:55296
	ds_read_b128 v[240:243], v141 offset:56320
	global_load_lds_dwordx4 v[66:67], off
	v_lshl_add_u64 v[66:67], v[244:245], 0, s[12:13]
	s_add_i32 m0, s62, 0x2000
	s_add_i32 s62, s63, s46
	global_load_lds_dwordx4 v[66:67], off
	s_mov_b32 m0, s62
	v_lshl_add_u64 v[66:67], v[246:247], 0, s[12:13]
	global_load_lds_dwordx4 v130, s[44:45]
	s_add_i32 m0, s62, 0x2000
	s_nop 0
	global_load_lds_dwordx4 v134, s[44:45]
	s_mov_b32 m0, s54
	s_nop 0
	global_load_lds_dwordx4 v[66:67], off
	v_lshl_add_u64 v[66:67], v[248:249], 0, s[12:13]
	s_mov_b32 m0, s55
	s_nop 0
	global_load_lds_dwordx4 v[66:67], off
	s_waitcnt vmcnt(8)
	s_waitcnt lgkmcnt(0)
	s_barrier
	s_setprio 1
	s_waitcnt lgkmcnt(0)
	v_mfma_f32_16x16x32_bf16 v[66:69], v[192:195], v[102:105], v[142:145]
	v_mfma_f32_16x16x32_bf16 v[70:73], v[200:203], v[102:105], v[148:151]
	v_mfma_f32_16x16x32_bf16 v[74:77], v[192:195], v[110:113], v[152:155]
	v_mfma_f32_16x16x32_bf16 v[78:81], v[200:203], v[110:113], v[156:159]
	v_mfma_f32_16x16x32_bf16 v[82:85], v[192:195], v[228:231], v[160:163]
	v_mfma_f32_16x16x32_bf16 v[86:89], v[200:203], v[228:231], v[164:167]
	v_mfma_f32_16x16x32_bf16 v[90:93], v[192:195], v[236:239], v[168:171]
	v_mfma_f32_16x16x32_bf16 v[94:97], v[200:203], v[236:239], v[172:175]
	v_mfma_f32_16x16x32_bf16 v[66:69], v[196:199], v[106:109], v[66:69]
	v_mfma_f32_16x16x32_bf16 v[70:73], v[204:207], v[106:109], v[70:73]
	v_mfma_f32_16x16x32_bf16 v[74:77], v[196:199], v[224:227], v[74:77]
	v_mfma_f32_16x16x32_bf16 v[78:81], v[204:207], v[224:227], v[78:81]
	v_mfma_f32_16x16x32_bf16 v[82:85], v[196:199], v[232:235], v[82:85]
	v_mfma_f32_16x16x32_bf16 v[86:89], v[204:207], v[232:235], v[86:89]
	v_mfma_f32_16x16x32_bf16 v[90:93], v[196:199], v[240:243], v[90:93]
	v_mfma_f32_16x16x32_bf16 v[94:97], v[204:207], v[240:243], v[94:97]
	s_setprio 0
	s_setprio 1
	v_mfma_f32_16x16x32_bf16 v[98:101], v[208:211], v[102:105], v[114:117]
	v_mfma_f32_16x16x32_bf16 v[102:105], v[216:219], v[102:105], v[122:125]
	v_mfma_f32_16x16x32_bf16 v[98:101], v[212:215], v[106:109], v[98:101]
	v_mfma_f32_16x16x32_bf16 v[102:105], v[220:223], v[106:109], v[102:105]
	v_mfma_f32_16x16x32_bf16 v[106:109], v[208:211], v[110:113], v[176:179]
	v_mfma_f32_16x16x32_bf16 v[110:113], v[216:219], v[110:113], v[180:183]
	v_mfma_f32_16x16x32_bf16 v[114:117], v[208:211], v[228:231], v[184:187]
	v_mfma_f32_16x16x32_bf16 v[118:121], v[216:219], v[228:231], v[118:121]
	v_mfma_f32_16x16x32_bf16 v[122:125], v[208:211], v[236:239], v[188:191]
	v_mfma_f32_16x16x32_bf16 v[126:129], v[216:219], v[236:239], v[126:129]
	v_mfma_f32_16x16x32_bf16 v[106:109], v[212:215], v[224:227], v[106:109]
	v_mfma_f32_16x16x32_bf16 v[110:113], v[220:223], v[224:227], v[110:113]
	v_mfma_f32_16x16x32_bf16 v[114:117], v[212:215], v[232:235], v[114:117]
	v_mfma_f32_16x16x32_bf16 v[118:121], v[220:223], v[232:235], v[118:121]
	s_setprio 2
	s_barrier
	v_mfma_f32_16x16x32_bf16 v[122:125], v[212:215], v[240:243], v[122:125]
	v_mfma_f32_16x16x32_bf16 v[126:129], v[220:223], v[240:243], v[126:129]
	s_setprio 0
	s_add_i32 s27, s27, 2
	s_cmp_ge_i32 s27, s15
	s_cbranch_scc0 .LBB0_495
	v_mov_b32_e32 v136, v130
	s_branch .LBB0_498

.LBB0_499:
	v_add_u32_e32 v133, s58, v140
	ds_read_b128 v[142:145], v133
	ds_read_b128 v[148:151], v133 offset:1024
	ds_read_b128 v[152:155], v133 offset:2048
	ds_read_b128 v[156:159], v133 offset:3072
	v_add_u32_e32 v133, s59, v140
	ds_read_b128 v[160:163], v133
	ds_read_b128 v[164:167], v133 offset:1024
	ds_read_b128 v[168:171], v133 offset:2048
	ds_read_b128 v[172:175], v133 offset:3072
	s_add_u32 s38, s36, 0xfff80080
	s_addc_u32 s39, s37, -1
	s_cmp_eq_u32 s42, 4
	s_cselect_b32 s41, s31, s39
	s_cselect_b32 s40, s30, s38
	s_cselect_b32 s39, s35, s27
	s_cselect_b32 s38, s34, s15
	s_mov_b32 m0, s56
	v_add_u32_e32 v141, 0, v1
	ds_read_b128 v[176:179], v141
	ds_read_b128 v[180:183], v141 offset:1024
	ds_read_b128 v[184:187], v141 offset:2048
	ds_read_b128 v[188:191], v141 offset:3072
	ds_read_b128 v[192:195], v141 offset:4096
	ds_read_b128 v[196:199], v141 offset:5120
	ds_read_b128 v[200:203], v141 offset:6144
	ds_read_b128 v[204:207], v141 offset:7168
	global_load_lds_dwordx4 v130, s[36:37]
	s_mov_b32 m0, s57
	v_mov_b32_e32 v133, v131
	global_load_lds_dwordx4 v132, s[36:37]
	s_waitcnt vmcnt(8)
	s_waitcnt lgkmcnt(0)
	s_barrier
	s_setprio 1
	s_waitcnt lgkmcnt(0)
	v_mfma_f32_16x16x32_bf16 v[2:5], v[142:145], v[176:179], v[2:5]
	v_mfma_f32_16x16x32_bf16 v[2:5], v[148:151], v[180:183], v[2:5]
	v_mfma_f32_16x16x32_bf16 v[6:9], v[156:159], v[180:183], v[6:9]
	v_mfma_f32_16x16x32_bf16 v[6:9], v[152:155], v[176:179], v[6:9]
	v_mfma_f32_16x16x32_bf16 v[14:17], v[152:155], v[184:187], v[14:17]
	v_mfma_f32_16x16x32_bf16 v[14:17], v[156:159], v[188:191], v[14:17]
	v_mfma_f32_16x16x32_bf16 v[10:13], v[148:151], v[188:191], v[10:13]
	v_mfma_f32_16x16x32_bf16 v[10:13], v[142:145], v[184:187], v[10:13]
	v_mfma_f32_16x16x32_bf16 v[18:21], v[142:145], v[192:195], v[18:21]
	v_mfma_f32_16x16x32_bf16 v[18:21], v[148:151], v[196:199], v[18:21]
	v_mfma_f32_16x16x32_bf16 v[22:25], v[156:159], v[196:199], v[22:25]
	v_mfma_f32_16x16x32_bf16 v[22:25], v[152:155], v[192:195], v[22:25]
	v_mfma_f32_16x16x32_bf16 v[30:33], v[152:155], v[200:203], v[30:33]
	v_mfma_f32_16x16x32_bf16 v[30:33], v[156:159], v[204:207], v[30:33]
	v_mfma_f32_16x16x32_bf16 v[26:29], v[148:151], v[204:207], v[26:29]
	v_mfma_f32_16x16x32_bf16 v[26:29], v[142:145], v[200:203], v[26:29]
	s_setprio 0
	s_setprio 1
	v_mfma_f32_16x16x32_bf16 v[34:37], v[160:163], v[176:179], v[34:37]
	v_mfma_f32_16x16x32_bf16 v[34:37], v[164:167], v[180:183], v[34:37]
	v_mfma_f32_16x16x32_bf16 v[38:41], v[172:175], v[180:183], v[38:41]
	v_mfma_f32_16x16x32_bf16 v[38:41], v[168:171], v[176:179], v[38:41]
	v_mfma_f32_16x16x32_bf16 v[46:49], v[168:171], v[184:187], v[46:49]
	v_mfma_f32_16x16x32_bf16 v[46:49], v[172:175], v[188:191], v[46:49]
	v_mfma_f32_16x16x32_bf16 v[42:45], v[164:167], v[188:191], v[42:45]
	v_mfma_f32_16x16x32_bf16 v[42:45], v[160:163], v[184:187], v[42:45]
	v_mfma_f32_16x16x32_bf16 v[50:53], v[160:163], v[192:195], v[50:53]
	v_mfma_f32_16x16x32_bf16 v[50:53], v[164:167], v[196:199], v[50:53]
	v_mfma_f32_16x16x32_bf16 v[54:57], v[172:175], v[196:199], v[54:57]
	v_mfma_f32_16x16x32_bf16 v[54:57], v[168:171], v[192:195], v[54:57]
	v_mfma_f32_16x16x32_bf16 v[62:65], v[168:171], v[200:203], v[62:65]
	v_mfma_f32_16x16x32_bf16 v[62:65], v[172:175], v[204:207], v[62:65]
	s_setprio 2
	s_barrier
	v_mfma_f32_16x16x32_bf16 v[58:61], v[164:167], v[204:207], v[58:61]
	v_mfma_f32_16x16x32_bf16 v[58:61], v[160:163], v[200:203], v[58:61]
	s_setprio 0
	s_add_i32 s43, s58, s46
	s_mov_b32 m0, s43
	ds_read_b128 v[176:179], v141 offset:16384
	ds_read_b128 v[180:183], v141 offset:17408
	ds_read_b128 v[184:187], v141 offset:18432
	ds_read_b128 v[188:191], v141 offset:19456
	ds_read_b128 v[192:195], v141 offset:20480
	ds_read_b128 v[196:199], v141 offset:21504
	ds_read_b128 v[200:203], v141 offset:22528
	ds_read_b128 v[204:207], v141 offset:23552
	global_load_lds_dwordx4 v136, s[38:39]
	s_add_i32 m0, s43, 0x2000
	s_add_u32 s44, s38, 0x400000
	s_addc_u32 s45, s39, 0
	s_add_i32 s43, s59, s46
	global_load_lds_dwordx4 v134, s[38:39]
	s_mov_b32 m0, s43
	v_mov_b32_e32 v137, v131
	global_load_lds_dwordx4 v136, s[44:45]
	s_add_i32 m0, s43, 0x2000
	v_mov_b32_e32 v135, v131
	global_load_lds_dwordx4 v134, s[44:45]
	s_mov_b32 m0, s47
	v_lshl_add_u64 v[138:139], s[38:39], 0, v[136:137]
	global_load_lds_dwordx4 v130, s[40:41]
	s_mov_b32 m0, s48
	v_lshl_add_u64 v[208:209], s[38:39], 0, v[134:135]
	global_load_lds_dwordx4 v132, s[40:41]
	s_waitcnt vmcnt(8)
	s_waitcnt lgkmcnt(0)
	v_lshl_add_u64 v[210:211], s[40:41], 0, v[130:131]
	v_lshl_add_u64 v[212:213], s[40:41], 0, v[132:133]
	s_barrier
	s_setprio 1
	s_waitcnt lgkmcnt(0)
	v_mfma_f32_16x16x32_bf16 v[66:69], v[142:145], v[176:179], v[66:69]
	v_mfma_f32_16x16x32_bf16 v[66:69], v[148:151], v[180:183], v[66:69]
	v_mfma_f32_16x16x32_bf16 v[70:73], v[156:159], v[180:183], v[70:73]
	v_mfma_f32_16x16x32_bf16 v[70:73], v[152:155], v[176:179], v[70:73]
	v_mfma_f32_16x16x32_bf16 v[78:81], v[152:155], v[184:187], v[78:81]
	v_mfma_f32_16x16x32_bf16 v[78:81], v[156:159], v[188:191], v[78:81]
	v_mfma_f32_16x16x32_bf16 v[74:77], v[148:151], v[188:191], v[74:77]
	v_mfma_f32_16x16x32_bf16 v[74:77], v[142:145], v[184:187], v[74:77]
	v_mfma_f32_16x16x32_bf16 v[82:85], v[142:145], v[192:195], v[82:85]
	v_mfma_f32_16x16x32_bf16 v[82:85], v[148:151], v[196:199], v[82:85]
	v_mfma_f32_16x16x32_bf16 v[86:89], v[156:159], v[196:199], v[86:89]
	v_mfma_f32_16x16x32_bf16 v[86:89], v[152:155], v[192:195], v[86:89]
	v_mfma_f32_16x16x32_bf16 v[94:97], v[152:155], v[200:203], v[94:97]
	v_mfma_f32_16x16x32_bf16 v[94:97], v[156:159], v[204:207], v[94:97]
	v_mfma_f32_16x16x32_bf16 v[90:93], v[148:151], v[204:207], v[90:93]
	v_mfma_f32_16x16x32_bf16 v[90:93], v[142:145], v[200:203], v[90:93]
	s_setprio 0
	s_setprio 1
	v_mfma_f32_16x16x32_bf16 v[98:101], v[160:163], v[176:179], v[98:101]
	v_mfma_f32_16x16x32_bf16 v[98:101], v[164:167], v[180:183], v[98:101]
	v_mfma_f32_16x16x32_bf16 v[102:105], v[172:175], v[180:183], v[102:105]
	v_mfma_f32_16x16x32_bf16 v[102:105], v[168:171], v[176:179], v[102:105]
	v_mfma_f32_16x16x32_bf16 v[110:113], v[168:171], v[184:187], v[110:113]
	v_mfma_f32_16x16x32_bf16 v[110:113], v[172:175], v[188:191], v[110:113]
	v_mfma_f32_16x16x32_bf16 v[106:109], v[164:167], v[188:191], v[106:109]
	v_mfma_f32_16x16x32_bf16 v[106:109], v[160:163], v[184:187], v[106:109]
	v_mfma_f32_16x16x32_bf16 v[114:117], v[160:163], v[192:195], v[114:117]
	v_mfma_f32_16x16x32_bf16 v[114:117], v[164:167], v[196:199], v[114:117]
	v_mfma_f32_16x16x32_bf16 v[118:121], v[172:175], v[196:199], v[118:121]
	v_mfma_f32_16x16x32_bf16 v[118:121], v[168:171], v[192:195], v[118:121]
	v_mfma_f32_16x16x32_bf16 v[126:129], v[168:171], v[200:203], v[126:129]
	v_mfma_f32_16x16x32_bf16 v[126:129], v[172:175], v[204:207], v[126:129]
	s_setprio 2
	s_barrier
	v_mfma_f32_16x16x32_bf16 v[122:125], v[164:167], v[204:207], v[122:125]
	v_mfma_f32_16x16x32_bf16 v[122:125], v[160:163], v[200:203], v[122:125]
	s_setprio 0
	s_add_i32 s43, 0, 0x18000
	v_add_u32_e32 v135, s43, v140
	s_add_i32 s44, 0, 0x1c000
	ds_read_b128 v[142:145], v135
	ds_read_b128 v[148:151], v135 offset:1024
	ds_read_b128 v[152:155], v135 offset:2048
	ds_read_b128 v[156:159], v135 offset:3072
	v_add_u32_e32 v135, s44, v140
	ds_read_b128 v[160:163], v135
	ds_read_b128 v[164:167], v135 offset:1024
	ds_read_b128 v[168:171], v135 offset:2048
	ds_read_b128 v[172:175], v135 offset:3072
	s_add_u32 s40, s40, 0x80000
	s_addc_u32 s41, s41, 0
	s_mov_b32 m0, s49
	ds_read_b128 v[176:179], v141 offset:32768
	ds_read_b128 v[180:183], v141 offset:33792
	ds_read_b128 v[184:187], v141 offset:34816
	ds_read_b128 v[188:191], v141 offset:35840
	ds_read_b128 v[192:195], v141 offset:36864
	ds_read_b128 v[196:199], v141 offset:37888
	ds_read_b128 v[200:203], v141 offset:38912
	ds_read_b128 v[204:207], v141 offset:39936
	global_load_lds_dwordx4 v130, s[40:41]
	s_mov_b32 m0, s50
	s_nop 0
	global_load_lds_dwordx4 v132, s[40:41]
	s_waitcnt vmcnt(8)
	s_waitcnt lgkmcnt(0)
	s_barrier
	s_setprio 1
	s_waitcnt lgkmcnt(0)
	v_mfma_f32_16x16x32_bf16 v[2:5], v[142:145], v[176:179], v[2:5]
	v_mfma_f32_16x16x32_bf16 v[2:5], v[148:151], v[180:183], v[2:5]
	v_mfma_f32_16x16x32_bf16 v[6:9], v[156:159], v[180:183], v[6:9]
	v_mfma_f32_16x16x32_bf16 v[6:9], v[152:155], v[176:179], v[6:9]
	v_mfma_f32_16x16x32_bf16 v[14:17], v[152:155], v[184:187], v[14:17]
	v_mfma_f32_16x16x32_bf16 v[14:17], v[156:159], v[188:191], v[14:17]
	v_mfma_f32_16x16x32_bf16 v[10:13], v[148:151], v[188:191], v[10:13]
	v_mfma_f32_16x16x32_bf16 v[10:13], v[142:145], v[184:187], v[10:13]
	v_mfma_f32_16x16x32_bf16 v[18:21], v[142:145], v[192:195], v[18:21]
	v_mfma_f32_16x16x32_bf16 v[18:21], v[148:151], v[196:199], v[18:21]
	v_mfma_f32_16x16x32_bf16 v[22:25], v[156:159], v[196:199], v[22:25]
	v_mfma_f32_16x16x32_bf16 v[22:25], v[152:155], v[192:195], v[22:25]
	v_mfma_f32_16x16x32_bf16 v[30:33], v[152:155], v[200:203], v[30:33]
	v_mfma_f32_16x16x32_bf16 v[30:33], v[156:159], v[204:207], v[30:33]
	v_mfma_f32_16x16x32_bf16 v[26:29], v[148:151], v[204:207], v[26:29]
	v_mfma_f32_16x16x32_bf16 v[26:29], v[142:145], v[200:203], v[26:29]
	s_setprio 0
	s_setprio 1
	v_mfma_f32_16x16x32_bf16 v[34:37], v[160:163], v[176:179], v[34:37]
	v_mfma_f32_16x16x32_bf16 v[34:37], v[164:167], v[180:183], v[34:37]
	v_mfma_f32_16x16x32_bf16 v[38:41], v[172:175], v[180:183], v[38:41]
	v_mfma_f32_16x16x32_bf16 v[38:41], v[168:171], v[176:179], v[38:41]
	v_mfma_f32_16x16x32_bf16 v[46:49], v[168:171], v[184:187], v[46:49]
	v_mfma_f32_16x16x32_bf16 v[46:49], v[172:175], v[188:191], v[46:49]
	v_mfma_f32_16x16x32_bf16 v[42:45], v[164:167], v[188:191], v[42:45]
	v_mfma_f32_16x16x32_bf16 v[42:45], v[160:163], v[184:187], v[42:45]
	v_mfma_f32_16x16x32_bf16 v[50:53], v[160:163], v[192:195], v[50:53]
	v_mfma_f32_16x16x32_bf16 v[50:53], v[164:167], v[196:199], v[50:53]
	v_mfma_f32_16x16x32_bf16 v[54:57], v[172:175], v[196:199], v[54:57]
	v_mfma_f32_16x16x32_bf16 v[54:57], v[168:171], v[192:195], v[54:57]
	v_mfma_f32_16x16x32_bf16 v[62:65], v[168:171], v[200:203], v[62:65]
	v_mfma_f32_16x16x32_bf16 v[62:65], v[172:175], v[204:207], v[62:65]
	s_setprio 2
	s_barrier
	v_mfma_f32_16x16x32_bf16 v[58:61], v[164:167], v[204:207], v[58:61]
	v_mfma_f32_16x16x32_bf16 v[58:61], v[160:163], v[200:203], v[58:61]
	s_setprio 0
	s_add_i32 s40, s43, s46
	v_lshl_add_u64 v[138:139], v[138:139], 0, s[6:7]
	s_mov_b32 m0, s40
	ds_read_b128 v[176:179], v141 offset:49152
	ds_read_b128 v[180:183], v141 offset:50176
	ds_read_b128 v[184:187], v141 offset:51200
	ds_read_b128 v[188:191], v141 offset:52224
	ds_read_b128 v[192:195], v141 offset:53248
	ds_read_b128 v[196:199], v141 offset:54272
	ds_read_b128 v[200:203], v141 offset:55296
	ds_read_b128 v[204:207], v141 offset:56320
	global_load_lds_dwordx4 v[138:139], off
	s_add_i32 m0, s40, 0x2000
	s_add_u32 s38, s38, 0x400080
	v_lshl_add_u64 v[138:139], v[208:209], 0, s[6:7]
	s_addc_u32 s39, s39, 0
	s_add_i32 s40, s44, s46
	global_load_lds_dwordx4 v[138:139], off
	s_mov_b32 m0, s40
	v_lshl_add_u64 v[138:139], v[210:211], 0, s[6:7]
	global_load_lds_dwordx4 v136, s[38:39]
	s_add_i32 m0, s40, 0x2000
	s_nop 0
	global_load_lds_dwordx4 v134, s[38:39]
	s_mov_b32 m0, s54
	s_nop 0
	global_load_lds_dwordx4 v[138:139], off
	v_lshl_add_u64 v[138:139], v[212:213], 0, s[6:7]
	s_mov_b32 m0, s55
	s_nop 0
	global_load_lds_dwordx4 v[138:139], off
	s_waitcnt vmcnt(8)
	s_waitcnt lgkmcnt(0)
	s_barrier
	s_setprio 1
	s_waitcnt lgkmcnt(0)
	v_mfma_f32_16x16x32_bf16 v[66:69], v[142:145], v[176:179], v[66:69]
	v_mfma_f32_16x16x32_bf16 v[66:69], v[148:151], v[180:183], v[66:69]
	v_mfma_f32_16x16x32_bf16 v[70:73], v[156:159], v[180:183], v[70:73]
	v_mfma_f32_16x16x32_bf16 v[70:73], v[152:155], v[176:179], v[70:73]
	v_mfma_f32_16x16x32_bf16 v[78:81], v[152:155], v[184:187], v[78:81]
	v_mfma_f32_16x16x32_bf16 v[78:81], v[156:159], v[188:191], v[78:81]
	v_mfma_f32_16x16x32_bf16 v[74:77], v[148:151], v[188:191], v[74:77]
	v_mfma_f32_16x16x32_bf16 v[74:77], v[142:145], v[184:187], v[74:77]
	v_mfma_f32_16x16x32_bf16 v[82:85], v[142:145], v[192:195], v[82:85]
	v_mfma_f32_16x16x32_bf16 v[82:85], v[148:151], v[196:199], v[82:85]
	v_mfma_f32_16x16x32_bf16 v[86:89], v[156:159], v[196:199], v[86:89]
	v_mfma_f32_16x16x32_bf16 v[86:89], v[152:155], v[192:195], v[86:89]
	v_mfma_f32_16x16x32_bf16 v[94:97], v[152:155], v[200:203], v[94:97]
	v_mfma_f32_16x16x32_bf16 v[94:97], v[156:159], v[204:207], v[94:97]
	v_mfma_f32_16x16x32_bf16 v[90:93], v[148:151], v[204:207], v[90:93]
	v_mfma_f32_16x16x32_bf16 v[90:93], v[142:145], v[200:203], v[90:93]
	s_setprio 0
	s_setprio 1
	v_mfma_f32_16x16x32_bf16 v[98:101], v[160:163], v[176:179], v[98:101]
	v_mfma_f32_16x16x32_bf16 v[98:101], v[164:167], v[180:183], v[98:101]
	v_mfma_f32_16x16x32_bf16 v[102:105], v[172:175], v[180:183], v[102:105]
	v_mfma_f32_16x16x32_bf16 v[102:105], v[168:171], v[176:179], v[102:105]
	v_mfma_f32_16x16x32_bf16 v[110:113], v[168:171], v[184:187], v[110:113]
	v_mfma_f32_16x16x32_bf16 v[110:113], v[172:175], v[188:191], v[110:113]
	v_mfma_f32_16x16x32_bf16 v[106:109], v[164:167], v[188:191], v[106:109]
	v_mfma_f32_16x16x32_bf16 v[106:109], v[160:163], v[184:187], v[106:109]
	v_mfma_f32_16x16x32_bf16 v[114:117], v[160:163], v[192:195], v[114:117]
	v_mfma_f32_16x16x32_bf16 v[114:117], v[164:167], v[196:199], v[114:117]
	v_mfma_f32_16x16x32_bf16 v[118:121], v[172:175], v[196:199], v[118:121]
	v_mfma_f32_16x16x32_bf16 v[118:121], v[168:171], v[192:195], v[118:121]
	v_mfma_f32_16x16x32_bf16 v[126:129], v[168:171], v[200:203], v[126:129]
	v_mfma_f32_16x16x32_bf16 v[126:129], v[172:175], v[204:207], v[126:129]
	s_setprio 2
	s_barrier
	v_mfma_f32_16x16x32_bf16 v[122:125], v[164:167], v[204:207], v[122:125]
	v_mfma_f32_16x16x32_bf16 v[122:125], v[160:163], v[200:203], v[122:125]
	s_setprio 0
	s_add_i32 s42, s42, 2
	s_add_u32 s36, s36, 0x100
	s_addc_u32 s37, s37, 0
	s_add_u32 s15, s15, 0x100
	s_addc_u32 s27, s27, 0
	s_cmp_gt_u32 s42, 5
	s_cbranch_scc0 .LBB0_499
	s_and_b64 vcc, exec, s[8:9]
	s_cbranch_vccz .LBB0_502
	s_barrier

.LBB0_528:
	s_add_i32 s53, 0, 0x10000
	s_add_i32 s72, 0, 0x14000
	v_add_u32_e32 v16, s53, v147
	v_add_u32_e32 v32, s72, v147
	ds_read_b128 v[4:7], v16
	ds_read_b128 v[8:11], v16 offset:1024
	ds_read_b128 v[12:15], v16 offset:2048
	ds_read_b128 v[16:19], v16 offset:3072
	ds_read_b128 v[20:23], v32
	ds_read_b128 v[24:27], v32 offset:1024
	ds_read_b128 v[28:31], v32 offset:2048
	ds_read_b128 v[32:35], v32 offset:3072
	v_add_u32_e32 v231, 0, v146
	ds_read_b128 v[36:39], v231
	ds_read_b128 v[40:43], v231 offset:1024
	ds_read_b128 v[44:47], v231 offset:2048
	ds_read_b128 v[48:51], v231 offset:3072
	ds_read_b128 v[52:55], v231 offset:4096
	ds_read_b128 v[56:59], v231 offset:5120
	ds_read_b128 v[60:63], v231 offset:6144
	ds_read_b128 v[64:67], v231 offset:7168
	s_waitcnt vmcnt(8)
	s_waitcnt lgkmcnt(0)
	s_barrier
	s_setprio 1
	s_waitcnt lgkmcnt(0)
	v_mfma_f32_16x16x32_f16 v[68:71], v[4:7], v[36:39], 0
	v_mfma_f32_16x16x32_f16 v[68:71], v[8:11], v[40:43], v[68:71]
	v_mfma_f32_16x16x32_f16 v[72:75], v[12:15], v[36:39], 0
	v_mfma_f32_16x16x32_f16 v[72:75], v[16:19], v[40:43], v[72:75]
	v_mfma_f32_16x16x32_f16 v[80:83], v[12:15], v[44:47], 0
	v_mfma_f32_16x16x32_f16 v[80:83], v[16:19], v[48:51], v[80:83]
	v_mfma_f32_16x16x32_f16 v[76:79], v[4:7], v[44:47], 0
	v_mfma_f32_16x16x32_f16 v[76:79], v[8:11], v[48:51], v[76:79]
	v_mfma_f32_16x16x32_f16 v[84:87], v[4:7], v[52:55], 0
	v_mfma_f32_16x16x32_f16 v[84:87], v[8:11], v[56:59], v[84:87]
	v_mfma_f32_16x16x32_f16 v[88:91], v[12:15], v[52:55], 0
	v_mfma_f32_16x16x32_f16 v[88:91], v[16:19], v[56:59], v[88:91]
	v_mfma_f32_16x16x32_f16 v[96:99], v[12:15], v[60:63], 0
	v_mfma_f32_16x16x32_f16 v[96:99], v[16:19], v[64:67], v[96:99]
	v_mfma_f32_16x16x32_f16 v[92:95], v[4:7], v[60:63], 0
	v_mfma_f32_16x16x32_f16 v[92:95], v[8:11], v[64:67], v[92:95]
	s_setprio 0
	s_setprio 1
	v_mfma_f32_16x16x32_f16 v[100:103], v[20:23], v[36:39], 0
	v_mfma_f32_16x16x32_f16 v[36:39], v[28:31], v[36:39], 0
	v_mfma_f32_16x16x32_f16 v[104:107], v[20:23], v[44:47], 0
	v_mfma_f32_16x16x32_f16 v[44:47], v[28:31], v[44:47], 0
	v_mfma_f32_16x16x32_f16 v[108:111], v[20:23], v[52:55], 0
	v_mfma_f32_16x16x32_f16 v[52:55], v[28:31], v[52:55], 0
	v_mfma_f32_16x16x32_f16 v[112:115], v[20:23], v[60:63], 0
	v_mfma_f32_16x16x32_f16 v[60:63], v[28:31], v[60:63], 0
	v_mfma_f32_16x16x32_f16 v[100:103], v[24:27], v[40:43], v[100:103]
	v_mfma_f32_16x16x32_f16 v[40:43], v[32:35], v[40:43], v[36:39]
	v_mfma_f32_16x16x32_f16 v[104:107], v[24:27], v[48:51], v[104:107]
	v_mfma_f32_16x16x32_f16 v[48:51], v[32:35], v[48:51], v[44:47]
	v_mfma_f32_16x16x32_f16 v[108:111], v[24:27], v[56:59], v[108:111]
	v_mfma_f32_16x16x32_f16 v[56:59], v[32:35], v[56:59], v[52:55]
	s_setprio 2
	s_barrier
	v_mfma_f32_16x16x32_f16 v[112:115], v[24:27], v[64:67], v[112:115]
	v_mfma_f32_16x16x32_f16 v[64:67], v[32:35], v[64:67], v[60:63]
	s_setprio 0
	v_lshl_add_u64 v[136:137], s[6:7], 0, v[2:3]
	s_add_i32 s53, s53, s38
	v_mov_b32_e32 v135, v3
	v_lshl_add_u64 v[140:141], v[136:137], 0, s[74:75]
	s_mov_b32 m0, s53
	v_lshl_add_u64 v[144:145], s[6:7], 0, v[134:135]
	ds_read_b128 v[36:39], v231 offset:16384
	ds_read_b128 v[44:47], v231 offset:17408
	ds_read_b128 v[52:55], v231 offset:18432
	ds_read_b128 v[60:63], v231 offset:19456
	ds_read_b128 v[116:119], v231 offset:20480
	ds_read_b128 v[120:123], v231 offset:21504
	ds_read_b128 v[124:127], v231 offset:22528
	ds_read_b128 v[128:131], v231 offset:23552
	global_load_lds_dwordx4 v[140:141], off
	v_lshl_add_u64 v[140:141], v[144:145], 0, s[74:75]
	s_add_i32 m0, s53, 0x2000
	s_add_i32 s53, s72, s38
	global_load_lds_dwordx4 v[140:141], off
	s_mov_b32 m0, s53
	v_mov_b32_e32 v139, v3
	global_load_lds_dwordx4 v2, s[16:17]
	s_add_i32 m0, s53, 0x2000
	v_lshl_add_u64 v[248:249], s[8:9], 0, v[138:139]
	v_mov_b32_e32 v133, v3
	global_load_lds_dwordx4 v134, s[16:17]
	v_lshl_add_u64 v[140:141], v[248:249], 0, s[74:75]
	s_mov_b32 m0, s58
	v_lshl_add_u64 v[250:251], s[8:9], 0, v[132:133]
	global_load_lds_dwordx4 v[140:141], off
	v_lshl_add_u64 v[140:141], v[250:251], 0, s[74:75]
	s_mov_b32 m0, s59
	s_nop 0
	global_load_lds_dwordx4 v[140:141], off
	s_waitcnt vmcnt(8)
	s_waitcnt lgkmcnt(0)
	s_barrier
	s_setprio 1
	s_waitcnt lgkmcnt(0)
	v_mfma_f32_16x16x32_f16 v[140:143], v[4:7], v[36:39], 0
	v_mfma_f32_16x16x32_f16 v[148:151], v[12:15], v[36:39], 0
	v_mfma_f32_16x16x32_f16 v[152:155], v[4:7], v[52:55], 0
	v_mfma_f32_16x16x32_f16 v[156:159], v[12:15], v[52:55], 0
	v_mfma_f32_16x16x32_f16 v[160:163], v[4:7], v[116:119], 0
	v_mfma_f32_16x16x32_f16 v[164:167], v[12:15], v[116:119], 0
	v_mfma_f32_16x16x32_f16 v[4:7], v[4:7], v[124:127], 0
	v_mfma_f32_16x16x32_f16 v[12:15], v[12:15], v[124:127], 0
	v_mfma_f32_16x16x32_f16 v[140:143], v[8:11], v[44:47], v[140:143]
	v_mfma_f32_16x16x32_f16 v[148:151], v[16:19], v[44:47], v[148:151]
	v_mfma_f32_16x16x32_f16 v[152:155], v[8:11], v[60:63], v[152:155]
	v_mfma_f32_16x16x32_f16 v[156:159], v[16:19], v[60:63], v[156:159]
	v_mfma_f32_16x16x32_f16 v[160:163], v[8:11], v[120:123], v[160:163]
	v_mfma_f32_16x16x32_f16 v[164:167], v[16:19], v[120:123], v[164:167]
	v_mfma_f32_16x16x32_f16 v[168:171], v[8:11], v[128:131], v[4:7]
	v_mfma_f32_16x16x32_f16 v[172:175], v[16:19], v[128:131], v[12:15]
	s_setprio 0
	s_setprio 1
	v_mfma_f32_16x16x32_f16 v[4:7], v[20:23], v[36:39], 0
	v_mfma_f32_16x16x32_f16 v[8:11], v[28:31], v[36:39], 0
	v_mfma_f32_16x16x32_f16 v[12:15], v[20:23], v[52:55], 0
	v_mfma_f32_16x16x32_f16 v[16:19], v[28:31], v[52:55], 0
	v_mfma_f32_16x16x32_f16 v[36:39], v[20:23], v[116:119], 0
	v_mfma_f32_16x16x32_f16 v[52:55], v[28:31], v[116:119], 0
	v_mfma_f32_16x16x32_f16 v[20:23], v[20:23], v[124:127], 0
	v_mfma_f32_16x16x32_f16 v[28:31], v[28:31], v[124:127], 0
	v_mfma_f32_16x16x32_f16 v[116:119], v[24:27], v[44:47], v[4:7]
	v_mfma_f32_16x16x32_f16 v[124:127], v[32:35], v[44:47], v[8:11]
	v_mfma_f32_16x16x32_f16 v[184:187], v[24:27], v[120:123], v[36:39]
	v_mfma_f32_16x16x32_f16 v[120:123], v[32:35], v[120:123], v[52:55]
	v_mfma_f32_16x16x32_f16 v[188:191], v[24:27], v[128:131], v[20:23]
	v_mfma_f32_16x16x32_f16 v[128:131], v[32:35], v[128:131], v[28:31]
	s_setprio 2
	s_barrier
	v_mfma_f32_16x16x32_f16 v[176:179], v[24:27], v[60:63], v[12:15]
	v_mfma_f32_16x16x32_f16 v[180:183], v[32:35], v[60:63], v[16:19]
	s_setprio 0
	s_add_i32 s53, 0, 0x18000
	v_add_u32_e32 v4, s53, v147
	s_add_i32 s72, 0, 0x1c000
	ds_read_b128 v[192:195], v4
	ds_read_b128 v[196:199], v4 offset:1024
	ds_read_b128 v[200:203], v4 offset:2048
	ds_read_b128 v[204:207], v4 offset:3072
	v_add_u32_e32 v4, s72, v147
	ds_read_b128 v[208:211], v4
	ds_read_b128 v[212:215], v4 offset:1024
	ds_read_b128 v[216:219], v4 offset:2048
	ds_read_b128 v[220:223], v4 offset:3072
	s_mov_b32 m0, s60
	ds_read_b128 v[44:47], v231 offset:32768
	ds_read_b128 v[52:55], v231 offset:33792
	ds_read_b128 v[60:63], v231 offset:34816
	ds_read_b128 v[224:227], v231 offset:35840
	ds_read_b128 v[232:235], v231 offset:36864
	ds_read_b128 v[236:239], v231 offset:37888
	ds_read_b128 v[240:243], v231 offset:38912
	ds_read_b128 v[244:247], v231 offset:39936
	global_load_lds_dwordx4 v138, s[26:27]
	s_mov_b32 m0, s61
	s_nop 0
	global_load_lds_dwordx4 v132, s[26:27]
	s_waitcnt vmcnt(8)
	s_waitcnt lgkmcnt(0)
	s_barrier
	s_setprio 1
	s_waitcnt lgkmcnt(0)
	v_mfma_f32_16x16x32_f16 v[4:7], v[192:195], v[44:47], v[68:71]
	v_mfma_f32_16x16x32_f16 v[8:11], v[200:203], v[44:47], v[72:75]
	v_mfma_f32_16x16x32_f16 v[12:15], v[192:195], v[60:63], v[76:79]
	v_mfma_f32_16x16x32_f16 v[16:19], v[200:203], v[60:63], v[80:83]
	v_mfma_f32_16x16x32_f16 v[20:23], v[192:195], v[232:235], v[84:87]
	v_mfma_f32_16x16x32_f16 v[24:27], v[200:203], v[232:235], v[88:91]
	v_mfma_f32_16x16x32_f16 v[28:31], v[192:195], v[240:243], v[92:95]
	v_mfma_f32_16x16x32_f16 v[32:35], v[200:203], v[240:243], v[96:99]
	v_mfma_f32_16x16x32_f16 v[4:7], v[196:199], v[52:55], v[4:7]
	v_mfma_f32_16x16x32_f16 v[8:11], v[204:207], v[52:55], v[8:11]
	v_mfma_f32_16x16x32_f16 v[12:15], v[196:199], v[224:227], v[12:15]
	v_mfma_f32_16x16x32_f16 v[16:19], v[204:207], v[224:227], v[16:19]
	v_mfma_f32_16x16x32_f16 v[20:23], v[196:199], v[236:239], v[20:23]
	v_mfma_f32_16x16x32_f16 v[24:27], v[204:207], v[236:239], v[24:27]
	v_mfma_f32_16x16x32_f16 v[28:31], v[196:199], v[244:247], v[28:31]
	v_mfma_f32_16x16x32_f16 v[32:35], v[204:207], v[244:247], v[32:35]
	s_setprio 0
	s_setprio 1
	v_mfma_f32_16x16x32_f16 v[36:39], v[208:211], v[44:47], v[100:103]
	v_mfma_f32_16x16x32_f16 v[40:43], v[216:219], v[44:47], v[40:43]
	v_mfma_f32_16x16x32_f16 v[36:39], v[212:215], v[52:55], v[36:39]
	v_mfma_f32_16x16x32_f16 v[40:43], v[220:223], v[52:55], v[40:43]
	v_mfma_f32_16x16x32_f16 v[44:47], v[208:211], v[60:63], v[104:107]
	v_mfma_f32_16x16x32_f16 v[48:51], v[216:219], v[60:63], v[48:51]
	v_mfma_f32_16x16x32_f16 v[52:55], v[208:211], v[232:235], v[108:111]
	v_mfma_f32_16x16x32_f16 v[56:59], v[216:219], v[232:235], v[56:59]
	v_mfma_f32_16x16x32_f16 v[60:63], v[208:211], v[240:243], v[112:115]
	v_mfma_f32_16x16x32_f16 v[64:67], v[216:219], v[240:243], v[64:67]
	v_mfma_f32_16x16x32_f16 v[44:47], v[212:215], v[224:227], v[44:47]
	v_mfma_f32_16x16x32_f16 v[48:51], v[220:223], v[224:227], v[48:51]
	v_mfma_f32_16x16x32_f16 v[52:55], v[212:215], v[236:239], v[52:55]
	v_mfma_f32_16x16x32_f16 v[56:59], v[220:223], v[236:239], v[56:59]
	s_setprio 2
	s_barrier
	v_mfma_f32_16x16x32_f16 v[60:63], v[212:215], v[244:247], v[60:63]
	v_mfma_f32_16x16x32_f16 v[64:67], v[220:223], v[244:247], v[64:67]
	s_setprio 0
	s_add_i32 s53, s53, s38
	v_lshl_add_u64 v[68:69], v[136:137], 0, s[24:25]
	s_mov_b32 m0, s53
	ds_read_b128 v[104:107], v231 offset:49152
	ds_read_b128 v[108:111], v231 offset:50176
	ds_read_b128 v[112:115], v231 offset:51200
	ds_read_b128 v[224:227], v231 offset:52224
	ds_read_b128 v[232:235], v231 offset:53248
	ds_read_b128 v[236:239], v231 offset:54272
	ds_read_b128 v[240:243], v231 offset:55296
	ds_read_b128 v[244:247], v231 offset:56320
	global_load_lds_dwordx4 v[68:69], off
	v_lshl_add_u64 v[68:69], v[144:145], 0, s[24:25]
	s_add_i32 m0, s53, 0x2000
	s_add_i32 s53, s72, s38
	global_load_lds_dwordx4 v[68:69], off
	s_mov_b32 m0, s53
	v_lshl_add_u64 v[68:69], v[248:249], 0, s[24:25]
	global_load_lds_dwordx4 v2, s[28:29]
	s_add_i32 m0, s53, 0x2000
	s_nop 0
	global_load_lds_dwordx4 v134, s[28:29]
	s_mov_b32 m0, s64
	s_nop 0
	global_load_lds_dwordx4 v[68:69], off
	v_lshl_add_u64 v[68:69], v[250:251], 0, s[24:25]
	s_mov_b32 m0, s65
	s_nop 0
	global_load_lds_dwordx4 v[68:69], off
	s_waitcnt vmcnt(8)
	s_waitcnt lgkmcnt(0)
	s_barrier
	s_setprio 1
	s_waitcnt lgkmcnt(0)
	v_mfma_f32_16x16x32_f16 v[68:71], v[192:195], v[104:107], v[140:143]
	v_mfma_f32_16x16x32_f16 v[72:75], v[200:203], v[104:107], v[148:151]
	v_mfma_f32_16x16x32_f16 v[76:79], v[192:195], v[112:115], v[152:155]
	v_mfma_f32_16x16x32_f16 v[80:83], v[200:203], v[112:115], v[156:159]
	v_mfma_f32_16x16x32_f16 v[84:87], v[192:195], v[232:235], v[160:163]
	v_mfma_f32_16x16x32_f16 v[88:91], v[200:203], v[232:235], v[164:167]
	v_mfma_f32_16x16x32_f16 v[92:95], v[192:195], v[240:243], v[168:171]
	v_mfma_f32_16x16x32_f16 v[96:99], v[200:203], v[240:243], v[172:175]
	v_mfma_f32_16x16x32_f16 v[68:71], v[196:199], v[108:111], v[68:71]
	v_mfma_f32_16x16x32_f16 v[72:75], v[204:207], v[108:111], v[72:75]
	v_mfma_f32_16x16x32_f16 v[76:79], v[196:199], v[224:227], v[76:79]
	v_mfma_f32_16x16x32_f16 v[80:83], v[204:207], v[224:227], v[80:83]
	v_mfma_f32_16x16x32_f16 v[84:87], v[196:199], v[236:239], v[84:87]
	v_mfma_f32_16x16x32_f16 v[88:91], v[204:207], v[236:239], v[88:91]
	v_mfma_f32_16x16x32_f16 v[92:95], v[196:199], v[244:247], v[92:95]
	v_mfma_f32_16x16x32_f16 v[96:99], v[204:207], v[244:247], v[96:99]
	s_setprio 0
	s_setprio 1
	v_mfma_f32_16x16x32_f16 v[100:103], v[208:211], v[104:107], v[116:119]
	v_mfma_f32_16x16x32_f16 v[104:107], v[216:219], v[104:107], v[124:127]
	v_mfma_f32_16x16x32_f16 v[100:103], v[212:215], v[108:111], v[100:103]
	v_mfma_f32_16x16x32_f16 v[104:107], v[220:223], v[108:111], v[104:107]
	v_mfma_f32_16x16x32_f16 v[108:111], v[208:211], v[112:115], v[176:179]
	v_mfma_f32_16x16x32_f16 v[112:115], v[216:219], v[112:115], v[180:183]
	v_mfma_f32_16x16x32_f16 v[116:119], v[208:211], v[232:235], v[184:187]
	v_mfma_f32_16x16x32_f16 v[120:123], v[216:219], v[232:235], v[120:123]
	v_mfma_f32_16x16x32_f16 v[124:127], v[208:211], v[240:243], v[188:191]
	v_mfma_f32_16x16x32_f16 v[128:131], v[216:219], v[240:243], v[128:131]
	v_mfma_f32_16x16x32_f16 v[108:111], v[212:215], v[224:227], v[108:111]
	v_mfma_f32_16x16x32_f16 v[112:115], v[220:223], v[224:227], v[112:115]
	v_mfma_f32_16x16x32_f16 v[116:119], v[212:215], v[236:239], v[116:119]
	v_mfma_f32_16x16x32_f16 v[120:123], v[220:223], v[236:239], v[120:123]
	s_setprio 2
	s_barrier
	v_mfma_f32_16x16x32_f16 v[124:127], v[212:215], v[244:247], v[124:127]
	v_mfma_f32_16x16x32_f16 v[128:131], v[220:223], v[244:247], v[128:131]
	s_setprio 0
	s_add_i32 s41, s41, 2
	s_cmp_ge_i32 s41, s40
	s_cbranch_scc0 .LBB0_528
	v_mov_b32_e32 v136, v2
	s_branch .LBB0_531

.LBB0_532:
	s_add_u32 s6, s8, 0xfff80080
	s_addc_u32 s7, s9, -1
	s_add_i32 s29, 0, 0x10000
	s_cmp_eq_u32 s28, 28
	s_cselect_b32 s17, s13, s7
	s_cselect_b32 s16, s12, s6
	v_add_u32_e32 v133, s29, v147
	s_cselect_b32 s7, s15, s27
	s_cselect_b32 s6, s14, s26
	s_add_i32 s53, 0, 0x14000
	ds_read_b128 v[138:141], v133
	ds_read_b128 v[142:145], v133 offset:1024
	ds_read_b128 v[148:151], v133 offset:2048
	ds_read_b128 v[152:155], v133 offset:3072
	v_add_u32_e32 v133, s53, v147
	ds_read_b128 v[156:159], v133
	ds_read_b128 v[160:163], v133 offset:1024
	ds_read_b128 v[164:167], v133 offset:2048
	ds_read_b128 v[168:171], v133 offset:3072
	s_mov_b32 m0, s66
	v_add_u32_e32 v212, 0, v146
	ds_read_b128 v[172:175], v212
	ds_read_b128 v[176:179], v212 offset:1024
	ds_read_b128 v[180:183], v212 offset:2048
	ds_read_b128 v[184:187], v212 offset:3072
	ds_read_b128 v[188:191], v212 offset:4096
	ds_read_b128 v[192:195], v212 offset:5120
	ds_read_b128 v[196:199], v212 offset:6144
	ds_read_b128 v[200:203], v212 offset:7168
	global_load_lds_dwordx4 v2, s[8:9]
	s_mov_b32 m0, s67
	v_mov_b32_e32 v133, v3
	global_load_lds_dwordx4 v132, s[8:9]
	s_waitcnt vmcnt(8)
	s_waitcnt lgkmcnt(0)
	s_barrier
	s_setprio 1
	s_waitcnt lgkmcnt(0)
	v_mfma_f32_16x16x32_f16 v[4:7], v[138:141], v[172:175], v[4:7]
	v_mfma_f32_16x16x32_f16 v[4:7], v[142:145], v[176:179], v[4:7]
	v_mfma_f32_16x16x32_f16 v[8:11], v[152:155], v[176:179], v[8:11]
	v_mfma_f32_16x16x32_f16 v[8:11], v[148:151], v[172:175], v[8:11]
	v_mfma_f32_16x16x32_f16 v[16:19], v[148:151], v[180:183], v[16:19]
	v_mfma_f32_16x16x32_f16 v[16:19], v[152:155], v[184:187], v[16:19]
	v_mfma_f32_16x16x32_f16 v[12:15], v[142:145], v[184:187], v[12:15]
	v_mfma_f32_16x16x32_f16 v[12:15], v[138:141], v[180:183], v[12:15]
	v_mfma_f32_16x16x32_f16 v[20:23], v[138:141], v[188:191], v[20:23]
	v_mfma_f32_16x16x32_f16 v[20:23], v[142:145], v[192:195], v[20:23]
	v_mfma_f32_16x16x32_f16 v[24:27], v[152:155], v[192:195], v[24:27]
	v_mfma_f32_16x16x32_f16 v[24:27], v[148:151], v[188:191], v[24:27]
	v_mfma_f32_16x16x32_f16 v[32:35], v[148:151], v[196:199], v[32:35]
	v_mfma_f32_16x16x32_f16 v[32:35], v[152:155], v[200:203], v[32:35]
	v_mfma_f32_16x16x32_f16 v[28:31], v[142:145], v[200:203], v[28:31]
	v_mfma_f32_16x16x32_f16 v[28:31], v[138:141], v[196:199], v[28:31]
	s_setprio 0
	s_setprio 1
	v_mfma_f32_16x16x32_f16 v[36:39], v[156:159], v[172:175], v[36:39]
	v_mfma_f32_16x16x32_f16 v[36:39], v[160:163], v[176:179], v[36:39]
	v_mfma_f32_16x16x32_f16 v[40:43], v[168:171], v[176:179], v[40:43]
	v_mfma_f32_16x16x32_f16 v[40:43], v[164:167], v[172:175], v[40:43]
	v_mfma_f32_16x16x32_f16 v[48:51], v[164:167], v[180:183], v[48:51]
	v_mfma_f32_16x16x32_f16 v[48:51], v[168:171], v[184:187], v[48:51]
	v_mfma_f32_16x16x32_f16 v[44:47], v[160:163], v[184:187], v[44:47]
	v_mfma_f32_16x16x32_f16 v[44:47], v[156:159], v[180:183], v[44:47]
	v_mfma_f32_16x16x32_f16 v[52:55], v[156:159], v[188:191], v[52:55]
	v_mfma_f32_16x16x32_f16 v[52:55], v[160:163], v[192:195], v[52:55]
	v_mfma_f32_16x16x32_f16 v[56:59], v[168:171], v[192:195], v[56:59]
	v_mfma_f32_16x16x32_f16 v[56:59], v[164:167], v[188:191], v[56:59]
	v_mfma_f32_16x16x32_f16 v[64:67], v[164:167], v[196:199], v[64:67]
	v_mfma_f32_16x16x32_f16 v[64:67], v[168:171], v[200:203], v[64:67]
	s_setprio 2
	s_barrier
	v_mfma_f32_16x16x32_f16 v[60:63], v[160:163], v[200:203], v[60:63]
	v_mfma_f32_16x16x32_f16 v[60:63], v[156:159], v[196:199], v[60:63]
	s_setprio 0
	s_add_i32 s29, s29, s38
	s_mov_b32 m0, s29
	ds_read_b128 v[172:175], v212 offset:16384
	ds_read_b128 v[176:179], v212 offset:17408
	ds_read_b128 v[180:183], v212 offset:18432
	ds_read_b128 v[184:187], v212 offset:19456
	ds_read_b128 v[188:191], v212 offset:20480
	ds_read_b128 v[192:195], v212 offset:21504
	ds_read_b128 v[196:199], v212 offset:22528
	ds_read_b128 v[200:203], v212 offset:23552
	global_load_lds_dwordx4 v136, s[6:7]
	s_add_i32 m0, s29, 0x2000
	s_add_u32 s40, s6, 0x80000
	s_addc_u32 s41, s7, 0
	s_add_i32 s29, s53, s38
	global_load_lds_dwordx4 v134, s[6:7]
	s_mov_b32 m0, s29
	v_mov_b32_e32 v137, v3
	global_load_lds_dwordx4 v136, s[40:41]
	s_add_i32 m0, s29, 0x2000
	v_mov_b32_e32 v135, v3
	global_load_lds_dwordx4 v134, s[40:41]
	s_mov_b32 m0, s58
	v_lshl_add_u64 v[204:205], s[6:7], 0, v[136:137]
	global_load_lds_dwordx4 v2, s[16:17]
	s_mov_b32 m0, s59
	v_lshl_add_u64 v[206:207], s[6:7], 0, v[134:135]
	global_load_lds_dwordx4 v132, s[16:17]
	s_waitcnt vmcnt(8)
	s_waitcnt lgkmcnt(0)
	v_lshl_add_u64 v[208:209], s[16:17], 0, v[2:3]
	v_lshl_add_u64 v[210:211], s[16:17], 0, v[132:133]
	s_barrier
	s_setprio 1
	s_waitcnt lgkmcnt(0)
	v_mfma_f32_16x16x32_f16 v[68:71], v[138:141], v[172:175], v[68:71]
	v_mfma_f32_16x16x32_f16 v[68:71], v[142:145], v[176:179], v[68:71]
	v_mfma_f32_16x16x32_f16 v[72:75], v[152:155], v[176:179], v[72:75]
	v_mfma_f32_16x16x32_f16 v[72:75], v[148:151], v[172:175], v[72:75]
	v_mfma_f32_16x16x32_f16 v[80:83], v[148:151], v[180:183], v[80:83]
	v_mfma_f32_16x16x32_f16 v[80:83], v[152:155], v[184:187], v[80:83]
	v_mfma_f32_16x16x32_f16 v[76:79], v[142:145], v[184:187], v[76:79]
	v_mfma_f32_16x16x32_f16 v[76:79], v[138:141], v[180:183], v[76:79]
	v_mfma_f32_16x16x32_f16 v[84:87], v[138:141], v[188:191], v[84:87]
	v_mfma_f32_16x16x32_f16 v[84:87], v[142:145], v[192:195], v[84:87]
	v_mfma_f32_16x16x32_f16 v[88:91], v[152:155], v[192:195], v[88:91]
	v_mfma_f32_16x16x32_f16 v[88:91], v[148:151], v[188:191], v[88:91]
	v_mfma_f32_16x16x32_f16 v[96:99], v[148:151], v[196:199], v[96:99]
	v_mfma_f32_16x16x32_f16 v[96:99], v[152:155], v[200:203], v[96:99]
	v_mfma_f32_16x16x32_f16 v[92:95], v[142:145], v[200:203], v[92:95]
	v_mfma_f32_16x16x32_f16 v[92:95], v[138:141], v[196:199], v[92:95]
	s_setprio 0
	s_setprio 1
	v_mfma_f32_16x16x32_f16 v[100:103], v[156:159], v[172:175], v[100:103]
	v_mfma_f32_16x16x32_f16 v[100:103], v[160:163], v[176:179], v[100:103]
	v_mfma_f32_16x16x32_f16 v[104:107], v[168:171], v[176:179], v[104:107]
	v_mfma_f32_16x16x32_f16 v[104:107], v[164:167], v[172:175], v[104:107]
	v_mfma_f32_16x16x32_f16 v[112:115], v[164:167], v[180:183], v[112:115]
	v_mfma_f32_16x16x32_f16 v[112:115], v[168:171], v[184:187], v[112:115]
	v_mfma_f32_16x16x32_f16 v[108:111], v[160:163], v[184:187], v[108:111]
	v_mfma_f32_16x16x32_f16 v[108:111], v[156:159], v[180:183], v[108:111]
	v_mfma_f32_16x16x32_f16 v[116:119], v[156:159], v[188:191], v[116:119]
	v_mfma_f32_16x16x32_f16 v[116:119], v[160:163], v[192:195], v[116:119]
	v_mfma_f32_16x16x32_f16 v[120:123], v[168:171], v[192:195], v[120:123]
	v_mfma_f32_16x16x32_f16 v[120:123], v[164:167], v[188:191], v[120:123]
	v_mfma_f32_16x16x32_f16 v[128:131], v[164:167], v[196:199], v[128:131]
	v_mfma_f32_16x16x32_f16 v[128:131], v[168:171], v[200:203], v[128:131]
	s_setprio 2
	s_barrier
	v_mfma_f32_16x16x32_f16 v[124:127], v[160:163], v[200:203], v[124:127]
	v_mfma_f32_16x16x32_f16 v[124:127], v[156:159], v[196:199], v[124:127]
	s_setprio 0
	s_add_i32 s29, 0, 0x18000
	v_add_u32_e32 v135, s29, v147
	s_add_i32 s40, 0, 0x1c000
	ds_read_b128 v[138:141], v135
	ds_read_b128 v[142:145], v135 offset:1024
	ds_read_b128 v[148:151], v135 offset:2048
	ds_read_b128 v[152:155], v135 offset:3072
	v_add_u32_e32 v135, s40, v147
	ds_read_b128 v[156:159], v135
	ds_read_b128 v[160:163], v135 offset:1024
	ds_read_b128 v[164:167], v135 offset:2048
	ds_read_b128 v[168:171], v135 offset:3072
	s_add_u32 s16, s16, 0x80000
	s_addc_u32 s17, s17, 0
	s_mov_b32 m0, s60
	ds_read_b128 v[172:175], v212 offset:32768
	ds_read_b128 v[176:179], v212 offset:33792
	ds_read_b128 v[180:183], v212 offset:34816
	ds_read_b128 v[184:187], v212 offset:35840
	ds_read_b128 v[188:191], v212 offset:36864
	ds_read_b128 v[192:195], v212 offset:37888
	ds_read_b128 v[196:199], v212 offset:38912
	ds_read_b128 v[200:203], v212 offset:39936
	global_load_lds_dwordx4 v2, s[16:17]
	s_mov_b32 m0, s61
	s_nop 0
	global_load_lds_dwordx4 v132, s[16:17]
	s_waitcnt vmcnt(8)
	s_waitcnt lgkmcnt(0)
	s_barrier
	s_setprio 1
	s_waitcnt lgkmcnt(0)
	v_mfma_f32_16x16x32_f16 v[4:7], v[138:141], v[172:175], v[4:7]
	v_mfma_f32_16x16x32_f16 v[4:7], v[142:145], v[176:179], v[4:7]
	v_mfma_f32_16x16x32_f16 v[8:11], v[152:155], v[176:179], v[8:11]
	v_mfma_f32_16x16x32_f16 v[8:11], v[148:151], v[172:175], v[8:11]
	v_mfma_f32_16x16x32_f16 v[16:19], v[148:151], v[180:183], v[16:19]
	v_mfma_f32_16x16x32_f16 v[16:19], v[152:155], v[184:187], v[16:19]
	v_mfma_f32_16x16x32_f16 v[12:15], v[142:145], v[184:187], v[12:15]
	v_mfma_f32_16x16x32_f16 v[12:15], v[138:141], v[180:183], v[12:15]
	v_mfma_f32_16x16x32_f16 v[20:23], v[138:141], v[188:191], v[20:23]
	v_mfma_f32_16x16x32_f16 v[20:23], v[142:145], v[192:195], v[20:23]
	v_mfma_f32_16x16x32_f16 v[24:27], v[152:155], v[192:195], v[24:27]
	v_mfma_f32_16x16x32_f16 v[24:27], v[148:151], v[188:191], v[24:27]
	v_mfma_f32_16x16x32_f16 v[32:35], v[148:151], v[196:199], v[32:35]
	v_mfma_f32_16x16x32_f16 v[32:35], v[152:155], v[200:203], v[32:35]
	v_mfma_f32_16x16x32_f16 v[28:31], v[142:145], v[200:203], v[28:31]
	v_mfma_f32_16x16x32_f16 v[28:31], v[138:141], v[196:199], v[28:31]
	s_setprio 0
	s_setprio 1
	v_mfma_f32_16x16x32_f16 v[36:39], v[156:159], v[172:175], v[36:39]
	v_mfma_f32_16x16x32_f16 v[36:39], v[160:163], v[176:179], v[36:39]
	v_mfma_f32_16x16x32_f16 v[40:43], v[168:171], v[176:179], v[40:43]
	v_mfma_f32_16x16x32_f16 v[40:43], v[164:167], v[172:175], v[40:43]
	v_mfma_f32_16x16x32_f16 v[48:51], v[164:167], v[180:183], v[48:51]
	v_mfma_f32_16x16x32_f16 v[48:51], v[168:171], v[184:187], v[48:51]
	v_mfma_f32_16x16x32_f16 v[44:47], v[160:163], v[184:187], v[44:47]
	v_mfma_f32_16x16x32_f16 v[44:47], v[156:159], v[180:183], v[44:47]
	v_mfma_f32_16x16x32_f16 v[52:55], v[156:159], v[188:191], v[52:55]
	v_mfma_f32_16x16x32_f16 v[52:55], v[160:163], v[192:195], v[52:55]
	v_mfma_f32_16x16x32_f16 v[56:59], v[168:171], v[192:195], v[56:59]
	v_mfma_f32_16x16x32_f16 v[56:59], v[164:167], v[188:191], v[56:59]
	v_mfma_f32_16x16x32_f16 v[64:67], v[164:167], v[196:199], v[64:67]
	v_mfma_f32_16x16x32_f16 v[64:67], v[168:171], v[200:203], v[64:67]
	s_setprio 2
	s_barrier
	v_mfma_f32_16x16x32_f16 v[60:63], v[160:163], v[200:203], v[60:63]
	v_mfma_f32_16x16x32_f16 v[60:63], v[156:159], v[196:199], v[60:63]
	s_setprio 0
	s_add_i32 s16, s29, s38
	v_lshl_add_u64 v[204:205], v[204:205], 0, s[86:87]
	s_mov_b32 m0, s16
	ds_read_b128 v[172:175], v212 offset:49152
	ds_read_b128 v[176:179], v212 offset:50176
	ds_read_b128 v[180:183], v212 offset:51200
	ds_read_b128 v[184:187], v212 offset:52224
	ds_read_b128 v[188:191], v212 offset:53248
	ds_read_b128 v[192:195], v212 offset:54272
	ds_read_b128 v[196:199], v212 offset:55296
	ds_read_b128 v[200:203], v212 offset:56320
	global_load_lds_dwordx4 v[204:205], off
	s_add_i32 m0, s16, 0x2000
	s_add_u32 s6, s6, 0x80080
	v_lshl_add_u64 v[204:205], v[206:207], 0, s[86:87]
	s_addc_u32 s7, s7, 0
	s_add_i32 s16, s40, s38
	global_load_lds_dwordx4 v[204:205], off
	s_mov_b32 m0, s16
	v_lshl_add_u64 v[204:205], v[208:209], 0, s[86:87]
	global_load_lds_dwordx4 v136, s[6:7]
	s_add_i32 m0, s16, 0x2000
	s_nop 0
	global_load_lds_dwordx4 v134, s[6:7]
	s_mov_b32 m0, s64
	s_nop 0
	global_load_lds_dwordx4 v[204:205], off
	v_lshl_add_u64 v[204:205], v[210:211], 0, s[86:87]
	s_mov_b32 m0, s65
	s_nop 0
	global_load_lds_dwordx4 v[204:205], off
	s_waitcnt vmcnt(8)
	s_waitcnt lgkmcnt(0)
	s_barrier
	s_setprio 1
	s_waitcnt lgkmcnt(0)
	v_mfma_f32_16x16x32_f16 v[68:71], v[138:141], v[172:175], v[68:71]
	v_mfma_f32_16x16x32_f16 v[68:71], v[142:145], v[176:179], v[68:71]
	v_mfma_f32_16x16x32_f16 v[72:75], v[152:155], v[176:179], v[72:75]
	v_mfma_f32_16x16x32_f16 v[72:75], v[148:151], v[172:175], v[72:75]
	v_mfma_f32_16x16x32_f16 v[80:83], v[148:151], v[180:183], v[80:83]
	v_mfma_f32_16x16x32_f16 v[80:83], v[152:155], v[184:187], v[80:83]
	v_mfma_f32_16x16x32_f16 v[76:79], v[142:145], v[184:187], v[76:79]
	v_mfma_f32_16x16x32_f16 v[76:79], v[138:141], v[180:183], v[76:79]
	v_mfma_f32_16x16x32_f16 v[84:87], v[138:141], v[188:191], v[84:87]
	v_mfma_f32_16x16x32_f16 v[84:87], v[142:145], v[192:195], v[84:87]
	v_mfma_f32_16x16x32_f16 v[88:91], v[152:155], v[192:195], v[88:91]
	v_mfma_f32_16x16x32_f16 v[88:91], v[148:151], v[188:191], v[88:91]
	v_mfma_f32_16x16x32_f16 v[96:99], v[148:151], v[196:199], v[96:99]
	v_mfma_f32_16x16x32_f16 v[96:99], v[152:155], v[200:203], v[96:99]
	v_mfma_f32_16x16x32_f16 v[92:95], v[142:145], v[200:203], v[92:95]
	v_mfma_f32_16x16x32_f16 v[92:95], v[138:141], v[196:199], v[92:95]
	s_setprio 0
	s_setprio 1
	v_mfma_f32_16x16x32_f16 v[100:103], v[156:159], v[172:175], v[100:103]
	v_mfma_f32_16x16x32_f16 v[100:103], v[160:163], v[176:179], v[100:103]
	v_mfma_f32_16x16x32_f16 v[104:107], v[168:171], v[176:179], v[104:107]
	v_mfma_f32_16x16x32_f16 v[104:107], v[164:167], v[172:175], v[104:107]
	v_mfma_f32_16x16x32_f16 v[112:115], v[164:167], v[180:183], v[112:115]
	v_mfma_f32_16x16x32_f16 v[112:115], v[168:171], v[184:187], v[112:115]
	v_mfma_f32_16x16x32_f16 v[108:111], v[160:163], v[184:187], v[108:111]
	v_mfma_f32_16x16x32_f16 v[108:111], v[156:159], v[180:183], v[108:111]
	v_mfma_f32_16x16x32_f16 v[116:119], v[156:159], v[188:191], v[116:119]
	v_mfma_f32_16x16x32_f16 v[116:119], v[160:163], v[192:195], v[116:119]
	v_mfma_f32_16x16x32_f16 v[120:123], v[168:171], v[192:195], v[120:123]
	v_mfma_f32_16x16x32_f16 v[120:123], v[164:167], v[188:191], v[120:123]
	v_mfma_f32_16x16x32_f16 v[128:131], v[164:167], v[196:199], v[128:131]
	v_mfma_f32_16x16x32_f16 v[128:131], v[168:171], v[200:203], v[128:131]
	s_setprio 2
	s_barrier
	v_mfma_f32_16x16x32_f16 v[124:127], v[160:163], v[200:203], v[124:127]
	v_mfma_f32_16x16x32_f16 v[124:127], v[156:159], v[196:199], v[124:127]
	s_setprio 0
	s_add_i32 s28, s28, 2
	s_add_u32 s8, s8, 0x100
	s_addc_u32 s9, s9, 0
	s_add_u32 s26, s26, 0x100
	s_addc_u32 s27, s27, 0
	s_cmp_gt_u32 s28, 29
	s_cbranch_scc0 .LBB0_532
	s_and_b64 vcc, exec, s[50:51]
	s_cbranch_vccz .LBB0_535
	s_barrier

.LBB0_641:
	s_add_i32 s43, 0, 0x10000
	s_add_i32 s71, 0, 0x14000
	v_add_u32_e32 v16, s43, v232
	v_add_u32_e32 v32, s71, v232
	ds_read_b128 v[4:7], v16
	ds_read_b128 v[8:11], v16 offset:1024
	ds_read_b128 v[12:15], v16 offset:2048
	ds_read_b128 v[16:19], v16 offset:3072
	ds_read_b128 v[20:23], v32
	ds_read_b128 v[24:27], v32 offset:1024
	ds_read_b128 v[28:31], v32 offset:2048
	ds_read_b128 v[32:35], v32 offset:3072
	v_add_u32_e32 v233, 0, v231
	ds_read_b128 v[36:39], v233
	ds_read_b128 v[40:43], v233 offset:1024
	ds_read_b128 v[44:47], v233 offset:2048
	ds_read_b128 v[48:51], v233 offset:3072
	ds_read_b128 v[52:55], v233 offset:4096
	ds_read_b128 v[56:59], v233 offset:5120
	ds_read_b128 v[60:63], v233 offset:6144
	ds_read_b128 v[64:67], v233 offset:7168
	s_waitcnt vmcnt(8)
	s_waitcnt lgkmcnt(0)
	s_barrier
	s_setprio 1
	s_waitcnt lgkmcnt(0)
	v_mfma_f32_16x16x32_bf16 v[68:71], v[4:7], v[36:39], 0
	v_mfma_f32_16x16x32_bf16 v[68:71], v[8:11], v[40:43], v[68:71]
	v_mfma_f32_16x16x32_bf16 v[72:75], v[12:15], v[36:39], 0
	v_mfma_f32_16x16x32_bf16 v[72:75], v[16:19], v[40:43], v[72:75]
	v_mfma_f32_16x16x32_bf16 v[80:83], v[12:15], v[44:47], 0
	v_mfma_f32_16x16x32_bf16 v[80:83], v[16:19], v[48:51], v[80:83]
	v_mfma_f32_16x16x32_bf16 v[76:79], v[4:7], v[44:47], 0
	v_mfma_f32_16x16x32_bf16 v[76:79], v[8:11], v[48:51], v[76:79]
	v_mfma_f32_16x16x32_bf16 v[84:87], v[4:7], v[52:55], 0
	v_mfma_f32_16x16x32_bf16 v[84:87], v[8:11], v[56:59], v[84:87]
	v_mfma_f32_16x16x32_bf16 v[88:91], v[12:15], v[52:55], 0
	v_mfma_f32_16x16x32_bf16 v[88:91], v[16:19], v[56:59], v[88:91]
	v_mfma_f32_16x16x32_bf16 v[96:99], v[12:15], v[60:63], 0
	v_mfma_f32_16x16x32_bf16 v[96:99], v[16:19], v[64:67], v[96:99]
	v_mfma_f32_16x16x32_bf16 v[92:95], v[4:7], v[60:63], 0
	v_mfma_f32_16x16x32_bf16 v[92:95], v[8:11], v[64:67], v[92:95]
	s_setprio 0
	s_setprio 1
	v_mfma_f32_16x16x32_bf16 v[100:103], v[20:23], v[36:39], 0
	v_mfma_f32_16x16x32_bf16 v[36:39], v[28:31], v[36:39], 0
	v_mfma_f32_16x16x32_bf16 v[104:107], v[20:23], v[44:47], 0
	v_mfma_f32_16x16x32_bf16 v[44:47], v[28:31], v[44:47], 0
	v_mfma_f32_16x16x32_bf16 v[108:111], v[20:23], v[52:55], 0
	v_mfma_f32_16x16x32_bf16 v[52:55], v[28:31], v[52:55], 0
	v_mfma_f32_16x16x32_bf16 v[112:115], v[20:23], v[60:63], 0
	v_mfma_f32_16x16x32_bf16 v[60:63], v[28:31], v[60:63], 0
	v_mfma_f32_16x16x32_bf16 v[100:103], v[24:27], v[40:43], v[100:103]
	v_mfma_f32_16x16x32_bf16 v[40:43], v[32:35], v[40:43], v[36:39]
	v_mfma_f32_16x16x32_bf16 v[104:107], v[24:27], v[48:51], v[104:107]
	v_mfma_f32_16x16x32_bf16 v[48:51], v[32:35], v[48:51], v[44:47]
	v_mfma_f32_16x16x32_bf16 v[108:111], v[24:27], v[56:59], v[108:111]
	v_mfma_f32_16x16x32_bf16 v[56:59], v[32:35], v[56:59], v[52:55]
	s_setprio 2
	s_barrier
	v_mfma_f32_16x16x32_bf16 v[112:115], v[24:27], v[64:67], v[112:115]
	v_mfma_f32_16x16x32_bf16 v[64:67], v[32:35], v[64:67], v[60:63]
	s_setprio 0
	v_lshl_add_u64 v[186:187], s[8:9], 0, v[2:3]
	s_add_i32 s43, s43, s54
	v_mov_b32_e32 v191, v3
	v_lshl_add_u64 v[134:135], v[186:187], 0, s[80:81]
	s_mov_b32 m0, s43
	v_lshl_add_u64 v[246:247], s[8:9], 0, v[190:191]
	ds_read_b128 v[36:39], v233 offset:16384
	ds_read_b128 v[44:47], v233 offset:17408
	ds_read_b128 v[52:55], v233 offset:18432
	ds_read_b128 v[60:63], v233 offset:19456
	ds_read_b128 v[116:119], v233 offset:20480
	ds_read_b128 v[120:123], v233 offset:21504
	ds_read_b128 v[124:127], v233 offset:22528
	ds_read_b128 v[128:131], v233 offset:23552
	global_load_lds_dwordx4 v[134:135], off
	v_lshl_add_u64 v[134:135], v[246:247], 0, s[80:81]
	s_add_i32 m0, s43, 0x2000
	s_add_i32 s43, s71, s54
	global_load_lds_dwordx4 v[134:135], off
	s_mov_b32 m0, s43
	v_mov_b32_e32 v133, v3
	global_load_lds_dwordx4 v2, s[16:17]
	s_add_i32 m0, s43, 0x2000
	v_lshl_add_u64 v[248:249], s[6:7], 0, v[132:133]
	v_mov_b32_e32 v189, v3
	global_load_lds_dwordx4 v190, s[16:17]
	v_lshl_add_u64 v[134:135], v[248:249], 0, s[80:81]
	s_mov_b32 m0, s55
	v_lshl_add_u64 v[250:251], s[6:7], 0, v[188:189]
	global_load_lds_dwordx4 v[134:135], off
	v_lshl_add_u64 v[134:135], v[250:251], 0, s[80:81]
	s_mov_b32 m0, s56
	s_nop 0
	global_load_lds_dwordx4 v[134:135], off
	s_waitcnt vmcnt(8)
	s_waitcnt lgkmcnt(0)
	s_barrier
	s_setprio 1
	s_waitcnt lgkmcnt(0)
	v_mfma_f32_16x16x32_bf16 v[134:137], v[4:7], v[36:39], 0
	v_mfma_f32_16x16x32_bf16 v[138:141], v[12:15], v[36:39], 0
	v_mfma_f32_16x16x32_bf16 v[142:145], v[4:7], v[52:55], 0
	v_mfma_f32_16x16x32_bf16 v[146:149], v[12:15], v[52:55], 0
	v_mfma_f32_16x16x32_bf16 v[150:153], v[4:7], v[116:119], 0
	v_mfma_f32_16x16x32_bf16 v[154:157], v[12:15], v[116:119], 0
	v_mfma_f32_16x16x32_bf16 v[4:7], v[4:7], v[124:127], 0
	v_mfma_f32_16x16x32_bf16 v[12:15], v[12:15], v[124:127], 0
	v_mfma_f32_16x16x32_bf16 v[134:137], v[8:11], v[44:47], v[134:137]
	v_mfma_f32_16x16x32_bf16 v[138:141], v[16:19], v[44:47], v[138:141]
	v_mfma_f32_16x16x32_bf16 v[142:145], v[8:11], v[60:63], v[142:145]
	v_mfma_f32_16x16x32_bf16 v[146:149], v[16:19], v[60:63], v[146:149]
	v_mfma_f32_16x16x32_bf16 v[150:153], v[8:11], v[120:123], v[150:153]
	v_mfma_f32_16x16x32_bf16 v[154:157], v[16:19], v[120:123], v[154:157]
	v_mfma_f32_16x16x32_bf16 v[158:161], v[8:11], v[128:131], v[4:7]
	v_mfma_f32_16x16x32_bf16 v[162:165], v[16:19], v[128:131], v[12:15]
	s_setprio 0
	s_setprio 1
	v_mfma_f32_16x16x32_bf16 v[4:7], v[20:23], v[36:39], 0
	v_mfma_f32_16x16x32_bf16 v[8:11], v[28:31], v[36:39], 0
	v_mfma_f32_16x16x32_bf16 v[12:15], v[20:23], v[52:55], 0
	v_mfma_f32_16x16x32_bf16 v[16:19], v[28:31], v[52:55], 0
	v_mfma_f32_16x16x32_bf16 v[36:39], v[20:23], v[116:119], 0
	v_mfma_f32_16x16x32_bf16 v[52:55], v[28:31], v[116:119], 0
	v_mfma_f32_16x16x32_bf16 v[20:23], v[20:23], v[124:127], 0
	v_mfma_f32_16x16x32_bf16 v[28:31], v[28:31], v[124:127], 0
	v_mfma_f32_16x16x32_bf16 v[116:119], v[24:27], v[44:47], v[4:7]
	v_mfma_f32_16x16x32_bf16 v[124:127], v[32:35], v[44:47], v[8:11]
	v_mfma_f32_16x16x32_bf16 v[174:177], v[24:27], v[120:123], v[36:39]
	v_mfma_f32_16x16x32_bf16 v[120:123], v[32:35], v[120:123], v[52:55]
	v_mfma_f32_16x16x32_bf16 v[178:181], v[24:27], v[128:131], v[20:23]
	v_mfma_f32_16x16x32_bf16 v[128:131], v[32:35], v[128:131], v[28:31]
	s_setprio 2
	s_barrier
	v_mfma_f32_16x16x32_bf16 v[166:169], v[24:27], v[60:63], v[12:15]
	v_mfma_f32_16x16x32_bf16 v[170:173], v[32:35], v[60:63], v[16:19]
	s_setprio 0
	s_add_i32 s43, 0, 0x18000
	v_add_u32_e32 v4, s43, v232
	s_add_i32 s71, 0, 0x1c000
	ds_read_b128 v[182:185], v4
	ds_read_b128 v[192:195], v4 offset:1024
	ds_read_b128 v[196:199], v4 offset:2048
	ds_read_b128 v[200:203], v4 offset:3072
	v_add_u32_e32 v4, s71, v232
	ds_read_b128 v[204:207], v4
	ds_read_b128 v[208:211], v4 offset:1024
	ds_read_b128 v[212:215], v4 offset:2048
	ds_read_b128 v[216:219], v4 offset:3072
	s_mov_b32 m0, s57
	ds_read_b128 v[44:47], v233 offset:32768
	ds_read_b128 v[52:55], v233 offset:33792
	ds_read_b128 v[60:63], v233 offset:34816
	ds_read_b128 v[220:223], v233 offset:35840
	ds_read_b128 v[224:227], v233 offset:36864
	ds_read_b128 v[234:237], v233 offset:37888
	ds_read_b128 v[238:241], v233 offset:38912
	ds_read_b128 v[242:245], v233 offset:39936
	global_load_lds_dwordx4 v132, s[26:27]
	s_mov_b32 m0, s58
	s_nop 0
	global_load_lds_dwordx4 v188, s[26:27]
	s_waitcnt vmcnt(8)
	s_waitcnt lgkmcnt(0)
	s_barrier
	s_setprio 1
	s_waitcnt lgkmcnt(0)
	v_mfma_f32_16x16x32_bf16 v[4:7], v[182:185], v[44:47], v[68:71]
	v_mfma_f32_16x16x32_bf16 v[8:11], v[196:199], v[44:47], v[72:75]
	v_mfma_f32_16x16x32_bf16 v[12:15], v[182:185], v[60:63], v[76:79]
	v_mfma_f32_16x16x32_bf16 v[16:19], v[196:199], v[60:63], v[80:83]
	v_mfma_f32_16x16x32_bf16 v[20:23], v[182:185], v[224:227], v[84:87]
	v_mfma_f32_16x16x32_bf16 v[24:27], v[196:199], v[224:227], v[88:91]
	v_mfma_f32_16x16x32_bf16 v[28:31], v[182:185], v[238:241], v[92:95]
	v_mfma_f32_16x16x32_bf16 v[32:35], v[196:199], v[238:241], v[96:99]
	v_mfma_f32_16x16x32_bf16 v[4:7], v[192:195], v[52:55], v[4:7]
	v_mfma_f32_16x16x32_bf16 v[8:11], v[200:203], v[52:55], v[8:11]
	v_mfma_f32_16x16x32_bf16 v[12:15], v[192:195], v[220:223], v[12:15]
	v_mfma_f32_16x16x32_bf16 v[16:19], v[200:203], v[220:223], v[16:19]
	v_mfma_f32_16x16x32_bf16 v[20:23], v[192:195], v[234:237], v[20:23]
	v_mfma_f32_16x16x32_bf16 v[24:27], v[200:203], v[234:237], v[24:27]
	v_mfma_f32_16x16x32_bf16 v[28:31], v[192:195], v[242:245], v[28:31]
	v_mfma_f32_16x16x32_bf16 v[32:35], v[200:203], v[242:245], v[32:35]
	s_setprio 0
	s_setprio 1
	v_mfma_f32_16x16x32_bf16 v[36:39], v[204:207], v[44:47], v[100:103]
	v_mfma_f32_16x16x32_bf16 v[40:43], v[212:215], v[44:47], v[40:43]
	v_mfma_f32_16x16x32_bf16 v[36:39], v[208:211], v[52:55], v[36:39]
	v_mfma_f32_16x16x32_bf16 v[40:43], v[216:219], v[52:55], v[40:43]
	v_mfma_f32_16x16x32_bf16 v[44:47], v[204:207], v[60:63], v[104:107]
	v_mfma_f32_16x16x32_bf16 v[48:51], v[212:215], v[60:63], v[48:51]
	v_mfma_f32_16x16x32_bf16 v[52:55], v[204:207], v[224:227], v[108:111]
	v_mfma_f32_16x16x32_bf16 v[56:59], v[212:215], v[224:227], v[56:59]
	v_mfma_f32_16x16x32_bf16 v[60:63], v[204:207], v[238:241], v[112:115]
	v_mfma_f32_16x16x32_bf16 v[64:67], v[212:215], v[238:241], v[64:67]
	v_mfma_f32_16x16x32_bf16 v[44:47], v[208:211], v[220:223], v[44:47]
	v_mfma_f32_16x16x32_bf16 v[48:51], v[216:219], v[220:223], v[48:51]
	v_mfma_f32_16x16x32_bf16 v[52:55], v[208:211], v[234:237], v[52:55]
	v_mfma_f32_16x16x32_bf16 v[56:59], v[216:219], v[234:237], v[56:59]
	s_setprio 2
	s_barrier
	v_mfma_f32_16x16x32_bf16 v[60:63], v[208:211], v[242:245], v[60:63]
	v_mfma_f32_16x16x32_bf16 v[64:67], v[216:219], v[242:245], v[64:67]
	s_setprio 0
	s_add_i32 s43, s43, s54
	v_lshl_add_u64 v[68:69], v[186:187], 0, s[0:1]
	s_mov_b32 m0, s43
	ds_read_b128 v[104:107], v233 offset:49152
	ds_read_b128 v[108:111], v233 offset:50176
	ds_read_b128 v[112:115], v233 offset:51200
	ds_read_b128 v[220:223], v233 offset:52224
	ds_read_b128 v[224:227], v233 offset:53248
	ds_read_b128 v[234:237], v233 offset:54272
	ds_read_b128 v[238:241], v233 offset:55296
	ds_read_b128 v[242:245], v233 offset:56320
	global_load_lds_dwordx4 v[68:69], off
	v_lshl_add_u64 v[68:69], v[246:247], 0, s[0:1]
	s_add_i32 m0, s43, 0x2000
	s_add_i32 s43, s71, s54
	global_load_lds_dwordx4 v[68:69], off
	s_mov_b32 m0, s43
	v_lshl_add_u64 v[68:69], v[248:249], 0, s[0:1]
	global_load_lds_dwordx4 v2, s[28:29]
	s_add_i32 m0, s43, 0x2000
	s_nop 0
	global_load_lds_dwordx4 v190, s[28:29]
	s_mov_b32 m0, s62
	s_nop 0
	global_load_lds_dwordx4 v[68:69], off
	v_lshl_add_u64 v[68:69], v[250:251], 0, s[0:1]
	s_mov_b32 m0, s63
	s_nop 0
	global_load_lds_dwordx4 v[68:69], off
	s_waitcnt vmcnt(8)
	s_waitcnt lgkmcnt(0)
	s_barrier
	s_setprio 1
	s_waitcnt lgkmcnt(0)
	v_mfma_f32_16x16x32_bf16 v[68:71], v[182:185], v[104:107], v[134:137]
	v_mfma_f32_16x16x32_bf16 v[72:75], v[196:199], v[104:107], v[138:141]
	v_mfma_f32_16x16x32_bf16 v[76:79], v[182:185], v[112:115], v[142:145]
	v_mfma_f32_16x16x32_bf16 v[80:83], v[196:199], v[112:115], v[146:149]
	v_mfma_f32_16x16x32_bf16 v[84:87], v[182:185], v[224:227], v[150:153]
	v_mfma_f32_16x16x32_bf16 v[88:91], v[196:199], v[224:227], v[154:157]
	v_mfma_f32_16x16x32_bf16 v[92:95], v[182:185], v[238:241], v[158:161]
	v_mfma_f32_16x16x32_bf16 v[96:99], v[196:199], v[238:241], v[162:165]
	v_mfma_f32_16x16x32_bf16 v[68:71], v[192:195], v[108:111], v[68:71]
	v_mfma_f32_16x16x32_bf16 v[72:75], v[200:203], v[108:111], v[72:75]
	v_mfma_f32_16x16x32_bf16 v[76:79], v[192:195], v[220:223], v[76:79]
	v_mfma_f32_16x16x32_bf16 v[80:83], v[200:203], v[220:223], v[80:83]
	v_mfma_f32_16x16x32_bf16 v[84:87], v[192:195], v[234:237], v[84:87]
	v_mfma_f32_16x16x32_bf16 v[88:91], v[200:203], v[234:237], v[88:91]
	v_mfma_f32_16x16x32_bf16 v[92:95], v[192:195], v[242:245], v[92:95]
	v_mfma_f32_16x16x32_bf16 v[96:99], v[200:203], v[242:245], v[96:99]
	s_setprio 0
	s_setprio 1
	v_mfma_f32_16x16x32_bf16 v[100:103], v[204:207], v[104:107], v[116:119]
	v_mfma_f32_16x16x32_bf16 v[104:107], v[212:215], v[104:107], v[124:127]
	v_mfma_f32_16x16x32_bf16 v[100:103], v[208:211], v[108:111], v[100:103]
	v_mfma_f32_16x16x32_bf16 v[104:107], v[216:219], v[108:111], v[104:107]
	v_mfma_f32_16x16x32_bf16 v[108:111], v[204:207], v[112:115], v[166:169]
	v_mfma_f32_16x16x32_bf16 v[112:115], v[212:215], v[112:115], v[170:173]
	v_mfma_f32_16x16x32_bf16 v[116:119], v[204:207], v[224:227], v[174:177]
	v_mfma_f32_16x16x32_bf16 v[120:123], v[212:215], v[224:227], v[120:123]
	v_mfma_f32_16x16x32_bf16 v[124:127], v[204:207], v[238:241], v[178:181]
	v_mfma_f32_16x16x32_bf16 v[128:131], v[212:215], v[238:241], v[128:131]
	v_mfma_f32_16x16x32_bf16 v[108:111], v[208:211], v[220:223], v[108:111]
	v_mfma_f32_16x16x32_bf16 v[112:115], v[216:219], v[220:223], v[112:115]
	v_mfma_f32_16x16x32_bf16 v[116:119], v[208:211], v[234:237], v[116:119]
	v_mfma_f32_16x16x32_bf16 v[120:123], v[216:219], v[234:237], v[120:123]
	s_setprio 2
	s_barrier
	v_mfma_f32_16x16x32_bf16 v[124:127], v[208:211], v[242:245], v[124:127]
	v_mfma_f32_16x16x32_bf16 v[128:131], v[216:219], v[242:245], v[128:131]
	s_setprio 0
	s_add_i32 s42, s42, 2
	s_cmp_ge_i32 s42, s38
	s_cbranch_scc0 .LBB0_641
	v_mov_b32_e32 v192, v2
	s_branch .LBB0_644

.LBB0_649:
	s_or_b32 s38, s28, 1
	s_lshl_b64 s[42:43], s[38:39], 7
	s_sub_u32 s38, 0, s42
	s_subb_u32 s42, 0, s43
	s_add_u32 s38, s6, s38
	s_addc_u32 s43, s7, s42
	s_add_i32 s71, 0, 0x10000
	s_add_i32 s72, 0, 0x14000
	v_add_u32_e32 v144, s71, v232
	v_add_u32_e32 v160, s72, v232
	s_waitcnt lgkmcnt(0)
	ds_read_b128 v[132:135], v144
	ds_read_b128 v[136:139], v144 offset:1024
	ds_read_b128 v[140:143], v144 offset:2048
	ds_read_b128 v[144:147], v144 offset:3072
	ds_read_b128 v[148:151], v160
	ds_read_b128 v[152:155], v160 offset:1024
	ds_read_b128 v[156:159], v160 offset:2048
	ds_read_b128 v[160:163], v160 offset:3072
	s_add_u32 s42, s38, 0x160000
	s_mov_b32 m0, s64
	v_add_u32_e32 v210, 0, v231
	s_addc_u32 s43, s43, 0
	ds_read_b128 v[164:167], v210
	ds_read_b128 v[168:171], v210 offset:1024
	ds_read_b128 v[172:175], v210 offset:2048
	ds_read_b128 v[176:179], v210 offset:3072
	ds_read_b128 v[180:183], v210 offset:4096
	ds_read_b128 v[184:187], v210 offset:5120
	ds_read_b128 v[194:197], v210 offset:6144
	ds_read_b128 v[198:201], v210 offset:7168
	global_load_lds_dwordx4 v2, s[42:43]
	s_mov_b32 m0, s65
	v_mov_b32_e32 v189, v3
	global_load_lds_dwordx4 v188, s[42:43]
	s_waitcnt vmcnt(8)
	s_waitcnt lgkmcnt(0)
	s_barrier
	s_setprio 1
	s_waitcnt lgkmcnt(0)
	v_mfma_f32_16x16x32_bf16 v[4:7], v[132:135], v[164:167], v[4:7]
	v_mfma_f32_16x16x32_bf16 v[4:7], v[136:139], v[168:171], v[4:7]
	v_mfma_f32_16x16x32_bf16 v[8:11], v[144:147], v[168:171], v[8:11]
	v_mfma_f32_16x16x32_bf16 v[8:11], v[140:143], v[164:167], v[8:11]
	v_mfma_f32_16x16x32_bf16 v[16:19], v[140:143], v[172:175], v[16:19]
	v_mfma_f32_16x16x32_bf16 v[16:19], v[144:147], v[176:179], v[16:19]
	v_mfma_f32_16x16x32_bf16 v[12:15], v[136:139], v[176:179], v[12:15]
	v_mfma_f32_16x16x32_bf16 v[12:15], v[132:135], v[172:175], v[12:15]
	v_mfma_f32_16x16x32_bf16 v[20:23], v[132:135], v[180:183], v[20:23]
	v_mfma_f32_16x16x32_bf16 v[20:23], v[136:139], v[184:187], v[20:23]
	v_mfma_f32_16x16x32_bf16 v[24:27], v[144:147], v[184:187], v[24:27]
	v_mfma_f32_16x16x32_bf16 v[24:27], v[140:143], v[180:183], v[24:27]
	v_mfma_f32_16x16x32_bf16 v[32:35], v[140:143], v[194:197], v[32:35]
	v_mfma_f32_16x16x32_bf16 v[32:35], v[144:147], v[198:201], v[32:35]
	v_mfma_f32_16x16x32_bf16 v[28:31], v[136:139], v[198:201], v[28:31]
	v_mfma_f32_16x16x32_bf16 v[28:31], v[132:135], v[194:197], v[28:31]
	s_setprio 0
	s_setprio 1
	v_mfma_f32_16x16x32_bf16 v[36:39], v[148:151], v[164:167], v[36:39]
	v_mfma_f32_16x16x32_bf16 v[36:39], v[152:155], v[168:171], v[36:39]
	v_mfma_f32_16x16x32_bf16 v[40:43], v[160:163], v[168:171], v[40:43]
	v_mfma_f32_16x16x32_bf16 v[40:43], v[156:159], v[164:167], v[40:43]
	v_mfma_f32_16x16x32_bf16 v[48:51], v[156:159], v[172:175], v[48:51]
	v_mfma_f32_16x16x32_bf16 v[48:51], v[160:163], v[176:179], v[48:51]
	v_mfma_f32_16x16x32_bf16 v[44:47], v[152:155], v[176:179], v[44:47]
	v_mfma_f32_16x16x32_bf16 v[44:47], v[148:151], v[172:175], v[44:47]
	v_mfma_f32_16x16x32_bf16 v[52:55], v[148:151], v[180:183], v[52:55]
	v_mfma_f32_16x16x32_bf16 v[52:55], v[152:155], v[184:187], v[52:55]
	v_mfma_f32_16x16x32_bf16 v[56:59], v[160:163], v[184:187], v[56:59]
	v_mfma_f32_16x16x32_bf16 v[56:59], v[156:159], v[180:183], v[56:59]
	v_mfma_f32_16x16x32_bf16 v[64:67], v[156:159], v[194:197], v[64:67]
	v_mfma_f32_16x16x32_bf16 v[64:67], v[160:163], v[198:201], v[64:67]
	s_setprio 2
	s_barrier
	v_mfma_f32_16x16x32_bf16 v[60:63], v[152:155], v[198:201], v[60:63]
	v_mfma_f32_16x16x32_bf16 v[60:63], v[148:151], v[194:197], v[60:63]
	s_setprio 0
	s_add_i32 s38, s71, s54
	s_mov_b32 m0, s38
	ds_read_b128 v[164:167], v210 offset:16384
	ds_read_b128 v[168:171], v210 offset:17408
	ds_read_b128 v[172:175], v210 offset:18432
	ds_read_b128 v[176:179], v210 offset:19456
	ds_read_b128 v[180:183], v210 offset:20480
	ds_read_b128 v[184:187], v210 offset:21504
	ds_read_b128 v[194:197], v210 offset:22528
	ds_read_b128 v[198:201], v210 offset:23552
	global_load_lds_dwordx4 v192, s[16:17]
	s_add_i32 m0, s38, 0x2000
	s_add_u32 s42, s16, 0x160000
	s_addc_u32 s43, s17, 0
	s_add_i32 s38, s72, s54
	global_load_lds_dwordx4 v190, s[16:17]
	s_mov_b32 m0, s38
	v_mov_b32_e32 v193, v3
	global_load_lds_dwordx4 v192, s[42:43]
	s_add_i32 m0, s38, 0x2000
	v_mov_b32_e32 v191, v3
	global_load_lds_dwordx4 v190, s[42:43]
	s_mov_b32 m0, s55
	v_lshl_add_u64 v[202:203], s[16:17], 0, v[192:193]
	global_load_lds_dwordx4 v2, s[26:27]
	s_mov_b32 m0, s56
	v_lshl_add_u64 v[204:205], s[16:17], 0, v[190:191]
	global_load_lds_dwordx4 v188, s[26:27]
	s_waitcnt vmcnt(8)
	s_waitcnt lgkmcnt(0)
	v_lshl_add_u64 v[206:207], s[26:27], 0, v[2:3]
	v_lshl_add_u64 v[208:209], s[26:27], 0, v[188:189]
	s_barrier
	s_setprio 1
	s_waitcnt lgkmcnt(0)
	v_mfma_f32_16x16x32_bf16 v[68:71], v[132:135], v[164:167], v[68:71]
	v_mfma_f32_16x16x32_bf16 v[68:71], v[136:139], v[168:171], v[68:71]
	v_mfma_f32_16x16x32_bf16 v[72:75], v[144:147], v[168:171], v[72:75]
	v_mfma_f32_16x16x32_bf16 v[72:75], v[140:143], v[164:167], v[72:75]
	v_mfma_f32_16x16x32_bf16 v[80:83], v[140:143], v[172:175], v[80:83]
	v_mfma_f32_16x16x32_bf16 v[80:83], v[144:147], v[176:179], v[80:83]
	v_mfma_f32_16x16x32_bf16 v[76:79], v[136:139], v[176:179], v[76:79]
	v_mfma_f32_16x16x32_bf16 v[76:79], v[132:135], v[172:175], v[76:79]
	v_mfma_f32_16x16x32_bf16 v[84:87], v[132:135], v[180:183], v[84:87]
	v_mfma_f32_16x16x32_bf16 v[84:87], v[136:139], v[184:187], v[84:87]
	v_mfma_f32_16x16x32_bf16 v[88:91], v[144:147], v[184:187], v[88:91]
	v_mfma_f32_16x16x32_bf16 v[88:91], v[140:143], v[180:183], v[88:91]
	v_mfma_f32_16x16x32_bf16 v[96:99], v[140:143], v[194:197], v[96:99]
	v_mfma_f32_16x16x32_bf16 v[96:99], v[144:147], v[198:201], v[96:99]
	v_mfma_f32_16x16x32_bf16 v[92:95], v[136:139], v[198:201], v[92:95]
	v_mfma_f32_16x16x32_bf16 v[92:95], v[132:135], v[194:197], v[92:95]
	s_setprio 0
	s_setprio 1
	v_mfma_f32_16x16x32_bf16 v[100:103], v[148:151], v[164:167], v[100:103]
	v_mfma_f32_16x16x32_bf16 v[100:103], v[152:155], v[168:171], v[100:103]
	v_mfma_f32_16x16x32_bf16 v[104:107], v[160:163], v[168:171], v[104:107]
	v_mfma_f32_16x16x32_bf16 v[104:107], v[156:159], v[164:167], v[104:107]
	v_mfma_f32_16x16x32_bf16 v[112:115], v[156:159], v[172:175], v[112:115]
	v_mfma_f32_16x16x32_bf16 v[112:115], v[160:163], v[176:179], v[112:115]
	v_mfma_f32_16x16x32_bf16 v[108:111], v[152:155], v[176:179], v[108:111]
	v_mfma_f32_16x16x32_bf16 v[108:111], v[148:151], v[172:175], v[108:111]
	v_mfma_f32_16x16x32_bf16 v[116:119], v[148:151], v[180:183], v[116:119]
	v_mfma_f32_16x16x32_bf16 v[116:119], v[152:155], v[184:187], v[116:119]
	v_mfma_f32_16x16x32_bf16 v[120:123], v[160:163], v[184:187], v[120:123]
	v_mfma_f32_16x16x32_bf16 v[120:123], v[156:159], v[180:183], v[120:123]
	v_mfma_f32_16x16x32_bf16 v[128:131], v[156:159], v[194:197], v[128:131]
	v_mfma_f32_16x16x32_bf16 v[128:131], v[160:163], v[198:201], v[128:131]
	s_setprio 2
	s_barrier
	v_mfma_f32_16x16x32_bf16 v[124:127], v[152:155], v[198:201], v[124:127]
	v_mfma_f32_16x16x32_bf16 v[124:127], v[148:151], v[194:197], v[124:127]
	s_setprio 0
	s_add_i32 s38, 0, 0x18000
	s_add_i32 s42, 0, 0x1c000
	v_add_u32_e32 v144, s38, v232
	v_add_u32_e32 v160, s42, v232
	ds_read_b128 v[132:135], v144
	ds_read_b128 v[136:139], v144 offset:1024
	ds_read_b128 v[140:143], v144 offset:2048
	ds_read_b128 v[144:147], v144 offset:3072
	ds_read_b128 v[148:151], v160
	ds_read_b128 v[152:155], v160 offset:1024
	ds_read_b128 v[156:159], v160 offset:2048
	ds_read_b128 v[160:163], v160 offset:3072
	s_add_u32 s26, s26, 0x160000
	s_addc_u32 s27, s27, 0
	s_mov_b32 m0, s57
	ds_read_b128 v[164:167], v210 offset:32768
	ds_read_b128 v[168:171], v210 offset:33792
	ds_read_b128 v[172:175], v210 offset:34816
	ds_read_b128 v[176:179], v210 offset:35840
	ds_read_b128 v[180:183], v210 offset:36864
	ds_read_b128 v[184:187], v210 offset:37888
	ds_read_b128 v[194:197], v210 offset:38912
	ds_read_b128 v[198:201], v210 offset:39936
	global_load_lds_dwordx4 v2, s[26:27]
	s_mov_b32 m0, s58
	s_nop 0
	global_load_lds_dwordx4 v188, s[26:27]
	s_waitcnt vmcnt(8)
	s_waitcnt lgkmcnt(0)
	s_barrier
	s_setprio 1
	s_waitcnt lgkmcnt(0)
	v_mfma_f32_16x16x32_bf16 v[4:7], v[132:135], v[164:167], v[4:7]
	v_mfma_f32_16x16x32_bf16 v[4:7], v[136:139], v[168:171], v[4:7]
	v_mfma_f32_16x16x32_bf16 v[8:11], v[144:147], v[168:171], v[8:11]
	v_mfma_f32_16x16x32_bf16 v[8:11], v[140:143], v[164:167], v[8:11]
	v_mfma_f32_16x16x32_bf16 v[16:19], v[140:143], v[172:175], v[16:19]
	v_mfma_f32_16x16x32_bf16 v[16:19], v[144:147], v[176:179], v[16:19]
	v_mfma_f32_16x16x32_bf16 v[12:15], v[136:139], v[176:179], v[12:15]
	v_mfma_f32_16x16x32_bf16 v[12:15], v[132:135], v[172:175], v[12:15]
	v_mfma_f32_16x16x32_bf16 v[20:23], v[132:135], v[180:183], v[20:23]
	v_mfma_f32_16x16x32_bf16 v[20:23], v[136:139], v[184:187], v[20:23]
	v_mfma_f32_16x16x32_bf16 v[24:27], v[144:147], v[184:187], v[24:27]
	v_mfma_f32_16x16x32_bf16 v[24:27], v[140:143], v[180:183], v[24:27]
	v_mfma_f32_16x16x32_bf16 v[32:35], v[140:143], v[194:197], v[32:35]
	v_mfma_f32_16x16x32_bf16 v[32:35], v[144:147], v[198:201], v[32:35]
	v_mfma_f32_16x16x32_bf16 v[28:31], v[136:139], v[198:201], v[28:31]
	v_mfma_f32_16x16x32_bf16 v[28:31], v[132:135], v[194:197], v[28:31]
	s_setprio 0
	s_setprio 1
	v_mfma_f32_16x16x32_bf16 v[36:39], v[148:151], v[164:167], v[36:39]
	v_mfma_f32_16x16x32_bf16 v[36:39], v[152:155], v[168:171], v[36:39]
	v_mfma_f32_16x16x32_bf16 v[40:43], v[160:163], v[168:171], v[40:43]
	v_mfma_f32_16x16x32_bf16 v[40:43], v[156:159], v[164:167], v[40:43]
	v_mfma_f32_16x16x32_bf16 v[48:51], v[156:159], v[172:175], v[48:51]
	v_mfma_f32_16x16x32_bf16 v[48:51], v[160:163], v[176:179], v[48:51]
	v_mfma_f32_16x16x32_bf16 v[44:47], v[152:155], v[176:179], v[44:47]
	v_mfma_f32_16x16x32_bf16 v[44:47], v[148:151], v[172:175], v[44:47]
	v_mfma_f32_16x16x32_bf16 v[52:55], v[148:151], v[180:183], v[52:55]
	v_mfma_f32_16x16x32_bf16 v[52:55], v[152:155], v[184:187], v[52:55]
	v_mfma_f32_16x16x32_bf16 v[56:59], v[160:163], v[184:187], v[56:59]
	v_mfma_f32_16x16x32_bf16 v[56:59], v[156:159], v[180:183], v[56:59]
	v_mfma_f32_16x16x32_bf16 v[64:67], v[156:159], v[194:197], v[64:67]
	v_mfma_f32_16x16x32_bf16 v[64:67], v[160:163], v[198:201], v[64:67]
	s_setprio 2
	s_barrier
	v_mfma_f32_16x16x32_bf16 v[60:63], v[152:155], v[198:201], v[60:63]
	v_mfma_f32_16x16x32_bf16 v[60:63], v[148:151], v[194:197], v[60:63]
	s_setprio 0
	s_add_i32 s26, s38, s54
	v_lshl_add_u64 v[202:203], v[202:203], 0, s[4:5]
	s_mov_b32 m0, s26
	ds_read_b128 v[164:167], v210 offset:49152
	ds_read_b128 v[168:171], v210 offset:50176
	ds_read_b128 v[172:175], v210 offset:51200
	ds_read_b128 v[176:179], v210 offset:52224
	ds_read_b128 v[180:183], v210 offset:53248
	ds_read_b128 v[184:187], v210 offset:54272
	ds_read_b128 v[194:197], v210 offset:55296
	ds_read_b128 v[198:201], v210 offset:56320
	global_load_lds_dwordx4 v[202:203], off
	s_add_i32 m0, s26, 0x2000
	s_add_u32 s16, s16, 0x15ff80
	v_lshl_add_u64 v[202:203], v[204:205], 0, s[4:5]
	s_addc_u32 s17, s17, 0
	s_add_i32 s26, s42, s54
	global_load_lds_dwordx4 v[202:203], off
	s_mov_b32 m0, s26
	v_lshl_add_u64 v[202:203], v[206:207], 0, s[4:5]
	global_load_lds_dwordx4 v192, s[16:17]
	s_add_i32 m0, s26, 0x2000
	s_nop 0
	global_load_lds_dwordx4 v190, s[16:17]
	s_mov_b32 m0, s62
	s_nop 0
	global_load_lds_dwordx4 v[202:203], off
	v_lshl_add_u64 v[202:203], v[208:209], 0, s[4:5]
	s_mov_b32 m0, s63
	s_nop 0
	global_load_lds_dwordx4 v[202:203], off
	s_waitcnt vmcnt(8)
	s_waitcnt lgkmcnt(0)
	s_barrier
	s_setprio 1
	s_waitcnt lgkmcnt(0)
	v_mfma_f32_16x16x32_bf16 v[68:71], v[132:135], v[164:167], v[68:71]
	v_mfma_f32_16x16x32_bf16 v[68:71], v[136:139], v[168:171], v[68:71]
	v_mfma_f32_16x16x32_bf16 v[72:75], v[144:147], v[168:171], v[72:75]
	v_mfma_f32_16x16x32_bf16 v[72:75], v[140:143], v[164:167], v[72:75]
	v_mfma_f32_16x16x32_bf16 v[80:83], v[140:143], v[172:175], v[80:83]
	v_mfma_f32_16x16x32_bf16 v[80:83], v[144:147], v[176:179], v[80:83]
	v_mfma_f32_16x16x32_bf16 v[76:79], v[136:139], v[176:179], v[76:79]
	v_mfma_f32_16x16x32_bf16 v[76:79], v[132:135], v[172:175], v[76:79]
	v_mfma_f32_16x16x32_bf16 v[84:87], v[132:135], v[180:183], v[84:87]
	v_mfma_f32_16x16x32_bf16 v[84:87], v[136:139], v[184:187], v[84:87]
	v_mfma_f32_16x16x32_bf16 v[88:91], v[144:147], v[184:187], v[88:91]
	v_mfma_f32_16x16x32_bf16 v[88:91], v[140:143], v[180:183], v[88:91]
	v_mfma_f32_16x16x32_bf16 v[96:99], v[140:143], v[194:197], v[96:99]
	v_mfma_f32_16x16x32_bf16 v[96:99], v[144:147], v[198:201], v[96:99]
	v_mfma_f32_16x16x32_bf16 v[92:95], v[136:139], v[198:201], v[92:95]
	v_mfma_f32_16x16x32_bf16 v[92:95], v[132:135], v[194:197], v[92:95]
	s_setprio 0
	s_setprio 1
	v_mfma_f32_16x16x32_bf16 v[100:103], v[148:151], v[164:167], v[100:103]
	v_mfma_f32_16x16x32_bf16 v[100:103], v[152:155], v[168:171], v[100:103]
	v_mfma_f32_16x16x32_bf16 v[104:107], v[160:163], v[168:171], v[104:107]
	v_mfma_f32_16x16x32_bf16 v[104:107], v[156:159], v[164:167], v[104:107]
	v_mfma_f32_16x16x32_bf16 v[112:115], v[156:159], v[172:175], v[112:115]
	v_mfma_f32_16x16x32_bf16 v[112:115], v[160:163], v[176:179], v[112:115]
	v_mfma_f32_16x16x32_bf16 v[108:111], v[152:155], v[176:179], v[108:111]
	v_mfma_f32_16x16x32_bf16 v[108:111], v[148:151], v[172:175], v[108:111]
	v_mfma_f32_16x16x32_bf16 v[116:119], v[148:151], v[180:183], v[116:119]
	v_mfma_f32_16x16x32_bf16 v[116:119], v[152:155], v[184:187], v[116:119]
	v_mfma_f32_16x16x32_bf16 v[120:123], v[160:163], v[184:187], v[120:123]
	v_mfma_f32_16x16x32_bf16 v[120:123], v[156:159], v[180:183], v[120:123]
	v_mfma_f32_16x16x32_bf16 v[128:131], v[156:159], v[194:197], v[128:131]
	v_mfma_f32_16x16x32_bf16 v[128:131], v[160:163], v[198:201], v[128:131]
	s_setprio 2
	s_barrier
	v_mfma_f32_16x16x32_bf16 v[124:127], v[152:155], v[198:201], v[124:127]
	v_mfma_f32_16x16x32_bf16 v[124:127], v[148:151], v[194:197], v[124:127]
	s_setprio 0
	s_cmpk_gt_u32 s28, 0x55
	s_cbranch_scc1 .LBB0_651
	s_mov_b32 s28, s29
	s_branch .LBB0_645

.LBB0_749:
	s_add_i32 s47, 0, 0x10000
	s_add_i32 s49, 0, 0x14000
	v_add_u32_e32 v16, s47, v147
	v_add_u32_e32 v32, s49, v147
	ds_read_b128 v[4:7], v16
	ds_read_b128 v[8:11], v16 offset:1024
	ds_read_b128 v[12:15], v16 offset:2048
	ds_read_b128 v[16:19], v16 offset:3072
	ds_read_b128 v[20:23], v32
	ds_read_b128 v[24:27], v32 offset:1024
	ds_read_b128 v[28:31], v32 offset:2048
	ds_read_b128 v[32:35], v32 offset:3072
	v_add_u32_e32 v231, 0, v146
	ds_read_b128 v[36:39], v231
	ds_read_b128 v[40:43], v231 offset:1024
	ds_read_b128 v[44:47], v231 offset:2048
	ds_read_b128 v[48:51], v231 offset:3072
	ds_read_b128 v[52:55], v231 offset:4096
	ds_read_b128 v[56:59], v231 offset:5120
	ds_read_b128 v[60:63], v231 offset:6144
	ds_read_b128 v[64:67], v231 offset:7168
	s_waitcnt vmcnt(8)
	s_waitcnt lgkmcnt(0)
	s_barrier
	s_setprio 1
	s_waitcnt lgkmcnt(0)
	v_mfma_f32_16x16x32_f16 v[68:71], v[4:7], v[36:39], 0
	v_mfma_f32_16x16x32_f16 v[68:71], v[8:11], v[40:43], v[68:71]
	v_mfma_f32_16x16x32_f16 v[72:75], v[12:15], v[36:39], 0
	v_mfma_f32_16x16x32_f16 v[72:75], v[16:19], v[40:43], v[72:75]
	v_mfma_f32_16x16x32_f16 v[80:83], v[12:15], v[44:47], 0
	v_mfma_f32_16x16x32_f16 v[80:83], v[16:19], v[48:51], v[80:83]
	v_mfma_f32_16x16x32_f16 v[76:79], v[4:7], v[44:47], 0
	v_mfma_f32_16x16x32_f16 v[76:79], v[8:11], v[48:51], v[76:79]
	v_mfma_f32_16x16x32_f16 v[84:87], v[4:7], v[52:55], 0
	v_mfma_f32_16x16x32_f16 v[84:87], v[8:11], v[56:59], v[84:87]
	v_mfma_f32_16x16x32_f16 v[88:91], v[12:15], v[52:55], 0
	v_mfma_f32_16x16x32_f16 v[88:91], v[16:19], v[56:59], v[88:91]
	v_mfma_f32_16x16x32_f16 v[96:99], v[12:15], v[60:63], 0
	v_mfma_f32_16x16x32_f16 v[96:99], v[16:19], v[64:67], v[96:99]
	v_mfma_f32_16x16x32_f16 v[92:95], v[4:7], v[60:63], 0
	v_mfma_f32_16x16x32_f16 v[92:95], v[8:11], v[64:67], v[92:95]
	s_setprio 0
	s_setprio 1
	v_mfma_f32_16x16x32_f16 v[100:103], v[20:23], v[36:39], 0
	v_mfma_f32_16x16x32_f16 v[36:39], v[28:31], v[36:39], 0
	v_mfma_f32_16x16x32_f16 v[104:107], v[20:23], v[44:47], 0
	v_mfma_f32_16x16x32_f16 v[44:47], v[28:31], v[44:47], 0
	v_mfma_f32_16x16x32_f16 v[108:111], v[20:23], v[52:55], 0
	v_mfma_f32_16x16x32_f16 v[52:55], v[28:31], v[52:55], 0
	v_mfma_f32_16x16x32_f16 v[112:115], v[20:23], v[60:63], 0
	v_mfma_f32_16x16x32_f16 v[60:63], v[28:31], v[60:63], 0
	v_mfma_f32_16x16x32_f16 v[100:103], v[24:27], v[40:43], v[100:103]
	v_mfma_f32_16x16x32_f16 v[40:43], v[32:35], v[40:43], v[36:39]
	v_mfma_f32_16x16x32_f16 v[104:107], v[24:27], v[48:51], v[104:107]
	v_mfma_f32_16x16x32_f16 v[48:51], v[32:35], v[48:51], v[44:47]
	v_mfma_f32_16x16x32_f16 v[108:111], v[24:27], v[56:59], v[108:111]
	v_mfma_f32_16x16x32_f16 v[56:59], v[32:35], v[56:59], v[52:55]
	s_setprio 2
	s_barrier
	v_mfma_f32_16x16x32_f16 v[112:115], v[24:27], v[64:67], v[112:115]
	v_mfma_f32_16x16x32_f16 v[64:67], v[32:35], v[64:67], v[60:63]
	s_setprio 0
	v_lshl_add_u64 v[136:137], s[6:7], 0, v[2:3]
	s_add_i32 s47, s47, s62
	v_mov_b32_e32 v135, v3
	v_lshl_add_u64 v[140:141], v[136:137], 0, s[74:75]
	s_mov_b32 m0, s47
	v_lshl_add_u64 v[144:145], s[6:7], 0, v[134:135]
	ds_read_b128 v[36:39], v231 offset:16384
	ds_read_b128 v[44:47], v231 offset:17408
	ds_read_b128 v[52:55], v231 offset:18432
	ds_read_b128 v[60:63], v231 offset:19456
	ds_read_b128 v[116:119], v231 offset:20480
	ds_read_b128 v[120:123], v231 offset:21504
	ds_read_b128 v[124:127], v231 offset:22528
	ds_read_b128 v[128:131], v231 offset:23552
	global_load_lds_dwordx4 v[140:141], off
	v_lshl_add_u64 v[140:141], v[144:145], 0, s[74:75]
	s_add_i32 m0, s47, 0x2000
	s_add_i32 s47, s49, s62
	global_load_lds_dwordx4 v[140:141], off
	s_mov_b32 m0, s47
	v_mov_b32_e32 v139, v3
	global_load_lds_dwordx4 v2, s[16:17]
	s_add_i32 m0, s47, 0x2000
	v_lshl_add_u64 v[248:249], s[8:9], 0, v[138:139]
	v_mov_b32_e32 v133, v3
	global_load_lds_dwordx4 v134, s[16:17]
	v_lshl_add_u64 v[140:141], v[248:249], 0, s[74:75]
	s_mov_b32 m0, s63
	v_lshl_add_u64 v[250:251], s[8:9], 0, v[132:133]
	global_load_lds_dwordx4 v[140:141], off
	v_lshl_add_u64 v[140:141], v[250:251], 0, s[74:75]
	s_mov_b32 m0, s64
	s_nop 0
	global_load_lds_dwordx4 v[140:141], off
	s_waitcnt vmcnt(8)
	s_waitcnt lgkmcnt(0)
	s_barrier
	s_setprio 1
	s_waitcnt lgkmcnt(0)
	v_mfma_f32_16x16x32_f16 v[140:143], v[4:7], v[36:39], 0
	v_mfma_f32_16x16x32_f16 v[148:151], v[12:15], v[36:39], 0
	v_mfma_f32_16x16x32_f16 v[152:155], v[4:7], v[52:55], 0
	v_mfma_f32_16x16x32_f16 v[156:159], v[12:15], v[52:55], 0
	v_mfma_f32_16x16x32_f16 v[160:163], v[4:7], v[116:119], 0
	v_mfma_f32_16x16x32_f16 v[164:167], v[12:15], v[116:119], 0
	v_mfma_f32_16x16x32_f16 v[4:7], v[4:7], v[124:127], 0
	v_mfma_f32_16x16x32_f16 v[12:15], v[12:15], v[124:127], 0
	v_mfma_f32_16x16x32_f16 v[140:143], v[8:11], v[44:47], v[140:143]
	v_mfma_f32_16x16x32_f16 v[148:151], v[16:19], v[44:47], v[148:151]
	v_mfma_f32_16x16x32_f16 v[152:155], v[8:11], v[60:63], v[152:155]
	v_mfma_f32_16x16x32_f16 v[156:159], v[16:19], v[60:63], v[156:159]
	v_mfma_f32_16x16x32_f16 v[160:163], v[8:11], v[120:123], v[160:163]
	v_mfma_f32_16x16x32_f16 v[164:167], v[16:19], v[120:123], v[164:167]
	v_mfma_f32_16x16x32_f16 v[168:171], v[8:11], v[128:131], v[4:7]
	v_mfma_f32_16x16x32_f16 v[172:175], v[16:19], v[128:131], v[12:15]
	s_setprio 0
	s_setprio 1
	v_mfma_f32_16x16x32_f16 v[4:7], v[20:23], v[36:39], 0
	v_mfma_f32_16x16x32_f16 v[8:11], v[28:31], v[36:39], 0
	v_mfma_f32_16x16x32_f16 v[12:15], v[20:23], v[52:55], 0
	v_mfma_f32_16x16x32_f16 v[16:19], v[28:31], v[52:55], 0
	v_mfma_f32_16x16x32_f16 v[36:39], v[20:23], v[116:119], 0
	v_mfma_f32_16x16x32_f16 v[52:55], v[28:31], v[116:119], 0
	v_mfma_f32_16x16x32_f16 v[20:23], v[20:23], v[124:127], 0
	v_mfma_f32_16x16x32_f16 v[28:31], v[28:31], v[124:127], 0
	v_mfma_f32_16x16x32_f16 v[116:119], v[24:27], v[44:47], v[4:7]
	v_mfma_f32_16x16x32_f16 v[124:127], v[32:35], v[44:47], v[8:11]
	v_mfma_f32_16x16x32_f16 v[184:187], v[24:27], v[120:123], v[36:39]
	v_mfma_f32_16x16x32_f16 v[120:123], v[32:35], v[120:123], v[52:55]
	v_mfma_f32_16x16x32_f16 v[188:191], v[24:27], v[128:131], v[20:23]
	v_mfma_f32_16x16x32_f16 v[128:131], v[32:35], v[128:131], v[28:31]
	s_setprio 2
	s_barrier
	v_mfma_f32_16x16x32_f16 v[176:179], v[24:27], v[60:63], v[12:15]
	v_mfma_f32_16x16x32_f16 v[180:183], v[32:35], v[60:63], v[16:19]
	s_setprio 0
	s_add_i32 s47, 0, 0x18000
	v_add_u32_e32 v4, s47, v147
	s_add_i32 s49, 0, 0x1c000
	ds_read_b128 v[192:195], v4
	ds_read_b128 v[196:199], v4 offset:1024
	ds_read_b128 v[200:203], v4 offset:2048
	ds_read_b128 v[204:207], v4 offset:3072
	v_add_u32_e32 v4, s49, v147
	ds_read_b128 v[208:211], v4
	ds_read_b128 v[212:215], v4 offset:1024
	ds_read_b128 v[216:219], v4 offset:2048
	ds_read_b128 v[220:223], v4 offset:3072
	s_mov_b32 m0, s65
	ds_read_b128 v[44:47], v231 offset:32768
	ds_read_b128 v[52:55], v231 offset:33792
	ds_read_b128 v[60:63], v231 offset:34816
	ds_read_b128 v[224:227], v231 offset:35840
	ds_read_b128 v[232:235], v231 offset:36864
	ds_read_b128 v[236:239], v231 offset:37888
	ds_read_b128 v[240:243], v231 offset:38912
	ds_read_b128 v[244:247], v231 offset:39936
	global_load_lds_dwordx4 v138, s[26:27]
	s_mov_b32 m0, s66
	s_nop 0
	global_load_lds_dwordx4 v132, s[26:27]
	s_waitcnt vmcnt(8)
	s_waitcnt lgkmcnt(0)
	s_barrier
	s_setprio 1
	s_waitcnt lgkmcnt(0)
	v_mfma_f32_16x16x32_f16 v[4:7], v[192:195], v[44:47], v[68:71]
	v_mfma_f32_16x16x32_f16 v[8:11], v[200:203], v[44:47], v[72:75]
	v_mfma_f32_16x16x32_f16 v[12:15], v[192:195], v[60:63], v[76:79]
	v_mfma_f32_16x16x32_f16 v[16:19], v[200:203], v[60:63], v[80:83]
	v_mfma_f32_16x16x32_f16 v[20:23], v[192:195], v[232:235], v[84:87]
	v_mfma_f32_16x16x32_f16 v[24:27], v[200:203], v[232:235], v[88:91]
	v_mfma_f32_16x16x32_f16 v[28:31], v[192:195], v[240:243], v[92:95]
	v_mfma_f32_16x16x32_f16 v[32:35], v[200:203], v[240:243], v[96:99]
	v_mfma_f32_16x16x32_f16 v[4:7], v[196:199], v[52:55], v[4:7]
	v_mfma_f32_16x16x32_f16 v[8:11], v[204:207], v[52:55], v[8:11]
	v_mfma_f32_16x16x32_f16 v[12:15], v[196:199], v[224:227], v[12:15]
	v_mfma_f32_16x16x32_f16 v[16:19], v[204:207], v[224:227], v[16:19]
	v_mfma_f32_16x16x32_f16 v[20:23], v[196:199], v[236:239], v[20:23]
	v_mfma_f32_16x16x32_f16 v[24:27], v[204:207], v[236:239], v[24:27]
	v_mfma_f32_16x16x32_f16 v[28:31], v[196:199], v[244:247], v[28:31]
	v_mfma_f32_16x16x32_f16 v[32:35], v[204:207], v[244:247], v[32:35]
	s_setprio 0
	s_setprio 1
	v_mfma_f32_16x16x32_f16 v[36:39], v[208:211], v[44:47], v[100:103]
	v_mfma_f32_16x16x32_f16 v[40:43], v[216:219], v[44:47], v[40:43]
	v_mfma_f32_16x16x32_f16 v[36:39], v[212:215], v[52:55], v[36:39]
	v_mfma_f32_16x16x32_f16 v[40:43], v[220:223], v[52:55], v[40:43]
	v_mfma_f32_16x16x32_f16 v[44:47], v[208:211], v[60:63], v[104:107]
	v_mfma_f32_16x16x32_f16 v[48:51], v[216:219], v[60:63], v[48:51]
	v_mfma_f32_16x16x32_f16 v[52:55], v[208:211], v[232:235], v[108:111]
	v_mfma_f32_16x16x32_f16 v[56:59], v[216:219], v[232:235], v[56:59]
	v_mfma_f32_16x16x32_f16 v[60:63], v[208:211], v[240:243], v[112:115]
	v_mfma_f32_16x16x32_f16 v[64:67], v[216:219], v[240:243], v[64:67]
	v_mfma_f32_16x16x32_f16 v[44:47], v[212:215], v[224:227], v[44:47]
	v_mfma_f32_16x16x32_f16 v[48:51], v[220:223], v[224:227], v[48:51]
	v_mfma_f32_16x16x32_f16 v[52:55], v[212:215], v[236:239], v[52:55]
	v_mfma_f32_16x16x32_f16 v[56:59], v[220:223], v[236:239], v[56:59]
	s_setprio 2
	s_barrier
	v_mfma_f32_16x16x32_f16 v[60:63], v[212:215], v[244:247], v[60:63]
	v_mfma_f32_16x16x32_f16 v[64:67], v[220:223], v[244:247], v[64:67]
	s_setprio 0
	s_add_i32 s47, s47, s62
	v_lshl_add_u64 v[68:69], v[136:137], 0, s[24:25]
	s_mov_b32 m0, s47
	ds_read_b128 v[104:107], v231 offset:49152
	ds_read_b128 v[108:111], v231 offset:50176
	ds_read_b128 v[112:115], v231 offset:51200
	ds_read_b128 v[224:227], v231 offset:52224
	ds_read_b128 v[232:235], v231 offset:53248
	ds_read_b128 v[236:239], v231 offset:54272
	ds_read_b128 v[240:243], v231 offset:55296
	ds_read_b128 v[244:247], v231 offset:56320
	global_load_lds_dwordx4 v[68:69], off
	v_lshl_add_u64 v[68:69], v[144:145], 0, s[24:25]
	s_add_i32 m0, s47, 0x2000
	s_add_i32 s47, s49, s62
	global_load_lds_dwordx4 v[68:69], off
	s_mov_b32 m0, s47
	v_lshl_add_u64 v[68:69], v[248:249], 0, s[24:25]
	global_load_lds_dwordx4 v2, s[28:29]
	s_add_i32 m0, s47, 0x2000
	s_nop 0
	global_load_lds_dwordx4 v134, s[28:29]
	s_mov_b32 m0, s69
	s_nop 0
	global_load_lds_dwordx4 v[68:69], off
	v_lshl_add_u64 v[68:69], v[250:251], 0, s[24:25]
	s_mov_b32 m0, s70
	s_nop 0
	global_load_lds_dwordx4 v[68:69], off
	s_waitcnt vmcnt(8)
	s_waitcnt lgkmcnt(0)
	s_barrier
	s_setprio 1
	s_waitcnt lgkmcnt(0)
	v_mfma_f32_16x16x32_f16 v[68:71], v[192:195], v[104:107], v[140:143]
	v_mfma_f32_16x16x32_f16 v[72:75], v[200:203], v[104:107], v[148:151]
	v_mfma_f32_16x16x32_f16 v[76:79], v[192:195], v[112:115], v[152:155]
	v_mfma_f32_16x16x32_f16 v[80:83], v[200:203], v[112:115], v[156:159]
	v_mfma_f32_16x16x32_f16 v[84:87], v[192:195], v[232:235], v[160:163]
	v_mfma_f32_16x16x32_f16 v[88:91], v[200:203], v[232:235], v[164:167]
	v_mfma_f32_16x16x32_f16 v[92:95], v[192:195], v[240:243], v[168:171]
	v_mfma_f32_16x16x32_f16 v[96:99], v[200:203], v[240:243], v[172:175]
	v_mfma_f32_16x16x32_f16 v[68:71], v[196:199], v[108:111], v[68:71]
	v_mfma_f32_16x16x32_f16 v[72:75], v[204:207], v[108:111], v[72:75]
	v_mfma_f32_16x16x32_f16 v[76:79], v[196:199], v[224:227], v[76:79]
	v_mfma_f32_16x16x32_f16 v[80:83], v[204:207], v[224:227], v[80:83]
	v_mfma_f32_16x16x32_f16 v[84:87], v[196:199], v[236:239], v[84:87]
	v_mfma_f32_16x16x32_f16 v[88:91], v[204:207], v[236:239], v[88:91]
	v_mfma_f32_16x16x32_f16 v[92:95], v[196:199], v[244:247], v[92:95]
	v_mfma_f32_16x16x32_f16 v[96:99], v[204:207], v[244:247], v[96:99]
	s_setprio 0
	s_setprio 1
	v_mfma_f32_16x16x32_f16 v[100:103], v[208:211], v[104:107], v[116:119]
	v_mfma_f32_16x16x32_f16 v[104:107], v[216:219], v[104:107], v[124:127]
	v_mfma_f32_16x16x32_f16 v[100:103], v[212:215], v[108:111], v[100:103]
	v_mfma_f32_16x16x32_f16 v[104:107], v[220:223], v[108:111], v[104:107]
	v_mfma_f32_16x16x32_f16 v[108:111], v[208:211], v[112:115], v[176:179]
	v_mfma_f32_16x16x32_f16 v[112:115], v[216:219], v[112:115], v[180:183]
	v_mfma_f32_16x16x32_f16 v[116:119], v[208:211], v[232:235], v[184:187]
	v_mfma_f32_16x16x32_f16 v[120:123], v[216:219], v[232:235], v[120:123]
	v_mfma_f32_16x16x32_f16 v[124:127], v[208:211], v[240:243], v[188:191]
	v_mfma_f32_16x16x32_f16 v[128:131], v[216:219], v[240:243], v[128:131]
	v_mfma_f32_16x16x32_f16 v[108:111], v[212:215], v[224:227], v[108:111]
	v_mfma_f32_16x16x32_f16 v[112:115], v[220:223], v[224:227], v[112:115]
	v_mfma_f32_16x16x32_f16 v[116:119], v[212:215], v[236:239], v[116:119]
	v_mfma_f32_16x16x32_f16 v[120:123], v[220:223], v[236:239], v[120:123]
	s_setprio 2
	s_barrier
	v_mfma_f32_16x16x32_f16 v[124:127], v[212:215], v[244:247], v[124:127]
	v_mfma_f32_16x16x32_f16 v[128:131], v[220:223], v[244:247], v[128:131]
	s_setprio 0
	s_add_i32 s45, s45, 2
	s_cmp_ge_i32 s45, s44
	s_cbranch_scc0 .LBB0_749
	v_mov_b32_e32 v136, v2
	s_branch .LBB0_752

.LBB0_753:
	s_add_u32 s6, s8, 0xfff80080
	s_addc_u32 s7, s9, -1
	s_add_i32 s29, 0, 0x10000
	s_cmp_eq_u32 s28, 28
	s_cselect_b32 s17, s13, s7
	s_cselect_b32 s16, s12, s6
	v_add_u32_e32 v133, s29, v147
	s_cselect_b32 s7, s15, s27
	s_cselect_b32 s6, s14, s26
	s_add_i32 s47, 0, 0x14000
	ds_read_b128 v[138:141], v133
	ds_read_b128 v[142:145], v133 offset:1024
	ds_read_b128 v[148:151], v133 offset:2048
	ds_read_b128 v[152:155], v133 offset:3072
	v_add_u32_e32 v133, s47, v147
	ds_read_b128 v[156:159], v133
	ds_read_b128 v[160:163], v133 offset:1024
	ds_read_b128 v[164:167], v133 offset:2048
	ds_read_b128 v[168:171], v133 offset:3072
	s_mov_b32 m0, s71
	v_add_u32_e32 v212, 0, v146
	ds_read_b128 v[172:175], v212
	ds_read_b128 v[176:179], v212 offset:1024
	ds_read_b128 v[180:183], v212 offset:2048
	ds_read_b128 v[184:187], v212 offset:3072
	ds_read_b128 v[188:191], v212 offset:4096
	ds_read_b128 v[192:195], v212 offset:5120
	ds_read_b128 v[196:199], v212 offset:6144
	ds_read_b128 v[200:203], v212 offset:7168
	global_load_lds_dwordx4 v2, s[8:9]
	s_mov_b32 m0, s72
	v_mov_b32_e32 v133, v3
	global_load_lds_dwordx4 v132, s[8:9]
	s_waitcnt vmcnt(8)
	s_waitcnt lgkmcnt(0)
	s_barrier
	s_setprio 1
	s_waitcnt lgkmcnt(0)
	v_mfma_f32_16x16x32_f16 v[4:7], v[138:141], v[172:175], v[4:7]
	v_mfma_f32_16x16x32_f16 v[4:7], v[142:145], v[176:179], v[4:7]
	v_mfma_f32_16x16x32_f16 v[8:11], v[152:155], v[176:179], v[8:11]
	v_mfma_f32_16x16x32_f16 v[8:11], v[148:151], v[172:175], v[8:11]
	v_mfma_f32_16x16x32_f16 v[16:19], v[148:151], v[180:183], v[16:19]
	v_mfma_f32_16x16x32_f16 v[16:19], v[152:155], v[184:187], v[16:19]
	v_mfma_f32_16x16x32_f16 v[12:15], v[142:145], v[184:187], v[12:15]
	v_mfma_f32_16x16x32_f16 v[12:15], v[138:141], v[180:183], v[12:15]
	v_mfma_f32_16x16x32_f16 v[20:23], v[138:141], v[188:191], v[20:23]
	v_mfma_f32_16x16x32_f16 v[20:23], v[142:145], v[192:195], v[20:23]
	v_mfma_f32_16x16x32_f16 v[24:27], v[152:155], v[192:195], v[24:27]
	v_mfma_f32_16x16x32_f16 v[24:27], v[148:151], v[188:191], v[24:27]
	v_mfma_f32_16x16x32_f16 v[32:35], v[148:151], v[196:199], v[32:35]
	v_mfma_f32_16x16x32_f16 v[32:35], v[152:155], v[200:203], v[32:35]
	v_mfma_f32_16x16x32_f16 v[28:31], v[142:145], v[200:203], v[28:31]
	v_mfma_f32_16x16x32_f16 v[28:31], v[138:141], v[196:199], v[28:31]
	s_setprio 0
	s_setprio 1
	v_mfma_f32_16x16x32_f16 v[36:39], v[156:159], v[172:175], v[36:39]
	v_mfma_f32_16x16x32_f16 v[36:39], v[160:163], v[176:179], v[36:39]
	v_mfma_f32_16x16x32_f16 v[40:43], v[168:171], v[176:179], v[40:43]
	v_mfma_f32_16x16x32_f16 v[40:43], v[164:167], v[172:175], v[40:43]
	v_mfma_f32_16x16x32_f16 v[48:51], v[164:167], v[180:183], v[48:51]
	v_mfma_f32_16x16x32_f16 v[48:51], v[168:171], v[184:187], v[48:51]
	v_mfma_f32_16x16x32_f16 v[44:47], v[160:163], v[184:187], v[44:47]
	v_mfma_f32_16x16x32_f16 v[44:47], v[156:159], v[180:183], v[44:47]
	v_mfma_f32_16x16x32_f16 v[52:55], v[156:159], v[188:191], v[52:55]
	v_mfma_f32_16x16x32_f16 v[52:55], v[160:163], v[192:195], v[52:55]
	v_mfma_f32_16x16x32_f16 v[56:59], v[168:171], v[192:195], v[56:59]
	v_mfma_f32_16x16x32_f16 v[56:59], v[164:167], v[188:191], v[56:59]
	v_mfma_f32_16x16x32_f16 v[64:67], v[164:167], v[196:199], v[64:67]
	v_mfma_f32_16x16x32_f16 v[64:67], v[168:171], v[200:203], v[64:67]
	s_setprio 2
	s_barrier
	v_mfma_f32_16x16x32_f16 v[60:63], v[160:163], v[200:203], v[60:63]
	v_mfma_f32_16x16x32_f16 v[60:63], v[156:159], v[196:199], v[60:63]
	s_setprio 0
	s_add_i32 s29, s29, s62
	s_mov_b32 m0, s29
	ds_read_b128 v[172:175], v212 offset:16384
	ds_read_b128 v[176:179], v212 offset:17408
	ds_read_b128 v[180:183], v212 offset:18432
	ds_read_b128 v[184:187], v212 offset:19456
	ds_read_b128 v[188:191], v212 offset:20480
	ds_read_b128 v[192:195], v212 offset:21504
	ds_read_b128 v[196:199], v212 offset:22528
	ds_read_b128 v[200:203], v212 offset:23552
	global_load_lds_dwordx4 v136, s[6:7]
	s_add_i32 m0, s29, 0x2000
	s_add_u32 s44, s6, 0x80000
	s_addc_u32 s45, s7, 0
	s_add_i32 s29, s47, s62
	global_load_lds_dwordx4 v134, s[6:7]
	s_mov_b32 m0, s29
	v_mov_b32_e32 v137, v3
	global_load_lds_dwordx4 v136, s[44:45]
	s_add_i32 m0, s29, 0x2000
	v_mov_b32_e32 v135, v3
	global_load_lds_dwordx4 v134, s[44:45]
	s_mov_b32 m0, s63
	v_lshl_add_u64 v[204:205], s[6:7], 0, v[136:137]
	global_load_lds_dwordx4 v2, s[16:17]
	s_mov_b32 m0, s64
	v_lshl_add_u64 v[206:207], s[6:7], 0, v[134:135]
	global_load_lds_dwordx4 v132, s[16:17]
	s_waitcnt vmcnt(8)
	s_waitcnt lgkmcnt(0)
	v_lshl_add_u64 v[208:209], s[16:17], 0, v[2:3]
	v_lshl_add_u64 v[210:211], s[16:17], 0, v[132:133]
	s_barrier
	s_setprio 1
	s_waitcnt lgkmcnt(0)
	v_mfma_f32_16x16x32_f16 v[68:71], v[138:141], v[172:175], v[68:71]
	v_mfma_f32_16x16x32_f16 v[68:71], v[142:145], v[176:179], v[68:71]
	v_mfma_f32_16x16x32_f16 v[72:75], v[152:155], v[176:179], v[72:75]
	v_mfma_f32_16x16x32_f16 v[72:75], v[148:151], v[172:175], v[72:75]
	v_mfma_f32_16x16x32_f16 v[80:83], v[148:151], v[180:183], v[80:83]
	v_mfma_f32_16x16x32_f16 v[80:83], v[152:155], v[184:187], v[80:83]
	v_mfma_f32_16x16x32_f16 v[76:79], v[142:145], v[184:187], v[76:79]
	v_mfma_f32_16x16x32_f16 v[76:79], v[138:141], v[180:183], v[76:79]
	v_mfma_f32_16x16x32_f16 v[84:87], v[138:141], v[188:191], v[84:87]
	v_mfma_f32_16x16x32_f16 v[84:87], v[142:145], v[192:195], v[84:87]
	v_mfma_f32_16x16x32_f16 v[88:91], v[152:155], v[192:195], v[88:91]
	v_mfma_f32_16x16x32_f16 v[88:91], v[148:151], v[188:191], v[88:91]
	v_mfma_f32_16x16x32_f16 v[96:99], v[148:151], v[196:199], v[96:99]
	v_mfma_f32_16x16x32_f16 v[96:99], v[152:155], v[200:203], v[96:99]
	v_mfma_f32_16x16x32_f16 v[92:95], v[142:145], v[200:203], v[92:95]
	v_mfma_f32_16x16x32_f16 v[92:95], v[138:141], v[196:199], v[92:95]
	s_setprio 0
	s_setprio 1
	v_mfma_f32_16x16x32_f16 v[100:103], v[156:159], v[172:175], v[100:103]
	v_mfma_f32_16x16x32_f16 v[100:103], v[160:163], v[176:179], v[100:103]
	v_mfma_f32_16x16x32_f16 v[104:107], v[168:171], v[176:179], v[104:107]
	v_mfma_f32_16x16x32_f16 v[104:107], v[164:167], v[172:175], v[104:107]
	v_mfma_f32_16x16x32_f16 v[112:115], v[164:167], v[180:183], v[112:115]
	v_mfma_f32_16x16x32_f16 v[112:115], v[168:171], v[184:187], v[112:115]
	v_mfma_f32_16x16x32_f16 v[108:111], v[160:163], v[184:187], v[108:111]
	v_mfma_f32_16x16x32_f16 v[108:111], v[156:159], v[180:183], v[108:111]
	v_mfma_f32_16x16x32_f16 v[116:119], v[156:159], v[188:191], v[116:119]
	v_mfma_f32_16x16x32_f16 v[116:119], v[160:163], v[192:195], v[116:119]
	v_mfma_f32_16x16x32_f16 v[120:123], v[168:171], v[192:195], v[120:123]
	v_mfma_f32_16x16x32_f16 v[120:123], v[164:167], v[188:191], v[120:123]
	v_mfma_f32_16x16x32_f16 v[128:131], v[164:167], v[196:199], v[128:131]
	v_mfma_f32_16x16x32_f16 v[128:131], v[168:171], v[200:203], v[128:131]
	s_setprio 2
	s_barrier
	v_mfma_f32_16x16x32_f16 v[124:127], v[160:163], v[200:203], v[124:127]
	v_mfma_f32_16x16x32_f16 v[124:127], v[156:159], v[196:199], v[124:127]
	s_setprio 0
	s_add_i32 s29, 0, 0x18000
	v_add_u32_e32 v135, s29, v147
	s_add_i32 s44, 0, 0x1c000
	ds_read_b128 v[138:141], v135
	ds_read_b128 v[142:145], v135 offset:1024
	ds_read_b128 v[148:151], v135 offset:2048
	ds_read_b128 v[152:155], v135 offset:3072
	v_add_u32_e32 v135, s44, v147
	ds_read_b128 v[156:159], v135
	ds_read_b128 v[160:163], v135 offset:1024
	ds_read_b128 v[164:167], v135 offset:2048
	ds_read_b128 v[168:171], v135 offset:3072
	s_add_u32 s16, s16, 0x80000
	s_addc_u32 s17, s17, 0
	s_mov_b32 m0, s65
	ds_read_b128 v[172:175], v212 offset:32768
	ds_read_b128 v[176:179], v212 offset:33792
	ds_read_b128 v[180:183], v212 offset:34816
	ds_read_b128 v[184:187], v212 offset:35840
	ds_read_b128 v[188:191], v212 offset:36864
	ds_read_b128 v[192:195], v212 offset:37888
	ds_read_b128 v[196:199], v212 offset:38912
	ds_read_b128 v[200:203], v212 offset:39936
	global_load_lds_dwordx4 v2, s[16:17]
	s_mov_b32 m0, s66
	s_nop 0
	global_load_lds_dwordx4 v132, s[16:17]
	s_waitcnt vmcnt(8)
	s_waitcnt lgkmcnt(0)
	s_barrier
	s_setprio 1
	s_waitcnt lgkmcnt(0)
	v_mfma_f32_16x16x32_f16 v[4:7], v[138:141], v[172:175], v[4:7]
	v_mfma_f32_16x16x32_f16 v[4:7], v[142:145], v[176:179], v[4:7]
	v_mfma_f32_16x16x32_f16 v[8:11], v[152:155], v[176:179], v[8:11]
	v_mfma_f32_16x16x32_f16 v[8:11], v[148:151], v[172:175], v[8:11]
	v_mfma_f32_16x16x32_f16 v[16:19], v[148:151], v[180:183], v[16:19]
	v_mfma_f32_16x16x32_f16 v[16:19], v[152:155], v[184:187], v[16:19]
	v_mfma_f32_16x16x32_f16 v[12:15], v[142:145], v[184:187], v[12:15]
	v_mfma_f32_16x16x32_f16 v[12:15], v[138:141], v[180:183], v[12:15]
	v_mfma_f32_16x16x32_f16 v[20:23], v[138:141], v[188:191], v[20:23]
	v_mfma_f32_16x16x32_f16 v[20:23], v[142:145], v[192:195], v[20:23]
	v_mfma_f32_16x16x32_f16 v[24:27], v[152:155], v[192:195], v[24:27]
	v_mfma_f32_16x16x32_f16 v[24:27], v[148:151], v[188:191], v[24:27]
	v_mfma_f32_16x16x32_f16 v[32:35], v[148:151], v[196:199], v[32:35]
	v_mfma_f32_16x16x32_f16 v[32:35], v[152:155], v[200:203], v[32:35]
	v_mfma_f32_16x16x32_f16 v[28:31], v[142:145], v[200:203], v[28:31]
	v_mfma_f32_16x16x32_f16 v[28:31], v[138:141], v[196:199], v[28:31]
	s_setprio 0
	s_setprio 1
	v_mfma_f32_16x16x32_f16 v[36:39], v[156:159], v[172:175], v[36:39]
	v_mfma_f32_16x16x32_f16 v[36:39], v[160:163], v[176:179], v[36:39]
	v_mfma_f32_16x16x32_f16 v[40:43], v[168:171], v[176:179], v[40:43]
	v_mfma_f32_16x16x32_f16 v[40:43], v[164:167], v[172:175], v[40:43]
	v_mfma_f32_16x16x32_f16 v[48:51], v[164:167], v[180:183], v[48:51]
	v_mfma_f32_16x16x32_f16 v[48:51], v[168:171], v[184:187], v[48:51]
	v_mfma_f32_16x16x32_f16 v[44:47], v[160:163], v[184:187], v[44:47]
	v_mfma_f32_16x16x32_f16 v[44:47], v[156:159], v[180:183], v[44:47]
	v_mfma_f32_16x16x32_f16 v[52:55], v[156:159], v[188:191], v[52:55]
	v_mfma_f32_16x16x32_f16 v[52:55], v[160:163], v[192:195], v[52:55]
	v_mfma_f32_16x16x32_f16 v[56:59], v[168:171], v[192:195], v[56:59]
	v_mfma_f32_16x16x32_f16 v[56:59], v[164:167], v[188:191], v[56:59]
	v_mfma_f32_16x16x32_f16 v[64:67], v[164:167], v[196:199], v[64:67]
	v_mfma_f32_16x16x32_f16 v[64:67], v[168:171], v[200:203], v[64:67]
	s_setprio 2
	s_barrier
	v_mfma_f32_16x16x32_f16 v[60:63], v[160:163], v[200:203], v[60:63]
	v_mfma_f32_16x16x32_f16 v[60:63], v[156:159], v[196:199], v[60:63]
	s_setprio 0
	s_add_i32 s16, s29, s62
	v_lshl_add_u64 v[204:205], v[204:205], 0, s[86:87]
	s_mov_b32 m0, s16
	ds_read_b128 v[172:175], v212 offset:49152
	ds_read_b128 v[176:179], v212 offset:50176
	ds_read_b128 v[180:183], v212 offset:51200
	ds_read_b128 v[184:187], v212 offset:52224
	ds_read_b128 v[188:191], v212 offset:53248
	ds_read_b128 v[192:195], v212 offset:54272
	ds_read_b128 v[196:199], v212 offset:55296
	ds_read_b128 v[200:203], v212 offset:56320
	global_load_lds_dwordx4 v[204:205], off
	s_add_i32 m0, s16, 0x2000
	s_add_u32 s6, s6, 0x80080
	v_lshl_add_u64 v[204:205], v[206:207], 0, s[86:87]
	s_addc_u32 s7, s7, 0
	s_add_i32 s16, s44, s62
	global_load_lds_dwordx4 v[204:205], off
	s_mov_b32 m0, s16
	v_lshl_add_u64 v[204:205], v[208:209], 0, s[86:87]
	global_load_lds_dwordx4 v136, s[6:7]
	s_add_i32 m0, s16, 0x2000
	s_nop 0
	global_load_lds_dwordx4 v134, s[6:7]
	s_mov_b32 m0, s69
	s_nop 0
	global_load_lds_dwordx4 v[204:205], off
	v_lshl_add_u64 v[204:205], v[210:211], 0, s[86:87]
	s_mov_b32 m0, s70
	s_nop 0
	global_load_lds_dwordx4 v[204:205], off
	s_waitcnt vmcnt(8)
	s_waitcnt lgkmcnt(0)
	s_barrier
	s_setprio 1
	s_waitcnt lgkmcnt(0)
	v_mfma_f32_16x16x32_f16 v[68:71], v[138:141], v[172:175], v[68:71]
	v_mfma_f32_16x16x32_f16 v[68:71], v[142:145], v[176:179], v[68:71]
	v_mfma_f32_16x16x32_f16 v[72:75], v[152:155], v[176:179], v[72:75]
	v_mfma_f32_16x16x32_f16 v[72:75], v[148:151], v[172:175], v[72:75]
	v_mfma_f32_16x16x32_f16 v[80:83], v[148:151], v[180:183], v[80:83]
	v_mfma_f32_16x16x32_f16 v[80:83], v[152:155], v[184:187], v[80:83]
	v_mfma_f32_16x16x32_f16 v[76:79], v[142:145], v[184:187], v[76:79]
	v_mfma_f32_16x16x32_f16 v[76:79], v[138:141], v[180:183], v[76:79]
	v_mfma_f32_16x16x32_f16 v[84:87], v[138:141], v[188:191], v[84:87]
	v_mfma_f32_16x16x32_f16 v[84:87], v[142:145], v[192:195], v[84:87]
	v_mfma_f32_16x16x32_f16 v[88:91], v[152:155], v[192:195], v[88:91]
	v_mfma_f32_16x16x32_f16 v[88:91], v[148:151], v[188:191], v[88:91]
	v_mfma_f32_16x16x32_f16 v[96:99], v[148:151], v[196:199], v[96:99]
	v_mfma_f32_16x16x32_f16 v[96:99], v[152:155], v[200:203], v[96:99]
	v_mfma_f32_16x16x32_f16 v[92:95], v[142:145], v[200:203], v[92:95]
	v_mfma_f32_16x16x32_f16 v[92:95], v[138:141], v[196:199], v[92:95]
	s_setprio 0
	s_setprio 1
	v_mfma_f32_16x16x32_f16 v[100:103], v[156:159], v[172:175], v[100:103]
	v_mfma_f32_16x16x32_f16 v[100:103], v[160:163], v[176:179], v[100:103]
	v_mfma_f32_16x16x32_f16 v[104:107], v[168:171], v[176:179], v[104:107]
	v_mfma_f32_16x16x32_f16 v[104:107], v[164:167], v[172:175], v[104:107]
	v_mfma_f32_16x16x32_f16 v[112:115], v[164:167], v[180:183], v[112:115]
	v_mfma_f32_16x16x32_f16 v[112:115], v[168:171], v[184:187], v[112:115]
	v_mfma_f32_16x16x32_f16 v[108:111], v[160:163], v[184:187], v[108:111]
	v_mfma_f32_16x16x32_f16 v[108:111], v[156:159], v[180:183], v[108:111]
	v_mfma_f32_16x16x32_f16 v[116:119], v[156:159], v[188:191], v[116:119]
	v_mfma_f32_16x16x32_f16 v[116:119], v[160:163], v[192:195], v[116:119]
	v_mfma_f32_16x16x32_f16 v[120:123], v[168:171], v[192:195], v[120:123]
	v_mfma_f32_16x16x32_f16 v[120:123], v[164:167], v[188:191], v[120:123]
	v_mfma_f32_16x16x32_f16 v[128:131], v[164:167], v[196:199], v[128:131]
	v_mfma_f32_16x16x32_f16 v[128:131], v[168:171], v[200:203], v[128:131]
	s_setprio 2
	s_barrier
	v_mfma_f32_16x16x32_f16 v[124:127], v[160:163], v[200:203], v[124:127]
	v_mfma_f32_16x16x32_f16 v[124:127], v[156:159], v[196:199], v[124:127]
	s_setprio 0
	s_add_i32 s28, s28, 2
	s_add_u32 s8, s8, 0x100
	s_addc_u32 s9, s9, 0
	s_add_u32 s26, s26, 0x100
	s_addc_u32 s27, s27, 0
	s_cmp_gt_u32 s28, 29
	s_cbranch_scc0 .LBB0_753
	s_and_b64 vcc, exec, s[52:53]
	s_cbranch_vccz .LBB0_756
	s_barrier

.LBB0_1175:
	s_add_i32 s61, 0, 0x10000
	s_add_i32 s79, 0, 0x14000
	v_add_u32_e32 v16, s61, v209
	v_add_u32_e32 v32, s79, v209
	ds_read_b128 v[4:7], v16
	ds_read_b128 v[8:11], v16 offset:1024
	ds_read_b128 v[12:15], v16 offset:2048
	ds_read_b128 v[16:19], v16 offset:3072
	ds_read_b128 v[20:23], v32
	ds_read_b128 v[24:27], v32 offset:1024
	ds_read_b128 v[28:31], v32 offset:2048
	ds_read_b128 v[32:35], v32 offset:3072
	v_add_u32_e32 v231, 0, v208
	ds_read_b128 v[36:39], v231
	ds_read_b128 v[40:43], v231 offset:1024
	ds_read_b128 v[44:47], v231 offset:2048
	ds_read_b128 v[48:51], v231 offset:3072
	ds_read_b128 v[52:55], v231 offset:4096
	ds_read_b128 v[56:59], v231 offset:5120
	ds_read_b128 v[60:63], v231 offset:6144
	ds_read_b128 v[64:67], v231 offset:7168
	s_waitcnt vmcnt(8)
	s_waitcnt lgkmcnt(0)
	s_barrier
	s_setprio 1
	s_waitcnt lgkmcnt(0)
	v_mfma_f32_16x16x32_bf16 v[68:71], v[4:7], v[36:39], 0
	v_mfma_f32_16x16x32_bf16 v[68:71], v[8:11], v[40:43], v[68:71]
	v_mfma_f32_16x16x32_bf16 v[72:75], v[12:15], v[36:39], 0
	v_mfma_f32_16x16x32_bf16 v[72:75], v[16:19], v[40:43], v[72:75]
	v_mfma_f32_16x16x32_bf16 v[80:83], v[12:15], v[44:47], 0
	v_mfma_f32_16x16x32_bf16 v[80:83], v[16:19], v[48:51], v[80:83]
	v_mfma_f32_16x16x32_bf16 v[76:79], v[4:7], v[44:47], 0
	v_mfma_f32_16x16x32_bf16 v[76:79], v[8:11], v[48:51], v[76:79]
	v_mfma_f32_16x16x32_bf16 v[84:87], v[4:7], v[52:55], 0
	v_mfma_f32_16x16x32_bf16 v[84:87], v[8:11], v[56:59], v[84:87]
	v_mfma_f32_16x16x32_bf16 v[88:91], v[12:15], v[52:55], 0
	v_mfma_f32_16x16x32_bf16 v[88:91], v[16:19], v[56:59], v[88:91]
	v_mfma_f32_16x16x32_bf16 v[96:99], v[12:15], v[60:63], 0
	v_mfma_f32_16x16x32_bf16 v[96:99], v[16:19], v[64:67], v[96:99]
	v_mfma_f32_16x16x32_bf16 v[92:95], v[4:7], v[60:63], 0
	v_mfma_f32_16x16x32_bf16 v[92:95], v[8:11], v[64:67], v[92:95]
	s_setprio 0
	s_setprio 1
	v_mfma_f32_16x16x32_bf16 v[100:103], v[20:23], v[36:39], 0
	v_mfma_f32_16x16x32_bf16 v[36:39], v[28:31], v[36:39], 0
	v_mfma_f32_16x16x32_bf16 v[104:107], v[20:23], v[44:47], 0
	v_mfma_f32_16x16x32_bf16 v[44:47], v[28:31], v[44:47], 0
	v_mfma_f32_16x16x32_bf16 v[108:111], v[20:23], v[52:55], 0
	v_mfma_f32_16x16x32_bf16 v[52:55], v[28:31], v[52:55], 0
	v_mfma_f32_16x16x32_bf16 v[112:115], v[20:23], v[60:63], 0
	v_mfma_f32_16x16x32_bf16 v[60:63], v[28:31], v[60:63], 0
	v_mfma_f32_16x16x32_bf16 v[100:103], v[24:27], v[40:43], v[100:103]
	v_mfma_f32_16x16x32_bf16 v[40:43], v[32:35], v[40:43], v[36:39]
	v_mfma_f32_16x16x32_bf16 v[104:107], v[24:27], v[48:51], v[104:107]
	v_mfma_f32_16x16x32_bf16 v[48:51], v[32:35], v[48:51], v[44:47]
	v_mfma_f32_16x16x32_bf16 v[108:111], v[24:27], v[56:59], v[108:111]
	v_mfma_f32_16x16x32_bf16 v[56:59], v[32:35], v[56:59], v[52:55]
	s_setprio 2
	s_barrier
	v_mfma_f32_16x16x32_bf16 v[112:115], v[24:27], v[64:67], v[112:115]
	v_mfma_f32_16x16x32_bf16 v[64:67], v[32:35], v[64:67], v[60:63]
	s_setprio 0
	v_lshl_add_u64 v[186:187], s[12:13], 0, v[2:3]
	s_add_i32 s61, s61, s36
	v_mov_b32_e32 v191, v3
	v_lshl_add_u64 v[134:135], v[186:187], 0, s[74:75]
	s_mov_b32 m0, s61
	v_lshl_add_u64 v[226:227], s[12:13], 0, v[190:191]
	ds_read_b128 v[36:39], v231 offset:16384
	ds_read_b128 v[44:47], v231 offset:17408
	ds_read_b128 v[52:55], v231 offset:18432
	ds_read_b128 v[60:63], v231 offset:19456
	ds_read_b128 v[116:119], v231 offset:20480
	ds_read_b128 v[120:123], v231 offset:21504
	ds_read_b128 v[124:127], v231 offset:22528
	ds_read_b128 v[128:131], v231 offset:23552
	global_load_lds_dwordx4 v[134:135], off
	v_lshl_add_u64 v[134:135], v[226:227], 0, s[74:75]
	s_add_i32 m0, s61, 0x2000
	s_add_i32 s61, s79, s36
	global_load_lds_dwordx4 v[134:135], off
	s_mov_b32 m0, s61
	v_mov_b32_e32 v133, v3
	global_load_lds_dwordx4 v2, s[16:17]
	s_add_i32 m0, s61, 0x2000
	v_lshl_add_u64 v[248:249], s[6:7], 0, v[132:133]
	v_mov_b32_e32 v189, v3
	global_load_lds_dwordx4 v190, s[16:17]
	v_lshl_add_u64 v[134:135], v[248:249], 0, s[74:75]
	s_mov_b32 m0, s37
	v_lshl_add_u64 v[250:251], s[6:7], 0, v[188:189]
	global_load_lds_dwordx4 v[134:135], off
	v_lshl_add_u64 v[134:135], v[250:251], 0, s[74:75]
	s_mov_b32 m0, s66
	s_nop 0
	global_load_lds_dwordx4 v[134:135], off
	s_waitcnt vmcnt(8)
	s_waitcnt lgkmcnt(0)
	s_barrier
	s_setprio 1
	s_waitcnt lgkmcnt(0)
	v_mfma_f32_16x16x32_bf16 v[134:137], v[4:7], v[36:39], 0
	v_mfma_f32_16x16x32_bf16 v[138:141], v[12:15], v[36:39], 0
	v_mfma_f32_16x16x32_bf16 v[142:145], v[4:7], v[52:55], 0
	v_mfma_f32_16x16x32_bf16 v[146:149], v[12:15], v[52:55], 0
	v_mfma_f32_16x16x32_bf16 v[150:153], v[4:7], v[116:119], 0
	v_mfma_f32_16x16x32_bf16 v[154:157], v[12:15], v[116:119], 0
	v_mfma_f32_16x16x32_bf16 v[4:7], v[4:7], v[124:127], 0
	v_mfma_f32_16x16x32_bf16 v[12:15], v[12:15], v[124:127], 0
	v_mfma_f32_16x16x32_bf16 v[134:137], v[8:11], v[44:47], v[134:137]
	v_mfma_f32_16x16x32_bf16 v[138:141], v[16:19], v[44:47], v[138:141]
	v_mfma_f32_16x16x32_bf16 v[142:145], v[8:11], v[60:63], v[142:145]
	v_mfma_f32_16x16x32_bf16 v[146:149], v[16:19], v[60:63], v[146:149]
	v_mfma_f32_16x16x32_bf16 v[150:153], v[8:11], v[120:123], v[150:153]
	v_mfma_f32_16x16x32_bf16 v[154:157], v[16:19], v[120:123], v[154:157]
	v_mfma_f32_16x16x32_bf16 v[158:161], v[8:11], v[128:131], v[4:7]
	v_mfma_f32_16x16x32_bf16 v[162:165], v[16:19], v[128:131], v[12:15]
	s_setprio 0
	s_setprio 1
	v_mfma_f32_16x16x32_bf16 v[4:7], v[20:23], v[36:39], 0
	v_mfma_f32_16x16x32_bf16 v[8:11], v[28:31], v[36:39], 0
	v_mfma_f32_16x16x32_bf16 v[12:15], v[20:23], v[52:55], 0
	v_mfma_f32_16x16x32_bf16 v[16:19], v[28:31], v[52:55], 0
	v_mfma_f32_16x16x32_bf16 v[36:39], v[20:23], v[116:119], 0
	v_mfma_f32_16x16x32_bf16 v[52:55], v[28:31], v[116:119], 0
	v_mfma_f32_16x16x32_bf16 v[20:23], v[20:23], v[124:127], 0
	v_mfma_f32_16x16x32_bf16 v[28:31], v[28:31], v[124:127], 0
	v_mfma_f32_16x16x32_bf16 v[116:119], v[24:27], v[44:47], v[4:7]
	v_mfma_f32_16x16x32_bf16 v[124:127], v[32:35], v[44:47], v[8:11]
	v_mfma_f32_16x16x32_bf16 v[174:177], v[24:27], v[120:123], v[36:39]
	v_mfma_f32_16x16x32_bf16 v[120:123], v[32:35], v[120:123], v[52:55]
	v_mfma_f32_16x16x32_bf16 v[178:181], v[24:27], v[128:131], v[20:23]
	v_mfma_f32_16x16x32_bf16 v[128:131], v[32:35], v[128:131], v[28:31]
	s_setprio 2
	s_barrier
	v_mfma_f32_16x16x32_bf16 v[166:169], v[24:27], v[60:63], v[12:15]
	v_mfma_f32_16x16x32_bf16 v[170:173], v[32:35], v[60:63], v[16:19]
	s_setprio 0
	s_add_i32 s61, 0, 0x18000
	v_add_u32_e32 v4, s61, v209
	s_add_i32 s79, 0, 0x1c000
	ds_read_b128 v[182:185], v4
	ds_read_b128 v[192:195], v4 offset:1024
	ds_read_b128 v[196:199], v4 offset:2048
	ds_read_b128 v[200:203], v4 offset:3072
	v_add_u32_e32 v4, s79, v209
	ds_read_b128 v[204:207], v4
	ds_read_b128 v[210:213], v4 offset:1024
	ds_read_b128 v[214:217], v4 offset:2048
	ds_read_b128 v[218:221], v4 offset:3072
	s_mov_b32 m0, s67
	ds_read_b128 v[44:47], v231 offset:32768
	ds_read_b128 v[52:55], v231 offset:33792
	ds_read_b128 v[60:63], v231 offset:34816
	ds_read_b128 v[222:225], v231 offset:35840
	ds_read_b128 v[232:235], v231 offset:36864
	ds_read_b128 v[236:239], v231 offset:37888
	ds_read_b128 v[240:243], v231 offset:38912
	ds_read_b128 v[244:247], v231 offset:39936
	global_load_lds_dwordx4 v132, s[26:27]
	s_mov_b32 m0, s68
	s_nop 0
	global_load_lds_dwordx4 v188, s[26:27]
	s_waitcnt vmcnt(8)
	s_waitcnt lgkmcnt(0)
	s_barrier
	s_setprio 1
	s_waitcnt lgkmcnt(0)
	v_mfma_f32_16x16x32_bf16 v[4:7], v[182:185], v[44:47], v[68:71]
	v_mfma_f32_16x16x32_bf16 v[8:11], v[196:199], v[44:47], v[72:75]
	v_mfma_f32_16x16x32_bf16 v[12:15], v[182:185], v[60:63], v[76:79]
	v_mfma_f32_16x16x32_bf16 v[16:19], v[196:199], v[60:63], v[80:83]
	v_mfma_f32_16x16x32_bf16 v[20:23], v[182:185], v[232:235], v[84:87]
	v_mfma_f32_16x16x32_bf16 v[24:27], v[196:199], v[232:235], v[88:91]
	v_mfma_f32_16x16x32_bf16 v[28:31], v[182:185], v[240:243], v[92:95]
	v_mfma_f32_16x16x32_bf16 v[32:35], v[196:199], v[240:243], v[96:99]
	v_mfma_f32_16x16x32_bf16 v[4:7], v[192:195], v[52:55], v[4:7]
	v_mfma_f32_16x16x32_bf16 v[8:11], v[200:203], v[52:55], v[8:11]
	v_mfma_f32_16x16x32_bf16 v[12:15], v[192:195], v[222:225], v[12:15]
	v_mfma_f32_16x16x32_bf16 v[16:19], v[200:203], v[222:225], v[16:19]
	v_mfma_f32_16x16x32_bf16 v[20:23], v[192:195], v[236:239], v[20:23]
	v_mfma_f32_16x16x32_bf16 v[24:27], v[200:203], v[236:239], v[24:27]
	v_mfma_f32_16x16x32_bf16 v[28:31], v[192:195], v[244:247], v[28:31]
	v_mfma_f32_16x16x32_bf16 v[32:35], v[200:203], v[244:247], v[32:35]
	s_setprio 0
	s_setprio 1
	v_mfma_f32_16x16x32_bf16 v[36:39], v[204:207], v[44:47], v[100:103]
	v_mfma_f32_16x16x32_bf16 v[40:43], v[214:217], v[44:47], v[40:43]
	v_mfma_f32_16x16x32_bf16 v[36:39], v[210:213], v[52:55], v[36:39]
	v_mfma_f32_16x16x32_bf16 v[40:43], v[218:221], v[52:55], v[40:43]
	v_mfma_f32_16x16x32_bf16 v[44:47], v[204:207], v[60:63], v[104:107]
	v_mfma_f32_16x16x32_bf16 v[48:51], v[214:217], v[60:63], v[48:51]
	v_mfma_f32_16x16x32_bf16 v[52:55], v[204:207], v[232:235], v[108:111]
	v_mfma_f32_16x16x32_bf16 v[56:59], v[214:217], v[232:235], v[56:59]
	v_mfma_f32_16x16x32_bf16 v[60:63], v[204:207], v[240:243], v[112:115]
	v_mfma_f32_16x16x32_bf16 v[64:67], v[214:217], v[240:243], v[64:67]
	v_mfma_f32_16x16x32_bf16 v[44:47], v[210:213], v[222:225], v[44:47]
	v_mfma_f32_16x16x32_bf16 v[48:51], v[218:221], v[222:225], v[48:51]
	v_mfma_f32_16x16x32_bf16 v[52:55], v[210:213], v[236:239], v[52:55]
	v_mfma_f32_16x16x32_bf16 v[56:59], v[218:221], v[236:239], v[56:59]
	s_setprio 2
	s_barrier
	v_mfma_f32_16x16x32_bf16 v[60:63], v[210:213], v[244:247], v[60:63]
	v_mfma_f32_16x16x32_bf16 v[64:67], v[218:221], v[244:247], v[64:67]
	s_setprio 0
	s_add_i32 s61, s61, s36
	v_lshl_add_u64 v[68:69], v[186:187], 0, s[24:25]
	s_mov_b32 m0, s61
	ds_read_b128 v[104:107], v231 offset:49152
	ds_read_b128 v[108:111], v231 offset:50176
	ds_read_b128 v[112:115], v231 offset:51200
	ds_read_b128 v[222:225], v231 offset:52224
	ds_read_b128 v[232:235], v231 offset:53248
	ds_read_b128 v[236:239], v231 offset:54272
	ds_read_b128 v[240:243], v231 offset:55296
	ds_read_b128 v[244:247], v231 offset:56320
	global_load_lds_dwordx4 v[68:69], off
	v_lshl_add_u64 v[68:69], v[226:227], 0, s[24:25]
	s_add_i32 m0, s61, 0x2000
	s_add_i32 s61, s79, s36
	global_load_lds_dwordx4 v[68:69], off
	s_mov_b32 m0, s61
	v_lshl_add_u64 v[68:69], v[248:249], 0, s[24:25]
	global_load_lds_dwordx4 v2, s[28:29]
	s_add_i32 m0, s61, 0x2000
	s_nop 0
	global_load_lds_dwordx4 v190, s[28:29]
	s_mov_b32 m0, s71
	s_nop 0
	global_load_lds_dwordx4 v[68:69], off
	v_lshl_add_u64 v[68:69], v[250:251], 0, s[24:25]
	s_mov_b32 m0, s72
	s_nop 0
	global_load_lds_dwordx4 v[68:69], off
	s_waitcnt vmcnt(8)
	s_waitcnt lgkmcnt(0)
	s_barrier
	s_setprio 1
	s_waitcnt lgkmcnt(0)
	v_mfma_f32_16x16x32_bf16 v[68:71], v[182:185], v[104:107], v[134:137]
	v_mfma_f32_16x16x32_bf16 v[72:75], v[196:199], v[104:107], v[138:141]
	v_mfma_f32_16x16x32_bf16 v[76:79], v[182:185], v[112:115], v[142:145]
	v_mfma_f32_16x16x32_bf16 v[80:83], v[196:199], v[112:115], v[146:149]
	v_mfma_f32_16x16x32_bf16 v[84:87], v[182:185], v[232:235], v[150:153]
	v_mfma_f32_16x16x32_bf16 v[88:91], v[196:199], v[232:235], v[154:157]
	v_mfma_f32_16x16x32_bf16 v[92:95], v[182:185], v[240:243], v[158:161]
	v_mfma_f32_16x16x32_bf16 v[96:99], v[196:199], v[240:243], v[162:165]
	v_mfma_f32_16x16x32_bf16 v[68:71], v[192:195], v[108:111], v[68:71]
	v_mfma_f32_16x16x32_bf16 v[72:75], v[200:203], v[108:111], v[72:75]
	v_mfma_f32_16x16x32_bf16 v[76:79], v[192:195], v[222:225], v[76:79]
	v_mfma_f32_16x16x32_bf16 v[80:83], v[200:203], v[222:225], v[80:83]
	v_mfma_f32_16x16x32_bf16 v[84:87], v[192:195], v[236:239], v[84:87]
	v_mfma_f32_16x16x32_bf16 v[88:91], v[200:203], v[236:239], v[88:91]
	v_mfma_f32_16x16x32_bf16 v[92:95], v[192:195], v[244:247], v[92:95]
	v_mfma_f32_16x16x32_bf16 v[96:99], v[200:203], v[244:247], v[96:99]
	s_setprio 0
	s_setprio 1
	v_mfma_f32_16x16x32_bf16 v[100:103], v[204:207], v[104:107], v[116:119]
	v_mfma_f32_16x16x32_bf16 v[104:107], v[214:217], v[104:107], v[124:127]
	v_mfma_f32_16x16x32_bf16 v[100:103], v[210:213], v[108:111], v[100:103]
	v_mfma_f32_16x16x32_bf16 v[104:107], v[218:221], v[108:111], v[104:107]
	v_mfma_f32_16x16x32_bf16 v[108:111], v[204:207], v[112:115], v[166:169]
	v_mfma_f32_16x16x32_bf16 v[112:115], v[214:217], v[112:115], v[170:173]
	v_mfma_f32_16x16x32_bf16 v[116:119], v[204:207], v[232:235], v[174:177]
	v_mfma_f32_16x16x32_bf16 v[120:123], v[214:217], v[232:235], v[120:123]
	v_mfma_f32_16x16x32_bf16 v[124:127], v[204:207], v[240:243], v[178:181]
	v_mfma_f32_16x16x32_bf16 v[128:131], v[214:217], v[240:243], v[128:131]
	v_mfma_f32_16x16x32_bf16 v[108:111], v[210:213], v[222:225], v[108:111]
	v_mfma_f32_16x16x32_bf16 v[112:115], v[218:221], v[222:225], v[112:115]
	v_mfma_f32_16x16x32_bf16 v[116:119], v[210:213], v[236:239], v[116:119]
	v_mfma_f32_16x16x32_bf16 v[120:123], v[218:221], v[236:239], v[120:123]
	s_setprio 2
	s_barrier
	v_mfma_f32_16x16x32_bf16 v[124:127], v[210:213], v[244:247], v[124:127]
	v_mfma_f32_16x16x32_bf16 v[128:131], v[218:221], v[244:247], v[128:131]
	s_setprio 0
	s_add_i32 s43, s43, 2
	s_cmp_ge_i32 s43, s42
	s_cbranch_scc0 .LBB0_1175
.LBB0_1176:
	s_add_i32 s12, 0, 0x10000
	s_add_i32 s13, 0, 0x14000
	v_mov_b32_e32 v192, v2
	v_mov_b32_e32 v2, v132
	v_add_u32_e32 v144, s12, v209
	v_add_u32_e32 v160, s13, v209
	ds_read_b128 v[132:135], v144
	ds_read_b128 v[136:139], v144 offset:1024
	ds_read_b128 v[140:143], v144 offset:2048
	ds_read_b128 v[144:147], v144 offset:3072
	ds_read_b128 v[148:151], v160
	ds_read_b128 v[152:155], v160 offset:1024
	ds_read_b128 v[156:159], v160 offset:2048
	ds_read_b128 v[160:163], v160 offset:3072
	s_add_u32 s6, s6, 0x80180
	s_mov_b32 m0, s73
	v_add_u32_e32 v212, 0, v208
	s_addc_u32 s7, s7, 0
	ds_read_b128 v[164:167], v212
	ds_read_b128 v[168:171], v212 offset:1024
	ds_read_b128 v[172:175], v212 offset:2048
	ds_read_b128 v[176:179], v212 offset:3072
	ds_read_b128 v[180:183], v212 offset:4096
	ds_read_b128 v[184:187], v212 offset:5120
	ds_read_b128 v[194:197], v212 offset:6144
	ds_read_b128 v[198:201], v212 offset:7168
	global_load_lds_dwordx4 v2, s[6:7]
	s_mov_b32 m0, s76
	v_mov_b32_e32 v189, v3
	global_load_lds_dwordx4 v188, s[6:7]
	s_waitcnt vmcnt(8)
	s_waitcnt lgkmcnt(0)
	s_barrier
	s_setprio 1
	s_waitcnt lgkmcnt(0)
	v_mfma_f32_16x16x32_bf16 v[4:7], v[132:135], v[164:167], v[4:7]
	v_mfma_f32_16x16x32_bf16 v[4:7], v[136:139], v[168:171], v[4:7]
	v_mfma_f32_16x16x32_bf16 v[8:11], v[144:147], v[168:171], v[8:11]
	v_mfma_f32_16x16x32_bf16 v[8:11], v[140:143], v[164:167], v[8:11]
	v_mfma_f32_16x16x32_bf16 v[16:19], v[140:143], v[172:175], v[16:19]
	v_mfma_f32_16x16x32_bf16 v[16:19], v[144:147], v[176:179], v[16:19]
	v_mfma_f32_16x16x32_bf16 v[12:15], v[136:139], v[176:179], v[12:15]
	v_mfma_f32_16x16x32_bf16 v[12:15], v[132:135], v[172:175], v[12:15]
	v_mfma_f32_16x16x32_bf16 v[20:23], v[132:135], v[180:183], v[20:23]
	v_mfma_f32_16x16x32_bf16 v[20:23], v[136:139], v[184:187], v[20:23]
	v_mfma_f32_16x16x32_bf16 v[24:27], v[144:147], v[184:187], v[24:27]
	v_mfma_f32_16x16x32_bf16 v[24:27], v[140:143], v[180:183], v[24:27]
	v_mfma_f32_16x16x32_bf16 v[32:35], v[140:143], v[194:197], v[32:35]
	v_mfma_f32_16x16x32_bf16 v[32:35], v[144:147], v[198:201], v[32:35]
	v_mfma_f32_16x16x32_bf16 v[28:31], v[136:139], v[198:201], v[28:31]
	v_mfma_f32_16x16x32_bf16 v[28:31], v[132:135], v[194:197], v[28:31]
	s_setprio 0
	s_setprio 1
	v_mfma_f32_16x16x32_bf16 v[36:39], v[148:151], v[164:167], v[36:39]
	v_mfma_f32_16x16x32_bf16 v[36:39], v[152:155], v[168:171], v[36:39]
	v_mfma_f32_16x16x32_bf16 v[40:43], v[160:163], v[168:171], v[40:43]
	v_mfma_f32_16x16x32_bf16 v[40:43], v[156:159], v[164:167], v[40:43]
	v_mfma_f32_16x16x32_bf16 v[48:51], v[156:159], v[172:175], v[48:51]
	v_mfma_f32_16x16x32_bf16 v[48:51], v[160:163], v[176:179], v[48:51]
	v_mfma_f32_16x16x32_bf16 v[44:47], v[152:155], v[176:179], v[44:47]
	v_mfma_f32_16x16x32_bf16 v[44:47], v[148:151], v[172:175], v[44:47]
	v_mfma_f32_16x16x32_bf16 v[52:55], v[148:151], v[180:183], v[52:55]
	v_mfma_f32_16x16x32_bf16 v[52:55], v[152:155], v[184:187], v[52:55]
	v_mfma_f32_16x16x32_bf16 v[56:59], v[160:163], v[184:187], v[56:59]
	v_mfma_f32_16x16x32_bf16 v[56:59], v[156:159], v[180:183], v[56:59]
	v_mfma_f32_16x16x32_bf16 v[64:67], v[156:159], v[194:197], v[64:67]
	v_mfma_f32_16x16x32_bf16 v[64:67], v[160:163], v[198:201], v[64:67]
	s_setprio 2
	s_barrier
	v_mfma_f32_16x16x32_bf16 v[60:63], v[152:155], v[198:201], v[60:63]
	v_mfma_f32_16x16x32_bf16 v[60:63], v[148:151], v[194:197], v[60:63]
	s_setprio 0
	s_add_i32 s6, s12, s36
	s_mov_b32 m0, s6
	ds_read_b128 v[164:167], v212 offset:16384
	ds_read_b128 v[168:171], v212 offset:17408
	ds_read_b128 v[172:175], v212 offset:18432
	ds_read_b128 v[176:179], v212 offset:19456
	ds_read_b128 v[180:183], v212 offset:20480
	ds_read_b128 v[184:187], v212 offset:21504
	ds_read_b128 v[194:197], v212 offset:22528
	ds_read_b128 v[198:201], v212 offset:23552
	global_load_lds_dwordx4 v192, s[14:15]
	s_add_i32 m0, s6, 0x2000
	s_add_u32 s6, s14, 0x10000
	s_addc_u32 s7, s15, 0
	s_add_i32 s12, s13, s36
	global_load_lds_dwordx4 v190, s[14:15]
	s_mov_b32 m0, s12
	v_mov_b32_e32 v193, v3
	global_load_lds_dwordx4 v192, s[6:7]
	s_add_i32 m0, s12, 0x2000
	v_mov_b32_e32 v191, v3
	global_load_lds_dwordx4 v190, s[6:7]
	s_mov_b32 m0, s37
	v_lshl_add_u64 v[202:203], s[14:15], 0, v[192:193]
	global_load_lds_dwordx4 v2, s[10:11]
	s_mov_b32 m0, s66
	v_lshl_add_u64 v[204:205], s[14:15], 0, v[190:191]
	global_load_lds_dwordx4 v188, s[10:11]
	s_waitcnt vmcnt(8)
	s_waitcnt lgkmcnt(0)
	v_lshl_add_u64 v[206:207], s[10:11], 0, v[2:3]
	v_lshl_add_u64 v[210:211], s[10:11], 0, v[188:189]
	s_barrier
	s_setprio 1
	s_waitcnt lgkmcnt(0)
	v_mfma_f32_16x16x32_bf16 v[68:71], v[132:135], v[164:167], v[68:71]
	v_mfma_f32_16x16x32_bf16 v[68:71], v[136:139], v[168:171], v[68:71]
	v_mfma_f32_16x16x32_bf16 v[72:75], v[144:147], v[168:171], v[72:75]
	v_mfma_f32_16x16x32_bf16 v[72:75], v[140:143], v[164:167], v[72:75]
	v_mfma_f32_16x16x32_bf16 v[80:83], v[140:143], v[172:175], v[80:83]
	v_mfma_f32_16x16x32_bf16 v[80:83], v[144:147], v[176:179], v[80:83]
	v_mfma_f32_16x16x32_bf16 v[76:79], v[136:139], v[176:179], v[76:79]
	v_mfma_f32_16x16x32_bf16 v[76:79], v[132:135], v[172:175], v[76:79]
	v_mfma_f32_16x16x32_bf16 v[84:87], v[132:135], v[180:183], v[84:87]
	v_mfma_f32_16x16x32_bf16 v[84:87], v[136:139], v[184:187], v[84:87]
	v_mfma_f32_16x16x32_bf16 v[88:91], v[144:147], v[184:187], v[88:91]
	v_mfma_f32_16x16x32_bf16 v[88:91], v[140:143], v[180:183], v[88:91]
	v_mfma_f32_16x16x32_bf16 v[96:99], v[140:143], v[194:197], v[96:99]
	v_mfma_f32_16x16x32_bf16 v[96:99], v[144:147], v[198:201], v[96:99]
	v_mfma_f32_16x16x32_bf16 v[92:95], v[136:139], v[198:201], v[92:95]
	v_mfma_f32_16x16x32_bf16 v[92:95], v[132:135], v[194:197], v[92:95]
	s_setprio 0
	s_setprio 1
	v_mfma_f32_16x16x32_bf16 v[100:103], v[148:151], v[164:167], v[100:103]
	v_mfma_f32_16x16x32_bf16 v[100:103], v[152:155], v[168:171], v[100:103]
	v_mfma_f32_16x16x32_bf16 v[104:107], v[160:163], v[168:171], v[104:107]
	v_mfma_f32_16x16x32_bf16 v[104:107], v[156:159], v[164:167], v[104:107]
	v_mfma_f32_16x16x32_bf16 v[112:115], v[156:159], v[172:175], v[112:115]
	v_mfma_f32_16x16x32_bf16 v[112:115], v[160:163], v[176:179], v[112:115]
	v_mfma_f32_16x16x32_bf16 v[108:111], v[152:155], v[176:179], v[108:111]
	v_mfma_f32_16x16x32_bf16 v[108:111], v[148:151], v[172:175], v[108:111]
	v_mfma_f32_16x16x32_bf16 v[116:119], v[148:151], v[180:183], v[116:119]
	v_mfma_f32_16x16x32_bf16 v[116:119], v[152:155], v[184:187], v[116:119]
	v_mfma_f32_16x16x32_bf16 v[120:123], v[160:163], v[184:187], v[120:123]
	v_mfma_f32_16x16x32_bf16 v[120:123], v[156:159], v[180:183], v[120:123]
	v_mfma_f32_16x16x32_bf16 v[128:131], v[156:159], v[194:197], v[128:131]
	v_mfma_f32_16x16x32_bf16 v[128:131], v[160:163], v[198:201], v[128:131]
	s_setprio 2
	s_barrier
	v_mfma_f32_16x16x32_bf16 v[124:127], v[152:155], v[198:201], v[124:127]
	v_mfma_f32_16x16x32_bf16 v[124:127], v[148:151], v[194:197], v[124:127]
	s_setprio 0
	s_add_i32 s12, 0, 0x18000
	s_add_i32 s13, 0, 0x1c000
	v_add_u32_e32 v144, s12, v209
	v_add_u32_e32 v160, s13, v209
	ds_read_b128 v[132:135], v144
	ds_read_b128 v[136:139], v144 offset:1024
	ds_read_b128 v[140:143], v144 offset:2048
	ds_read_b128 v[144:147], v144 offset:3072
	ds_read_b128 v[148:151], v160
	ds_read_b128 v[152:155], v160 offset:1024
	ds_read_b128 v[156:159], v160 offset:2048
	ds_read_b128 v[160:163], v160 offset:3072
	s_add_u32 s6, s10, 0x80000
	s_addc_u32 s7, s11, 0
	s_mov_b32 m0, s67
	ds_read_b128 v[164:167], v212 offset:32768
	ds_read_b128 v[168:171], v212 offset:33792
	ds_read_b128 v[172:175], v212 offset:34816
	ds_read_b128 v[176:179], v212 offset:35840
	ds_read_b128 v[180:183], v212 offset:36864
	ds_read_b128 v[184:187], v212 offset:37888
	ds_read_b128 v[194:197], v212 offset:38912
	ds_read_b128 v[198:201], v212 offset:39936
	global_load_lds_dwordx4 v2, s[6:7]
	s_mov_b32 m0, s68
	s_nop 0
	global_load_lds_dwordx4 v188, s[6:7]
	s_waitcnt vmcnt(8)
	s_waitcnt lgkmcnt(0)
	s_barrier
	s_setprio 1
	s_waitcnt lgkmcnt(0)
	v_mfma_f32_16x16x32_bf16 v[4:7], v[132:135], v[164:167], v[4:7]
	v_mfma_f32_16x16x32_bf16 v[4:7], v[136:139], v[168:171], v[4:7]
	v_mfma_f32_16x16x32_bf16 v[8:11], v[144:147], v[168:171], v[8:11]
	v_mfma_f32_16x16x32_bf16 v[8:11], v[140:143], v[164:167], v[8:11]
	v_mfma_f32_16x16x32_bf16 v[16:19], v[140:143], v[172:175], v[16:19]
	v_mfma_f32_16x16x32_bf16 v[16:19], v[144:147], v[176:179], v[16:19]
	v_mfma_f32_16x16x32_bf16 v[12:15], v[136:139], v[176:179], v[12:15]
	v_mfma_f32_16x16x32_bf16 v[12:15], v[132:135], v[172:175], v[12:15]
	v_mfma_f32_16x16x32_bf16 v[20:23], v[132:135], v[180:183], v[20:23]
	v_mfma_f32_16x16x32_bf16 v[20:23], v[136:139], v[184:187], v[20:23]
	v_mfma_f32_16x16x32_bf16 v[24:27], v[144:147], v[184:187], v[24:27]
	v_mfma_f32_16x16x32_bf16 v[24:27], v[140:143], v[180:183], v[24:27]
	v_mfma_f32_16x16x32_bf16 v[32:35], v[140:143], v[194:197], v[32:35]
	v_mfma_f32_16x16x32_bf16 v[32:35], v[144:147], v[198:201], v[32:35]
	v_mfma_f32_16x16x32_bf16 v[28:31], v[136:139], v[198:201], v[28:31]
	v_mfma_f32_16x16x32_bf16 v[28:31], v[132:135], v[194:197], v[28:31]
	s_setprio 0
	s_setprio 1
	v_mfma_f32_16x16x32_bf16 v[36:39], v[148:151], v[164:167], v[36:39]
	v_mfma_f32_16x16x32_bf16 v[36:39], v[152:155], v[168:171], v[36:39]
	v_mfma_f32_16x16x32_bf16 v[40:43], v[160:163], v[168:171], v[40:43]
	v_mfma_f32_16x16x32_bf16 v[40:43], v[156:159], v[164:167], v[40:43]
	v_mfma_f32_16x16x32_bf16 v[48:51], v[156:159], v[172:175], v[48:51]
	v_mfma_f32_16x16x32_bf16 v[48:51], v[160:163], v[176:179], v[48:51]
	v_mfma_f32_16x16x32_bf16 v[44:47], v[152:155], v[176:179], v[44:47]
	v_mfma_f32_16x16x32_bf16 v[44:47], v[148:151], v[172:175], v[44:47]
	v_mfma_f32_16x16x32_bf16 v[52:55], v[148:151], v[180:183], v[52:55]
	v_mfma_f32_16x16x32_bf16 v[52:55], v[152:155], v[184:187], v[52:55]
	v_mfma_f32_16x16x32_bf16 v[56:59], v[160:163], v[184:187], v[56:59]
	v_mfma_f32_16x16x32_bf16 v[56:59], v[156:159], v[180:183], v[56:59]
	v_mfma_f32_16x16x32_bf16 v[64:67], v[156:159], v[194:197], v[64:67]
	v_mfma_f32_16x16x32_bf16 v[64:67], v[160:163], v[198:201], v[64:67]
	s_setprio 2
	s_barrier
	v_mfma_f32_16x16x32_bf16 v[60:63], v[152:155], v[198:201], v[60:63]
	v_mfma_f32_16x16x32_bf16 v[60:63], v[148:151], v[194:197], v[60:63]
	s_setprio 0
	s_add_i32 s6, s12, s36
	v_lshl_add_u64 v[202:203], v[202:203], 0, s[86:87]
	s_mov_b32 m0, s6
	ds_read_b128 v[164:167], v212 offset:49152
	ds_read_b128 v[168:171], v212 offset:50176
	ds_read_b128 v[172:175], v212 offset:51200
	ds_read_b128 v[176:179], v212 offset:52224
	ds_read_b128 v[180:183], v212 offset:53248
	ds_read_b128 v[184:187], v212 offset:54272
	ds_read_b128 v[194:197], v212 offset:55296
	ds_read_b128 v[198:201], v212 offset:56320
	global_load_lds_dwordx4 v[202:203], off
	s_add_i32 m0, s6, 0x2000
	s_add_u32 s6, s14, 0x10080
	v_lshl_add_u64 v[202:203], v[204:205], 0, s[86:87]
	s_addc_u32 s7, s15, 0
	s_add_i32 s12, s13, s36
	global_load_lds_dwordx4 v[202:203], off
	s_mov_b32 m0, s12
	v_lshl_add_u64 v[202:203], v[206:207], 0, s[86:87]
	global_load_lds_dwordx4 v192, s[6:7]
	s_add_i32 m0, s12, 0x2000
	s_nop 0
	global_load_lds_dwordx4 v190, s[6:7]
	s_mov_b32 m0, s71
	s_nop 0
	global_load_lds_dwordx4 v[202:203], off
	v_lshl_add_u64 v[202:203], v[210:211], 0, s[86:87]
	s_mov_b32 m0, s72
	s_nop 0
	global_load_lds_dwordx4 v[202:203], off
	s_waitcnt vmcnt(8)
	s_waitcnt lgkmcnt(0)
	s_barrier
	s_setprio 1
	s_waitcnt lgkmcnt(0)
	v_mfma_f32_16x16x32_bf16 v[68:71], v[132:135], v[164:167], v[68:71]
	v_mfma_f32_16x16x32_bf16 v[68:71], v[136:139], v[168:171], v[68:71]
	v_mfma_f32_16x16x32_bf16 v[72:75], v[144:147], v[168:171], v[72:75]
	v_mfma_f32_16x16x32_bf16 v[72:75], v[140:143], v[164:167], v[72:75]
	v_mfma_f32_16x16x32_bf16 v[80:83], v[140:143], v[172:175], v[80:83]
	v_mfma_f32_16x16x32_bf16 v[80:83], v[144:147], v[176:179], v[80:83]
	v_mfma_f32_16x16x32_bf16 v[76:79], v[136:139], v[176:179], v[76:79]
	v_mfma_f32_16x16x32_bf16 v[76:79], v[132:135], v[172:175], v[76:79]
	v_mfma_f32_16x16x32_bf16 v[84:87], v[132:135], v[180:183], v[84:87]
	v_mfma_f32_16x16x32_bf16 v[84:87], v[136:139], v[184:187], v[84:87]
	v_mfma_f32_16x16x32_bf16 v[88:91], v[144:147], v[184:187], v[88:91]
	v_mfma_f32_16x16x32_bf16 v[88:91], v[140:143], v[180:183], v[88:91]
	v_mfma_f32_16x16x32_bf16 v[96:99], v[140:143], v[194:197], v[96:99]
	v_mfma_f32_16x16x32_bf16 v[96:99], v[144:147], v[198:201], v[96:99]
	v_mfma_f32_16x16x32_bf16 v[92:95], v[136:139], v[198:201], v[92:95]
	v_mfma_f32_16x16x32_bf16 v[92:95], v[132:135], v[194:197], v[92:95]
	s_setprio 0
	s_setprio 1
	v_mfma_f32_16x16x32_bf16 v[100:103], v[148:151], v[164:167], v[100:103]
	v_mfma_f32_16x16x32_bf16 v[100:103], v[152:155], v[168:171], v[100:103]
	v_mfma_f32_16x16x32_bf16 v[104:107], v[160:163], v[168:171], v[104:107]
	v_mfma_f32_16x16x32_bf16 v[104:107], v[156:159], v[164:167], v[104:107]
	v_mfma_f32_16x16x32_bf16 v[112:115], v[156:159], v[172:175], v[112:115]
	v_mfma_f32_16x16x32_bf16 v[112:115], v[160:163], v[176:179], v[112:115]
	v_mfma_f32_16x16x32_bf16 v[108:111], v[152:155], v[176:179], v[108:111]
	v_mfma_f32_16x16x32_bf16 v[108:111], v[148:151], v[172:175], v[108:111]
	v_mfma_f32_16x16x32_bf16 v[116:119], v[148:151], v[180:183], v[116:119]
	v_mfma_f32_16x16x32_bf16 v[116:119], v[152:155], v[184:187], v[116:119]
	v_mfma_f32_16x16x32_bf16 v[120:123], v[160:163], v[184:187], v[120:123]
	v_mfma_f32_16x16x32_bf16 v[120:123], v[156:159], v[180:183], v[120:123]
	v_mfma_f32_16x16x32_bf16 v[128:131], v[156:159], v[194:197], v[128:131]
	v_mfma_f32_16x16x32_bf16 v[128:131], v[160:163], v[198:201], v[128:131]
	s_setprio 2
	s_barrier
	v_mfma_f32_16x16x32_bf16 v[124:127], v[152:155], v[198:201], v[124:127]
	v_mfma_f32_16x16x32_bf16 v[124:127], v[148:151], v[194:197], v[124:127]
	s_setprio 0
	s_and_b64 vcc, exec, s[58:59]
	s_cbranch_vccz .LBB0_1178
	s_barrier

.LBB0_1625:
	s_add_i32 s51, 0, 0x10000
	s_add_i32 s72, 0, 0x14000
	v_add_u32_e32 v16, s51, v232
	v_add_u32_e32 v32, s72, v232
	ds_read_b128 v[4:7], v16
	ds_read_b128 v[8:11], v16 offset:1024
	ds_read_b128 v[12:15], v16 offset:2048
	ds_read_b128 v[16:19], v16 offset:3072
	ds_read_b128 v[20:23], v32
	ds_read_b128 v[24:27], v32 offset:1024
	ds_read_b128 v[28:31], v32 offset:2048
	ds_read_b128 v[32:35], v32 offset:3072
	v_add_u32_e32 v233, 0, v231
	ds_read_b128 v[36:39], v233
	ds_read_b128 v[40:43], v233 offset:1024
	ds_read_b128 v[44:47], v233 offset:2048
	ds_read_b128 v[48:51], v233 offset:3072
	ds_read_b128 v[52:55], v233 offset:4096
	ds_read_b128 v[56:59], v233 offset:5120
	ds_read_b128 v[60:63], v233 offset:6144
	ds_read_b128 v[64:67], v233 offset:7168
	s_waitcnt vmcnt(8)
	s_waitcnt lgkmcnt(0)
	s_barrier
	s_setprio 1
	s_waitcnt lgkmcnt(0)
	v_mfma_f32_16x16x32_bf16 v[68:71], v[4:7], v[36:39], 0
	v_mfma_f32_16x16x32_bf16 v[68:71], v[8:11], v[40:43], v[68:71]
	v_mfma_f32_16x16x32_bf16 v[72:75], v[12:15], v[36:39], 0
	v_mfma_f32_16x16x32_bf16 v[72:75], v[16:19], v[40:43], v[72:75]
	v_mfma_f32_16x16x32_bf16 v[80:83], v[12:15], v[44:47], 0
	v_mfma_f32_16x16x32_bf16 v[80:83], v[16:19], v[48:51], v[80:83]
	v_mfma_f32_16x16x32_bf16 v[76:79], v[4:7], v[44:47], 0
	v_mfma_f32_16x16x32_bf16 v[76:79], v[8:11], v[48:51], v[76:79]
	v_mfma_f32_16x16x32_bf16 v[84:87], v[4:7], v[52:55], 0
	v_mfma_f32_16x16x32_bf16 v[84:87], v[8:11], v[56:59], v[84:87]
	v_mfma_f32_16x16x32_bf16 v[88:91], v[12:15], v[52:55], 0
	v_mfma_f32_16x16x32_bf16 v[88:91], v[16:19], v[56:59], v[88:91]
	v_mfma_f32_16x16x32_bf16 v[96:99], v[12:15], v[60:63], 0
	v_mfma_f32_16x16x32_bf16 v[96:99], v[16:19], v[64:67], v[96:99]
	v_mfma_f32_16x16x32_bf16 v[92:95], v[4:7], v[60:63], 0
	v_mfma_f32_16x16x32_bf16 v[92:95], v[8:11], v[64:67], v[92:95]
	s_setprio 0
	s_setprio 1
	v_mfma_f32_16x16x32_bf16 v[100:103], v[20:23], v[36:39], 0
	v_mfma_f32_16x16x32_bf16 v[36:39], v[28:31], v[36:39], 0
	v_mfma_f32_16x16x32_bf16 v[104:107], v[20:23], v[44:47], 0
	v_mfma_f32_16x16x32_bf16 v[44:47], v[28:31], v[44:47], 0
	v_mfma_f32_16x16x32_bf16 v[108:111], v[20:23], v[52:55], 0
	v_mfma_f32_16x16x32_bf16 v[52:55], v[28:31], v[52:55], 0
	v_mfma_f32_16x16x32_bf16 v[112:115], v[20:23], v[60:63], 0
	v_mfma_f32_16x16x32_bf16 v[60:63], v[28:31], v[60:63], 0
	v_mfma_f32_16x16x32_bf16 v[100:103], v[24:27], v[40:43], v[100:103]
	v_mfma_f32_16x16x32_bf16 v[40:43], v[32:35], v[40:43], v[36:39]
	v_mfma_f32_16x16x32_bf16 v[104:107], v[24:27], v[48:51], v[104:107]
	v_mfma_f32_16x16x32_bf16 v[48:51], v[32:35], v[48:51], v[44:47]
	v_mfma_f32_16x16x32_bf16 v[108:111], v[24:27], v[56:59], v[108:111]
	v_mfma_f32_16x16x32_bf16 v[56:59], v[32:35], v[56:59], v[52:55]
	s_setprio 2
	s_barrier
	v_mfma_f32_16x16x32_bf16 v[112:115], v[24:27], v[64:67], v[112:115]
	v_mfma_f32_16x16x32_bf16 v[64:67], v[32:35], v[64:67], v[60:63]
	s_setprio 0
	v_lshl_add_u64 v[186:187], s[12:13], 0, v[2:3]
	s_add_i32 s51, s51, s56
	v_mov_b32_e32 v191, v3
	v_lshl_add_u64 v[134:135], v[186:187], 0, s[74:75]
	s_mov_b32 m0, s51
	v_lshl_add_u64 v[246:247], s[12:13], 0, v[190:191]
	ds_read_b128 v[36:39], v233 offset:16384
	ds_read_b128 v[44:47], v233 offset:17408
	ds_read_b128 v[52:55], v233 offset:18432
	ds_read_b128 v[60:63], v233 offset:19456
	ds_read_b128 v[116:119], v233 offset:20480
	ds_read_b128 v[120:123], v233 offset:21504
	ds_read_b128 v[124:127], v233 offset:22528
	ds_read_b128 v[128:131], v233 offset:23552
	global_load_lds_dwordx4 v[134:135], off
	v_lshl_add_u64 v[134:135], v[246:247], 0, s[74:75]
	s_add_i32 m0, s51, 0x2000
	s_add_i32 s51, s72, s56
	global_load_lds_dwordx4 v[134:135], off
	s_mov_b32 m0, s51
	v_mov_b32_e32 v133, v3
	global_load_lds_dwordx4 v2, s[16:17]
	s_add_i32 m0, s51, 0x2000
	v_lshl_add_u64 v[248:249], s[14:15], 0, v[132:133]
	v_mov_b32_e32 v189, v3
	global_load_lds_dwordx4 v190, s[16:17]
	v_lshl_add_u64 v[134:135], v[248:249], 0, s[74:75]
	s_mov_b32 m0, s57
	v_lshl_add_u64 v[250:251], s[14:15], 0, v[188:189]
	global_load_lds_dwordx4 v[134:135], off
	v_lshl_add_u64 v[134:135], v[250:251], 0, s[74:75]
	s_mov_b32 m0, s58
	s_nop 0
	global_load_lds_dwordx4 v[134:135], off
	s_waitcnt vmcnt(8)
	s_waitcnt lgkmcnt(0)
	s_barrier
	s_setprio 1
	s_waitcnt lgkmcnt(0)
	v_mfma_f32_16x16x32_bf16 v[134:137], v[4:7], v[36:39], 0
	v_mfma_f32_16x16x32_bf16 v[138:141], v[12:15], v[36:39], 0
	v_mfma_f32_16x16x32_bf16 v[142:145], v[4:7], v[52:55], 0
	v_mfma_f32_16x16x32_bf16 v[146:149], v[12:15], v[52:55], 0
	v_mfma_f32_16x16x32_bf16 v[150:153], v[4:7], v[116:119], 0
	v_mfma_f32_16x16x32_bf16 v[154:157], v[12:15], v[116:119], 0
	v_mfma_f32_16x16x32_bf16 v[4:7], v[4:7], v[124:127], 0
	v_mfma_f32_16x16x32_bf16 v[12:15], v[12:15], v[124:127], 0
	v_mfma_f32_16x16x32_bf16 v[134:137], v[8:11], v[44:47], v[134:137]
	v_mfma_f32_16x16x32_bf16 v[138:141], v[16:19], v[44:47], v[138:141]
	v_mfma_f32_16x16x32_bf16 v[142:145], v[8:11], v[60:63], v[142:145]
	v_mfma_f32_16x16x32_bf16 v[146:149], v[16:19], v[60:63], v[146:149]
	v_mfma_f32_16x16x32_bf16 v[150:153], v[8:11], v[120:123], v[150:153]
	v_mfma_f32_16x16x32_bf16 v[154:157], v[16:19], v[120:123], v[154:157]
	v_mfma_f32_16x16x32_bf16 v[158:161], v[8:11], v[128:131], v[4:7]
	v_mfma_f32_16x16x32_bf16 v[162:165], v[16:19], v[128:131], v[12:15]
	s_setprio 0
	s_setprio 1
	v_mfma_f32_16x16x32_bf16 v[4:7], v[20:23], v[36:39], 0
	v_mfma_f32_16x16x32_bf16 v[8:11], v[28:31], v[36:39], 0
	v_mfma_f32_16x16x32_bf16 v[12:15], v[20:23], v[52:55], 0
	v_mfma_f32_16x16x32_bf16 v[16:19], v[28:31], v[52:55], 0
	v_mfma_f32_16x16x32_bf16 v[36:39], v[20:23], v[116:119], 0
	v_mfma_f32_16x16x32_bf16 v[52:55], v[28:31], v[116:119], 0
	v_mfma_f32_16x16x32_bf16 v[20:23], v[20:23], v[124:127], 0
	v_mfma_f32_16x16x32_bf16 v[28:31], v[28:31], v[124:127], 0
	v_mfma_f32_16x16x32_bf16 v[116:119], v[24:27], v[44:47], v[4:7]
	v_mfma_f32_16x16x32_bf16 v[124:127], v[32:35], v[44:47], v[8:11]
	v_mfma_f32_16x16x32_bf16 v[174:177], v[24:27], v[120:123], v[36:39]
	v_mfma_f32_16x16x32_bf16 v[120:123], v[32:35], v[120:123], v[52:55]
	v_mfma_f32_16x16x32_bf16 v[178:181], v[24:27], v[128:131], v[20:23]
	v_mfma_f32_16x16x32_bf16 v[128:131], v[32:35], v[128:131], v[28:31]
	s_setprio 2
	s_barrier
	v_mfma_f32_16x16x32_bf16 v[166:169], v[24:27], v[60:63], v[12:15]
	v_mfma_f32_16x16x32_bf16 v[170:173], v[32:35], v[60:63], v[16:19]
	s_setprio 0
	s_add_i32 s51, 0, 0x18000
	v_add_u32_e32 v4, s51, v232
	s_add_i32 s72, 0, 0x1c000
	ds_read_b128 v[182:185], v4
	ds_read_b128 v[192:195], v4 offset:1024
	ds_read_b128 v[196:199], v4 offset:2048
	ds_read_b128 v[200:203], v4 offset:3072
	v_add_u32_e32 v4, s72, v232
	ds_read_b128 v[204:207], v4
	ds_read_b128 v[208:211], v4 offset:1024
	ds_read_b128 v[212:215], v4 offset:2048
	ds_read_b128 v[216:219], v4 offset:3072
	s_mov_b32 m0, s59
	ds_read_b128 v[44:47], v233 offset:32768
	ds_read_b128 v[52:55], v233 offset:33792
	ds_read_b128 v[60:63], v233 offset:34816
	ds_read_b128 v[220:223], v233 offset:35840
	ds_read_b128 v[224:227], v233 offset:36864
	ds_read_b128 v[234:237], v233 offset:37888
	ds_read_b128 v[238:241], v233 offset:38912
	ds_read_b128 v[242:245], v233 offset:39936
	global_load_lds_dwordx4 v132, s[26:27]
	s_mov_b32 m0, s60
	s_nop 0
	global_load_lds_dwordx4 v188, s[26:27]
	s_waitcnt vmcnt(8)
	s_waitcnt lgkmcnt(0)
	s_barrier
	s_setprio 1
	s_waitcnt lgkmcnt(0)
	v_mfma_f32_16x16x32_bf16 v[4:7], v[182:185], v[44:47], v[68:71]
	v_mfma_f32_16x16x32_bf16 v[8:11], v[196:199], v[44:47], v[72:75]
	v_mfma_f32_16x16x32_bf16 v[12:15], v[182:185], v[60:63], v[76:79]
	v_mfma_f32_16x16x32_bf16 v[16:19], v[196:199], v[60:63], v[80:83]
	v_mfma_f32_16x16x32_bf16 v[20:23], v[182:185], v[224:227], v[84:87]
	v_mfma_f32_16x16x32_bf16 v[24:27], v[196:199], v[224:227], v[88:91]
	v_mfma_f32_16x16x32_bf16 v[28:31], v[182:185], v[238:241], v[92:95]
	v_mfma_f32_16x16x32_bf16 v[32:35], v[196:199], v[238:241], v[96:99]
	v_mfma_f32_16x16x32_bf16 v[4:7], v[192:195], v[52:55], v[4:7]
	v_mfma_f32_16x16x32_bf16 v[8:11], v[200:203], v[52:55], v[8:11]
	v_mfma_f32_16x16x32_bf16 v[12:15], v[192:195], v[220:223], v[12:15]
	v_mfma_f32_16x16x32_bf16 v[16:19], v[200:203], v[220:223], v[16:19]
	v_mfma_f32_16x16x32_bf16 v[20:23], v[192:195], v[234:237], v[20:23]
	v_mfma_f32_16x16x32_bf16 v[24:27], v[200:203], v[234:237], v[24:27]
	v_mfma_f32_16x16x32_bf16 v[28:31], v[192:195], v[242:245], v[28:31]
	v_mfma_f32_16x16x32_bf16 v[32:35], v[200:203], v[242:245], v[32:35]
	s_setprio 0
	s_setprio 1
	v_mfma_f32_16x16x32_bf16 v[36:39], v[204:207], v[44:47], v[100:103]
	v_mfma_f32_16x16x32_bf16 v[40:43], v[212:215], v[44:47], v[40:43]
	v_mfma_f32_16x16x32_bf16 v[36:39], v[208:211], v[52:55], v[36:39]
	v_mfma_f32_16x16x32_bf16 v[40:43], v[216:219], v[52:55], v[40:43]
	v_mfma_f32_16x16x32_bf16 v[44:47], v[204:207], v[60:63], v[104:107]
	v_mfma_f32_16x16x32_bf16 v[48:51], v[212:215], v[60:63], v[48:51]
	v_mfma_f32_16x16x32_bf16 v[52:55], v[204:207], v[224:227], v[108:111]
	v_mfma_f32_16x16x32_bf16 v[56:59], v[212:215], v[224:227], v[56:59]
	v_mfma_f32_16x16x32_bf16 v[60:63], v[204:207], v[238:241], v[112:115]
	v_mfma_f32_16x16x32_bf16 v[64:67], v[212:215], v[238:241], v[64:67]
	v_mfma_f32_16x16x32_bf16 v[44:47], v[208:211], v[220:223], v[44:47]
	v_mfma_f32_16x16x32_bf16 v[48:51], v[216:219], v[220:223], v[48:51]
	v_mfma_f32_16x16x32_bf16 v[52:55], v[208:211], v[234:237], v[52:55]
	v_mfma_f32_16x16x32_bf16 v[56:59], v[216:219], v[234:237], v[56:59]
	s_setprio 2
	s_barrier
	v_mfma_f32_16x16x32_bf16 v[60:63], v[208:211], v[242:245], v[60:63]
	v_mfma_f32_16x16x32_bf16 v[64:67], v[216:219], v[242:245], v[64:67]
	s_setprio 0
	s_add_i32 s51, s51, s56
	v_lshl_add_u64 v[68:69], v[186:187], 0, s[24:25]
	s_mov_b32 m0, s51
	ds_read_b128 v[104:107], v233 offset:49152
	ds_read_b128 v[108:111], v233 offset:50176
	ds_read_b128 v[112:115], v233 offset:51200
	ds_read_b128 v[220:223], v233 offset:52224
	ds_read_b128 v[224:227], v233 offset:53248
	ds_read_b128 v[234:237], v233 offset:54272
	ds_read_b128 v[238:241], v233 offset:55296
	ds_read_b128 v[242:245], v233 offset:56320
	global_load_lds_dwordx4 v[68:69], off
	v_lshl_add_u64 v[68:69], v[246:247], 0, s[24:25]
	s_add_i32 m0, s51, 0x2000
	s_add_i32 s51, s72, s56
	global_load_lds_dwordx4 v[68:69], off
	s_mov_b32 m0, s51
	v_lshl_add_u64 v[68:69], v[248:249], 0, s[24:25]
	global_load_lds_dwordx4 v2, s[28:29]
	s_add_i32 m0, s51, 0x2000
	s_nop 0
	global_load_lds_dwordx4 v190, s[28:29]
	s_mov_b32 m0, s64
	s_nop 0
	global_load_lds_dwordx4 v[68:69], off
	v_lshl_add_u64 v[68:69], v[250:251], 0, s[24:25]
	s_mov_b32 m0, s65
	s_nop 0
	global_load_lds_dwordx4 v[68:69], off
	s_waitcnt vmcnt(8)
	s_waitcnt lgkmcnt(0)
	s_barrier
	s_setprio 1
	s_waitcnt lgkmcnt(0)
	v_mfma_f32_16x16x32_bf16 v[68:71], v[182:185], v[104:107], v[134:137]
	v_mfma_f32_16x16x32_bf16 v[72:75], v[196:199], v[104:107], v[138:141]
	v_mfma_f32_16x16x32_bf16 v[76:79], v[182:185], v[112:115], v[142:145]
	v_mfma_f32_16x16x32_bf16 v[80:83], v[196:199], v[112:115], v[146:149]
	v_mfma_f32_16x16x32_bf16 v[84:87], v[182:185], v[224:227], v[150:153]
	v_mfma_f32_16x16x32_bf16 v[88:91], v[196:199], v[224:227], v[154:157]
	v_mfma_f32_16x16x32_bf16 v[92:95], v[182:185], v[238:241], v[158:161]
	v_mfma_f32_16x16x32_bf16 v[96:99], v[196:199], v[238:241], v[162:165]
	v_mfma_f32_16x16x32_bf16 v[68:71], v[192:195], v[108:111], v[68:71]
	v_mfma_f32_16x16x32_bf16 v[72:75], v[200:203], v[108:111], v[72:75]
	v_mfma_f32_16x16x32_bf16 v[76:79], v[192:195], v[220:223], v[76:79]
	v_mfma_f32_16x16x32_bf16 v[80:83], v[200:203], v[220:223], v[80:83]
	v_mfma_f32_16x16x32_bf16 v[84:87], v[192:195], v[234:237], v[84:87]
	v_mfma_f32_16x16x32_bf16 v[88:91], v[200:203], v[234:237], v[88:91]
	v_mfma_f32_16x16x32_bf16 v[92:95], v[192:195], v[242:245], v[92:95]
	v_mfma_f32_16x16x32_bf16 v[96:99], v[200:203], v[242:245], v[96:99]
	s_setprio 0
	s_setprio 1
	v_mfma_f32_16x16x32_bf16 v[100:103], v[204:207], v[104:107], v[116:119]
	v_mfma_f32_16x16x32_bf16 v[104:107], v[212:215], v[104:107], v[124:127]
	v_mfma_f32_16x16x32_bf16 v[100:103], v[208:211], v[108:111], v[100:103]
	v_mfma_f32_16x16x32_bf16 v[104:107], v[216:219], v[108:111], v[104:107]
	v_mfma_f32_16x16x32_bf16 v[108:111], v[204:207], v[112:115], v[166:169]
	v_mfma_f32_16x16x32_bf16 v[112:115], v[212:215], v[112:115], v[170:173]
	v_mfma_f32_16x16x32_bf16 v[116:119], v[204:207], v[224:227], v[174:177]
	v_mfma_f32_16x16x32_bf16 v[120:123], v[212:215], v[224:227], v[120:123]
	v_mfma_f32_16x16x32_bf16 v[124:127], v[204:207], v[238:241], v[178:181]
	v_mfma_f32_16x16x32_bf16 v[128:131], v[212:215], v[238:241], v[128:131]
	v_mfma_f32_16x16x32_bf16 v[108:111], v[208:211], v[220:223], v[108:111]
	v_mfma_f32_16x16x32_bf16 v[112:115], v[216:219], v[220:223], v[112:115]
	v_mfma_f32_16x16x32_bf16 v[116:119], v[208:211], v[234:237], v[116:119]
	v_mfma_f32_16x16x32_bf16 v[120:123], v[216:219], v[234:237], v[120:123]
	s_setprio 2
	s_barrier
	v_mfma_f32_16x16x32_bf16 v[124:127], v[208:211], v[242:245], v[124:127]
	v_mfma_f32_16x16x32_bf16 v[128:131], v[216:219], v[242:245], v[128:131]
	s_setprio 0
	s_add_i32 s43, s43, 2
	s_cmp_ge_i32 s43, s42
	s_cbranch_scc0 .LBB0_1625
	v_mov_b32_e32 v192, v2
	s_branch .LBB0_1628

.LBB0_1629:
	s_add_u32 s12, s14, 0xfff80080
	s_addc_u32 s13, s15, -1
	s_add_i32 s29, 0, 0x10000
	s_cmp_eq_u32 s28, 28
	s_cselect_b32 s17, s9, s13
	s_cselect_b32 s16, s8, s12
	s_cselect_b32 s13, s11, s27
	s_cselect_b32 s12, s10, s26
	s_add_i32 s51, 0, 0x14000
	v_add_u32_e32 v144, s29, v232
	v_add_u32_e32 v160, s51, v232
	s_waitcnt lgkmcnt(0)
	ds_read_b128 v[132:135], v144
	ds_read_b128 v[136:139], v144 offset:1024
	ds_read_b128 v[140:143], v144 offset:2048
	ds_read_b128 v[144:147], v144 offset:3072
	ds_read_b128 v[148:151], v160
	ds_read_b128 v[152:155], v160 offset:1024
	ds_read_b128 v[156:159], v160 offset:2048
	ds_read_b128 v[160:163], v160 offset:3072
	s_mov_b32 m0, s66
	v_add_u32_e32 v210, 0, v231
	ds_read_b128 v[164:167], v210
	ds_read_b128 v[168:171], v210 offset:1024
	ds_read_b128 v[172:175], v210 offset:2048
	ds_read_b128 v[176:179], v210 offset:3072
	ds_read_b128 v[180:183], v210 offset:4096
	ds_read_b128 v[184:187], v210 offset:5120
	ds_read_b128 v[194:197], v210 offset:6144
	ds_read_b128 v[198:201], v210 offset:7168
	global_load_lds_dwordx4 v2, s[14:15]
	s_mov_b32 m0, s67
	v_mov_b32_e32 v189, v3
	global_load_lds_dwordx4 v188, s[14:15]
	s_waitcnt vmcnt(8)
	s_waitcnt lgkmcnt(0)
	s_barrier
	s_setprio 1
	s_waitcnt lgkmcnt(0)
	v_mfma_f32_16x16x32_bf16 v[4:7], v[132:135], v[164:167], v[4:7]
	v_mfma_f32_16x16x32_bf16 v[4:7], v[136:139], v[168:171], v[4:7]
	v_mfma_f32_16x16x32_bf16 v[8:11], v[144:147], v[168:171], v[8:11]
	v_mfma_f32_16x16x32_bf16 v[8:11], v[140:143], v[164:167], v[8:11]
	v_mfma_f32_16x16x32_bf16 v[16:19], v[140:143], v[172:175], v[16:19]
	v_mfma_f32_16x16x32_bf16 v[16:19], v[144:147], v[176:179], v[16:19]
	v_mfma_f32_16x16x32_bf16 v[12:15], v[136:139], v[176:179], v[12:15]
	v_mfma_f32_16x16x32_bf16 v[12:15], v[132:135], v[172:175], v[12:15]
	v_mfma_f32_16x16x32_bf16 v[20:23], v[132:135], v[180:183], v[20:23]
	v_mfma_f32_16x16x32_bf16 v[20:23], v[136:139], v[184:187], v[20:23]
	v_mfma_f32_16x16x32_bf16 v[24:27], v[144:147], v[184:187], v[24:27]
	v_mfma_f32_16x16x32_bf16 v[24:27], v[140:143], v[180:183], v[24:27]
	v_mfma_f32_16x16x32_bf16 v[32:35], v[140:143], v[194:197], v[32:35]
	v_mfma_f32_16x16x32_bf16 v[32:35], v[144:147], v[198:201], v[32:35]
	v_mfma_f32_16x16x32_bf16 v[28:31], v[136:139], v[198:201], v[28:31]
	v_mfma_f32_16x16x32_bf16 v[28:31], v[132:135], v[194:197], v[28:31]
	s_setprio 0
	s_setprio 1
	v_mfma_f32_16x16x32_bf16 v[36:39], v[148:151], v[164:167], v[36:39]
	v_mfma_f32_16x16x32_bf16 v[36:39], v[152:155], v[168:171], v[36:39]
	v_mfma_f32_16x16x32_bf16 v[40:43], v[160:163], v[168:171], v[40:43]
	v_mfma_f32_16x16x32_bf16 v[40:43], v[156:159], v[164:167], v[40:43]
	v_mfma_f32_16x16x32_bf16 v[48:51], v[156:159], v[172:175], v[48:51]
	v_mfma_f32_16x16x32_bf16 v[48:51], v[160:163], v[176:179], v[48:51]
	v_mfma_f32_16x16x32_bf16 v[44:47], v[152:155], v[176:179], v[44:47]
	v_mfma_f32_16x16x32_bf16 v[44:47], v[148:151], v[172:175], v[44:47]
	v_mfma_f32_16x16x32_bf16 v[52:55], v[148:151], v[180:183], v[52:55]
	v_mfma_f32_16x16x32_bf16 v[52:55], v[152:155], v[184:187], v[52:55]
	v_mfma_f32_16x16x32_bf16 v[56:59], v[160:163], v[184:187], v[56:59]
	v_mfma_f32_16x16x32_bf16 v[56:59], v[156:159], v[180:183], v[56:59]
	v_mfma_f32_16x16x32_bf16 v[64:67], v[156:159], v[194:197], v[64:67]
	v_mfma_f32_16x16x32_bf16 v[64:67], v[160:163], v[198:201], v[64:67]
	s_setprio 2
	s_barrier
	v_mfma_f32_16x16x32_bf16 v[60:63], v[152:155], v[198:201], v[60:63]
	v_mfma_f32_16x16x32_bf16 v[60:63], v[148:151], v[194:197], v[60:63]
	s_setprio 0
	s_add_i32 s29, s29, s56
	s_mov_b32 m0, s29
	ds_read_b128 v[164:167], v210 offset:16384
	ds_read_b128 v[168:171], v210 offset:17408
	ds_read_b128 v[172:175], v210 offset:18432
	ds_read_b128 v[176:179], v210 offset:19456
	ds_read_b128 v[180:183], v210 offset:20480
	ds_read_b128 v[184:187], v210 offset:21504
	ds_read_b128 v[194:197], v210 offset:22528
	ds_read_b128 v[198:201], v210 offset:23552
	global_load_lds_dwordx4 v192, s[12:13]
	s_add_i32 m0, s29, 0x2000
	s_add_u32 s42, s12, 0x80000
	s_addc_u32 s43, s13, 0
	s_add_i32 s29, s51, s56
	global_load_lds_dwordx4 v190, s[12:13]
	s_mov_b32 m0, s29
	v_mov_b32_e32 v193, v3
	global_load_lds_dwordx4 v192, s[42:43]
	s_add_i32 m0, s29, 0x2000
	v_mov_b32_e32 v191, v3
	global_load_lds_dwordx4 v190, s[42:43]
	s_mov_b32 m0, s57
	v_lshl_add_u64 v[202:203], s[12:13], 0, v[192:193]
	global_load_lds_dwordx4 v2, s[16:17]
	s_mov_b32 m0, s58
	v_lshl_add_u64 v[204:205], s[12:13], 0, v[190:191]
	global_load_lds_dwordx4 v188, s[16:17]
	s_waitcnt vmcnt(8)
	s_waitcnt lgkmcnt(0)
	v_lshl_add_u64 v[206:207], s[16:17], 0, v[2:3]
	v_lshl_add_u64 v[208:209], s[16:17], 0, v[188:189]
	s_barrier
	s_setprio 1
	s_waitcnt lgkmcnt(0)
	v_mfma_f32_16x16x32_bf16 v[68:71], v[132:135], v[164:167], v[68:71]
	v_mfma_f32_16x16x32_bf16 v[68:71], v[136:139], v[168:171], v[68:71]
	v_mfma_f32_16x16x32_bf16 v[72:75], v[144:147], v[168:171], v[72:75]
	v_mfma_f32_16x16x32_bf16 v[72:75], v[140:143], v[164:167], v[72:75]
	v_mfma_f32_16x16x32_bf16 v[80:83], v[140:143], v[172:175], v[80:83]
	v_mfma_f32_16x16x32_bf16 v[80:83], v[144:147], v[176:179], v[80:83]
	v_mfma_f32_16x16x32_bf16 v[76:79], v[136:139], v[176:179], v[76:79]
	v_mfma_f32_16x16x32_bf16 v[76:79], v[132:135], v[172:175], v[76:79]
	v_mfma_f32_16x16x32_bf16 v[84:87], v[132:135], v[180:183], v[84:87]
	v_mfma_f32_16x16x32_bf16 v[84:87], v[136:139], v[184:187], v[84:87]
	v_mfma_f32_16x16x32_bf16 v[88:91], v[144:147], v[184:187], v[88:91]
	v_mfma_f32_16x16x32_bf16 v[88:91], v[140:143], v[180:183], v[88:91]
	v_mfma_f32_16x16x32_bf16 v[96:99], v[140:143], v[194:197], v[96:99]
	v_mfma_f32_16x16x32_bf16 v[96:99], v[144:147], v[198:201], v[96:99]
	v_mfma_f32_16x16x32_bf16 v[92:95], v[136:139], v[198:201], v[92:95]
	v_mfma_f32_16x16x32_bf16 v[92:95], v[132:135], v[194:197], v[92:95]
	s_setprio 0
	s_setprio 1
	v_mfma_f32_16x16x32_bf16 v[100:103], v[148:151], v[164:167], v[100:103]
	v_mfma_f32_16x16x32_bf16 v[100:103], v[152:155], v[168:171], v[100:103]
	v_mfma_f32_16x16x32_bf16 v[104:107], v[160:163], v[168:171], v[104:107]
	v_mfma_f32_16x16x32_bf16 v[104:107], v[156:159], v[164:167], v[104:107]
	v_mfma_f32_16x16x32_bf16 v[112:115], v[156:159], v[172:175], v[112:115]
	v_mfma_f32_16x16x32_bf16 v[112:115], v[160:163], v[176:179], v[112:115]
	v_mfma_f32_16x16x32_bf16 v[108:111], v[152:155], v[176:179], v[108:111]
	v_mfma_f32_16x16x32_bf16 v[108:111], v[148:151], v[172:175], v[108:111]
	v_mfma_f32_16x16x32_bf16 v[116:119], v[148:151], v[180:183], v[116:119]
	v_mfma_f32_16x16x32_bf16 v[116:119], v[152:155], v[184:187], v[116:119]
	v_mfma_f32_16x16x32_bf16 v[120:123], v[160:163], v[184:187], v[120:123]
	v_mfma_f32_16x16x32_bf16 v[120:123], v[156:159], v[180:183], v[120:123]
	v_mfma_f32_16x16x32_bf16 v[128:131], v[156:159], v[194:197], v[128:131]
	v_mfma_f32_16x16x32_bf16 v[128:131], v[160:163], v[198:201], v[128:131]
	s_setprio 2
	s_barrier
	v_mfma_f32_16x16x32_bf16 v[124:127], v[152:155], v[198:201], v[124:127]
	v_mfma_f32_16x16x32_bf16 v[124:127], v[148:151], v[194:197], v[124:127]
	s_setprio 0
	s_add_i32 s29, 0, 0x18000
	s_add_i32 s42, 0, 0x1c000
	v_add_u32_e32 v144, s29, v232
	v_add_u32_e32 v160, s42, v232
	ds_read_b128 v[132:135], v144
	ds_read_b128 v[136:139], v144 offset:1024
	ds_read_b128 v[140:143], v144 offset:2048
	ds_read_b128 v[144:147], v144 offset:3072
	ds_read_b128 v[148:151], v160
	ds_read_b128 v[152:155], v160 offset:1024
	ds_read_b128 v[156:159], v160 offset:2048
	ds_read_b128 v[160:163], v160 offset:3072
	s_add_u32 s16, s16, 0x80000
	s_addc_u32 s17, s17, 0
	s_mov_b32 m0, s59
	ds_read_b128 v[164:167], v210 offset:32768
	ds_read_b128 v[168:171], v210 offset:33792
	ds_read_b128 v[172:175], v210 offset:34816
	ds_read_b128 v[176:179], v210 offset:35840
	ds_read_b128 v[180:183], v210 offset:36864
	ds_read_b128 v[184:187], v210 offset:37888
	ds_read_b128 v[194:197], v210 offset:38912
	ds_read_b128 v[198:201], v210 offset:39936
	global_load_lds_dwordx4 v2, s[16:17]
	s_mov_b32 m0, s60
	s_nop 0
	global_load_lds_dwordx4 v188, s[16:17]
	s_waitcnt vmcnt(8)
	s_waitcnt lgkmcnt(0)
	s_barrier
	s_setprio 1
	s_waitcnt lgkmcnt(0)
	v_mfma_f32_16x16x32_bf16 v[4:7], v[132:135], v[164:167], v[4:7]
	v_mfma_f32_16x16x32_bf16 v[4:7], v[136:139], v[168:171], v[4:7]
	v_mfma_f32_16x16x32_bf16 v[8:11], v[144:147], v[168:171], v[8:11]
	v_mfma_f32_16x16x32_bf16 v[8:11], v[140:143], v[164:167], v[8:11]
	v_mfma_f32_16x16x32_bf16 v[16:19], v[140:143], v[172:175], v[16:19]
	v_mfma_f32_16x16x32_bf16 v[16:19], v[144:147], v[176:179], v[16:19]
	v_mfma_f32_16x16x32_bf16 v[12:15], v[136:139], v[176:179], v[12:15]
	v_mfma_f32_16x16x32_bf16 v[12:15], v[132:135], v[172:175], v[12:15]
	v_mfma_f32_16x16x32_bf16 v[20:23], v[132:135], v[180:183], v[20:23]
	v_mfma_f32_16x16x32_bf16 v[20:23], v[136:139], v[184:187], v[20:23]
	v_mfma_f32_16x16x32_bf16 v[24:27], v[144:147], v[184:187], v[24:27]
	v_mfma_f32_16x16x32_bf16 v[24:27], v[140:143], v[180:183], v[24:27]
	v_mfma_f32_16x16x32_bf16 v[32:35], v[140:143], v[194:197], v[32:35]
	v_mfma_f32_16x16x32_bf16 v[32:35], v[144:147], v[198:201], v[32:35]
	v_mfma_f32_16x16x32_bf16 v[28:31], v[136:139], v[198:201], v[28:31]
	v_mfma_f32_16x16x32_bf16 v[28:31], v[132:135], v[194:197], v[28:31]
	s_setprio 0
	s_setprio 1
	v_mfma_f32_16x16x32_bf16 v[36:39], v[148:151], v[164:167], v[36:39]
	v_mfma_f32_16x16x32_bf16 v[36:39], v[152:155], v[168:171], v[36:39]
	v_mfma_f32_16x16x32_bf16 v[40:43], v[160:163], v[168:171], v[40:43]
	v_mfma_f32_16x16x32_bf16 v[40:43], v[156:159], v[164:167], v[40:43]
	v_mfma_f32_16x16x32_bf16 v[48:51], v[156:159], v[172:175], v[48:51]
	v_mfma_f32_16x16x32_bf16 v[48:51], v[160:163], v[176:179], v[48:51]
	v_mfma_f32_16x16x32_bf16 v[44:47], v[152:155], v[176:179], v[44:47]
	v_mfma_f32_16x16x32_bf16 v[44:47], v[148:151], v[172:175], v[44:47]
	v_mfma_f32_16x16x32_bf16 v[52:55], v[148:151], v[180:183], v[52:55]
	v_mfma_f32_16x16x32_bf16 v[52:55], v[152:155], v[184:187], v[52:55]
	v_mfma_f32_16x16x32_bf16 v[56:59], v[160:163], v[184:187], v[56:59]
	v_mfma_f32_16x16x32_bf16 v[56:59], v[156:159], v[180:183], v[56:59]
	v_mfma_f32_16x16x32_bf16 v[64:67], v[156:159], v[194:197], v[64:67]
	v_mfma_f32_16x16x32_bf16 v[64:67], v[160:163], v[198:201], v[64:67]
	s_setprio 2
	s_barrier
	v_mfma_f32_16x16x32_bf16 v[60:63], v[152:155], v[198:201], v[60:63]
	v_mfma_f32_16x16x32_bf16 v[60:63], v[148:151], v[194:197], v[60:63]
	s_setprio 0
	s_add_i32 s16, s29, s56
	v_lshl_add_u64 v[202:203], v[202:203], 0, s[86:87]
	s_mov_b32 m0, s16
	ds_read_b128 v[164:167], v210 offset:49152
	ds_read_b128 v[168:171], v210 offset:50176
	ds_read_b128 v[172:175], v210 offset:51200
	ds_read_b128 v[176:179], v210 offset:52224
	ds_read_b128 v[180:183], v210 offset:53248
	ds_read_b128 v[184:187], v210 offset:54272
	ds_read_b128 v[194:197], v210 offset:55296
	ds_read_b128 v[198:201], v210 offset:56320
	global_load_lds_dwordx4 v[202:203], off
	s_add_i32 m0, s16, 0x2000
	s_add_u32 s12, s12, 0x80080
	v_lshl_add_u64 v[202:203], v[204:205], 0, s[86:87]
	s_addc_u32 s13, s13, 0
	s_add_i32 s16, s42, s56
	global_load_lds_dwordx4 v[202:203], off
	s_mov_b32 m0, s16
	v_lshl_add_u64 v[202:203], v[206:207], 0, s[86:87]
	global_load_lds_dwordx4 v192, s[12:13]
	s_add_i32 m0, s16, 0x2000
	s_nop 0
	global_load_lds_dwordx4 v190, s[12:13]
	s_mov_b32 m0, s64
	s_nop 0
	global_load_lds_dwordx4 v[202:203], off
	v_lshl_add_u64 v[202:203], v[208:209], 0, s[86:87]
	s_mov_b32 m0, s65
	s_nop 0
	global_load_lds_dwordx4 v[202:203], off
	s_waitcnt vmcnt(8)
	s_waitcnt lgkmcnt(0)
	s_barrier
	s_setprio 1
	s_waitcnt lgkmcnt(0)
	v_mfma_f32_16x16x32_bf16 v[68:71], v[132:135], v[164:167], v[68:71]
	v_mfma_f32_16x16x32_bf16 v[68:71], v[136:139], v[168:171], v[68:71]
	v_mfma_f32_16x16x32_bf16 v[72:75], v[144:147], v[168:171], v[72:75]
	v_mfma_f32_16x16x32_bf16 v[72:75], v[140:143], v[164:167], v[72:75]
	v_mfma_f32_16x16x32_bf16 v[80:83], v[140:143], v[172:175], v[80:83]
	v_mfma_f32_16x16x32_bf16 v[80:83], v[144:147], v[176:179], v[80:83]
	v_mfma_f32_16x16x32_bf16 v[76:79], v[136:139], v[176:179], v[76:79]
	v_mfma_f32_16x16x32_bf16 v[76:79], v[132:135], v[172:175], v[76:79]
	v_mfma_f32_16x16x32_bf16 v[84:87], v[132:135], v[180:183], v[84:87]
	v_mfma_f32_16x16x32_bf16 v[84:87], v[136:139], v[184:187], v[84:87]
	v_mfma_f32_16x16x32_bf16 v[88:91], v[144:147], v[184:187], v[88:91]
	v_mfma_f32_16x16x32_bf16 v[88:91], v[140:143], v[180:183], v[88:91]
	v_mfma_f32_16x16x32_bf16 v[96:99], v[140:143], v[194:197], v[96:99]
	v_mfma_f32_16x16x32_bf16 v[96:99], v[144:147], v[198:201], v[96:99]
	v_mfma_f32_16x16x32_bf16 v[92:95], v[136:139], v[198:201], v[92:95]
	v_mfma_f32_16x16x32_bf16 v[92:95], v[132:135], v[194:197], v[92:95]
	s_setprio 0
	s_setprio 1
	v_mfma_f32_16x16x32_bf16 v[100:103], v[148:151], v[164:167], v[100:103]
	v_mfma_f32_16x16x32_bf16 v[100:103], v[152:155], v[168:171], v[100:103]
	v_mfma_f32_16x16x32_bf16 v[104:107], v[160:163], v[168:171], v[104:107]
	v_mfma_f32_16x16x32_bf16 v[104:107], v[156:159], v[164:167], v[104:107]
	v_mfma_f32_16x16x32_bf16 v[112:115], v[156:159], v[172:175], v[112:115]
	v_mfma_f32_16x16x32_bf16 v[112:115], v[160:163], v[176:179], v[112:115]
	v_mfma_f32_16x16x32_bf16 v[108:111], v[152:155], v[176:179], v[108:111]
	v_mfma_f32_16x16x32_bf16 v[108:111], v[148:151], v[172:175], v[108:111]
	v_mfma_f32_16x16x32_bf16 v[116:119], v[148:151], v[180:183], v[116:119]
	v_mfma_f32_16x16x32_bf16 v[116:119], v[152:155], v[184:187], v[116:119]
	v_mfma_f32_16x16x32_bf16 v[120:123], v[160:163], v[184:187], v[120:123]
	v_mfma_f32_16x16x32_bf16 v[120:123], v[156:159], v[180:183], v[120:123]
	v_mfma_f32_16x16x32_bf16 v[128:131], v[156:159], v[194:197], v[128:131]
	v_mfma_f32_16x16x32_bf16 v[128:131], v[160:163], v[198:201], v[128:131]
	s_setprio 2
	s_barrier
	v_mfma_f32_16x16x32_bf16 v[124:127], v[152:155], v[198:201], v[124:127]
	v_mfma_f32_16x16x32_bf16 v[124:127], v[148:151], v[194:197], v[124:127]
	s_setprio 0
	s_add_i32 s28, s28, 2
	s_add_u32 s14, s14, 0x100
	s_addc_u32 s15, s15, 0
	s_add_u32 s26, s26, 0x100
	s_addc_u32 s27, s27, 0
	s_cmp_gt_u32 s28, 29
	s_cbranch_scc0 .LBB0_1629
	s_and_b64 vcc, exec, s[48:49]
	s_cbranch_vccz .LBB0_1632
	s_barrier

.LBB0_2065:
	s_add_i32 s51, 0, 0x10000
	s_add_i32 s71, 0, 0x14000
	v_add_u32_e32 v16, s51, v232
	v_add_u32_e32 v32, s71, v232
	ds_read_b128 v[4:7], v16
	ds_read_b128 v[8:11], v16 offset:1024
	ds_read_b128 v[12:15], v16 offset:2048
	ds_read_b128 v[16:19], v16 offset:3072
	ds_read_b128 v[20:23], v32
	ds_read_b128 v[24:27], v32 offset:1024
	ds_read_b128 v[28:31], v32 offset:2048
	ds_read_b128 v[32:35], v32 offset:3072
	v_add_u32_e32 v233, 0, v231
	ds_read_b128 v[36:39], v233
	ds_read_b128 v[40:43], v233 offset:1024
	ds_read_b128 v[44:47], v233 offset:2048
	ds_read_b128 v[48:51], v233 offset:3072
	ds_read_b128 v[52:55], v233 offset:4096
	ds_read_b128 v[56:59], v233 offset:5120
	ds_read_b128 v[60:63], v233 offset:6144
	ds_read_b128 v[64:67], v233 offset:7168
	s_waitcnt vmcnt(8)
	s_waitcnt lgkmcnt(0)
	s_barrier
	s_setprio 1
	s_waitcnt lgkmcnt(0)
	v_mfma_f32_16x16x32_bf16 v[68:71], v[4:7], v[36:39], 0
	v_mfma_f32_16x16x32_bf16 v[68:71], v[8:11], v[40:43], v[68:71]
	v_mfma_f32_16x16x32_bf16 v[72:75], v[12:15], v[36:39], 0
	v_mfma_f32_16x16x32_bf16 v[72:75], v[16:19], v[40:43], v[72:75]
	v_mfma_f32_16x16x32_bf16 v[80:83], v[12:15], v[44:47], 0
	v_mfma_f32_16x16x32_bf16 v[80:83], v[16:19], v[48:51], v[80:83]
	v_mfma_f32_16x16x32_bf16 v[76:79], v[4:7], v[44:47], 0
	v_mfma_f32_16x16x32_bf16 v[76:79], v[8:11], v[48:51], v[76:79]
	v_mfma_f32_16x16x32_bf16 v[84:87], v[4:7], v[52:55], 0
	v_mfma_f32_16x16x32_bf16 v[84:87], v[8:11], v[56:59], v[84:87]
	v_mfma_f32_16x16x32_bf16 v[88:91], v[12:15], v[52:55], 0
	v_mfma_f32_16x16x32_bf16 v[88:91], v[16:19], v[56:59], v[88:91]
	v_mfma_f32_16x16x32_bf16 v[96:99], v[12:15], v[60:63], 0
	v_mfma_f32_16x16x32_bf16 v[96:99], v[16:19], v[64:67], v[96:99]
	v_mfma_f32_16x16x32_bf16 v[92:95], v[4:7], v[60:63], 0
	v_mfma_f32_16x16x32_bf16 v[92:95], v[8:11], v[64:67], v[92:95]
	s_setprio 0
	s_setprio 1
	v_mfma_f32_16x16x32_bf16 v[100:103], v[20:23], v[36:39], 0
	v_mfma_f32_16x16x32_bf16 v[36:39], v[28:31], v[36:39], 0
	v_mfma_f32_16x16x32_bf16 v[104:107], v[20:23], v[44:47], 0
	v_mfma_f32_16x16x32_bf16 v[44:47], v[28:31], v[44:47], 0
	v_mfma_f32_16x16x32_bf16 v[108:111], v[20:23], v[52:55], 0
	v_mfma_f32_16x16x32_bf16 v[52:55], v[28:31], v[52:55], 0
	v_mfma_f32_16x16x32_bf16 v[112:115], v[20:23], v[60:63], 0
	v_mfma_f32_16x16x32_bf16 v[60:63], v[28:31], v[60:63], 0
	v_mfma_f32_16x16x32_bf16 v[100:103], v[24:27], v[40:43], v[100:103]
	v_mfma_f32_16x16x32_bf16 v[40:43], v[32:35], v[40:43], v[36:39]
	v_mfma_f32_16x16x32_bf16 v[104:107], v[24:27], v[48:51], v[104:107]
	v_mfma_f32_16x16x32_bf16 v[48:51], v[32:35], v[48:51], v[44:47]
	v_mfma_f32_16x16x32_bf16 v[108:111], v[24:27], v[56:59], v[108:111]
	v_mfma_f32_16x16x32_bf16 v[56:59], v[32:35], v[56:59], v[52:55]
	s_setprio 2
	s_barrier
	v_mfma_f32_16x16x32_bf16 v[112:115], v[24:27], v[64:67], v[112:115]
	v_mfma_f32_16x16x32_bf16 v[64:67], v[32:35], v[64:67], v[60:63]
	s_setprio 0
	v_lshl_add_u64 v[186:187], s[12:13], 0, v[2:3]
	s_add_i32 s51, s51, s38
	v_mov_b32_e32 v191, v3
	v_lshl_add_u64 v[134:135], v[186:187], 0, s[74:75]
	s_mov_b32 m0, s51
	v_lshl_add_u64 v[246:247], s[12:13], 0, v[190:191]
	ds_read_b128 v[36:39], v233 offset:16384
	ds_read_b128 v[44:47], v233 offset:17408
	ds_read_b128 v[52:55], v233 offset:18432
	ds_read_b128 v[60:63], v233 offset:19456
	ds_read_b128 v[116:119], v233 offset:20480
	ds_read_b128 v[120:123], v233 offset:21504
	ds_read_b128 v[124:127], v233 offset:22528
	ds_read_b128 v[128:131], v233 offset:23552
	global_load_lds_dwordx4 v[134:135], off
	v_lshl_add_u64 v[134:135], v[246:247], 0, s[74:75]
	s_add_i32 m0, s51, 0x2000
	s_add_i32 s51, s71, s38
	global_load_lds_dwordx4 v[134:135], off
	s_mov_b32 m0, s51
	v_mov_b32_e32 v133, v3
	global_load_lds_dwordx4 v2, s[16:17]
	s_add_i32 m0, s51, 0x2000
	v_lshl_add_u64 v[248:249], s[14:15], 0, v[132:133]
	v_mov_b32_e32 v189, v3
	global_load_lds_dwordx4 v190, s[16:17]
	v_lshl_add_u64 v[134:135], v[248:249], 0, s[74:75]
	s_mov_b32 m0, s56
	v_lshl_add_u64 v[250:251], s[14:15], 0, v[188:189]
	global_load_lds_dwordx4 v[134:135], off
	v_lshl_add_u64 v[134:135], v[250:251], 0, s[74:75]
	s_mov_b32 m0, s57
	s_nop 0
	global_load_lds_dwordx4 v[134:135], off
	s_waitcnt vmcnt(8)
	s_waitcnt lgkmcnt(0)
	s_barrier
	s_setprio 1
	s_waitcnt lgkmcnt(0)
	v_mfma_f32_16x16x32_bf16 v[134:137], v[4:7], v[36:39], 0
	v_mfma_f32_16x16x32_bf16 v[138:141], v[12:15], v[36:39], 0
	v_mfma_f32_16x16x32_bf16 v[142:145], v[4:7], v[52:55], 0
	v_mfma_f32_16x16x32_bf16 v[146:149], v[12:15], v[52:55], 0
	v_mfma_f32_16x16x32_bf16 v[150:153], v[4:7], v[116:119], 0
	v_mfma_f32_16x16x32_bf16 v[154:157], v[12:15], v[116:119], 0
	v_mfma_f32_16x16x32_bf16 v[4:7], v[4:7], v[124:127], 0
	v_mfma_f32_16x16x32_bf16 v[12:15], v[12:15], v[124:127], 0
	v_mfma_f32_16x16x32_bf16 v[134:137], v[8:11], v[44:47], v[134:137]
	v_mfma_f32_16x16x32_bf16 v[138:141], v[16:19], v[44:47], v[138:141]
	v_mfma_f32_16x16x32_bf16 v[142:145], v[8:11], v[60:63], v[142:145]
	v_mfma_f32_16x16x32_bf16 v[146:149], v[16:19], v[60:63], v[146:149]
	v_mfma_f32_16x16x32_bf16 v[150:153], v[8:11], v[120:123], v[150:153]
	v_mfma_f32_16x16x32_bf16 v[154:157], v[16:19], v[120:123], v[154:157]
	v_mfma_f32_16x16x32_bf16 v[158:161], v[8:11], v[128:131], v[4:7]
	v_mfma_f32_16x16x32_bf16 v[162:165], v[16:19], v[128:131], v[12:15]
	s_setprio 0
	s_setprio 1
	v_mfma_f32_16x16x32_bf16 v[4:7], v[20:23], v[36:39], 0
	v_mfma_f32_16x16x32_bf16 v[8:11], v[28:31], v[36:39], 0
	v_mfma_f32_16x16x32_bf16 v[12:15], v[20:23], v[52:55], 0
	v_mfma_f32_16x16x32_bf16 v[16:19], v[28:31], v[52:55], 0
	v_mfma_f32_16x16x32_bf16 v[36:39], v[20:23], v[116:119], 0
	v_mfma_f32_16x16x32_bf16 v[52:55], v[28:31], v[116:119], 0
	v_mfma_f32_16x16x32_bf16 v[20:23], v[20:23], v[124:127], 0
	v_mfma_f32_16x16x32_bf16 v[28:31], v[28:31], v[124:127], 0
	v_mfma_f32_16x16x32_bf16 v[116:119], v[24:27], v[44:47], v[4:7]
	v_mfma_f32_16x16x32_bf16 v[124:127], v[32:35], v[44:47], v[8:11]
	v_mfma_f32_16x16x32_bf16 v[174:177], v[24:27], v[120:123], v[36:39]
	v_mfma_f32_16x16x32_bf16 v[120:123], v[32:35], v[120:123], v[52:55]
	v_mfma_f32_16x16x32_bf16 v[178:181], v[24:27], v[128:131], v[20:23]
	v_mfma_f32_16x16x32_bf16 v[128:131], v[32:35], v[128:131], v[28:31]
	s_setprio 2
	s_barrier
	v_mfma_f32_16x16x32_bf16 v[166:169], v[24:27], v[60:63], v[12:15]
	v_mfma_f32_16x16x32_bf16 v[170:173], v[32:35], v[60:63], v[16:19]
	s_setprio 0
	s_add_i32 s51, 0, 0x18000
	v_add_u32_e32 v4, s51, v232
	s_add_i32 s71, 0, 0x1c000
	ds_read_b128 v[182:185], v4
	ds_read_b128 v[192:195], v4 offset:1024
	ds_read_b128 v[196:199], v4 offset:2048
	ds_read_b128 v[200:203], v4 offset:3072
	v_add_u32_e32 v4, s71, v232
	ds_read_b128 v[204:207], v4
	ds_read_b128 v[208:211], v4 offset:1024
	ds_read_b128 v[212:215], v4 offset:2048
	ds_read_b128 v[216:219], v4 offset:3072
	s_mov_b32 m0, s58
	ds_read_b128 v[44:47], v233 offset:32768
	ds_read_b128 v[52:55], v233 offset:33792
	ds_read_b128 v[60:63], v233 offset:34816
	ds_read_b128 v[220:223], v233 offset:35840
	ds_read_b128 v[224:227], v233 offset:36864
	ds_read_b128 v[234:237], v233 offset:37888
	ds_read_b128 v[238:241], v233 offset:38912
	ds_read_b128 v[242:245], v233 offset:39936
	global_load_lds_dwordx4 v132, s[26:27]
	s_mov_b32 m0, s59
	s_nop 0
	global_load_lds_dwordx4 v188, s[26:27]
	s_waitcnt vmcnt(8)
	s_waitcnt lgkmcnt(0)
	s_barrier
	s_setprio 1
	s_waitcnt lgkmcnt(0)
	v_mfma_f32_16x16x32_bf16 v[4:7], v[182:185], v[44:47], v[68:71]
	v_mfma_f32_16x16x32_bf16 v[8:11], v[196:199], v[44:47], v[72:75]
	v_mfma_f32_16x16x32_bf16 v[12:15], v[182:185], v[60:63], v[76:79]
	v_mfma_f32_16x16x32_bf16 v[16:19], v[196:199], v[60:63], v[80:83]
	v_mfma_f32_16x16x32_bf16 v[20:23], v[182:185], v[224:227], v[84:87]
	v_mfma_f32_16x16x32_bf16 v[24:27], v[196:199], v[224:227], v[88:91]
	v_mfma_f32_16x16x32_bf16 v[28:31], v[182:185], v[238:241], v[92:95]
	v_mfma_f32_16x16x32_bf16 v[32:35], v[196:199], v[238:241], v[96:99]
	v_mfma_f32_16x16x32_bf16 v[4:7], v[192:195], v[52:55], v[4:7]
	v_mfma_f32_16x16x32_bf16 v[8:11], v[200:203], v[52:55], v[8:11]
	v_mfma_f32_16x16x32_bf16 v[12:15], v[192:195], v[220:223], v[12:15]
	v_mfma_f32_16x16x32_bf16 v[16:19], v[200:203], v[220:223], v[16:19]
	v_mfma_f32_16x16x32_bf16 v[20:23], v[192:195], v[234:237], v[20:23]
	v_mfma_f32_16x16x32_bf16 v[24:27], v[200:203], v[234:237], v[24:27]
	v_mfma_f32_16x16x32_bf16 v[28:31], v[192:195], v[242:245], v[28:31]
	v_mfma_f32_16x16x32_bf16 v[32:35], v[200:203], v[242:245], v[32:35]
	s_setprio 0
	s_setprio 1
	v_mfma_f32_16x16x32_bf16 v[36:39], v[204:207], v[44:47], v[100:103]
	v_mfma_f32_16x16x32_bf16 v[40:43], v[212:215], v[44:47], v[40:43]
	v_mfma_f32_16x16x32_bf16 v[36:39], v[208:211], v[52:55], v[36:39]
	v_mfma_f32_16x16x32_bf16 v[40:43], v[216:219], v[52:55], v[40:43]
	v_mfma_f32_16x16x32_bf16 v[44:47], v[204:207], v[60:63], v[104:107]
	v_mfma_f32_16x16x32_bf16 v[48:51], v[212:215], v[60:63], v[48:51]
	v_mfma_f32_16x16x32_bf16 v[52:55], v[204:207], v[224:227], v[108:111]
	v_mfma_f32_16x16x32_bf16 v[56:59], v[212:215], v[224:227], v[56:59]
	v_mfma_f32_16x16x32_bf16 v[60:63], v[204:207], v[238:241], v[112:115]
	v_mfma_f32_16x16x32_bf16 v[64:67], v[212:215], v[238:241], v[64:67]
	v_mfma_f32_16x16x32_bf16 v[44:47], v[208:211], v[220:223], v[44:47]
	v_mfma_f32_16x16x32_bf16 v[48:51], v[216:219], v[220:223], v[48:51]
	v_mfma_f32_16x16x32_bf16 v[52:55], v[208:211], v[234:237], v[52:55]
	v_mfma_f32_16x16x32_bf16 v[56:59], v[216:219], v[234:237], v[56:59]
	s_setprio 2
	s_barrier
	v_mfma_f32_16x16x32_bf16 v[60:63], v[208:211], v[242:245], v[60:63]
	v_mfma_f32_16x16x32_bf16 v[64:67], v[216:219], v[242:245], v[64:67]
	s_setprio 0
	s_add_i32 s51, s51, s38
	v_lshl_add_u64 v[68:69], v[186:187], 0, s[24:25]
	s_mov_b32 m0, s51
	ds_read_b128 v[104:107], v233 offset:49152
	ds_read_b128 v[108:111], v233 offset:50176
	ds_read_b128 v[112:115], v233 offset:51200
	ds_read_b128 v[220:223], v233 offset:52224
	ds_read_b128 v[224:227], v233 offset:53248
	ds_read_b128 v[234:237], v233 offset:54272
	ds_read_b128 v[238:241], v233 offset:55296
	ds_read_b128 v[242:245], v233 offset:56320
	global_load_lds_dwordx4 v[68:69], off
	v_lshl_add_u64 v[68:69], v[246:247], 0, s[24:25]
	s_add_i32 m0, s51, 0x2000
	s_add_i32 s51, s71, s38
	global_load_lds_dwordx4 v[68:69], off
	s_mov_b32 m0, s51
	v_lshl_add_u64 v[68:69], v[248:249], 0, s[24:25]
	global_load_lds_dwordx4 v2, s[28:29]
	s_add_i32 m0, s51, 0x2000
	s_nop 0
	global_load_lds_dwordx4 v190, s[28:29]
	s_mov_b32 m0, s63
	s_nop 0
	global_load_lds_dwordx4 v[68:69], off
	v_lshl_add_u64 v[68:69], v[250:251], 0, s[24:25]
	s_mov_b32 m0, s64
	s_nop 0
	global_load_lds_dwordx4 v[68:69], off
	s_waitcnt vmcnt(8)
	s_waitcnt lgkmcnt(0)
	s_barrier
	s_setprio 1
	s_waitcnt lgkmcnt(0)
	v_mfma_f32_16x16x32_bf16 v[68:71], v[182:185], v[104:107], v[134:137]
	v_mfma_f32_16x16x32_bf16 v[72:75], v[196:199], v[104:107], v[138:141]
	v_mfma_f32_16x16x32_bf16 v[76:79], v[182:185], v[112:115], v[142:145]
	v_mfma_f32_16x16x32_bf16 v[80:83], v[196:199], v[112:115], v[146:149]
	v_mfma_f32_16x16x32_bf16 v[84:87], v[182:185], v[224:227], v[150:153]
	v_mfma_f32_16x16x32_bf16 v[88:91], v[196:199], v[224:227], v[154:157]
	v_mfma_f32_16x16x32_bf16 v[92:95], v[182:185], v[238:241], v[158:161]
	v_mfma_f32_16x16x32_bf16 v[96:99], v[196:199], v[238:241], v[162:165]
	v_mfma_f32_16x16x32_bf16 v[68:71], v[192:195], v[108:111], v[68:71]
	v_mfma_f32_16x16x32_bf16 v[72:75], v[200:203], v[108:111], v[72:75]
	v_mfma_f32_16x16x32_bf16 v[76:79], v[192:195], v[220:223], v[76:79]
	v_mfma_f32_16x16x32_bf16 v[80:83], v[200:203], v[220:223], v[80:83]
	v_mfma_f32_16x16x32_bf16 v[84:87], v[192:195], v[234:237], v[84:87]
	v_mfma_f32_16x16x32_bf16 v[88:91], v[200:203], v[234:237], v[88:91]
	v_mfma_f32_16x16x32_bf16 v[92:95], v[192:195], v[242:245], v[92:95]
	v_mfma_f32_16x16x32_bf16 v[96:99], v[200:203], v[242:245], v[96:99]
	s_setprio 0
	s_setprio 1
	v_mfma_f32_16x16x32_bf16 v[100:103], v[204:207], v[104:107], v[116:119]
	v_mfma_f32_16x16x32_bf16 v[104:107], v[212:215], v[104:107], v[124:127]
	v_mfma_f32_16x16x32_bf16 v[100:103], v[208:211], v[108:111], v[100:103]
	v_mfma_f32_16x16x32_bf16 v[104:107], v[216:219], v[108:111], v[104:107]
	v_mfma_f32_16x16x32_bf16 v[108:111], v[204:207], v[112:115], v[166:169]
	v_mfma_f32_16x16x32_bf16 v[112:115], v[212:215], v[112:115], v[170:173]
	v_mfma_f32_16x16x32_bf16 v[116:119], v[204:207], v[224:227], v[174:177]
	v_mfma_f32_16x16x32_bf16 v[120:123], v[212:215], v[224:227], v[120:123]
	v_mfma_f32_16x16x32_bf16 v[124:127], v[204:207], v[238:241], v[178:181]
	v_mfma_f32_16x16x32_bf16 v[128:131], v[212:215], v[238:241], v[128:131]
	v_mfma_f32_16x16x32_bf16 v[108:111], v[208:211], v[220:223], v[108:111]
	v_mfma_f32_16x16x32_bf16 v[112:115], v[216:219], v[220:223], v[112:115]
	v_mfma_f32_16x16x32_bf16 v[116:119], v[208:211], v[234:237], v[116:119]
	v_mfma_f32_16x16x32_bf16 v[120:123], v[216:219], v[234:237], v[120:123]
	s_setprio 2
	s_barrier
	v_mfma_f32_16x16x32_bf16 v[124:127], v[208:211], v[242:245], v[124:127]
	v_mfma_f32_16x16x32_bf16 v[128:131], v[216:219], v[242:245], v[128:131]
	s_setprio 0
	s_add_i32 s45, s45, 2
	s_cmp_ge_i32 s45, s44
	s_cbranch_scc0 .LBB0_2065
	v_mov_b32_e32 v192, v2
	s_branch .LBB0_2068

.LBB0_2069:
	s_add_u32 s12, s14, 0xfff80080
	s_addc_u32 s13, s15, -1
	s_add_i32 s29, 0, 0x10000
	s_cmp_eq_u32 s28, 4
	s_cselect_b32 s17, s9, s13
	s_cselect_b32 s16, s8, s12
	s_cselect_b32 s13, s11, s27
	s_cselect_b32 s12, s10, s26
	s_add_i32 s51, 0, 0x14000
	v_add_u32_e32 v144, s29, v232
	v_add_u32_e32 v160, s51, v232
	s_waitcnt lgkmcnt(0)
	ds_read_b128 v[132:135], v144
	ds_read_b128 v[136:139], v144 offset:1024
	ds_read_b128 v[140:143], v144 offset:2048
	ds_read_b128 v[144:147], v144 offset:3072
	ds_read_b128 v[148:151], v160
	ds_read_b128 v[152:155], v160 offset:1024
	ds_read_b128 v[156:159], v160 offset:2048
	ds_read_b128 v[160:163], v160 offset:3072
	s_mov_b32 m0, s65
	v_add_u32_e32 v210, 0, v231
	ds_read_b128 v[164:167], v210
	ds_read_b128 v[168:171], v210 offset:1024
	ds_read_b128 v[172:175], v210 offset:2048
	ds_read_b128 v[176:179], v210 offset:3072
	ds_read_b128 v[180:183], v210 offset:4096
	ds_read_b128 v[184:187], v210 offset:5120
	ds_read_b128 v[194:197], v210 offset:6144
	ds_read_b128 v[198:201], v210 offset:7168
	global_load_lds_dwordx4 v2, s[14:15]
	s_mov_b32 m0, s66
	v_mov_b32_e32 v189, v3
	global_load_lds_dwordx4 v188, s[14:15]
	s_waitcnt vmcnt(8)
	s_waitcnt lgkmcnt(0)
	s_barrier
	s_setprio 1
	s_waitcnt lgkmcnt(0)
	v_mfma_f32_16x16x32_bf16 v[4:7], v[132:135], v[164:167], v[4:7]
	v_mfma_f32_16x16x32_bf16 v[4:7], v[136:139], v[168:171], v[4:7]
	v_mfma_f32_16x16x32_bf16 v[8:11], v[144:147], v[168:171], v[8:11]
	v_mfma_f32_16x16x32_bf16 v[8:11], v[140:143], v[164:167], v[8:11]
	v_mfma_f32_16x16x32_bf16 v[16:19], v[140:143], v[172:175], v[16:19]
	v_mfma_f32_16x16x32_bf16 v[16:19], v[144:147], v[176:179], v[16:19]
	v_mfma_f32_16x16x32_bf16 v[12:15], v[136:139], v[176:179], v[12:15]
	v_mfma_f32_16x16x32_bf16 v[12:15], v[132:135], v[172:175], v[12:15]
	v_mfma_f32_16x16x32_bf16 v[20:23], v[132:135], v[180:183], v[20:23]
	v_mfma_f32_16x16x32_bf16 v[20:23], v[136:139], v[184:187], v[20:23]
	v_mfma_f32_16x16x32_bf16 v[24:27], v[144:147], v[184:187], v[24:27]
	v_mfma_f32_16x16x32_bf16 v[24:27], v[140:143], v[180:183], v[24:27]
	v_mfma_f32_16x16x32_bf16 v[32:35], v[140:143], v[194:197], v[32:35]
	v_mfma_f32_16x16x32_bf16 v[32:35], v[144:147], v[198:201], v[32:35]
	v_mfma_f32_16x16x32_bf16 v[28:31], v[136:139], v[198:201], v[28:31]
	v_mfma_f32_16x16x32_bf16 v[28:31], v[132:135], v[194:197], v[28:31]
	s_setprio 0
	s_setprio 1
	v_mfma_f32_16x16x32_bf16 v[36:39], v[148:151], v[164:167], v[36:39]
	v_mfma_f32_16x16x32_bf16 v[36:39], v[152:155], v[168:171], v[36:39]
	v_mfma_f32_16x16x32_bf16 v[40:43], v[160:163], v[168:171], v[40:43]
	v_mfma_f32_16x16x32_bf16 v[40:43], v[156:159], v[164:167], v[40:43]
	v_mfma_f32_16x16x32_bf16 v[48:51], v[156:159], v[172:175], v[48:51]
	v_mfma_f32_16x16x32_bf16 v[48:51], v[160:163], v[176:179], v[48:51]
	v_mfma_f32_16x16x32_bf16 v[44:47], v[152:155], v[176:179], v[44:47]
	v_mfma_f32_16x16x32_bf16 v[44:47], v[148:151], v[172:175], v[44:47]
	v_mfma_f32_16x16x32_bf16 v[52:55], v[148:151], v[180:183], v[52:55]
	v_mfma_f32_16x16x32_bf16 v[52:55], v[152:155], v[184:187], v[52:55]
	v_mfma_f32_16x16x32_bf16 v[56:59], v[160:163], v[184:187], v[56:59]
	v_mfma_f32_16x16x32_bf16 v[56:59], v[156:159], v[180:183], v[56:59]
	v_mfma_f32_16x16x32_bf16 v[64:67], v[156:159], v[194:197], v[64:67]
	v_mfma_f32_16x16x32_bf16 v[64:67], v[160:163], v[198:201], v[64:67]
	s_setprio 2
	s_barrier
	v_mfma_f32_16x16x32_bf16 v[60:63], v[152:155], v[198:201], v[60:63]
	v_mfma_f32_16x16x32_bf16 v[60:63], v[148:151], v[194:197], v[60:63]
	s_setprio 0
	s_add_i32 s29, s29, s38
	s_mov_b32 m0, s29
	ds_read_b128 v[164:167], v210 offset:16384
	ds_read_b128 v[168:171], v210 offset:17408
	ds_read_b128 v[172:175], v210 offset:18432
	ds_read_b128 v[176:179], v210 offset:19456
	ds_read_b128 v[180:183], v210 offset:20480
	ds_read_b128 v[184:187], v210 offset:21504
	ds_read_b128 v[194:197], v210 offset:22528
	ds_read_b128 v[198:201], v210 offset:23552
	global_load_lds_dwordx4 v192, s[12:13]
	s_add_i32 m0, s29, 0x2000
	s_add_u32 s44, s12, 0x20000
	s_addc_u32 s45, s13, 0
	s_add_i32 s29, s51, s38
	global_load_lds_dwordx4 v190, s[12:13]
	s_mov_b32 m0, s29
	v_mov_b32_e32 v193, v3
	global_load_lds_dwordx4 v192, s[44:45]
	s_add_i32 m0, s29, 0x2000
	v_mov_b32_e32 v191, v3
	global_load_lds_dwordx4 v190, s[44:45]
	s_mov_b32 m0, s56
	v_lshl_add_u64 v[202:203], s[12:13], 0, v[192:193]
	global_load_lds_dwordx4 v2, s[16:17]
	s_mov_b32 m0, s57
	v_lshl_add_u64 v[204:205], s[12:13], 0, v[190:191]
	global_load_lds_dwordx4 v188, s[16:17]
	s_waitcnt vmcnt(8)
	s_waitcnt lgkmcnt(0)
	v_lshl_add_u64 v[206:207], s[16:17], 0, v[2:3]
	v_lshl_add_u64 v[208:209], s[16:17], 0, v[188:189]
	s_barrier
	s_setprio 1
	s_waitcnt lgkmcnt(0)
	v_mfma_f32_16x16x32_bf16 v[68:71], v[132:135], v[164:167], v[68:71]
	v_mfma_f32_16x16x32_bf16 v[68:71], v[136:139], v[168:171], v[68:71]
	v_mfma_f32_16x16x32_bf16 v[72:75], v[144:147], v[168:171], v[72:75]
	v_mfma_f32_16x16x32_bf16 v[72:75], v[140:143], v[164:167], v[72:75]
	v_mfma_f32_16x16x32_bf16 v[80:83], v[140:143], v[172:175], v[80:83]
	v_mfma_f32_16x16x32_bf16 v[80:83], v[144:147], v[176:179], v[80:83]
	v_mfma_f32_16x16x32_bf16 v[76:79], v[136:139], v[176:179], v[76:79]
	v_mfma_f32_16x16x32_bf16 v[76:79], v[132:135], v[172:175], v[76:79]
	v_mfma_f32_16x16x32_bf16 v[84:87], v[132:135], v[180:183], v[84:87]
	v_mfma_f32_16x16x32_bf16 v[84:87], v[136:139], v[184:187], v[84:87]
	v_mfma_f32_16x16x32_bf16 v[88:91], v[144:147], v[184:187], v[88:91]
	v_mfma_f32_16x16x32_bf16 v[88:91], v[140:143], v[180:183], v[88:91]
	v_mfma_f32_16x16x32_bf16 v[96:99], v[140:143], v[194:197], v[96:99]
	v_mfma_f32_16x16x32_bf16 v[96:99], v[144:147], v[198:201], v[96:99]
	v_mfma_f32_16x16x32_bf16 v[92:95], v[136:139], v[198:201], v[92:95]
	v_mfma_f32_16x16x32_bf16 v[92:95], v[132:135], v[194:197], v[92:95]
	s_setprio 0
	s_setprio 1
	v_mfma_f32_16x16x32_bf16 v[100:103], v[148:151], v[164:167], v[100:103]
	v_mfma_f32_16x16x32_bf16 v[100:103], v[152:155], v[168:171], v[100:103]
	v_mfma_f32_16x16x32_bf16 v[104:107], v[160:163], v[168:171], v[104:107]
	v_mfma_f32_16x16x32_bf16 v[104:107], v[156:159], v[164:167], v[104:107]
	v_mfma_f32_16x16x32_bf16 v[112:115], v[156:159], v[172:175], v[112:115]
	v_mfma_f32_16x16x32_bf16 v[112:115], v[160:163], v[176:179], v[112:115]
	v_mfma_f32_16x16x32_bf16 v[108:111], v[152:155], v[176:179], v[108:111]
	v_mfma_f32_16x16x32_bf16 v[108:111], v[148:151], v[172:175], v[108:111]
	v_mfma_f32_16x16x32_bf16 v[116:119], v[148:151], v[180:183], v[116:119]
	v_mfma_f32_16x16x32_bf16 v[116:119], v[152:155], v[184:187], v[116:119]
	v_mfma_f32_16x16x32_bf16 v[120:123], v[160:163], v[184:187], v[120:123]
	v_mfma_f32_16x16x32_bf16 v[120:123], v[156:159], v[180:183], v[120:123]
	v_mfma_f32_16x16x32_bf16 v[128:131], v[156:159], v[194:197], v[128:131]
	v_mfma_f32_16x16x32_bf16 v[128:131], v[160:163], v[198:201], v[128:131]
	s_setprio 2
	s_barrier
	v_mfma_f32_16x16x32_bf16 v[124:127], v[152:155], v[198:201], v[124:127]
	v_mfma_f32_16x16x32_bf16 v[124:127], v[148:151], v[194:197], v[124:127]
	s_setprio 0
	s_add_i32 s29, 0, 0x18000
	s_add_i32 s44, 0, 0x1c000
	v_add_u32_e32 v144, s29, v232
	v_add_u32_e32 v160, s44, v232
	ds_read_b128 v[132:135], v144
	ds_read_b128 v[136:139], v144 offset:1024
	ds_read_b128 v[140:143], v144 offset:2048
	ds_read_b128 v[144:147], v144 offset:3072
	ds_read_b128 v[148:151], v160
	ds_read_b128 v[152:155], v160 offset:1024
	ds_read_b128 v[156:159], v160 offset:2048
	ds_read_b128 v[160:163], v160 offset:3072
	s_add_u32 s16, s16, 0x80000
	s_addc_u32 s17, s17, 0
	s_mov_b32 m0, s58
	ds_read_b128 v[164:167], v210 offset:32768
	ds_read_b128 v[168:171], v210 offset:33792
	ds_read_b128 v[172:175], v210 offset:34816
	ds_read_b128 v[176:179], v210 offset:35840
	ds_read_b128 v[180:183], v210 offset:36864
	ds_read_b128 v[184:187], v210 offset:37888
	ds_read_b128 v[194:197], v210 offset:38912
	ds_read_b128 v[198:201], v210 offset:39936
	global_load_lds_dwordx4 v2, s[16:17]
	s_mov_b32 m0, s59
	s_nop 0
	global_load_lds_dwordx4 v188, s[16:17]
	s_waitcnt vmcnt(8)
	s_waitcnt lgkmcnt(0)
	s_barrier
	s_setprio 1
	s_waitcnt lgkmcnt(0)
	v_mfma_f32_16x16x32_bf16 v[4:7], v[132:135], v[164:167], v[4:7]
	v_mfma_f32_16x16x32_bf16 v[4:7], v[136:139], v[168:171], v[4:7]
	v_mfma_f32_16x16x32_bf16 v[8:11], v[144:147], v[168:171], v[8:11]
	v_mfma_f32_16x16x32_bf16 v[8:11], v[140:143], v[164:167], v[8:11]
	v_mfma_f32_16x16x32_bf16 v[16:19], v[140:143], v[172:175], v[16:19]
	v_mfma_f32_16x16x32_bf16 v[16:19], v[144:147], v[176:179], v[16:19]
	v_mfma_f32_16x16x32_bf16 v[12:15], v[136:139], v[176:179], v[12:15]
	v_mfma_f32_16x16x32_bf16 v[12:15], v[132:135], v[172:175], v[12:15]
	v_mfma_f32_16x16x32_bf16 v[20:23], v[132:135], v[180:183], v[20:23]
	v_mfma_f32_16x16x32_bf16 v[20:23], v[136:139], v[184:187], v[20:23]
	v_mfma_f32_16x16x32_bf16 v[24:27], v[144:147], v[184:187], v[24:27]
	v_mfma_f32_16x16x32_bf16 v[24:27], v[140:143], v[180:183], v[24:27]
	v_mfma_f32_16x16x32_bf16 v[32:35], v[140:143], v[194:197], v[32:35]
	v_mfma_f32_16x16x32_bf16 v[32:35], v[144:147], v[198:201], v[32:35]
	v_mfma_f32_16x16x32_bf16 v[28:31], v[136:139], v[198:201], v[28:31]
	v_mfma_f32_16x16x32_bf16 v[28:31], v[132:135], v[194:197], v[28:31]
	s_setprio 0
	s_setprio 1
	v_mfma_f32_16x16x32_bf16 v[36:39], v[148:151], v[164:167], v[36:39]
	v_mfma_f32_16x16x32_bf16 v[36:39], v[152:155], v[168:171], v[36:39]
	v_mfma_f32_16x16x32_bf16 v[40:43], v[160:163], v[168:171], v[40:43]
	v_mfma_f32_16x16x32_bf16 v[40:43], v[156:159], v[164:167], v[40:43]
	v_mfma_f32_16x16x32_bf16 v[48:51], v[156:159], v[172:175], v[48:51]
	v_mfma_f32_16x16x32_bf16 v[48:51], v[160:163], v[176:179], v[48:51]
	v_mfma_f32_16x16x32_bf16 v[44:47], v[152:155], v[176:179], v[44:47]
	v_mfma_f32_16x16x32_bf16 v[44:47], v[148:151], v[172:175], v[44:47]
	v_mfma_f32_16x16x32_bf16 v[52:55], v[148:151], v[180:183], v[52:55]
	v_mfma_f32_16x16x32_bf16 v[52:55], v[152:155], v[184:187], v[52:55]
	v_mfma_f32_16x16x32_bf16 v[56:59], v[160:163], v[184:187], v[56:59]
	v_mfma_f32_16x16x32_bf16 v[56:59], v[156:159], v[180:183], v[56:59]
	v_mfma_f32_16x16x32_bf16 v[64:67], v[156:159], v[194:197], v[64:67]
	v_mfma_f32_16x16x32_bf16 v[64:67], v[160:163], v[198:201], v[64:67]
	s_setprio 2
	s_barrier
	v_mfma_f32_16x16x32_bf16 v[60:63], v[152:155], v[198:201], v[60:63]
	v_mfma_f32_16x16x32_bf16 v[60:63], v[148:151], v[194:197], v[60:63]
	s_setprio 0
	s_add_i32 s16, s29, s38
	v_lshl_add_u64 v[202:203], v[202:203], 0, s[86:87]
	s_mov_b32 m0, s16
	ds_read_b128 v[164:167], v210 offset:49152
	ds_read_b128 v[168:171], v210 offset:50176
	ds_read_b128 v[172:175], v210 offset:51200
	ds_read_b128 v[176:179], v210 offset:52224
	ds_read_b128 v[180:183], v210 offset:53248
	ds_read_b128 v[184:187], v210 offset:54272
	ds_read_b128 v[194:197], v210 offset:55296
	ds_read_b128 v[198:201], v210 offset:56320
	global_load_lds_dwordx4 v[202:203], off
	s_add_i32 m0, s16, 0x2000
	s_add_u32 s12, s12, 0x20080
	v_lshl_add_u64 v[202:203], v[204:205], 0, s[86:87]
	s_addc_u32 s13, s13, 0
	s_add_i32 s16, s44, s38
	global_load_lds_dwordx4 v[202:203], off
	s_mov_b32 m0, s16
	v_lshl_add_u64 v[202:203], v[206:207], 0, s[86:87]
	global_load_lds_dwordx4 v192, s[12:13]
	s_add_i32 m0, s16, 0x2000
	s_nop 0
	global_load_lds_dwordx4 v190, s[12:13]
	s_mov_b32 m0, s63
	s_nop 0
	global_load_lds_dwordx4 v[202:203], off
	v_lshl_add_u64 v[202:203], v[208:209], 0, s[86:87]
	s_mov_b32 m0, s64
	s_nop 0
	global_load_lds_dwordx4 v[202:203], off
	s_waitcnt vmcnt(8)
	s_waitcnt lgkmcnt(0)
	s_barrier
	s_setprio 1
	s_waitcnt lgkmcnt(0)
	v_mfma_f32_16x16x32_bf16 v[68:71], v[132:135], v[164:167], v[68:71]
	v_mfma_f32_16x16x32_bf16 v[68:71], v[136:139], v[168:171], v[68:71]
	v_mfma_f32_16x16x32_bf16 v[72:75], v[144:147], v[168:171], v[72:75]
	v_mfma_f32_16x16x32_bf16 v[72:75], v[140:143], v[164:167], v[72:75]
	v_mfma_f32_16x16x32_bf16 v[80:83], v[140:143], v[172:175], v[80:83]
	v_mfma_f32_16x16x32_bf16 v[80:83], v[144:147], v[176:179], v[80:83]
	v_mfma_f32_16x16x32_bf16 v[76:79], v[136:139], v[176:179], v[76:79]
	v_mfma_f32_16x16x32_bf16 v[76:79], v[132:135], v[172:175], v[76:79]
	v_mfma_f32_16x16x32_bf16 v[84:87], v[132:135], v[180:183], v[84:87]
	v_mfma_f32_16x16x32_bf16 v[84:87], v[136:139], v[184:187], v[84:87]
	v_mfma_f32_16x16x32_bf16 v[88:91], v[144:147], v[184:187], v[88:91]
	v_mfma_f32_16x16x32_bf16 v[88:91], v[140:143], v[180:183], v[88:91]
	v_mfma_f32_16x16x32_bf16 v[96:99], v[140:143], v[194:197], v[96:99]
	v_mfma_f32_16x16x32_bf16 v[96:99], v[144:147], v[198:201], v[96:99]
	v_mfma_f32_16x16x32_bf16 v[92:95], v[136:139], v[198:201], v[92:95]
	v_mfma_f32_16x16x32_bf16 v[92:95], v[132:135], v[194:197], v[92:95]
	s_setprio 0
	s_setprio 1
	v_mfma_f32_16x16x32_bf16 v[100:103], v[148:151], v[164:167], v[100:103]
	v_mfma_f32_16x16x32_bf16 v[100:103], v[152:155], v[168:171], v[100:103]
	v_mfma_f32_16x16x32_bf16 v[104:107], v[160:163], v[168:171], v[104:107]
	v_mfma_f32_16x16x32_bf16 v[104:107], v[156:159], v[164:167], v[104:107]
	v_mfma_f32_16x16x32_bf16 v[112:115], v[156:159], v[172:175], v[112:115]
	v_mfma_f32_16x16x32_bf16 v[112:115], v[160:163], v[176:179], v[112:115]
	v_mfma_f32_16x16x32_bf16 v[108:111], v[152:155], v[176:179], v[108:111]
	v_mfma_f32_16x16x32_bf16 v[108:111], v[148:151], v[172:175], v[108:111]
	v_mfma_f32_16x16x32_bf16 v[116:119], v[148:151], v[180:183], v[116:119]
	v_mfma_f32_16x16x32_bf16 v[116:119], v[152:155], v[184:187], v[116:119]
	v_mfma_f32_16x16x32_bf16 v[120:123], v[160:163], v[184:187], v[120:123]
	v_mfma_f32_16x16x32_bf16 v[120:123], v[156:159], v[180:183], v[120:123]
	v_mfma_f32_16x16x32_bf16 v[128:131], v[156:159], v[194:197], v[128:131]
	v_mfma_f32_16x16x32_bf16 v[128:131], v[160:163], v[198:201], v[128:131]
	s_setprio 2
	s_barrier
	v_mfma_f32_16x16x32_bf16 v[124:127], v[152:155], v[198:201], v[124:127]
	v_mfma_f32_16x16x32_bf16 v[124:127], v[148:151], v[194:197], v[124:127]
	s_setprio 0
	s_add_i32 s28, s28, 2
	s_add_u32 s14, s14, 0x100
	s_addc_u32 s15, s15, 0
	s_add_u32 s26, s26, 0x100
	s_addc_u32 s27, s27, 0
	s_cmp_gt_u32 s28, 5
	s_cbranch_scc0 .LBB0_2069
	s_and_b64 vcc, exec, s[48:49]
	s_cbranch_vccz .LBB0_2072
	s_barrier

.LBB0_2159:
	s_add_i32 s68, 0, 0x10000
	s_add_i32 s69, 0, 0x14000
	v_add_u32_e32 v16, s68, v143
	v_add_u32_e32 v32, s69, v143
	ds_read_b128 v[4:7], v16
	ds_read_b128 v[8:11], v16 offset:1024
	ds_read_b128 v[12:15], v16 offset:2048
	ds_read_b128 v[16:19], v16 offset:3072
	ds_read_b128 v[20:23], v32
	ds_read_b128 v[24:27], v32 offset:1024
	ds_read_b128 v[28:31], v32 offset:2048
	ds_read_b128 v[32:35], v32 offset:3072
	v_add_u32_e32 v231, 0, v142
	ds_read_b128 v[36:39], v231
	ds_read_b128 v[40:43], v231 offset:1024
	ds_read_b128 v[44:47], v231 offset:2048
	ds_read_b128 v[48:51], v231 offset:3072
	ds_read_b128 v[52:55], v231 offset:4096
	ds_read_b128 v[56:59], v231 offset:5120
	ds_read_b128 v[60:63], v231 offset:6144
	ds_read_b128 v[64:67], v231 offset:7168
	s_waitcnt vmcnt(8)
	s_waitcnt lgkmcnt(0)
	s_barrier
	s_setprio 1
	s_waitcnt lgkmcnt(0)
	v_mfma_f32_16x16x32_f16 v[68:71], v[4:7], v[36:39], 0
	v_mfma_f32_16x16x32_f16 v[72:75], v[12:15], v[36:39], 0
	v_mfma_f32_16x16x32_f16 v[76:79], v[4:7], v[44:47], 0
	v_mfma_f32_16x16x32_f16 v[80:83], v[12:15], v[44:47], 0
	v_mfma_f32_16x16x32_f16 v[84:87], v[4:7], v[52:55], 0
	v_mfma_f32_16x16x32_f16 v[88:91], v[12:15], v[52:55], 0
	v_mfma_f32_16x16x32_f16 v[92:95], v[4:7], v[60:63], 0
	v_mfma_f32_16x16x32_f16 v[96:99], v[12:15], v[60:63], 0
	v_mfma_f32_16x16x32_f16 v[68:71], v[8:11], v[40:43], v[68:71]
	v_mfma_f32_16x16x32_f16 v[72:75], v[16:19], v[40:43], v[72:75]
	v_mfma_f32_16x16x32_f16 v[76:79], v[8:11], v[48:51], v[76:79]
	v_mfma_f32_16x16x32_f16 v[80:83], v[16:19], v[48:51], v[80:83]
	v_mfma_f32_16x16x32_f16 v[84:87], v[8:11], v[56:59], v[84:87]
	v_mfma_f32_16x16x32_f16 v[88:91], v[16:19], v[56:59], v[88:91]
	v_mfma_f32_16x16x32_f16 v[92:95], v[8:11], v[64:67], v[92:95]
	v_mfma_f32_16x16x32_f16 v[100:103], v[16:19], v[64:67], v[96:99]
	s_setprio 0
	s_setprio 1
	v_mfma_f32_16x16x32_f16 v[96:99], v[20:23], v[36:39], 0
	v_mfma_f32_16x16x32_f16 v[36:39], v[28:31], v[36:39], 0
	v_mfma_f32_16x16x32_f16 v[104:107], v[20:23], v[44:47], 0
	v_mfma_f32_16x16x32_f16 v[44:47], v[28:31], v[44:47], 0
	v_mfma_f32_16x16x32_f16 v[108:111], v[20:23], v[52:55], 0
	v_mfma_f32_16x16x32_f16 v[52:55], v[28:31], v[52:55], 0
	v_mfma_f32_16x16x32_f16 v[112:115], v[20:23], v[60:63], 0
	v_mfma_f32_16x16x32_f16 v[60:63], v[28:31], v[60:63], 0
	v_mfma_f32_16x16x32_f16 v[116:119], v[24:27], v[40:43], v[96:99]
	v_mfma_f32_16x16x32_f16 v[36:39], v[32:35], v[40:43], v[36:39]
	v_mfma_f32_16x16x32_f16 v[40:43], v[24:27], v[48:51], v[104:107]
	v_mfma_f32_16x16x32_f16 v[44:47], v[32:35], v[48:51], v[44:47]
	v_mfma_f32_16x16x32_f16 v[48:51], v[24:27], v[56:59], v[108:111]
	v_mfma_f32_16x16x32_f16 v[52:55], v[32:35], v[56:59], v[52:55]
	s_setprio 2
	s_barrier
	v_mfma_f32_16x16x32_f16 v[56:59], v[24:27], v[64:67], v[112:115]
	v_mfma_f32_16x16x32_f16 v[60:63], v[32:35], v[64:67], v[60:63]
	s_setprio 0
	v_lshl_add_u64 v[138:139], s[8:9], 0, v[2:3]
	s_add_i32 s68, s68, s53
	v_mov_b32_e32 v135, v3
	v_lshl_add_u64 v[144:145], v[138:139], 0, s[74:75]
	s_mov_b32 m0, s68
	v_lshl_add_u64 v[192:193], s[8:9], 0, v[134:135]
	ds_read_b128 v[64:67], v231 offset:16384
	ds_read_b128 v[96:99], v231 offset:17408
	ds_read_b128 v[104:107], v231 offset:18432
	ds_read_b128 v[108:111], v231 offset:19456
	ds_read_b128 v[112:115], v231 offset:20480
	ds_read_b128 v[120:123], v231 offset:21504
	ds_read_b128 v[124:127], v231 offset:22528
	ds_read_b128 v[128:131], v231 offset:23552
	global_load_lds_dwordx4 v[144:145], off
	v_lshl_add_u64 v[144:145], v[192:193], 0, s[74:75]
	s_add_i32 m0, s68, 0x2000
	s_add_i32 s68, s69, s53
	global_load_lds_dwordx4 v[144:145], off
	s_mov_b32 m0, s68
	v_mov_b32_e32 v137, v3
	global_load_lds_dwordx4 v2, s[40:41]
	s_add_i32 m0, s68, 0x2000
	v_lshl_add_u64 v[248:249], s[6:7], 0, v[136:137]
	v_mov_b32_e32 v133, v3
	global_load_lds_dwordx4 v134, s[40:41]
	v_lshl_add_u64 v[144:145], v[248:249], 0, s[74:75]
	s_mov_b32 m0, s54
	v_lshl_add_u64 v[250:251], s[6:7], 0, v[132:133]
	global_load_lds_dwordx4 v[144:145], off
	v_lshl_add_u64 v[144:145], v[250:251], 0, s[74:75]
	s_mov_b32 m0, s55
	s_nop 0
	global_load_lds_dwordx4 v[144:145], off
	s_waitcnt vmcnt(8)
	s_waitcnt lgkmcnt(0)
	s_barrier
	s_setprio 1
	s_waitcnt lgkmcnt(0)
	v_mfma_f32_16x16x32_f16 v[144:147], v[4:7], v[64:67], 0
	v_mfma_f32_16x16x32_f16 v[148:151], v[12:15], v[64:67], 0
	v_mfma_f32_16x16x32_f16 v[152:155], v[4:7], v[104:107], 0
	v_mfma_f32_16x16x32_f16 v[156:159], v[12:15], v[104:107], 0
	v_mfma_f32_16x16x32_f16 v[160:163], v[4:7], v[112:115], 0
	v_mfma_f32_16x16x32_f16 v[164:167], v[12:15], v[112:115], 0
	v_mfma_f32_16x16x32_f16 v[4:7], v[4:7], v[124:127], 0
	v_mfma_f32_16x16x32_f16 v[12:15], v[12:15], v[124:127], 0
	v_mfma_f32_16x16x32_f16 v[144:147], v[8:11], v[96:99], v[144:147]
	v_mfma_f32_16x16x32_f16 v[152:155], v[8:11], v[108:111], v[152:155]
	v_mfma_f32_16x16x32_f16 v[160:163], v[8:11], v[120:123], v[160:163]
	v_mfma_f32_16x16x32_f16 v[4:7], v[8:11], v[128:131], v[4:7]
	v_mfma_f32_16x16x32_f16 v[8:11], v[16:19], v[128:131], v[12:15]
	v_mfma_f32_16x16x32_f16 v[148:151], v[16:19], v[96:99], v[148:151]
	v_mfma_f32_16x16x32_f16 v[156:159], v[16:19], v[108:111], v[156:159]
	v_mfma_f32_16x16x32_f16 v[164:167], v[16:19], v[120:123], v[164:167]
	s_setprio 0
	s_setprio 1
	v_mfma_f32_16x16x32_f16 v[12:15], v[20:23], v[64:67], 0
	v_mfma_f32_16x16x32_f16 v[16:19], v[28:31], v[64:67], 0
	v_mfma_f32_16x16x32_f16 v[64:67], v[20:23], v[104:107], 0
	v_mfma_f32_16x16x32_f16 v[104:107], v[28:31], v[104:107], 0
	v_mfma_f32_16x16x32_f16 v[168:171], v[20:23], v[112:115], 0
	v_mfma_f32_16x16x32_f16 v[112:115], v[28:31], v[112:115], 0
	v_mfma_f32_16x16x32_f16 v[20:23], v[20:23], v[124:127], 0
	v_mfma_f32_16x16x32_f16 v[28:31], v[28:31], v[124:127], 0
	v_mfma_f32_16x16x32_f16 v[12:15], v[24:27], v[96:99], v[12:15]
	v_mfma_f32_16x16x32_f16 v[172:175], v[32:35], v[96:99], v[16:19]
	v_mfma_f32_16x16x32_f16 v[176:179], v[24:27], v[108:111], v[64:67]
	v_mfma_f32_16x16x32_f16 v[180:183], v[32:35], v[108:111], v[104:107]
	v_mfma_f32_16x16x32_f16 v[168:171], v[24:27], v[120:123], v[168:171]
	v_mfma_f32_16x16x32_f16 v[184:187], v[32:35], v[120:123], v[112:115]
	s_setprio 2
	s_barrier
	v_mfma_f32_16x16x32_f16 v[188:191], v[24:27], v[128:131], v[20:23]
	v_mfma_f32_16x16x32_f16 v[196:199], v[32:35], v[128:131], v[28:31]
	s_setprio 0
	s_add_i32 s68, 0, 0x18000
	v_add_u32_e32 v24, s68, v143
	s_add_i32 s69, 0, 0x1c000
	ds_read_b128 v[16:19], v24
	ds_read_b128 v[20:23], v24 offset:1024
	ds_read_b128 v[28:31], v24 offset:2048
	ds_read_b128 v[200:203], v24 offset:3072
	v_add_u32_e32 v24, s69, v143
	ds_read_b128 v[204:207], v24
	ds_read_b128 v[208:211], v24 offset:1024
	ds_read_b128 v[212:215], v24 offset:2048
	ds_read_b128 v[216:219], v24 offset:3072
	s_mov_b32 m0, s56
	ds_read_b128 v[24:27], v231 offset:32768
	ds_read_b128 v[32:35], v231 offset:33792
	ds_read_b128 v[64:67], v231 offset:34816
	ds_read_b128 v[220:223], v231 offset:35840
	ds_read_b128 v[224:227], v231 offset:36864
	ds_read_b128 v[232:235], v231 offset:37888
	ds_read_b128 v[236:239], v231 offset:38912
	ds_read_b128 v[240:243], v231 offset:39936
	global_load_lds_dwordx4 v136, s[42:43]
	s_mov_b32 m0, s57
	s_nop 0
	global_load_lds_dwordx4 v132, s[42:43]
	s_waitcnt vmcnt(8)
	s_waitcnt lgkmcnt(0)
	s_barrier
	s_setprio 1
	s_waitcnt lgkmcnt(0)
	v_mfma_f32_16x16x32_f16 v[68:71], v[16:19], v[24:27], v[68:71]
	v_mfma_f32_16x16x32_f16 v[128:131], v[20:23], v[32:35], v[68:71]
	v_mfma_f32_16x16x32_f16 v[68:71], v[28:31], v[24:27], v[72:75]
	v_mfma_f32_16x16x32_f16 v[120:123], v[200:203], v[32:35], v[68:71]
	v_mfma_f32_16x16x32_f16 v[68:71], v[16:19], v[64:67], v[76:79]
	v_mfma_f32_16x16x32_f16 v[112:115], v[20:23], v[220:223], v[68:71]
	v_mfma_f32_16x16x32_f16 v[68:71], v[28:31], v[64:67], v[80:83]
	v_mfma_f32_16x16x32_f16 v[104:107], v[200:203], v[220:223], v[68:71]
	v_mfma_f32_16x16x32_f16 v[68:71], v[16:19], v[224:227], v[84:87]
	v_mfma_f32_16x16x32_f16 v[96:99], v[20:23], v[232:235], v[68:71]
	v_mfma_f32_16x16x32_f16 v[68:71], v[28:31], v[224:227], v[88:91]
	v_mfma_f32_16x16x32_f16 v[88:91], v[200:203], v[232:235], v[68:71]
	v_mfma_f32_16x16x32_f16 v[68:71], v[16:19], v[236:239], v[92:95]
	v_mfma_f32_16x16x32_f16 v[80:83], v[20:23], v[240:243], v[68:71]
	v_mfma_f32_16x16x32_f16 v[68:71], v[28:31], v[236:239], v[100:103]
	v_mfma_f32_16x16x32_f16 v[72:75], v[200:203], v[240:243], v[68:71]
	s_setprio 0
	s_setprio 1
	v_mfma_f32_16x16x32_f16 v[68:71], v[204:207], v[24:27], v[116:119]
	v_mfma_f32_16x16x32_f16 v[24:27], v[212:215], v[24:27], v[36:39]
	v_mfma_f32_16x16x32_f16 v[116:119], v[216:219], v[32:35], v[24:27]
	v_mfma_f32_16x16x32_f16 v[24:27], v[204:207], v[64:67], v[40:43]
	v_mfma_f32_16x16x32_f16 v[108:111], v[208:211], v[220:223], v[24:27]
	v_mfma_f32_16x16x32_f16 v[24:27], v[212:215], v[64:67], v[44:47]
	v_mfma_f32_16x16x32_f16 v[100:103], v[216:219], v[220:223], v[24:27]
	v_mfma_f32_16x16x32_f16 v[24:27], v[204:207], v[224:227], v[48:51]
	v_mfma_f32_16x16x32_f16 v[92:95], v[208:211], v[232:235], v[24:27]
	v_mfma_f32_16x16x32_f16 v[24:27], v[212:215], v[224:227], v[52:55]
	v_mfma_f32_16x16x32_f16 v[84:87], v[216:219], v[232:235], v[24:27]
	v_mfma_f32_16x16x32_f16 v[24:27], v[204:207], v[236:239], v[56:59]
	v_mfma_f32_16x16x32_f16 v[76:79], v[208:211], v[240:243], v[24:27]
	v_mfma_f32_16x16x32_f16 v[24:27], v[212:215], v[236:239], v[60:63]
	s_setprio 2
	s_barrier
	v_mfma_f32_16x16x32_f16 v[124:127], v[208:211], v[32:35], v[68:71]
	v_mfma_f32_16x16x32_f16 v[68:71], v[216:219], v[240:243], v[24:27]
	s_setprio 0
	s_add_i32 s68, s68, s53
	s_nop 2
	v_lshl_add_u64 v[24:25], v[138:139], 0, s[24:25]
	s_mov_b32 m0, s68
	ds_read_b128 v[36:39], v231 offset:49152
	ds_read_b128 v[44:47], v231 offset:50176
	ds_read_b128 v[220:223], v231 offset:51200
	ds_read_b128 v[224:227], v231 offset:52224
	ds_read_b128 v[232:235], v231 offset:53248
	ds_read_b128 v[236:239], v231 offset:54272
	ds_read_b128 v[240:243], v231 offset:55296
	ds_read_b128 v[244:247], v231 offset:56320
	global_load_lds_dwordx4 v[24:25], off
	v_lshl_add_u64 v[24:25], v[192:193], 0, s[24:25]
	s_add_i32 m0, s68, 0x2000
	s_add_i32 s68, s69, s53
	global_load_lds_dwordx4 v[24:25], off
	s_mov_b32 m0, s68
	v_lshl_add_u64 v[24:25], v[248:249], 0, s[24:25]
	global_load_lds_dwordx4 v2, s[44:45]
	s_add_i32 m0, s68, 0x2000
	s_nop 0
	global_load_lds_dwordx4 v134, s[44:45]
	s_mov_b32 m0, s59
	s_nop 0
	global_load_lds_dwordx4 v[24:25], off
	v_lshl_add_u64 v[24:25], v[250:251], 0, s[24:25]
	s_mov_b32 m0, s60
	s_nop 0
	global_load_lds_dwordx4 v[24:25], off
	s_waitcnt vmcnt(8)
	s_waitcnt lgkmcnt(0)
	s_barrier
	s_setprio 1
	s_waitcnt lgkmcnt(0)
	v_mfma_f32_16x16x32_f16 v[24:27], v[16:19], v[36:39], v[144:147]
	v_mfma_f32_16x16x32_f16 v[64:67], v[20:23], v[44:47], v[24:27]
	v_mfma_f32_16x16x32_f16 v[24:27], v[28:31], v[36:39], v[148:151]
	v_mfma_f32_16x16x32_f16 v[56:59], v[200:203], v[44:47], v[24:27]
	v_mfma_f32_16x16x32_f16 v[24:27], v[16:19], v[220:223], v[152:155]
	v_mfma_f32_16x16x32_f16 v[48:51], v[20:23], v[224:227], v[24:27]
	v_mfma_f32_16x16x32_f16 v[24:27], v[28:31], v[220:223], v[156:159]
	v_mfma_f32_16x16x32_f16 v[40:43], v[200:203], v[224:227], v[24:27]
	v_mfma_f32_16x16x32_f16 v[24:27], v[16:19], v[232:235], v[160:163]
	v_mfma_f32_16x16x32_f16 v[4:7], v[16:19], v[240:243], v[4:7]
	v_mfma_f32_16x16x32_f16 v[32:35], v[20:23], v[236:239], v[24:27]
	v_mfma_f32_16x16x32_f16 v[24:27], v[28:31], v[232:235], v[164:167]
	v_mfma_f32_16x16x32_f16 v[16:19], v[20:23], v[244:247], v[4:7]
	v_mfma_f32_16x16x32_f16 v[4:7], v[28:31], v[240:243], v[8:11]
	v_mfma_f32_16x16x32_f16 v[24:27], v[200:203], v[236:239], v[24:27]
	v_mfma_f32_16x16x32_f16 v[8:11], v[200:203], v[244:247], v[4:7]
	s_setprio 0
	s_setprio 1
	v_mfma_f32_16x16x32_f16 v[4:7], v[204:207], v[36:39], v[12:15]
	v_mfma_f32_16x16x32_f16 v[60:63], v[208:211], v[44:47], v[4:7]
	v_mfma_f32_16x16x32_f16 v[4:7], v[212:215], v[36:39], v[172:175]
	v_mfma_f32_16x16x32_f16 v[52:55], v[216:219], v[44:47], v[4:7]
	v_mfma_f32_16x16x32_f16 v[4:7], v[204:207], v[220:223], v[176:179]
	v_mfma_f32_16x16x32_f16 v[44:47], v[208:211], v[224:227], v[4:7]
	v_mfma_f32_16x16x32_f16 v[4:7], v[212:215], v[220:223], v[180:183]
	v_mfma_f32_16x16x32_f16 v[36:39], v[216:219], v[224:227], v[4:7]
	v_mfma_f32_16x16x32_f16 v[4:7], v[204:207], v[232:235], v[168:171]
	v_mfma_f32_16x16x32_f16 v[28:31], v[208:211], v[236:239], v[4:7]
	v_mfma_f32_16x16x32_f16 v[4:7], v[212:215], v[232:235], v[184:187]
	v_mfma_f32_16x16x32_f16 v[20:23], v[216:219], v[236:239], v[4:7]
	v_mfma_f32_16x16x32_f16 v[4:7], v[204:207], v[240:243], v[188:191]
	v_mfma_f32_16x16x32_f16 v[12:15], v[208:211], v[244:247], v[4:7]
	s_setprio 2
	s_barrier
	v_mfma_f32_16x16x32_f16 v[4:7], v[212:215], v[240:243], v[196:199]
	v_mfma_f32_16x16x32_f16 v[4:7], v[216:219], v[244:247], v[4:7]
	s_setprio 0
	s_add_i32 s67, s67, 2
	s_cmp_ge_i32 s67, s11
	s_cbranch_scc0 .LBB0_2159

.LBB0_2161:
	s_add_u32 s68, s6, s40
	s_addc_u32 s69, s7, s41
	s_add_u32 s42, s68, 0x200
	s_addc_u32 s43, s69, 0
	s_add_u32 s44, s8, s40
	s_addc_u32 s45, s9, s41
	s_add_u32 s67, s44, 0x200
	s_addc_u32 s70, s45, 0
	s_add_i32 s71, 0, 0x10000
	s_cmp_eq_u32 s11, 28
	s_cselect_b32 s45, s29, s43
	s_cselect_b32 s44, s28, s42
	v_add_u32_e32 v133, s71, v143
	s_cselect_b32 s43, s37, s70
	s_cselect_b32 s42, s36, s67
	s_add_i32 s67, 0, 0x14000
	ds_read_b128 v[144:147], v133
	ds_read_b128 v[148:151], v133 offset:1024
	ds_read_b128 v[152:155], v133 offset:2048
	ds_read_b128 v[156:159], v133 offset:3072
	v_add_u32_e32 v133, s67, v143
	ds_read_b128 v[160:163], v133
	ds_read_b128 v[164:167], v133 offset:1024
	ds_read_b128 v[168:171], v133 offset:2048
	ds_read_b128 v[172:175], v133 offset:3072
	v_lshl_add_u64 v[136:137], s[68:69], 0, v[2:3]
	s_mov_b32 m0, s61
	v_add_u32_e32 v216, 0, v142
	v_lshl_add_u64 v[136:137], v[136:137], 0, s[34:35]
	v_mov_b32_e32 v133, v3
	ds_read_b128 v[176:179], v216
	ds_read_b128 v[180:183], v216 offset:1024
	ds_read_b128 v[184:187], v216 offset:2048
	ds_read_b128 v[188:191], v216 offset:3072
	ds_read_b128 v[196:199], v216 offset:4096
	ds_read_b128 v[200:203], v216 offset:5120
	ds_read_b128 v[204:207], v216 offset:6144
	ds_read_b128 v[208:211], v216 offset:7168
	global_load_lds_dwordx4 v[136:137], off
	v_lshl_add_u64 v[136:137], s[68:69], 0, v[132:133]
	v_lshl_add_u64 v[136:137], v[136:137], 0, s[34:35]
	s_mov_b32 m0, s62
	s_nop 0
	global_load_lds_dwordx4 v[136:137], off
	s_waitcnt vmcnt(8)
	s_waitcnt lgkmcnt(0)
	s_barrier
	s_setprio 1
	s_waitcnt lgkmcnt(0)
	v_mfma_f32_16x16x32_f16 v[128:131], v[144:147], v[176:179], v[128:131]
	v_mfma_f32_16x16x32_f16 v[128:131], v[148:151], v[180:183], v[128:131]
	v_mfma_f32_16x16x32_f16 v[120:123], v[156:159], v[180:183], v[120:123]
	v_mfma_f32_16x16x32_f16 v[120:123], v[152:155], v[176:179], v[120:123]
	v_mfma_f32_16x16x32_f16 v[104:107], v[152:155], v[184:187], v[104:107]
	v_mfma_f32_16x16x32_f16 v[104:107], v[156:159], v[188:191], v[104:107]
	v_mfma_f32_16x16x32_f16 v[112:115], v[148:151], v[188:191], v[112:115]
	v_mfma_f32_16x16x32_f16 v[112:115], v[144:147], v[184:187], v[112:115]
	v_mfma_f32_16x16x32_f16 v[96:99], v[144:147], v[196:199], v[96:99]
	v_mfma_f32_16x16x32_f16 v[96:99], v[148:151], v[200:203], v[96:99]
	v_mfma_f32_16x16x32_f16 v[88:91], v[156:159], v[200:203], v[88:91]
	v_mfma_f32_16x16x32_f16 v[88:91], v[152:155], v[196:199], v[88:91]
	v_mfma_f32_16x16x32_f16 v[72:75], v[152:155], v[204:207], v[72:75]
	v_mfma_f32_16x16x32_f16 v[72:75], v[156:159], v[208:211], v[72:75]
	v_mfma_f32_16x16x32_f16 v[80:83], v[148:151], v[208:211], v[80:83]
	v_mfma_f32_16x16x32_f16 v[80:83], v[144:147], v[204:207], v[80:83]
	s_setprio 0
	s_setprio 1
	v_mfma_f32_16x16x32_f16 v[124:127], v[160:163], v[176:179], v[124:127]
	v_mfma_f32_16x16x32_f16 v[124:127], v[164:167], v[180:183], v[124:127]
	v_mfma_f32_16x16x32_f16 v[116:119], v[172:175], v[180:183], v[116:119]
	v_mfma_f32_16x16x32_f16 v[116:119], v[168:171], v[176:179], v[116:119]
	v_mfma_f32_16x16x32_f16 v[100:103], v[168:171], v[184:187], v[100:103]
	v_mfma_f32_16x16x32_f16 v[100:103], v[172:175], v[188:191], v[100:103]
	v_mfma_f32_16x16x32_f16 v[108:111], v[164:167], v[188:191], v[108:111]
	v_mfma_f32_16x16x32_f16 v[108:111], v[160:163], v[184:187], v[108:111]
	v_mfma_f32_16x16x32_f16 v[92:95], v[160:163], v[196:199], v[92:95]
	v_mfma_f32_16x16x32_f16 v[92:95], v[164:167], v[200:203], v[92:95]
	v_mfma_f32_16x16x32_f16 v[84:87], v[172:175], v[200:203], v[84:87]
	v_mfma_f32_16x16x32_f16 v[84:87], v[168:171], v[196:199], v[84:87]
	v_mfma_f32_16x16x32_f16 v[68:71], v[168:171], v[204:207], v[68:71]
	v_mfma_f32_16x16x32_f16 v[68:71], v[172:175], v[208:211], v[68:71]
	s_setprio 2
	s_barrier
	v_mfma_f32_16x16x32_f16 v[76:79], v[164:167], v[208:211], v[76:79]
	v_mfma_f32_16x16x32_f16 v[76:79], v[160:163], v[204:207], v[76:79]
	s_setprio 0
	s_add_i32 s68, s71, s53
	s_mov_b32 m0, s68
	ds_read_b128 v[176:179], v216 offset:16384
	ds_read_b128 v[180:183], v216 offset:17408
	ds_read_b128 v[184:187], v216 offset:18432
	ds_read_b128 v[188:191], v216 offset:19456
	ds_read_b128 v[196:199], v216 offset:20480
	ds_read_b128 v[200:203], v216 offset:21504
	ds_read_b128 v[204:207], v216 offset:22528
	ds_read_b128 v[208:211], v216 offset:23552
	global_load_lds_dwordx4 v138, s[42:43]
	s_add_i32 m0, s68, 0x2000
	s_add_u32 s68, s42, 0x80000
	s_addc_u32 s69, s43, 0
	s_add_i32 s67, s67, s53
	global_load_lds_dwordx4 v134, s[42:43]
	s_mov_b32 m0, s67
	v_mov_b32_e32 v139, v3
	global_load_lds_dwordx4 v138, s[68:69]
	s_add_i32 m0, s67, 0x2000
	v_mov_b32_e32 v135, v3
	global_load_lds_dwordx4 v134, s[68:69]
	s_mov_b32 m0, s54
	v_lshl_add_u64 v[136:137], s[42:43], 0, v[138:139]
	global_load_lds_dwordx4 v2, s[44:45]
	s_mov_b32 m0, s55
	v_lshl_add_u64 v[192:193], s[42:43], 0, v[134:135]
	global_load_lds_dwordx4 v132, s[44:45]
	s_waitcnt vmcnt(8)
	s_waitcnt lgkmcnt(0)
	v_lshl_add_u64 v[212:213], s[44:45], 0, v[2:3]
	v_lshl_add_u64 v[214:215], s[44:45], 0, v[132:133]
	s_barrier
	s_setprio 1
	s_waitcnt lgkmcnt(0)
	v_mfma_f32_16x16x32_f16 v[64:67], v[144:147], v[176:179], v[64:67]
	v_mfma_f32_16x16x32_f16 v[64:67], v[148:151], v[180:183], v[64:67]
	v_mfma_f32_16x16x32_f16 v[56:59], v[156:159], v[180:183], v[56:59]
	v_mfma_f32_16x16x32_f16 v[56:59], v[152:155], v[176:179], v[56:59]
	v_mfma_f32_16x16x32_f16 v[40:43], v[152:155], v[184:187], v[40:43]
	v_mfma_f32_16x16x32_f16 v[40:43], v[156:159], v[188:191], v[40:43]
	v_mfma_f32_16x16x32_f16 v[48:51], v[148:151], v[188:191], v[48:51]
	v_mfma_f32_16x16x32_f16 v[48:51], v[144:147], v[184:187], v[48:51]
	v_mfma_f32_16x16x32_f16 v[32:35], v[144:147], v[196:199], v[32:35]
	v_mfma_f32_16x16x32_f16 v[32:35], v[148:151], v[200:203], v[32:35]
	v_mfma_f32_16x16x32_f16 v[24:27], v[156:159], v[200:203], v[24:27]
	v_mfma_f32_16x16x32_f16 v[24:27], v[152:155], v[196:199], v[24:27]
	v_mfma_f32_16x16x32_f16 v[8:11], v[152:155], v[204:207], v[8:11]
	v_mfma_f32_16x16x32_f16 v[8:11], v[156:159], v[208:211], v[8:11]
	v_mfma_f32_16x16x32_f16 v[16:19], v[148:151], v[208:211], v[16:19]
	v_mfma_f32_16x16x32_f16 v[16:19], v[144:147], v[204:207], v[16:19]
	s_setprio 0
	s_setprio 1
	v_mfma_f32_16x16x32_f16 v[60:63], v[160:163], v[176:179], v[60:63]
	v_mfma_f32_16x16x32_f16 v[60:63], v[164:167], v[180:183], v[60:63]
	v_mfma_f32_16x16x32_f16 v[52:55], v[172:175], v[180:183], v[52:55]
	v_mfma_f32_16x16x32_f16 v[52:55], v[168:171], v[176:179], v[52:55]
	v_mfma_f32_16x16x32_f16 v[36:39], v[168:171], v[184:187], v[36:39]
	v_mfma_f32_16x16x32_f16 v[36:39], v[172:175], v[188:191], v[36:39]
	v_mfma_f32_16x16x32_f16 v[44:47], v[164:167], v[188:191], v[44:47]
	v_mfma_f32_16x16x32_f16 v[44:47], v[160:163], v[184:187], v[44:47]
	v_mfma_f32_16x16x32_f16 v[28:31], v[160:163], v[196:199], v[28:31]
	v_mfma_f32_16x16x32_f16 v[28:31], v[164:167], v[200:203], v[28:31]
	v_mfma_f32_16x16x32_f16 v[20:23], v[172:175], v[200:203], v[20:23]
	v_mfma_f32_16x16x32_f16 v[20:23], v[168:171], v[196:199], v[20:23]
	v_mfma_f32_16x16x32_f16 v[4:7], v[168:171], v[204:207], v[4:7]
	v_mfma_f32_16x16x32_f16 v[4:7], v[172:175], v[208:211], v[4:7]
	s_setprio 2
	s_barrier
	v_mfma_f32_16x16x32_f16 v[12:15], v[164:167], v[208:211], v[12:15]
	v_mfma_f32_16x16x32_f16 v[12:15], v[160:163], v[204:207], v[12:15]
	s_setprio 0
	s_add_i32 s67, 0, 0x18000
	v_add_u32_e32 v135, s67, v143
	s_add_i32 s68, 0, 0x1c000
	ds_read_b128 v[144:147], v135
	ds_read_b128 v[148:151], v135 offset:1024
	ds_read_b128 v[152:155], v135 offset:2048
	ds_read_b128 v[156:159], v135 offset:3072
	v_add_u32_e32 v135, s68, v143
	ds_read_b128 v[160:163], v135
	ds_read_b128 v[164:167], v135 offset:1024
	ds_read_b128 v[168:171], v135 offset:2048
	ds_read_b128 v[172:175], v135 offset:3072
	s_add_u32 s44, s44, 0x80000
	s_addc_u32 s45, s45, 0
	s_mov_b32 m0, s56
	ds_read_b128 v[176:179], v216 offset:32768
	ds_read_b128 v[180:183], v216 offset:33792
	ds_read_b128 v[184:187], v216 offset:34816
	ds_read_b128 v[188:191], v216 offset:35840
	ds_read_b128 v[196:199], v216 offset:36864
	ds_read_b128 v[200:203], v216 offset:37888
	ds_read_b128 v[204:207], v216 offset:38912
	ds_read_b128 v[208:211], v216 offset:39936
	global_load_lds_dwordx4 v2, s[44:45]
	s_mov_b32 m0, s57
	s_nop 0
	global_load_lds_dwordx4 v132, s[44:45]
	s_waitcnt vmcnt(8)
	s_waitcnt lgkmcnt(0)
	s_barrier
	s_setprio 1
	s_waitcnt lgkmcnt(0)
	v_mfma_f32_16x16x32_f16 v[128:131], v[144:147], v[176:179], v[128:131]
	v_mfma_f32_16x16x32_f16 v[128:131], v[148:151], v[180:183], v[128:131]
	v_mfma_f32_16x16x32_f16 v[120:123], v[156:159], v[180:183], v[120:123]
	v_mfma_f32_16x16x32_f16 v[120:123], v[152:155], v[176:179], v[120:123]
	v_mfma_f32_16x16x32_f16 v[104:107], v[152:155], v[184:187], v[104:107]
	v_mfma_f32_16x16x32_f16 v[104:107], v[156:159], v[188:191], v[104:107]
	v_mfma_f32_16x16x32_f16 v[112:115], v[148:151], v[188:191], v[112:115]
	v_mfma_f32_16x16x32_f16 v[112:115], v[144:147], v[184:187], v[112:115]
	v_mfma_f32_16x16x32_f16 v[96:99], v[144:147], v[196:199], v[96:99]
	v_mfma_f32_16x16x32_f16 v[96:99], v[148:151], v[200:203], v[96:99]
	v_mfma_f32_16x16x32_f16 v[88:91], v[156:159], v[200:203], v[88:91]
	v_mfma_f32_16x16x32_f16 v[88:91], v[152:155], v[196:199], v[88:91]
	v_mfma_f32_16x16x32_f16 v[72:75], v[152:155], v[204:207], v[72:75]
	v_mfma_f32_16x16x32_f16 v[72:75], v[156:159], v[208:211], v[72:75]
	v_mfma_f32_16x16x32_f16 v[80:83], v[148:151], v[208:211], v[80:83]
	v_mfma_f32_16x16x32_f16 v[80:83], v[144:147], v[204:207], v[80:83]
	s_setprio 0
	s_setprio 1
	v_mfma_f32_16x16x32_f16 v[124:127], v[160:163], v[176:179], v[124:127]
	v_mfma_f32_16x16x32_f16 v[124:127], v[164:167], v[180:183], v[124:127]
	v_mfma_f32_16x16x32_f16 v[116:119], v[172:175], v[180:183], v[116:119]
	v_mfma_f32_16x16x32_f16 v[116:119], v[168:171], v[176:179], v[116:119]
	v_mfma_f32_16x16x32_f16 v[100:103], v[168:171], v[184:187], v[100:103]
	v_mfma_f32_16x16x32_f16 v[100:103], v[172:175], v[188:191], v[100:103]
	v_mfma_f32_16x16x32_f16 v[108:111], v[164:167], v[188:191], v[108:111]
	v_mfma_f32_16x16x32_f16 v[108:111], v[160:163], v[184:187], v[108:111]
	v_mfma_f32_16x16x32_f16 v[92:95], v[160:163], v[196:199], v[92:95]
	v_mfma_f32_16x16x32_f16 v[92:95], v[164:167], v[200:203], v[92:95]
	v_mfma_f32_16x16x32_f16 v[84:87], v[172:175], v[200:203], v[84:87]
	v_mfma_f32_16x16x32_f16 v[84:87], v[168:171], v[196:199], v[84:87]
	v_mfma_f32_16x16x32_f16 v[68:71], v[168:171], v[204:207], v[68:71]
	v_mfma_f32_16x16x32_f16 v[68:71], v[172:175], v[208:211], v[68:71]
	s_setprio 2
	s_barrier
	v_mfma_f32_16x16x32_f16 v[76:79], v[164:167], v[208:211], v[76:79]
	v_mfma_f32_16x16x32_f16 v[76:79], v[160:163], v[204:207], v[76:79]
	s_setprio 0
	s_add_i32 s44, s67, s53
	v_lshl_add_u64 v[136:137], v[136:137], 0, s[86:87]
	s_mov_b32 m0, s44
	ds_read_b128 v[176:179], v216 offset:49152
	ds_read_b128 v[180:183], v216 offset:50176
	ds_read_b128 v[184:187], v216 offset:51200
	ds_read_b128 v[188:191], v216 offset:52224
	ds_read_b128 v[196:199], v216 offset:53248
	ds_read_b128 v[200:203], v216 offset:54272
	ds_read_b128 v[204:207], v216 offset:55296
	ds_read_b128 v[208:211], v216 offset:56320
	global_load_lds_dwordx4 v[136:137], off
	s_add_i32 m0, s44, 0x2000
	s_add_u32 s42, s42, 0x80080
	v_lshl_add_u64 v[136:137], v[192:193], 0, s[86:87]
	s_addc_u32 s43, s43, 0
	s_add_i32 s44, s68, s53
	global_load_lds_dwordx4 v[136:137], off
	s_mov_b32 m0, s44
	v_lshl_add_u64 v[136:137], v[212:213], 0, s[86:87]
	global_load_lds_dwordx4 v138, s[42:43]
	s_add_i32 m0, s44, 0x2000
	s_nop 0
	global_load_lds_dwordx4 v134, s[42:43]
	s_mov_b32 m0, s59
	s_nop 0
	global_load_lds_dwordx4 v[136:137], off
	v_lshl_add_u64 v[136:137], v[214:215], 0, s[86:87]
	s_mov_b32 m0, s60
	s_nop 0
	global_load_lds_dwordx4 v[136:137], off
	s_waitcnt vmcnt(8)
	s_waitcnt lgkmcnt(0)
	s_barrier
	s_setprio 1
	s_waitcnt lgkmcnt(0)
	v_mfma_f32_16x16x32_f16 v[64:67], v[144:147], v[176:179], v[64:67]
	v_mfma_f32_16x16x32_f16 v[64:67], v[148:151], v[180:183], v[64:67]
	v_mfma_f32_16x16x32_f16 v[56:59], v[156:159], v[180:183], v[56:59]
	v_mfma_f32_16x16x32_f16 v[56:59], v[152:155], v[176:179], v[56:59]
	v_mfma_f32_16x16x32_f16 v[40:43], v[152:155], v[184:187], v[40:43]
	v_mfma_f32_16x16x32_f16 v[40:43], v[156:159], v[188:191], v[40:43]
	v_mfma_f32_16x16x32_f16 v[48:51], v[148:151], v[188:191], v[48:51]
	v_mfma_f32_16x16x32_f16 v[48:51], v[144:147], v[184:187], v[48:51]
	v_mfma_f32_16x16x32_f16 v[32:35], v[144:147], v[196:199], v[32:35]
	v_mfma_f32_16x16x32_f16 v[32:35], v[148:151], v[200:203], v[32:35]
	v_mfma_f32_16x16x32_f16 v[24:27], v[156:159], v[200:203], v[24:27]
	v_mfma_f32_16x16x32_f16 v[24:27], v[152:155], v[196:199], v[24:27]
	v_mfma_f32_16x16x32_f16 v[8:11], v[152:155], v[204:207], v[8:11]
	v_mfma_f32_16x16x32_f16 v[8:11], v[156:159], v[208:211], v[8:11]
	v_mfma_f32_16x16x32_f16 v[16:19], v[148:151], v[208:211], v[16:19]
	v_mfma_f32_16x16x32_f16 v[16:19], v[144:147], v[204:207], v[16:19]
	s_setprio 0
	s_setprio 1
	v_mfma_f32_16x16x32_f16 v[60:63], v[160:163], v[176:179], v[60:63]
	v_mfma_f32_16x16x32_f16 v[60:63], v[164:167], v[180:183], v[60:63]
	v_mfma_f32_16x16x32_f16 v[52:55], v[172:175], v[180:183], v[52:55]
	v_mfma_f32_16x16x32_f16 v[52:55], v[168:171], v[176:179], v[52:55]
	v_mfma_f32_16x16x32_f16 v[36:39], v[168:171], v[184:187], v[36:39]
	v_mfma_f32_16x16x32_f16 v[36:39], v[172:175], v[188:191], v[36:39]
	v_mfma_f32_16x16x32_f16 v[44:47], v[164:167], v[188:191], v[44:47]
	v_mfma_f32_16x16x32_f16 v[44:47], v[160:163], v[184:187], v[44:47]
	v_mfma_f32_16x16x32_f16 v[28:31], v[160:163], v[196:199], v[28:31]
	v_mfma_f32_16x16x32_f16 v[28:31], v[164:167], v[200:203], v[28:31]
	v_mfma_f32_16x16x32_f16 v[20:23], v[172:175], v[200:203], v[20:23]
	v_mfma_f32_16x16x32_f16 v[20:23], v[168:171], v[196:199], v[20:23]
	v_mfma_f32_16x16x32_f16 v[4:7], v[168:171], v[204:207], v[4:7]
	v_mfma_f32_16x16x32_f16 v[4:7], v[172:175], v[208:211], v[4:7]
	s_setprio 2
	s_barrier
	v_mfma_f32_16x16x32_f16 v[12:15], v[164:167], v[208:211], v[12:15]
	v_mfma_f32_16x16x32_f16 v[12:15], v[160:163], v[204:207], v[12:15]
	s_setprio 0
	s_add_i32 s11, s11, 2
	s_add_u32 s40, s40, 0x100
	s_addc_u32 s41, s41, 0
	s_cmp_gt_u32 s11, 29
	s_cbranch_scc0 .LBB0_2161
	s_andn2_b64 vcc, exec, s[26:27]
	s_cbranch_vccnz .LBB0_2164
	s_add_u32 s6, s28, 0x80080
	s_addc_u32 s7, s29, 0
	s_mov_b32 m0, s61
	v_lshl_add_u64 v[144:145], s[6:7], 0, v[2:3]
	v_lshl_add_u64 v[136:137], s[6:7], 0, v[132:133]
	global_load_lds_dwordx4 v[144:145], off
	s_mov_b32 m0, s62
	s_mov_b32 s47, s65
	global_load_lds_dwordx4 v[136:137], off
	s_mov_b32 s64, s10
	s_mov_b64 s[8:9], s[14:15]
	s_mov_b64 s[6:7], s[12:13]
	s_mov_b32 s63, s66

.LBB0_2269:
	s_add_i32 s51, 0, 0x10000
	s_add_i32 s71, 0, 0x14000
	v_add_u32_e32 v16, s51, v232
	v_add_u32_e32 v32, s71, v232
	ds_read_b128 v[4:7], v16
	ds_read_b128 v[8:11], v16 offset:1024
	ds_read_b128 v[12:15], v16 offset:2048
	ds_read_b128 v[16:19], v16 offset:3072
	ds_read_b128 v[20:23], v32
	ds_read_b128 v[24:27], v32 offset:1024
	ds_read_b128 v[28:31], v32 offset:2048
	ds_read_b128 v[32:35], v32 offset:3072
	v_add_u32_e32 v233, 0, v231
	ds_read_b128 v[36:39], v233
	ds_read_b128 v[40:43], v233 offset:1024
	ds_read_b128 v[44:47], v233 offset:2048
	ds_read_b128 v[48:51], v233 offset:3072
	ds_read_b128 v[52:55], v233 offset:4096
	ds_read_b128 v[56:59], v233 offset:5120
	ds_read_b128 v[60:63], v233 offset:6144
	ds_read_b128 v[64:67], v233 offset:7168
	s_waitcnt vmcnt(8)
	s_waitcnt lgkmcnt(0)
	s_barrier
	s_setprio 1
	s_waitcnt lgkmcnt(0)
	v_mfma_f32_16x16x32_bf16 v[68:71], v[4:7], v[36:39], 0
	v_mfma_f32_16x16x32_bf16 v[68:71], v[8:11], v[40:43], v[68:71]
	v_mfma_f32_16x16x32_bf16 v[72:75], v[12:15], v[36:39], 0
	v_mfma_f32_16x16x32_bf16 v[72:75], v[16:19], v[40:43], v[72:75]
	v_mfma_f32_16x16x32_bf16 v[80:83], v[12:15], v[44:47], 0
	v_mfma_f32_16x16x32_bf16 v[80:83], v[16:19], v[48:51], v[80:83]
	v_mfma_f32_16x16x32_bf16 v[76:79], v[4:7], v[44:47], 0
	v_mfma_f32_16x16x32_bf16 v[76:79], v[8:11], v[48:51], v[76:79]
	v_mfma_f32_16x16x32_bf16 v[84:87], v[4:7], v[52:55], 0
	v_mfma_f32_16x16x32_bf16 v[84:87], v[8:11], v[56:59], v[84:87]
	v_mfma_f32_16x16x32_bf16 v[88:91], v[12:15], v[52:55], 0
	v_mfma_f32_16x16x32_bf16 v[88:91], v[16:19], v[56:59], v[88:91]
	v_mfma_f32_16x16x32_bf16 v[96:99], v[12:15], v[60:63], 0
	v_mfma_f32_16x16x32_bf16 v[96:99], v[16:19], v[64:67], v[96:99]
	v_mfma_f32_16x16x32_bf16 v[92:95], v[4:7], v[60:63], 0
	v_mfma_f32_16x16x32_bf16 v[92:95], v[8:11], v[64:67], v[92:95]
	s_setprio 0
	s_setprio 1
	v_mfma_f32_16x16x32_bf16 v[100:103], v[20:23], v[36:39], 0
	v_mfma_f32_16x16x32_bf16 v[36:39], v[28:31], v[36:39], 0
	v_mfma_f32_16x16x32_bf16 v[104:107], v[20:23], v[44:47], 0
	v_mfma_f32_16x16x32_bf16 v[44:47], v[28:31], v[44:47], 0
	v_mfma_f32_16x16x32_bf16 v[108:111], v[20:23], v[52:55], 0
	v_mfma_f32_16x16x32_bf16 v[52:55], v[28:31], v[52:55], 0
	v_mfma_f32_16x16x32_bf16 v[112:115], v[20:23], v[60:63], 0
	v_mfma_f32_16x16x32_bf16 v[60:63], v[28:31], v[60:63], 0
	v_mfma_f32_16x16x32_bf16 v[100:103], v[24:27], v[40:43], v[100:103]
	v_mfma_f32_16x16x32_bf16 v[40:43], v[32:35], v[40:43], v[36:39]
	v_mfma_f32_16x16x32_bf16 v[104:107], v[24:27], v[48:51], v[104:107]
	v_mfma_f32_16x16x32_bf16 v[48:51], v[32:35], v[48:51], v[44:47]
	v_mfma_f32_16x16x32_bf16 v[108:111], v[24:27], v[56:59], v[108:111]
	v_mfma_f32_16x16x32_bf16 v[56:59], v[32:35], v[56:59], v[52:55]
	s_setprio 2
	s_barrier
	v_mfma_f32_16x16x32_bf16 v[112:115], v[24:27], v[64:67], v[112:115]
	v_mfma_f32_16x16x32_bf16 v[64:67], v[32:35], v[64:67], v[60:63]
	s_setprio 0
	v_lshl_add_u64 v[186:187], s[12:13], 0, v[2:3]
	s_add_i32 s51, s51, s38
	v_mov_b32_e32 v191, v3
	v_lshl_add_u64 v[134:135], v[186:187], 0, s[74:75]
	s_mov_b32 m0, s51
	v_lshl_add_u64 v[246:247], s[12:13], 0, v[190:191]
	ds_read_b128 v[36:39], v233 offset:16384
	ds_read_b128 v[44:47], v233 offset:17408
	ds_read_b128 v[52:55], v233 offset:18432
	ds_read_b128 v[60:63], v233 offset:19456
	ds_read_b128 v[116:119], v233 offset:20480
	ds_read_b128 v[120:123], v233 offset:21504
	ds_read_b128 v[124:127], v233 offset:22528
	ds_read_b128 v[128:131], v233 offset:23552
	global_load_lds_dwordx4 v[134:135], off
	v_lshl_add_u64 v[134:135], v[246:247], 0, s[74:75]
	s_add_i32 m0, s51, 0x2000
	s_add_i32 s51, s71, s38
	global_load_lds_dwordx4 v[134:135], off
	s_mov_b32 m0, s51
	v_mov_b32_e32 v133, v3
	global_load_lds_dwordx4 v2, s[16:17]
	s_add_i32 m0, s51, 0x2000
	v_lshl_add_u64 v[248:249], s[14:15], 0, v[132:133]
	v_mov_b32_e32 v189, v3
	global_load_lds_dwordx4 v190, s[16:17]
	v_lshl_add_u64 v[134:135], v[248:249], 0, s[74:75]
	s_mov_b32 m0, s56
	v_lshl_add_u64 v[250:251], s[14:15], 0, v[188:189]
	global_load_lds_dwordx4 v[134:135], off
	v_lshl_add_u64 v[134:135], v[250:251], 0, s[74:75]
	s_mov_b32 m0, s57
	s_nop 0
	global_load_lds_dwordx4 v[134:135], off
	s_waitcnt vmcnt(8)
	s_waitcnt lgkmcnt(0)
	s_barrier
	s_setprio 1
	s_waitcnt lgkmcnt(0)
	v_mfma_f32_16x16x32_bf16 v[134:137], v[4:7], v[36:39], 0
	v_mfma_f32_16x16x32_bf16 v[138:141], v[12:15], v[36:39], 0
	v_mfma_f32_16x16x32_bf16 v[142:145], v[4:7], v[52:55], 0
	v_mfma_f32_16x16x32_bf16 v[146:149], v[12:15], v[52:55], 0
	v_mfma_f32_16x16x32_bf16 v[150:153], v[4:7], v[116:119], 0
	v_mfma_f32_16x16x32_bf16 v[154:157], v[12:15], v[116:119], 0
	v_mfma_f32_16x16x32_bf16 v[4:7], v[4:7], v[124:127], 0
	v_mfma_f32_16x16x32_bf16 v[12:15], v[12:15], v[124:127], 0
	v_mfma_f32_16x16x32_bf16 v[134:137], v[8:11], v[44:47], v[134:137]
	v_mfma_f32_16x16x32_bf16 v[138:141], v[16:19], v[44:47], v[138:141]
	v_mfma_f32_16x16x32_bf16 v[142:145], v[8:11], v[60:63], v[142:145]
	v_mfma_f32_16x16x32_bf16 v[146:149], v[16:19], v[60:63], v[146:149]
	v_mfma_f32_16x16x32_bf16 v[150:153], v[8:11], v[120:123], v[150:153]
	v_mfma_f32_16x16x32_bf16 v[154:157], v[16:19], v[120:123], v[154:157]
	v_mfma_f32_16x16x32_bf16 v[158:161], v[8:11], v[128:131], v[4:7]
	v_mfma_f32_16x16x32_bf16 v[162:165], v[16:19], v[128:131], v[12:15]
	s_setprio 0
	s_setprio 1
	v_mfma_f32_16x16x32_bf16 v[4:7], v[20:23], v[36:39], 0
	v_mfma_f32_16x16x32_bf16 v[8:11], v[28:31], v[36:39], 0
	v_mfma_f32_16x16x32_bf16 v[12:15], v[20:23], v[52:55], 0
	v_mfma_f32_16x16x32_bf16 v[16:19], v[28:31], v[52:55], 0
	v_mfma_f32_16x16x32_bf16 v[36:39], v[20:23], v[116:119], 0
	v_mfma_f32_16x16x32_bf16 v[52:55], v[28:31], v[116:119], 0
	v_mfma_f32_16x16x32_bf16 v[20:23], v[20:23], v[124:127], 0
	v_mfma_f32_16x16x32_bf16 v[28:31], v[28:31], v[124:127], 0
	v_mfma_f32_16x16x32_bf16 v[116:119], v[24:27], v[44:47], v[4:7]
	v_mfma_f32_16x16x32_bf16 v[124:127], v[32:35], v[44:47], v[8:11]
	v_mfma_f32_16x16x32_bf16 v[174:177], v[24:27], v[120:123], v[36:39]
	v_mfma_f32_16x16x32_bf16 v[120:123], v[32:35], v[120:123], v[52:55]
	v_mfma_f32_16x16x32_bf16 v[178:181], v[24:27], v[128:131], v[20:23]
	v_mfma_f32_16x16x32_bf16 v[128:131], v[32:35], v[128:131], v[28:31]
	s_setprio 2
	s_barrier
	v_mfma_f32_16x16x32_bf16 v[166:169], v[24:27], v[60:63], v[12:15]
	v_mfma_f32_16x16x32_bf16 v[170:173], v[32:35], v[60:63], v[16:19]
	s_setprio 0
	s_add_i32 s51, 0, 0x18000
	v_add_u32_e32 v4, s51, v232
	s_add_i32 s71, 0, 0x1c000
	ds_read_b128 v[182:185], v4
	ds_read_b128 v[192:195], v4 offset:1024
	ds_read_b128 v[196:199], v4 offset:2048
	ds_read_b128 v[200:203], v4 offset:3072
	v_add_u32_e32 v4, s71, v232
	ds_read_b128 v[204:207], v4
	ds_read_b128 v[208:211], v4 offset:1024
	ds_read_b128 v[212:215], v4 offset:2048
	ds_read_b128 v[216:219], v4 offset:3072
	s_mov_b32 m0, s58
	ds_read_b128 v[44:47], v233 offset:32768
	ds_read_b128 v[52:55], v233 offset:33792
	ds_read_b128 v[60:63], v233 offset:34816
	ds_read_b128 v[220:223], v233 offset:35840
	ds_read_b128 v[224:227], v233 offset:36864
	ds_read_b128 v[234:237], v233 offset:37888
	ds_read_b128 v[238:241], v233 offset:38912
	ds_read_b128 v[242:245], v233 offset:39936
	global_load_lds_dwordx4 v132, s[26:27]
	s_mov_b32 m0, s59
	s_nop 0
	global_load_lds_dwordx4 v188, s[26:27]
	s_waitcnt vmcnt(8)
	s_waitcnt lgkmcnt(0)
	s_barrier
	s_setprio 1
	s_waitcnt lgkmcnt(0)
	v_mfma_f32_16x16x32_bf16 v[4:7], v[182:185], v[44:47], v[68:71]
	v_mfma_f32_16x16x32_bf16 v[8:11], v[196:199], v[44:47], v[72:75]
	v_mfma_f32_16x16x32_bf16 v[12:15], v[182:185], v[60:63], v[76:79]
	v_mfma_f32_16x16x32_bf16 v[16:19], v[196:199], v[60:63], v[80:83]
	v_mfma_f32_16x16x32_bf16 v[20:23], v[182:185], v[224:227], v[84:87]
	v_mfma_f32_16x16x32_bf16 v[24:27], v[196:199], v[224:227], v[88:91]
	v_mfma_f32_16x16x32_bf16 v[28:31], v[182:185], v[238:241], v[92:95]
	v_mfma_f32_16x16x32_bf16 v[32:35], v[196:199], v[238:241], v[96:99]
	v_mfma_f32_16x16x32_bf16 v[4:7], v[192:195], v[52:55], v[4:7]
	v_mfma_f32_16x16x32_bf16 v[8:11], v[200:203], v[52:55], v[8:11]
	v_mfma_f32_16x16x32_bf16 v[12:15], v[192:195], v[220:223], v[12:15]
	v_mfma_f32_16x16x32_bf16 v[16:19], v[200:203], v[220:223], v[16:19]
	v_mfma_f32_16x16x32_bf16 v[20:23], v[192:195], v[234:237], v[20:23]
	v_mfma_f32_16x16x32_bf16 v[24:27], v[200:203], v[234:237], v[24:27]
	v_mfma_f32_16x16x32_bf16 v[28:31], v[192:195], v[242:245], v[28:31]
	v_mfma_f32_16x16x32_bf16 v[32:35], v[200:203], v[242:245], v[32:35]
	s_setprio 0
	s_setprio 1
	v_mfma_f32_16x16x32_bf16 v[36:39], v[204:207], v[44:47], v[100:103]
	v_mfma_f32_16x16x32_bf16 v[40:43], v[212:215], v[44:47], v[40:43]
	v_mfma_f32_16x16x32_bf16 v[36:39], v[208:211], v[52:55], v[36:39]
	v_mfma_f32_16x16x32_bf16 v[40:43], v[216:219], v[52:55], v[40:43]
	v_mfma_f32_16x16x32_bf16 v[44:47], v[204:207], v[60:63], v[104:107]
	v_mfma_f32_16x16x32_bf16 v[48:51], v[212:215], v[60:63], v[48:51]
	v_mfma_f32_16x16x32_bf16 v[52:55], v[204:207], v[224:227], v[108:111]
	v_mfma_f32_16x16x32_bf16 v[56:59], v[212:215], v[224:227], v[56:59]
	v_mfma_f32_16x16x32_bf16 v[60:63], v[204:207], v[238:241], v[112:115]
	v_mfma_f32_16x16x32_bf16 v[64:67], v[212:215], v[238:241], v[64:67]
	v_mfma_f32_16x16x32_bf16 v[44:47], v[208:211], v[220:223], v[44:47]
	v_mfma_f32_16x16x32_bf16 v[48:51], v[216:219], v[220:223], v[48:51]
	v_mfma_f32_16x16x32_bf16 v[52:55], v[208:211], v[234:237], v[52:55]
	v_mfma_f32_16x16x32_bf16 v[56:59], v[216:219], v[234:237], v[56:59]
	s_setprio 2
	s_barrier
	v_mfma_f32_16x16x32_bf16 v[60:63], v[208:211], v[242:245], v[60:63]
	v_mfma_f32_16x16x32_bf16 v[64:67], v[216:219], v[242:245], v[64:67]
	s_setprio 0
	s_add_i32 s51, s51, s38
	v_lshl_add_u64 v[68:69], v[186:187], 0, s[24:25]
	s_mov_b32 m0, s51
	ds_read_b128 v[104:107], v233 offset:49152
	ds_read_b128 v[108:111], v233 offset:50176
	ds_read_b128 v[112:115], v233 offset:51200
	ds_read_b128 v[220:223], v233 offset:52224
	ds_read_b128 v[224:227], v233 offset:53248
	ds_read_b128 v[234:237], v233 offset:54272
	ds_read_b128 v[238:241], v233 offset:55296
	ds_read_b128 v[242:245], v233 offset:56320
	global_load_lds_dwordx4 v[68:69], off
	v_lshl_add_u64 v[68:69], v[246:247], 0, s[24:25]
	s_add_i32 m0, s51, 0x2000
	s_add_i32 s51, s71, s38
	global_load_lds_dwordx4 v[68:69], off
	s_mov_b32 m0, s51
	v_lshl_add_u64 v[68:69], v[248:249], 0, s[24:25]
	global_load_lds_dwordx4 v2, s[28:29]
	s_add_i32 m0, s51, 0x2000
	s_nop 0
	global_load_lds_dwordx4 v190, s[28:29]
	s_mov_b32 m0, s63
	s_nop 0
	global_load_lds_dwordx4 v[68:69], off
	v_lshl_add_u64 v[68:69], v[250:251], 0, s[24:25]
	s_mov_b32 m0, s64
	s_nop 0
	global_load_lds_dwordx4 v[68:69], off
	s_waitcnt vmcnt(8)
	s_waitcnt lgkmcnt(0)
	s_barrier
	s_setprio 1
	s_waitcnt lgkmcnt(0)
	v_mfma_f32_16x16x32_bf16 v[68:71], v[182:185], v[104:107], v[134:137]
	v_mfma_f32_16x16x32_bf16 v[72:75], v[196:199], v[104:107], v[138:141]
	v_mfma_f32_16x16x32_bf16 v[76:79], v[182:185], v[112:115], v[142:145]
	v_mfma_f32_16x16x32_bf16 v[80:83], v[196:199], v[112:115], v[146:149]
	v_mfma_f32_16x16x32_bf16 v[84:87], v[182:185], v[224:227], v[150:153]
	v_mfma_f32_16x16x32_bf16 v[88:91], v[196:199], v[224:227], v[154:157]
	v_mfma_f32_16x16x32_bf16 v[92:95], v[182:185], v[238:241], v[158:161]
	v_mfma_f32_16x16x32_bf16 v[96:99], v[196:199], v[238:241], v[162:165]
	v_mfma_f32_16x16x32_bf16 v[68:71], v[192:195], v[108:111], v[68:71]
	v_mfma_f32_16x16x32_bf16 v[72:75], v[200:203], v[108:111], v[72:75]
	v_mfma_f32_16x16x32_bf16 v[76:79], v[192:195], v[220:223], v[76:79]
	v_mfma_f32_16x16x32_bf16 v[80:83], v[200:203], v[220:223], v[80:83]
	v_mfma_f32_16x16x32_bf16 v[84:87], v[192:195], v[234:237], v[84:87]
	v_mfma_f32_16x16x32_bf16 v[88:91], v[200:203], v[234:237], v[88:91]
	v_mfma_f32_16x16x32_bf16 v[92:95], v[192:195], v[242:245], v[92:95]
	v_mfma_f32_16x16x32_bf16 v[96:99], v[200:203], v[242:245], v[96:99]
	s_setprio 0
	s_setprio 1
	v_mfma_f32_16x16x32_bf16 v[100:103], v[204:207], v[104:107], v[116:119]
	v_mfma_f32_16x16x32_bf16 v[104:107], v[212:215], v[104:107], v[124:127]
	v_mfma_f32_16x16x32_bf16 v[100:103], v[208:211], v[108:111], v[100:103]
	v_mfma_f32_16x16x32_bf16 v[104:107], v[216:219], v[108:111], v[104:107]
	v_mfma_f32_16x16x32_bf16 v[108:111], v[204:207], v[112:115], v[166:169]
	v_mfma_f32_16x16x32_bf16 v[112:115], v[212:215], v[112:115], v[170:173]
	v_mfma_f32_16x16x32_bf16 v[116:119], v[204:207], v[224:227], v[174:177]
	v_mfma_f32_16x16x32_bf16 v[120:123], v[212:215], v[224:227], v[120:123]
	v_mfma_f32_16x16x32_bf16 v[124:127], v[204:207], v[238:241], v[178:181]
	v_mfma_f32_16x16x32_bf16 v[128:131], v[212:215], v[238:241], v[128:131]
	v_mfma_f32_16x16x32_bf16 v[108:111], v[208:211], v[220:223], v[108:111]
	v_mfma_f32_16x16x32_bf16 v[112:115], v[216:219], v[220:223], v[112:115]
	v_mfma_f32_16x16x32_bf16 v[116:119], v[208:211], v[234:237], v[116:119]
	v_mfma_f32_16x16x32_bf16 v[120:123], v[216:219], v[234:237], v[120:123]
	s_setprio 2
	s_barrier
	v_mfma_f32_16x16x32_bf16 v[124:127], v[208:211], v[242:245], v[124:127]
	v_mfma_f32_16x16x32_bf16 v[128:131], v[216:219], v[242:245], v[128:131]
	s_setprio 0
	s_add_i32 s41, s41, 2
	s_cmp_ge_i32 s41, s40
	s_cbranch_scc0 .LBB0_2269
	v_mov_b32_e32 v192, v2
	s_branch .LBB0_2272

.LBB0_2273:
	s_add_u32 s12, s14, 0xfffc0080
	s_addc_u32 s13, s15, -1
	s_add_i32 s29, 0, 0x10000
	s_cmp_eq_u32 s28, 12
	s_cselect_b32 s17, s9, s13
	s_cselect_b32 s16, s8, s12
	s_cselect_b32 s13, s11, s27
	s_cselect_b32 s12, s10, s26
	s_add_i32 s51, 0, 0x14000
	v_add_u32_e32 v144, s29, v232
	v_add_u32_e32 v160, s51, v232
	s_waitcnt lgkmcnt(0)
	ds_read_b128 v[132:135], v144
	ds_read_b128 v[136:139], v144 offset:1024
	ds_read_b128 v[140:143], v144 offset:2048
	ds_read_b128 v[144:147], v144 offset:3072
	ds_read_b128 v[148:151], v160
	ds_read_b128 v[152:155], v160 offset:1024
	ds_read_b128 v[156:159], v160 offset:2048
	ds_read_b128 v[160:163], v160 offset:3072
	s_mov_b32 m0, s65
	v_add_u32_e32 v210, 0, v231
	ds_read_b128 v[164:167], v210
	ds_read_b128 v[168:171], v210 offset:1024
	ds_read_b128 v[172:175], v210 offset:2048
	ds_read_b128 v[176:179], v210 offset:3072
	ds_read_b128 v[180:183], v210 offset:4096
	ds_read_b128 v[184:187], v210 offset:5120
	ds_read_b128 v[194:197], v210 offset:6144
	ds_read_b128 v[198:201], v210 offset:7168
	global_load_lds_dwordx4 v2, s[14:15]
	s_mov_b32 m0, s66
	v_mov_b32_e32 v189, v3
	global_load_lds_dwordx4 v188, s[14:15]
	s_waitcnt vmcnt(8)
	s_waitcnt lgkmcnt(0)
	s_barrier
	s_setprio 1
	s_waitcnt lgkmcnt(0)
	v_mfma_f32_16x16x32_bf16 v[4:7], v[132:135], v[164:167], v[4:7]
	v_mfma_f32_16x16x32_bf16 v[4:7], v[136:139], v[168:171], v[4:7]
	v_mfma_f32_16x16x32_bf16 v[8:11], v[144:147], v[168:171], v[8:11]
	v_mfma_f32_16x16x32_bf16 v[8:11], v[140:143], v[164:167], v[8:11]
	v_mfma_f32_16x16x32_bf16 v[16:19], v[140:143], v[172:175], v[16:19]
	v_mfma_f32_16x16x32_bf16 v[16:19], v[144:147], v[176:179], v[16:19]
	v_mfma_f32_16x16x32_bf16 v[12:15], v[136:139], v[176:179], v[12:15]
	v_mfma_f32_16x16x32_bf16 v[12:15], v[132:135], v[172:175], v[12:15]
	v_mfma_f32_16x16x32_bf16 v[20:23], v[132:135], v[180:183], v[20:23]
	v_mfma_f32_16x16x32_bf16 v[20:23], v[136:139], v[184:187], v[20:23]
	v_mfma_f32_16x16x32_bf16 v[24:27], v[144:147], v[184:187], v[24:27]
	v_mfma_f32_16x16x32_bf16 v[24:27], v[140:143], v[180:183], v[24:27]
	v_mfma_f32_16x16x32_bf16 v[32:35], v[140:143], v[194:197], v[32:35]
	v_mfma_f32_16x16x32_bf16 v[32:35], v[144:147], v[198:201], v[32:35]
	v_mfma_f32_16x16x32_bf16 v[28:31], v[136:139], v[198:201], v[28:31]
	v_mfma_f32_16x16x32_bf16 v[28:31], v[132:135], v[194:197], v[28:31]
	s_setprio 0
	s_setprio 1
	v_mfma_f32_16x16x32_bf16 v[36:39], v[148:151], v[164:167], v[36:39]
	v_mfma_f32_16x16x32_bf16 v[36:39], v[152:155], v[168:171], v[36:39]
	v_mfma_f32_16x16x32_bf16 v[40:43], v[160:163], v[168:171], v[40:43]
	v_mfma_f32_16x16x32_bf16 v[40:43], v[156:159], v[164:167], v[40:43]
	v_mfma_f32_16x16x32_bf16 v[48:51], v[156:159], v[172:175], v[48:51]
	v_mfma_f32_16x16x32_bf16 v[48:51], v[160:163], v[176:179], v[48:51]
	v_mfma_f32_16x16x32_bf16 v[44:47], v[152:155], v[176:179], v[44:47]
	v_mfma_f32_16x16x32_bf16 v[44:47], v[148:151], v[172:175], v[44:47]
	v_mfma_f32_16x16x32_bf16 v[52:55], v[148:151], v[180:183], v[52:55]
	v_mfma_f32_16x16x32_bf16 v[52:55], v[152:155], v[184:187], v[52:55]
	v_mfma_f32_16x16x32_bf16 v[56:59], v[160:163], v[184:187], v[56:59]
	v_mfma_f32_16x16x32_bf16 v[56:59], v[156:159], v[180:183], v[56:59]
	v_mfma_f32_16x16x32_bf16 v[64:67], v[156:159], v[194:197], v[64:67]
	v_mfma_f32_16x16x32_bf16 v[64:67], v[160:163], v[198:201], v[64:67]
	s_setprio 2
	s_barrier
	v_mfma_f32_16x16x32_bf16 v[60:63], v[152:155], v[198:201], v[60:63]
	v_mfma_f32_16x16x32_bf16 v[60:63], v[148:151], v[194:197], v[60:63]
	s_setprio 0
	s_add_i32 s29, s29, s38
	s_mov_b32 m0, s29
	ds_read_b128 v[164:167], v210 offset:16384
	ds_read_b128 v[168:171], v210 offset:17408
	ds_read_b128 v[172:175], v210 offset:18432
	ds_read_b128 v[176:179], v210 offset:19456
	ds_read_b128 v[180:183], v210 offset:20480
	ds_read_b128 v[184:187], v210 offset:21504
	ds_read_b128 v[194:197], v210 offset:22528
	ds_read_b128 v[198:201], v210 offset:23552
	global_load_lds_dwordx4 v192, s[12:13]
	s_add_i32 m0, s29, 0x2000
	s_add_u32 s40, s12, 0x100000
	s_addc_u32 s41, s13, 0
	s_add_i32 s29, s51, s38
	global_load_lds_dwordx4 v190, s[12:13]
	s_mov_b32 m0, s29
	v_mov_b32_e32 v193, v3
	global_load_lds_dwordx4 v192, s[40:41]
	s_add_i32 m0, s29, 0x2000
	v_mov_b32_e32 v191, v3
	global_load_lds_dwordx4 v190, s[40:41]
	s_mov_b32 m0, s56
	v_lshl_add_u64 v[202:203], s[12:13], 0, v[192:193]
	global_load_lds_dwordx4 v2, s[16:17]
	s_mov_b32 m0, s57
	v_lshl_add_u64 v[204:205], s[12:13], 0, v[190:191]
	global_load_lds_dwordx4 v188, s[16:17]
	s_waitcnt vmcnt(8)
	s_waitcnt lgkmcnt(0)
	v_lshl_add_u64 v[206:207], s[16:17], 0, v[2:3]
	v_lshl_add_u64 v[208:209], s[16:17], 0, v[188:189]
	s_barrier
	s_setprio 1
	s_waitcnt lgkmcnt(0)
	v_mfma_f32_16x16x32_bf16 v[68:71], v[132:135], v[164:167], v[68:71]
	v_mfma_f32_16x16x32_bf16 v[68:71], v[136:139], v[168:171], v[68:71]
	v_mfma_f32_16x16x32_bf16 v[72:75], v[144:147], v[168:171], v[72:75]
	v_mfma_f32_16x16x32_bf16 v[72:75], v[140:143], v[164:167], v[72:75]
	v_mfma_f32_16x16x32_bf16 v[80:83], v[140:143], v[172:175], v[80:83]
	v_mfma_f32_16x16x32_bf16 v[80:83], v[144:147], v[176:179], v[80:83]
	v_mfma_f32_16x16x32_bf16 v[76:79], v[136:139], v[176:179], v[76:79]
	v_mfma_f32_16x16x32_bf16 v[76:79], v[132:135], v[172:175], v[76:79]
	v_mfma_f32_16x16x32_bf16 v[84:87], v[132:135], v[180:183], v[84:87]
	v_mfma_f32_16x16x32_bf16 v[84:87], v[136:139], v[184:187], v[84:87]
	v_mfma_f32_16x16x32_bf16 v[88:91], v[144:147], v[184:187], v[88:91]
	v_mfma_f32_16x16x32_bf16 v[88:91], v[140:143], v[180:183], v[88:91]
	v_mfma_f32_16x16x32_bf16 v[96:99], v[140:143], v[194:197], v[96:99]
	v_mfma_f32_16x16x32_bf16 v[96:99], v[144:147], v[198:201], v[96:99]
	v_mfma_f32_16x16x32_bf16 v[92:95], v[136:139], v[198:201], v[92:95]
	v_mfma_f32_16x16x32_bf16 v[92:95], v[132:135], v[194:197], v[92:95]
	s_setprio 0
	s_setprio 1
	v_mfma_f32_16x16x32_bf16 v[100:103], v[148:151], v[164:167], v[100:103]
	v_mfma_f32_16x16x32_bf16 v[100:103], v[152:155], v[168:171], v[100:103]
	v_mfma_f32_16x16x32_bf16 v[104:107], v[160:163], v[168:171], v[104:107]
	v_mfma_f32_16x16x32_bf16 v[104:107], v[156:159], v[164:167], v[104:107]
	v_mfma_f32_16x16x32_bf16 v[112:115], v[156:159], v[172:175], v[112:115]
	v_mfma_f32_16x16x32_bf16 v[112:115], v[160:163], v[176:179], v[112:115]
	v_mfma_f32_16x16x32_bf16 v[108:111], v[152:155], v[176:179], v[108:111]
	v_mfma_f32_16x16x32_bf16 v[108:111], v[148:151], v[172:175], v[108:111]
	v_mfma_f32_16x16x32_bf16 v[116:119], v[148:151], v[180:183], v[116:119]
	v_mfma_f32_16x16x32_bf16 v[116:119], v[152:155], v[184:187], v[116:119]
	v_mfma_f32_16x16x32_bf16 v[120:123], v[160:163], v[184:187], v[120:123]
	v_mfma_f32_16x16x32_bf16 v[120:123], v[156:159], v[180:183], v[120:123]
	v_mfma_f32_16x16x32_bf16 v[128:131], v[156:159], v[194:197], v[128:131]
	v_mfma_f32_16x16x32_bf16 v[128:131], v[160:163], v[198:201], v[128:131]
	s_setprio 2
	s_barrier
	v_mfma_f32_16x16x32_bf16 v[124:127], v[152:155], v[198:201], v[124:127]
	v_mfma_f32_16x16x32_bf16 v[124:127], v[148:151], v[194:197], v[124:127]
	s_setprio 0
	s_add_i32 s29, 0, 0x18000
	s_add_i32 s40, 0, 0x1c000
	v_add_u32_e32 v144, s29, v232
	v_add_u32_e32 v160, s40, v232
	ds_read_b128 v[132:135], v144
	ds_read_b128 v[136:139], v144 offset:1024
	ds_read_b128 v[140:143], v144 offset:2048
	ds_read_b128 v[144:147], v144 offset:3072
	ds_read_b128 v[148:151], v160
	ds_read_b128 v[152:155], v160 offset:1024
	ds_read_b128 v[156:159], v160 offset:2048
	ds_read_b128 v[160:163], v160 offset:3072
	s_add_u32 s16, s16, 0x40000
	s_addc_u32 s17, s17, 0
	s_mov_b32 m0, s58
	ds_read_b128 v[164:167], v210 offset:32768
	ds_read_b128 v[168:171], v210 offset:33792
	ds_read_b128 v[172:175], v210 offset:34816
	ds_read_b128 v[176:179], v210 offset:35840
	ds_read_b128 v[180:183], v210 offset:36864
	ds_read_b128 v[184:187], v210 offset:37888
	ds_read_b128 v[194:197], v210 offset:38912
	ds_read_b128 v[198:201], v210 offset:39936
	global_load_lds_dwordx4 v2, s[16:17]
	s_mov_b32 m0, s59
	s_nop 0
	global_load_lds_dwordx4 v188, s[16:17]
	s_waitcnt vmcnt(8)
	s_waitcnt lgkmcnt(0)
	s_barrier
	s_setprio 1
	s_waitcnt lgkmcnt(0)
	v_mfma_f32_16x16x32_bf16 v[4:7], v[132:135], v[164:167], v[4:7]
	v_mfma_f32_16x16x32_bf16 v[4:7], v[136:139], v[168:171], v[4:7]
	v_mfma_f32_16x16x32_bf16 v[8:11], v[144:147], v[168:171], v[8:11]
	v_mfma_f32_16x16x32_bf16 v[8:11], v[140:143], v[164:167], v[8:11]
	v_mfma_f32_16x16x32_bf16 v[16:19], v[140:143], v[172:175], v[16:19]
	v_mfma_f32_16x16x32_bf16 v[16:19], v[144:147], v[176:179], v[16:19]
	v_mfma_f32_16x16x32_bf16 v[12:15], v[136:139], v[176:179], v[12:15]
	v_mfma_f32_16x16x32_bf16 v[12:15], v[132:135], v[172:175], v[12:15]
	v_mfma_f32_16x16x32_bf16 v[20:23], v[132:135], v[180:183], v[20:23]
	v_mfma_f32_16x16x32_bf16 v[20:23], v[136:139], v[184:187], v[20:23]
	v_mfma_f32_16x16x32_bf16 v[24:27], v[144:147], v[184:187], v[24:27]
	v_mfma_f32_16x16x32_bf16 v[24:27], v[140:143], v[180:183], v[24:27]
	v_mfma_f32_16x16x32_bf16 v[32:35], v[140:143], v[194:197], v[32:35]
	v_mfma_f32_16x16x32_bf16 v[32:35], v[144:147], v[198:201], v[32:35]
	v_mfma_f32_16x16x32_bf16 v[28:31], v[136:139], v[198:201], v[28:31]
	v_mfma_f32_16x16x32_bf16 v[28:31], v[132:135], v[194:197], v[28:31]
	s_setprio 0
	s_setprio 1
	v_mfma_f32_16x16x32_bf16 v[36:39], v[148:151], v[164:167], v[36:39]
	v_mfma_f32_16x16x32_bf16 v[36:39], v[152:155], v[168:171], v[36:39]
	v_mfma_f32_16x16x32_bf16 v[40:43], v[160:163], v[168:171], v[40:43]
	v_mfma_f32_16x16x32_bf16 v[40:43], v[156:159], v[164:167], v[40:43]
	v_mfma_f32_16x16x32_bf16 v[48:51], v[156:159], v[172:175], v[48:51]
	v_mfma_f32_16x16x32_bf16 v[48:51], v[160:163], v[176:179], v[48:51]
	v_mfma_f32_16x16x32_bf16 v[44:47], v[152:155], v[176:179], v[44:47]
	v_mfma_f32_16x16x32_bf16 v[44:47], v[148:151], v[172:175], v[44:47]
	v_mfma_f32_16x16x32_bf16 v[52:55], v[148:151], v[180:183], v[52:55]
	v_mfma_f32_16x16x32_bf16 v[52:55], v[152:155], v[184:187], v[52:55]
	v_mfma_f32_16x16x32_bf16 v[56:59], v[160:163], v[184:187], v[56:59]
	v_mfma_f32_16x16x32_bf16 v[56:59], v[156:159], v[180:183], v[56:59]
	v_mfma_f32_16x16x32_bf16 v[64:67], v[156:159], v[194:197], v[64:67]
	v_mfma_f32_16x16x32_bf16 v[64:67], v[160:163], v[198:201], v[64:67]
	s_setprio 2
	s_barrier
	v_mfma_f32_16x16x32_bf16 v[60:63], v[152:155], v[198:201], v[60:63]
	v_mfma_f32_16x16x32_bf16 v[60:63], v[148:151], v[194:197], v[60:63]
	s_setprio 0
	s_add_i32 s16, s29, s38
	v_lshl_add_u64 v[202:203], v[202:203], 0, s[86:87]
	s_mov_b32 m0, s16
	ds_read_b128 v[164:167], v210 offset:49152
	ds_read_b128 v[168:171], v210 offset:50176
	ds_read_b128 v[172:175], v210 offset:51200
	ds_read_b128 v[176:179], v210 offset:52224
	ds_read_b128 v[180:183], v210 offset:53248
	ds_read_b128 v[184:187], v210 offset:54272
	ds_read_b128 v[194:197], v210 offset:55296
	ds_read_b128 v[198:201], v210 offset:56320
	global_load_lds_dwordx4 v[202:203], off
	s_add_i32 m0, s16, 0x2000
	s_add_u32 s12, s12, 0x100080
	v_lshl_add_u64 v[202:203], v[204:205], 0, s[86:87]
	s_addc_u32 s13, s13, 0
	s_add_i32 s16, s40, s38
	global_load_lds_dwordx4 v[202:203], off
	s_mov_b32 m0, s16
	v_lshl_add_u64 v[202:203], v[206:207], 0, s[86:87]
	global_load_lds_dwordx4 v192, s[12:13]
	s_add_i32 m0, s16, 0x2000
	s_nop 0
	global_load_lds_dwordx4 v190, s[12:13]
	s_mov_b32 m0, s63
	s_nop 0
	global_load_lds_dwordx4 v[202:203], off
	v_lshl_add_u64 v[202:203], v[208:209], 0, s[86:87]
	s_mov_b32 m0, s64
	s_nop 0
	global_load_lds_dwordx4 v[202:203], off
	s_waitcnt vmcnt(8)
	s_waitcnt lgkmcnt(0)
	s_barrier
	s_setprio 1
	s_waitcnt lgkmcnt(0)
	v_mfma_f32_16x16x32_bf16 v[68:71], v[132:135], v[164:167], v[68:71]
	v_mfma_f32_16x16x32_bf16 v[68:71], v[136:139], v[168:171], v[68:71]
	v_mfma_f32_16x16x32_bf16 v[72:75], v[144:147], v[168:171], v[72:75]
	v_mfma_f32_16x16x32_bf16 v[72:75], v[140:143], v[164:167], v[72:75]
	v_mfma_f32_16x16x32_bf16 v[80:83], v[140:143], v[172:175], v[80:83]
	v_mfma_f32_16x16x32_bf16 v[80:83], v[144:147], v[176:179], v[80:83]
	v_mfma_f32_16x16x32_bf16 v[76:79], v[136:139], v[176:179], v[76:79]
	v_mfma_f32_16x16x32_bf16 v[76:79], v[132:135], v[172:175], v[76:79]
	v_mfma_f32_16x16x32_bf16 v[84:87], v[132:135], v[180:183], v[84:87]
	v_mfma_f32_16x16x32_bf16 v[84:87], v[136:139], v[184:187], v[84:87]
	v_mfma_f32_16x16x32_bf16 v[88:91], v[144:147], v[184:187], v[88:91]
	v_mfma_f32_16x16x32_bf16 v[88:91], v[140:143], v[180:183], v[88:91]
	v_mfma_f32_16x16x32_bf16 v[96:99], v[140:143], v[194:197], v[96:99]
	v_mfma_f32_16x16x32_bf16 v[96:99], v[144:147], v[198:201], v[96:99]
	v_mfma_f32_16x16x32_bf16 v[92:95], v[136:139], v[198:201], v[92:95]
	v_mfma_f32_16x16x32_bf16 v[92:95], v[132:135], v[194:197], v[92:95]
	s_setprio 0
	s_setprio 1
	v_mfma_f32_16x16x32_bf16 v[100:103], v[148:151], v[164:167], v[100:103]
	v_mfma_f32_16x16x32_bf16 v[100:103], v[152:155], v[168:171], v[100:103]
	v_mfma_f32_16x16x32_bf16 v[104:107], v[160:163], v[168:171], v[104:107]
	v_mfma_f32_16x16x32_bf16 v[104:107], v[156:159], v[164:167], v[104:107]
	v_mfma_f32_16x16x32_bf16 v[112:115], v[156:159], v[172:175], v[112:115]
	v_mfma_f32_16x16x32_bf16 v[112:115], v[160:163], v[176:179], v[112:115]
	v_mfma_f32_16x16x32_bf16 v[108:111], v[152:155], v[176:179], v[108:111]
	v_mfma_f32_16x16x32_bf16 v[108:111], v[148:151], v[172:175], v[108:111]
	v_mfma_f32_16x16x32_bf16 v[116:119], v[148:151], v[180:183], v[116:119]
	v_mfma_f32_16x16x32_bf16 v[116:119], v[152:155], v[184:187], v[116:119]
	v_mfma_f32_16x16x32_bf16 v[120:123], v[160:163], v[184:187], v[120:123]
	v_mfma_f32_16x16x32_bf16 v[120:123], v[156:159], v[180:183], v[120:123]
	v_mfma_f32_16x16x32_bf16 v[128:131], v[156:159], v[194:197], v[128:131]
	v_mfma_f32_16x16x32_bf16 v[128:131], v[160:163], v[198:201], v[128:131]
	s_setprio 2
	s_barrier
	v_mfma_f32_16x16x32_bf16 v[124:127], v[152:155], v[198:201], v[124:127]
	v_mfma_f32_16x16x32_bf16 v[124:127], v[148:151], v[194:197], v[124:127]
	s_setprio 0
	s_add_i32 s28, s28, 2
	s_add_u32 s14, s14, 0x100
	s_addc_u32 s15, s15, 0
	s_add_u32 s26, s26, 0x100
	s_addc_u32 s27, s27, 0
	s_cmp_gt_u32 s28, 13
	s_cbranch_scc0 .LBB0_2273
	s_and_b64 vcc, exec, s[48:49]
	s_cbranch_vccz .LBB0_2276
	s_barrier
